# GEMM K-loop priority asymmetric by workgroup half (blockIdx<256: prio 3, else 2), epilogue prio 1, reset at grid barrier
# baseline (speedup 1.0000x reference)
.LBB0_146:
	s_ashr_i32 s8, s10, 3
	s_lshl_b32 s11, s8, 1
	s_and_b32 s9, s8, -16
	s_and_b32 s11, s11, 14
	s_or_b32 s9, s11, s9
	s_bfe_u32 s11, s8, 0x10003
	s_or_b32 s9, s9, s11
	s_cmp_lt_i32 s8, 0
	s_cselect_b32 s8, s9, s8
	s_lshl_b32 s9, s10, 5
	s_and_b32 s9, s9, 0xe0
	s_add_i32 s8, s8, s9
	s_ashr_i32 s9, s8, 31
	s_lshr_b32 s9, s9, 27
	s_add_i32 s9, s8, s9
	s_and_b32 s11, s9, 0xffffffe0
	s_sub_i32 s8, s8, s11
	s_ashr_i32 s11, s8, 31
	s_lshr_b32 s11, s11, 29
	s_add_i32 s11, s8, s11
	s_ashr_i32 s12, s11, 3
	s_lshl_b32 s9, s9, 5
	s_and_b32 s9, s9, 0xfffffc00
	s_lshl_b32 s11, s12, 8
	s_add_i32 s11, s11, s9
	s_lshl_b32 s9, s12, 10
	s_lshl_b32 s8, s8, 7
	v_mov_b32_e32 v6, v188
	s_sub_i32 s12, s8, s9
	s_mov_b32 s13, 0x30000
	v_ashrrev_i32_e32 v7, 3, v6
	v_lshlrev_b32_e32 v4, 4, v6
	v_and_b32_e32 v176, 0x70, v4
	v_add_u32_e32 v4, s12, v7
	v_ashrrev_i32_e32 v5, 31, v4
	v_add_u32_e32 v0, s11, v7
	v_lshlrev_b64 v[4:5], 11, v[4:5]
	v_ashrrev_i32_e32 v1, 31, v0
	v_lshl_add_u64 v[4:5], s[4:5], 0, v[4:5]
	v_xor_b32_e32 v8, v7, v6
	v_lshlrev_b64 v[0:1], 11, v[0:1]
	v_lshl_add_u64 v[178:179], v[4:5], 0, v[176:177]
	v_lshlrev_b32_e32 v4, 4, v8
	v_lshl_add_u64 v[2:3], s[2:3], 0, v[0:1]
	v_and_b32_e32 v4, 0x70, v4
	v_lshl_add_u64 v[2:3], v[2:3], 0, v[176:177]
	v_lshl_or_b32 v176, v7, 7, v4
	v_lshrrev_b32_e32 v4, 4, v6
	v_and_b32_e32 v15, 7, v6
	v_bitop3_b32 v20, v4, v15, 3 bitop3:0x6c
	v_add_co_u32_e32 v4, vcc, s13, v178
	v_lshlrev_b32_e32 v12, 7, v6
	s_nop 0
	v_addc_co_u32_e32 v5, vcc, 0, v179, vcc
	v_bfe_u32 v14, v6, 4, 2
	v_add_co_u32_e32 v6, vcc, s14, v178
	s_mov_b32 s8, 0x70000
	s_nop 0
	v_addc_co_u32_e32 v7, vcc, 0, v179, vcc
	global_load_dwordx4 v[8:11], v[4:5], off
	global_load_dwordx4 v[16:19], v[6:7], off
	v_add_co_u32_e32 v4, vcc, s31, v178
	v_and_b32_e32 v13, 0xffffc780, v12
	s_nop 0
	v_addc_co_u32_e32 v5, vcc, 0, v179, vcc
	v_add_co_u32_e32 v6, vcc, s8, v2
	s_mov_b32 s8, 0x60000
	s_nop 0
	v_addc_co_u32_e32 v7, vcc, 0, v3, vcc
	global_load_dwordx4 v[32:35], v[4:5], off
	global_load_dwordx4 v[40:43], v[6:7], off
	v_add_co_u32_e32 v4, vcc, s8, v2
	s_mov_b32 s8, 0x50000
	s_nop 0
	v_addc_co_u32_e32 v5, vcc, 0, v3, vcc
	v_add_co_u32_e32 v6, vcc, s8, v2
	v_and_b32_e32 v12, 0x2780, v12
	s_nop 0
	v_addc_co_u32_e32 v7, vcc, 0, v3, vcc
	global_load_dwordx4 v[60:63], v[4:5], off
	global_load_dwordx4 v[68:71], v[6:7], off
	v_add_co_u32_e32 v4, vcc, 0x40000, v2
	v_bitop3_b32 v14, v14, v15, 4 bitop3:0x36
	s_nop 0
	v_addc_co_u32_e32 v5, vcc, 0, v3, vcc
	v_add_co_u32_e32 v6, vcc, s13, v2
	v_lshl_or_b32 v0, v15, 4, v0
	s_nop 0
	v_addc_co_u32_e32 v7, vcc, 0, v3, vcc
	global_load_dwordx4 v[80:83], v[4:5], off
	global_load_dwordx4 v[88:91], v[6:7], off
	v_add_co_u32_e32 v4, vcc, s14, v2
	v_mov_b32_e32 v140, 0
	s_nop 0
	v_addc_co_u32_e32 v5, vcc, 0, v3, vcc
	v_add_co_u32_e32 v6, vcc, 0x10000, v2
	v_lshl_add_u64 v[180:181], s[34:35], 0, v[0:1]
	s_nop 0
	v_addc_co_u32_e32 v7, vcc, 0, v3, vcc
	global_load_dwordx4 v[104:107], v[4:5], off
	global_load_dwordx4 v[112:115], v[6:7], off
	global_load_dwordx4 v[56:59], v[178:179], off
	global_load_dwordx4 v[116:119], v[2:3], off
	v_lshlrev_b32_e32 v2, 4, v20
	v_or_b32_e32 v185, v13, v2
	v_or_b32_e32 v184, v12, v2
	v_lshlrev_b32_e32 v2, 4, v14
	v_or_b32_e32 v183, v13, v2
	v_or_b32_e32 v182, v12, v2
	s_mov_b64 s[8:9], 0
	v_mov_b32_e32 v141, v140
	v_mov_b32_e32 v142, v140
	v_mov_b32_e32 v143, v140
	v_mov_b32_e32 v0, v140
	v_mov_b32_e32 v1, v140
	v_mov_b32_e32 v2, v140
	v_mov_b32_e32 v3, v140
	v_mov_b32_e32 v4, v140
	v_mov_b32_e32 v5, v140
	v_mov_b32_e32 v6, v140
	v_mov_b32_e32 v7, v140
	v_mov_b32_e32 v12, v140
	v_mov_b32_e32 v13, v140
	v_mov_b32_e32 v14, v140
	v_mov_b32_e32 v15, v140
	v_mov_b32_e32 v20, v140
	v_mov_b32_e32 v21, v140
	v_mov_b32_e32 v22, v140
	v_mov_b32_e32 v23, v140
	v_mov_b32_e32 v24, v140
	v_mov_b32_e32 v25, v140
	v_mov_b32_e32 v26, v140
	v_mov_b32_e32 v27, v140
	v_mov_b32_e32 v28, v140
	v_mov_b32_e32 v29, v140
	v_mov_b32_e32 v30, v140
	v_mov_b32_e32 v31, v140
	v_mov_b32_e32 v36, v140
	v_mov_b32_e32 v37, v140
	v_mov_b32_e32 v38, v140
	v_mov_b32_e32 v39, v140
	v_mov_b32_e32 v44, v140
	v_mov_b32_e32 v45, v140
	v_mov_b32_e32 v46, v140
	v_mov_b32_e32 v47, v140
	v_mov_b32_e32 v48, v140
	v_mov_b32_e32 v49, v140
	v_mov_b32_e32 v50, v140
	v_mov_b32_e32 v51, v140
	v_mov_b32_e32 v52, v140
	v_mov_b32_e32 v53, v140
	v_mov_b32_e32 v54, v140
	v_mov_b32_e32 v55, v140
	v_mov_b32_e32 v64, v140
	v_mov_b32_e32 v65, v140
	v_mov_b32_e32 v66, v140
	v_mov_b32_e32 v67, v140
	v_mov_b32_e32 v72, v140
	v_mov_b32_e32 v73, v140
	v_mov_b32_e32 v74, v140
	v_mov_b32_e32 v75, v140
	v_mov_b32_e32 v76, v140
	v_mov_b32_e32 v77, v140
	v_mov_b32_e32 v78, v140
	v_mov_b32_e32 v79, v140
	v_mov_b32_e32 v84, v140
	v_mov_b32_e32 v85, v140
	v_mov_b32_e32 v86, v140
	v_mov_b32_e32 v87, v140
	v_mov_b32_e32 v92, v140
	v_mov_b32_e32 v93, v140
	v_mov_b32_e32 v94, v140
	v_mov_b32_e32 v95, v140
	v_mov_b32_e32 v96, v140
	v_mov_b32_e32 v97, v140
	v_mov_b32_e32 v98, v140
	v_mov_b32_e32 v99, v140
	v_mov_b32_e32 v100, v140
	v_mov_b32_e32 v101, v140
	v_mov_b32_e32 v102, v140
	v_mov_b32_e32 v103, v140
	v_mov_b32_e32 v108, v140
	v_mov_b32_e32 v109, v140
	v_mov_b32_e32 v110, v140
	v_mov_b32_e32 v111, v140
	v_mov_b32_e32 v120, v140
	v_mov_b32_e32 v121, v140
	v_mov_b32_e32 v122, v140
	v_mov_b32_e32 v123, v140
	v_mov_b32_e32 v124, v140
	v_mov_b32_e32 v125, v140
	v_mov_b32_e32 v126, v140
	v_mov_b32_e32 v127, v140
	v_mov_b32_e32 v128, v140
	v_mov_b32_e32 v129, v140
	v_mov_b32_e32 v130, v140
	v_mov_b32_e32 v131, v140
	v_mov_b32_e32 v132, v140
	v_mov_b32_e32 v133, v140
	v_mov_b32_e32 v134, v140
	v_mov_b32_e32 v135, v140
	v_mov_b32_e32 v136, v140
	v_mov_b32_e32 v137, v140
	v_mov_b32_e32 v138, v140
	v_mov_b32_e32 v139, v140
	v_mov_b32_e32 v144, v140
	v_mov_b32_e32 v145, v140
	v_mov_b32_e32 v146, v140
	v_mov_b32_e32 v147, v140
	v_mov_b32_e32 v148, v140
	v_mov_b32_e32 v149, v140
	v_mov_b32_e32 v150, v140
	v_mov_b32_e32 v151, v140
	v_mov_b32_e32 v152, v140
	v_mov_b32_e32 v153, v140
	v_mov_b32_e32 v154, v140
	v_mov_b32_e32 v155, v140
	v_mov_b32_e32 v156, v140
	v_mov_b32_e32 v157, v140
	v_mov_b32_e32 v158, v140
	v_mov_b32_e32 v159, v140
	v_mov_b32_e32 v160, v140
	v_mov_b32_e32 v161, v140
	v_mov_b32_e32 v162, v140
	v_mov_b32_e32 v163, v140
	v_mov_b32_e32 v164, v140
	v_mov_b32_e32 v165, v140
	v_mov_b32_e32 v166, v140
	v_mov_b32_e32 v167, v140
	v_mov_b32_e32 v168, v140
	v_mov_b32_e32 v169, v140
	v_mov_b32_e32 v170, v140
	v_mov_b32_e32 v171, v140
	v_mov_b32_e32 v172, v140
	v_mov_b32_e32 v173, v140
	v_mov_b32_e32 v174, v140
	v_mov_b32_e32 v175, v140
	v_readlane_b32 vcc_lo, v253, 0
	s_cmpk_lt_u32 vcc_lo, 0x100
	s_cbranch_scc1 .Lprio_hi1
	s_setprio 2
	s_branch .Lprio_done1
.Lprio_hi1:
	s_setprio 3
.Lprio_done1:
	v_readlane_b32 s98, v253, 3
	v_readlane_b32 s99, v253, 4
	v_and_b32_e32 v224, 15, v188
	v_bfe_u32 v225, v188, 4, 2
	v_lshrrev_b32_e32 v226, 2, v224
	v_sub_u32_e32 v226, 0, v226
	v_and_b32_e32 v226, 3, v226
	v_xor_b32_e32 v225, v225, v226
	v_lshlrev_b32_e32 v225, 4, v225
	v_lshl_or_b32 v225, v224, 6, v225
	v_bfe_u32 v226, v188, 7, 1
	v_lshl_or_b32 v185, v226, 13, v225
	v_bfe_u32 v226, v188, 6, 1
	v_lshl_or_b32 v184, v226, 12, v225
	v_add_u32_e32 v184, 0x4000, v184
	v_lshrrev_b32_e32 v224, 3, v188
	v_bfe_u32 v225, v188, 2, 1
	v_lshrrev_b32_e32 v226, 2, v224
	v_sub_u32_e32 v226, 0, v226
	v_and_b32_e32 v226, 3, v226
	v_and_b32_e32 v227, 3, v188
	v_xor_b32_e32 v226, v227, v226
	v_lshlrev_b32_e32 v226, 4, v226
	v_xor_b32_e32 v224, v224, v225
	v_lshl_or_b32 v226, v224, 6, v226
	v_mul_u32_u24_e32 v225, 0x6000, v225
	v_add_u32_e32 v183, v225, v226
	s_mov_b32 m0, 0
	s_sub_u32 vcc_lo, s8, s98
	v_add_u32_e32 v186, vcc_lo, v178
	v_add_u32_e32 v187, vcc_lo, v180
	s_barrier
	s_waitcnt vmcnt(0)
	ds_write_b128 v183, v[116:119]
	ds_write_b128 v183, v[112:115] offset:2048
	ds_write_b128 v183, v[104:107] offset:4096
	ds_write_b128 v183, v[88:91] offset:6144
	ds_write_b128 v183, v[80:83] offset:8192
	ds_write_b128 v183, v[68:71] offset:10240
	ds_write_b128 v183, v[60:63] offset:12288
	ds_write_b128 v183, v[40:43] offset:14336
	ds_write_b128 v183, v[56:59] offset:16384
	ds_write_b128 v183, v[32:35] offset:18432
	ds_write_b128 v183, v[16:19] offset:20480
	ds_write_b128 v183, v[8:11] offset:22528
	v_cmp_gt_u32_e32 vcc, 0x6000, v183
	v_add_u32_e32 v182, 0xc000, v183
	v_add_u32_e32 v183, 0xffffa000, v183
	s_nop 0
	v_cndmask_b32_e32 v183, v183, v182, vcc
	v_add_u32_e32 v116, s26, v187
	global_load_dwordx4 v[116:119], v116, s[98:99] offset:128
	v_add_u32_e32 v112, s27, v187
	global_load_dwordx4 v[112:115], v112, s[98:99] offset:128
	v_add_u32_e32 v104, s20, v187
	global_load_dwordx4 v[104:107], v104, s[98:99] offset:128
	v_add_u32_e32 v88, s21, v187
	global_load_dwordx4 v[88:91], v88, s[98:99] offset:128
	v_add_u32_e32 v80, s56, v187
	global_load_dwordx4 v[80:83], v80, s[98:99] offset:128
	v_add_u32_e32 v68, s57, v187
	global_load_dwordx4 v[68:71], v68, s[98:99] offset:128
	v_add_u32_e32 v60, s24, v187
	global_load_dwordx4 v[60:63], v60, s[98:99] offset:128
	v_add_u32_e32 v40, s96, v187
	global_load_dwordx4 v[40:43], v40, s[98:99] offset:128
	v_mov_b32_e32 v56, v186
	global_load_dwordx4 v[56:59], v56, s[98:99] offset:128
	v_add_u32_e32 v32, s31, v186
	global_load_dwordx4 v[32:35], v32, s[98:99] offset:128
	v_add_u32_e32 v16, s14, v186
	global_load_dwordx4 v[16:19], v16, s[98:99] offset:128
	v_add_u32_e32 v8, s13, v186
	global_load_dwordx4 v[8:11], v8, s[98:99] offset:128
	s_add_u32 s8, s8, 0x80
	s_addc_u32 s9, s9, 0
.LBB0_147:
	s_waitcnt lgkmcnt(0)
	s_barrier
	ds_read_b128 v[224:227], v184
	ds_read_b128 v[228:231], v184 offset:1024
	ds_read_b128 v[232:235], v184 offset:2048
	ds_read_b128 v[236:239], v184 offset:3072
	ds_read_b128 v[190:193], v185
	ds_read_b128 v[194:197], v185 offset:1024
	ds_read_b128 v[198:201], v185 offset:2048
	ds_read_b128 v[204:207], v185 offset:3072
	ds_read_b128 v[208:211], v185 offset:4096
	ds_read_b128 v[212:215], v185 offset:5120
	ds_read_b128 v[216:219], v185 offset:6144
	ds_read_b128 v[220:223], v185 offset:7168
	s_movk_i32 vcc_lo, 0x6000
	s_cmp_eq_u32 m0, 2
	s_cselect_b32 vcc_lo, 0xffff4000, vcc_lo
	s_add_u32 m0, m0, 1
	s_cmp_eq_u32 m0, 3
	s_cselect_b32 m0, 0, m0
	v_add_u32_e32 v185, vcc_lo, v185
	v_add_u32_e32 v184, vcc_lo, v184
	v_xor_b32_e32 v185, 64, v185
	v_xor_b32_e32 v184, 64, v184
	s_waitcnt lgkmcnt(7)
	v_mfma_f32_16x16x32_bf16 v[172:175], v[224:227], v[190:193], v[172:175]
	v_mfma_f32_16x16x32_bf16 v[168:171], v[228:231], v[190:193], v[168:171]
	v_mfma_f32_16x16x32_bf16 v[164:167], v[232:235], v[190:193], v[164:167]
	v_mfma_f32_16x16x32_bf16 v[160:163], v[236:239], v[190:193], v[160:163]
	ds_read_b128 v[190:193], v185
	s_waitcnt lgkmcnt(7)
	v_mfma_f32_16x16x32_bf16 v[156:159], v[224:227], v[194:197], v[156:159]
	v_mfma_f32_16x16x32_bf16 v[152:155], v[228:231], v[194:197], v[152:155]
	v_mfma_f32_16x16x32_bf16 v[148:151], v[232:235], v[194:197], v[148:151]
	v_mfma_f32_16x16x32_bf16 v[144:147], v[236:239], v[194:197], v[144:147]
	ds_read_b128 v[194:197], v185 offset:1024
	s_waitcnt lgkmcnt(7)
	v_mfma_f32_16x16x32_bf16 v[136:139], v[224:227], v[198:201], v[136:139]
	v_mfma_f32_16x16x32_bf16 v[132:135], v[228:231], v[198:201], v[132:135]
	v_mfma_f32_16x16x32_bf16 v[128:131], v[232:235], v[198:201], v[128:131]
	v_mfma_f32_16x16x32_bf16 v[124:127], v[236:239], v[198:201], v[124:127]
	ds_read_b128 v[198:201], v185 offset:2048
	s_waitcnt lgkmcnt(7)
	v_mfma_f32_16x16x32_bf16 v[120:123], v[224:227], v[204:207], v[120:123]
	v_mfma_f32_16x16x32_bf16 v[108:111], v[228:231], v[204:207], v[108:111]
	v_mfma_f32_16x16x32_bf16 v[100:103], v[232:235], v[204:207], v[100:103]
	v_mfma_f32_16x16x32_bf16 v[96:99], v[236:239], v[204:207], v[96:99]
	ds_read_b128 v[204:207], v185 offset:3072
	s_waitcnt lgkmcnt(7)
	v_mfma_f32_16x16x32_bf16 v[92:95], v[224:227], v[208:211], v[92:95]
	v_mfma_f32_16x16x32_bf16 v[84:87], v[228:231], v[208:211], v[84:87]
	v_mfma_f32_16x16x32_bf16 v[76:79], v[232:235], v[208:211], v[76:79]
	v_mfma_f32_16x16x32_bf16 v[72:75], v[236:239], v[208:211], v[72:75]
	ds_read_b128 v[208:211], v185 offset:4096
	s_waitcnt lgkmcnt(7)
	v_mfma_f32_16x16x32_bf16 v[64:67], v[224:227], v[212:215], v[64:67]
	v_mfma_f32_16x16x32_bf16 v[52:55], v[228:231], v[212:215], v[52:55]
	v_mfma_f32_16x16x32_bf16 v[48:51], v[232:235], v[212:215], v[48:51]
	v_mfma_f32_16x16x32_bf16 v[44:47], v[236:239], v[212:215], v[44:47]
	ds_read_b128 v[212:215], v185 offset:5120
	s_waitcnt lgkmcnt(7)
	v_mfma_f32_16x16x32_bf16 v[36:39], v[224:227], v[216:219], v[36:39]
	v_mfma_f32_16x16x32_bf16 v[28:31], v[228:231], v[216:219], v[28:31]
	v_mfma_f32_16x16x32_bf16 v[24:27], v[232:235], v[216:219], v[24:27]
	v_mfma_f32_16x16x32_bf16 v[20:23], v[236:239], v[216:219], v[20:23]
	ds_read_b128 v[216:219], v185 offset:6144
	s_waitcnt lgkmcnt(7)
	v_mfma_f32_16x16x32_bf16 v[12:15], v[224:227], v[220:223], v[12:15]
	v_mfma_f32_16x16x32_bf16 v[4:7], v[228:231], v[220:223], v[4:7]
	v_mfma_f32_16x16x32_bf16 v[0:3], v[232:235], v[220:223], v[0:3]
	v_mfma_f32_16x16x32_bf16 v[140:143], v[236:239], v[220:223], v[140:143]
	ds_read_b128 v[220:223], v185 offset:7168
	ds_read_b128 v[224:227], v184
	ds_read_b128 v[228:231], v184 offset:1024
	ds_read_b128 v[232:235], v184 offset:2048
	ds_read_b128 v[236:239], v184 offset:3072
	s_movk_i32 vcc_lo, 0x6000
	s_cmp_eq_u32 m0, 2
	s_cselect_b32 vcc_lo, 0xffff4000, vcc_lo
	s_add_u32 m0, m0, 1
	s_cmp_eq_u32 m0, 3
	s_cselect_b32 m0, 0, m0
	v_add_u32_e32 v185, vcc_lo, v185
	v_add_u32_e32 v184, vcc_lo, v184
	v_xor_b32_e32 v185, 64, v185
	v_xor_b32_e32 v184, 64, v184
	s_sub_u32 vcc_lo, s8, s98
	v_add_u32_e32 v186, vcc_lo, v178
	v_add_u32_e32 v187, vcc_lo, v180
	s_barrier
	s_waitcnt lgkmcnt(0)
	v_mfma_f32_16x16x32_bf16 v[172:175], v[224:227], v[190:193], v[172:175]
	s_waitcnt vmcnt(11)
	v_mfma_f32_16x16x32_bf16 v[168:171], v[228:231], v[190:193], v[168:171]
	ds_write_b128 v183, v[116:119]
	v_add_u32_e32 v116, s26, v187
	v_mfma_f32_16x16x32_bf16 v[164:167], v[232:235], v[190:193], v[164:167]
	global_load_dwordx4 v[116:119], v116, s[98:99] offset:128
	v_mfma_f32_16x16x32_bf16 v[160:163], v[236:239], v[190:193], v[160:163]
	s_waitcnt vmcnt(11)
	ds_write_b128 v183, v[112:115] offset:2048
	v_mfma_f32_16x16x32_bf16 v[156:159], v[224:227], v[194:197], v[156:159]
	v_add_u32_e32 v112, s27, v187
	v_mfma_f32_16x16x32_bf16 v[152:155], v[228:231], v[194:197], v[152:155]
	global_load_dwordx4 v[112:115], v112, s[98:99] offset:128
	s_waitcnt vmcnt(11)
	v_mfma_f32_16x16x32_bf16 v[148:151], v[232:235], v[194:197], v[148:151]
	ds_write_b128 v183, v[104:107] offset:4096
	v_mfma_f32_16x16x32_bf16 v[144:147], v[236:239], v[194:197], v[144:147]
	v_add_u32_e32 v104, s20, v187
	global_load_dwordx4 v[104:107], v104, s[98:99] offset:128
	v_mfma_f32_16x16x32_bf16 v[136:139], v[224:227], v[198:201], v[136:139]
	s_waitcnt vmcnt(11)
	v_mfma_f32_16x16x32_bf16 v[132:135], v[228:231], v[198:201], v[132:135]
	ds_write_b128 v183, v[88:91] offset:6144
	v_add_u32_e32 v88, s21, v187
	v_mfma_f32_16x16x32_bf16 v[128:131], v[232:235], v[198:201], v[128:131]
	global_load_dwordx4 v[88:91], v88, s[98:99] offset:128
	v_mfma_f32_16x16x32_bf16 v[124:127], v[236:239], v[198:201], v[124:127]
	s_waitcnt vmcnt(11)
	ds_write_b128 v183, v[80:83] offset:8192
	v_mfma_f32_16x16x32_bf16 v[120:123], v[224:227], v[204:207], v[120:123]
	v_add_u32_e32 v80, s56, v187
	v_mfma_f32_16x16x32_bf16 v[108:111], v[228:231], v[204:207], v[108:111]
	global_load_dwordx4 v[80:83], v80, s[98:99] offset:128
	s_waitcnt vmcnt(11)
	v_mfma_f32_16x16x32_bf16 v[100:103], v[232:235], v[204:207], v[100:103]
	ds_write_b128 v183, v[68:71] offset:10240
	v_mfma_f32_16x16x32_bf16 v[96:99], v[236:239], v[204:207], v[96:99]
	v_add_u32_e32 v68, s57, v187
	global_load_dwordx4 v[68:71], v68, s[98:99] offset:128
	v_mfma_f32_16x16x32_bf16 v[92:95], v[224:227], v[208:211], v[92:95]
	s_waitcnt vmcnt(11)
	v_mfma_f32_16x16x32_bf16 v[84:87], v[228:231], v[208:211], v[84:87]
	ds_write_b128 v183, v[60:63] offset:12288
	v_add_u32_e32 v60, s24, v187
	v_mfma_f32_16x16x32_bf16 v[76:79], v[232:235], v[208:211], v[76:79]
	global_load_dwordx4 v[60:63], v60, s[98:99] offset:128
	v_mfma_f32_16x16x32_bf16 v[72:75], v[236:239], v[208:211], v[72:75]
	s_waitcnt vmcnt(11)
	ds_write_b128 v183, v[40:43] offset:14336
	v_mfma_f32_16x16x32_bf16 v[64:67], v[224:227], v[212:215], v[64:67]
	v_add_u32_e32 v40, s96, v187
	v_mfma_f32_16x16x32_bf16 v[52:55], v[228:231], v[212:215], v[52:55]
	global_load_dwordx4 v[40:43], v40, s[98:99] offset:128
	s_waitcnt vmcnt(11)
	v_mfma_f32_16x16x32_bf16 v[48:51], v[232:235], v[212:215], v[48:51]
	ds_write_b128 v183, v[56:59] offset:16384
	v_mfma_f32_16x16x32_bf16 v[44:47], v[236:239], v[212:215], v[44:47]
	v_mov_b32_e32 v56, v186
	global_load_dwordx4 v[56:59], v56, s[98:99] offset:128
	v_mfma_f32_16x16x32_bf16 v[36:39], v[224:227], v[216:219], v[36:39]
	s_waitcnt vmcnt(11)
	v_mfma_f32_16x16x32_bf16 v[28:31], v[228:231], v[216:219], v[28:31]
	ds_write_b128 v183, v[32:35] offset:18432
	v_add_u32_e32 v32, s31, v186
	v_mfma_f32_16x16x32_bf16 v[24:27], v[232:235], v[216:219], v[24:27]
	global_load_dwordx4 v[32:35], v32, s[98:99] offset:128
	v_mfma_f32_16x16x32_bf16 v[20:23], v[236:239], v[216:219], v[20:23]
	s_waitcnt vmcnt(11)
	ds_write_b128 v183, v[16:19] offset:20480
	v_mfma_f32_16x16x32_bf16 v[12:15], v[224:227], v[220:223], v[12:15]
	v_add_u32_e32 v16, s14, v186
	v_mfma_f32_16x16x32_bf16 v[4:7], v[228:231], v[220:223], v[4:7]
	global_load_dwordx4 v[16:19], v16, s[98:99] offset:128
	s_waitcnt vmcnt(11)
	v_mfma_f32_16x16x32_bf16 v[0:3], v[232:235], v[220:223], v[0:3]
	ds_write_b128 v183, v[8:11] offset:22528
	v_mfma_f32_16x16x32_bf16 v[140:143], v[236:239], v[220:223], v[140:143]
	v_add_u32_e32 v8, s13, v186
	global_load_dwordx4 v[8:11], v8, s[98:99] offset:128
	v_cmp_gt_u32_e32 vcc, 0x6000, v183
	v_add_u32_e32 v182, 0xc000, v183
	v_add_u32_e32 v183, 0xffffa000, v183
	s_nop 0
	v_cndmask_b32_e32 v183, v183, v182, vcc
	s_add_u32 s8, s8, 0x80
	s_addc_u32 s9, s9, 0
	s_cmpk_lg_i32 s8, 0x780
	s_cbranch_scc1 .LBB0_147
	s_waitcnt lgkmcnt(0)
	s_barrier
	ds_read_b128 v[224:227], v184
	ds_read_b128 v[228:231], v184 offset:1024
	ds_read_b128 v[232:235], v184 offset:2048
	ds_read_b128 v[236:239], v184 offset:3072
	ds_read_b128 v[190:193], v185
	ds_read_b128 v[194:197], v185 offset:1024
	ds_read_b128 v[198:201], v185 offset:2048
	ds_read_b128 v[204:207], v185 offset:3072
	ds_read_b128 v[208:211], v185 offset:4096
	ds_read_b128 v[212:215], v185 offset:5120
	ds_read_b128 v[216:219], v185 offset:6144
	ds_read_b128 v[220:223], v185 offset:7168
	s_movk_i32 vcc_lo, 0x6000
	s_cmp_eq_u32 m0, 2
	s_cselect_b32 vcc_lo, 0xffff4000, vcc_lo
	s_add_u32 m0, m0, 1
	s_cmp_eq_u32 m0, 3
	s_cselect_b32 m0, 0, m0
	v_add_u32_e32 v185, vcc_lo, v185
	v_add_u32_e32 v184, vcc_lo, v184
	v_xor_b32_e32 v185, 64, v185
	v_xor_b32_e32 v184, 64, v184
	s_waitcnt lgkmcnt(7)
	v_mfma_f32_16x16x32_bf16 v[172:175], v[224:227], v[190:193], v[172:175]
	v_mfma_f32_16x16x32_bf16 v[168:171], v[228:231], v[190:193], v[168:171]
	v_mfma_f32_16x16x32_bf16 v[164:167], v[232:235], v[190:193], v[164:167]
	v_mfma_f32_16x16x32_bf16 v[160:163], v[236:239], v[190:193], v[160:163]
	ds_read_b128 v[190:193], v185
	s_waitcnt lgkmcnt(7)
	v_mfma_f32_16x16x32_bf16 v[156:159], v[224:227], v[194:197], v[156:159]
	v_mfma_f32_16x16x32_bf16 v[152:155], v[228:231], v[194:197], v[152:155]
	v_mfma_f32_16x16x32_bf16 v[148:151], v[232:235], v[194:197], v[148:151]
	v_mfma_f32_16x16x32_bf16 v[144:147], v[236:239], v[194:197], v[144:147]
	ds_read_b128 v[194:197], v185 offset:1024
	s_waitcnt lgkmcnt(7)
	v_mfma_f32_16x16x32_bf16 v[136:139], v[224:227], v[198:201], v[136:139]
	v_mfma_f32_16x16x32_bf16 v[132:135], v[228:231], v[198:201], v[132:135]
	v_mfma_f32_16x16x32_bf16 v[128:131], v[232:235], v[198:201], v[128:131]
	v_mfma_f32_16x16x32_bf16 v[124:127], v[236:239], v[198:201], v[124:127]
	ds_read_b128 v[198:201], v185 offset:2048
	s_waitcnt lgkmcnt(7)
	v_mfma_f32_16x16x32_bf16 v[120:123], v[224:227], v[204:207], v[120:123]
	v_mfma_f32_16x16x32_bf16 v[108:111], v[228:231], v[204:207], v[108:111]
	v_mfma_f32_16x16x32_bf16 v[100:103], v[232:235], v[204:207], v[100:103]
	v_mfma_f32_16x16x32_bf16 v[96:99], v[236:239], v[204:207], v[96:99]
	ds_read_b128 v[204:207], v185 offset:3072
	s_waitcnt lgkmcnt(7)
	v_mfma_f32_16x16x32_bf16 v[92:95], v[224:227], v[208:211], v[92:95]
	v_mfma_f32_16x16x32_bf16 v[84:87], v[228:231], v[208:211], v[84:87]
	v_mfma_f32_16x16x32_bf16 v[76:79], v[232:235], v[208:211], v[76:79]
	v_mfma_f32_16x16x32_bf16 v[72:75], v[236:239], v[208:211], v[72:75]
	ds_read_b128 v[208:211], v185 offset:4096
	s_waitcnt lgkmcnt(7)
	v_mfma_f32_16x16x32_bf16 v[64:67], v[224:227], v[212:215], v[64:67]
	v_mfma_f32_16x16x32_bf16 v[52:55], v[228:231], v[212:215], v[52:55]
	v_mfma_f32_16x16x32_bf16 v[48:51], v[232:235], v[212:215], v[48:51]
	v_mfma_f32_16x16x32_bf16 v[44:47], v[236:239], v[212:215], v[44:47]
	ds_read_b128 v[212:215], v185 offset:5120
	s_waitcnt lgkmcnt(7)
	v_mfma_f32_16x16x32_bf16 v[36:39], v[224:227], v[216:219], v[36:39]
	v_mfma_f32_16x16x32_bf16 v[28:31], v[228:231], v[216:219], v[28:31]
	v_mfma_f32_16x16x32_bf16 v[24:27], v[232:235], v[216:219], v[24:27]
	v_mfma_f32_16x16x32_bf16 v[20:23], v[236:239], v[216:219], v[20:23]
	ds_read_b128 v[216:219], v185 offset:6144
	s_waitcnt lgkmcnt(7)
	v_mfma_f32_16x16x32_bf16 v[12:15], v[224:227], v[220:223], v[12:15]
	v_mfma_f32_16x16x32_bf16 v[4:7], v[228:231], v[220:223], v[4:7]
	v_mfma_f32_16x16x32_bf16 v[0:3], v[232:235], v[220:223], v[0:3]
	v_mfma_f32_16x16x32_bf16 v[140:143], v[236:239], v[220:223], v[140:143]
	ds_read_b128 v[220:223], v185 offset:7168
	ds_read_b128 v[224:227], v184
	ds_read_b128 v[228:231], v184 offset:1024
	ds_read_b128 v[232:235], v184 offset:2048
	ds_read_b128 v[236:239], v184 offset:3072
	s_movk_i32 vcc_lo, 0x6000
	s_cmp_eq_u32 m0, 2
	s_cselect_b32 vcc_lo, 0xffff4000, vcc_lo
	s_add_u32 m0, m0, 1
	s_cmp_eq_u32 m0, 3
	s_cselect_b32 m0, 0, m0
	v_add_u32_e32 v185, vcc_lo, v185
	v_add_u32_e32 v184, vcc_lo, v184
	v_xor_b32_e32 v185, 64, v185
	v_xor_b32_e32 v184, 64, v184
	s_waitcnt lgkmcnt(0)
	v_mfma_f32_16x16x32_bf16 v[172:175], v[224:227], v[190:193], v[172:175]
	v_mfma_f32_16x16x32_bf16 v[168:171], v[228:231], v[190:193], v[168:171]
	v_mfma_f32_16x16x32_bf16 v[164:167], v[232:235], v[190:193], v[164:167]
	v_mfma_f32_16x16x32_bf16 v[160:163], v[236:239], v[190:193], v[160:163]
	v_mfma_f32_16x16x32_bf16 v[156:159], v[224:227], v[194:197], v[156:159]
	v_mfma_f32_16x16x32_bf16 v[152:155], v[228:231], v[194:197], v[152:155]
	v_mfma_f32_16x16x32_bf16 v[148:151], v[232:235], v[194:197], v[148:151]
	v_mfma_f32_16x16x32_bf16 v[144:147], v[236:239], v[194:197], v[144:147]
	v_mfma_f32_16x16x32_bf16 v[136:139], v[224:227], v[198:201], v[136:139]
	v_mfma_f32_16x16x32_bf16 v[132:135], v[228:231], v[198:201], v[132:135]
	v_mfma_f32_16x16x32_bf16 v[128:131], v[232:235], v[198:201], v[128:131]
	v_mfma_f32_16x16x32_bf16 v[124:127], v[236:239], v[198:201], v[124:127]
	v_mfma_f32_16x16x32_bf16 v[120:123], v[224:227], v[204:207], v[120:123]
	v_mfma_f32_16x16x32_bf16 v[108:111], v[228:231], v[204:207], v[108:111]
	v_mfma_f32_16x16x32_bf16 v[100:103], v[232:235], v[204:207], v[100:103]
	v_mfma_f32_16x16x32_bf16 v[96:99], v[236:239], v[204:207], v[96:99]
	v_mfma_f32_16x16x32_bf16 v[92:95], v[224:227], v[208:211], v[92:95]
	v_mfma_f32_16x16x32_bf16 v[84:87], v[228:231], v[208:211], v[84:87]
	v_mfma_f32_16x16x32_bf16 v[76:79], v[232:235], v[208:211], v[76:79]
	v_mfma_f32_16x16x32_bf16 v[72:75], v[236:239], v[208:211], v[72:75]
	v_mfma_f32_16x16x32_bf16 v[64:67], v[224:227], v[212:215], v[64:67]
	v_mfma_f32_16x16x32_bf16 v[52:55], v[228:231], v[212:215], v[52:55]
	v_mfma_f32_16x16x32_bf16 v[48:51], v[232:235], v[212:215], v[48:51]
	v_mfma_f32_16x16x32_bf16 v[44:47], v[236:239], v[212:215], v[44:47]
	v_mfma_f32_16x16x32_bf16 v[36:39], v[224:227], v[216:219], v[36:39]
	v_mfma_f32_16x16x32_bf16 v[28:31], v[228:231], v[216:219], v[28:31]
	v_mfma_f32_16x16x32_bf16 v[24:27], v[232:235], v[216:219], v[24:27]
	v_mfma_f32_16x16x32_bf16 v[20:23], v[236:239], v[216:219], v[20:23]
	v_mfma_f32_16x16x32_bf16 v[12:15], v[224:227], v[220:223], v[12:15]
	v_mfma_f32_16x16x32_bf16 v[4:7], v[228:231], v[220:223], v[4:7]
	v_mfma_f32_16x16x32_bf16 v[0:3], v[232:235], v[220:223], v[0:3]
	v_mfma_f32_16x16x32_bf16 v[140:143], v[236:239], v[220:223], v[140:143]
	v_lshrrev_b32_e32 v224, 4, v188
	v_and_b32_e32 v225, 7, v188
	v_bitop3_b32 v226, v224, v225, 3 bitop3:0x6c
	v_lshlrev_b32_e32 v227, 7, v188
	v_bfe_u32 v228, v188, 4, 2
	v_and_b32_e32 v229, 0xffffc780, v227
	v_and_b32_e32 v227, 0x2780, v227
	v_bitop3_b32 v228, v228, v225, 4 bitop3:0x36
	v_lshlrev_b32_e32 v226, 4, v226
	v_lshlrev_b32_e32 v228, 4, v228
	v_or_b32_e32 v185, v229, v226
	v_or_b32_e32 v184, v227, v226
	v_or_b32_e32 v183, v229, v228
	v_or_b32_e32 v182, v227, v228
	s_waitcnt vmcnt(0)
	s_setprio 1
	s_barrier
	s_waitcnt vmcnt(10)
	ds_write_b128 v176, v[116:119]
	s_waitcnt vmcnt(9)
	ds_write_b128 v176, v[112:115] offset:4096
	s_waitcnt vmcnt(8)
	ds_write_b128 v176, v[104:107] offset:8192
	s_waitcnt vmcnt(7)
	ds_write_b128 v176, v[88:91] offset:12288
	s_waitcnt vmcnt(6)
	ds_write_b128 v176, v[80:83] offset:16384
	s_waitcnt vmcnt(5)
	ds_write_b128 v176, v[68:71] offset:20480
	s_waitcnt vmcnt(4)
	ds_write_b128 v176, v[60:63] offset:24576
	s_waitcnt vmcnt(3)
	ds_write_b128 v176, v[40:43] offset:28672
	ds_write_b128 v176, v[56:59] offset:32768
	s_waitcnt vmcnt(2)
	ds_write_b128 v176, v[32:35] offset:36864
	s_waitcnt vmcnt(1)
	ds_write_b128 v176, v[16:19] offset:40960
	s_waitcnt vmcnt(0)
	ds_write_b128 v176, v[8:11] offset:45056
	s_waitcnt lgkmcnt(0)
	s_barrier
	ds_read_b128 v[8:11], v185
	ds_read_b128 v[16:19], v185 offset:2048
	ds_read_b128 v[32:35], v185 offset:4096
	ds_read_b128 v[40:43], v185 offset:6144
	ds_read_b128 v[56:59], v185 offset:8192
	ds_read_b128 v[60:63], v185 offset:10240
	ds_read_b128 v[68:71], v185 offset:12288
	ds_read_b128 v[80:83], v185 offset:14336
	ds_read_b128 v[88:91], v184 offset:32768
	ds_read_b128 v[104:107], v184 offset:34816
	ds_read_b128 v[112:115], v184 offset:36864
	ds_read_b128 v[116:119], v184 offset:38912
	s_waitcnt lgkmcnt(3)
	v_mfma_f32_16x16x32_bf16 v[172:175], v[88:91], v[8:11], v[172:175]
	s_waitcnt lgkmcnt(2)
	v_mfma_f32_16x16x32_bf16 v[168:171], v[104:107], v[8:11], v[168:171]
	s_waitcnt lgkmcnt(1)
	v_mfma_f32_16x16x32_bf16 v[164:167], v[112:115], v[8:11], v[164:167]
	s_waitcnt lgkmcnt(0)
	v_mfma_f32_16x16x32_bf16 v[8:11], v[116:119], v[8:11], v[160:163]
	v_mfma_f32_16x16x32_bf16 v[156:159], v[88:91], v[16:19], v[156:159]
	v_mfma_f32_16x16x32_bf16 v[152:155], v[104:107], v[16:19], v[152:155]
	v_mfma_f32_16x16x32_bf16 v[148:151], v[112:115], v[16:19], v[148:151]
	v_mfma_f32_16x16x32_bf16 v[16:19], v[116:119], v[16:19], v[144:147]
	v_mfma_f32_16x16x32_bf16 v[136:139], v[88:91], v[32:35], v[136:139]
	v_mfma_f32_16x16x32_bf16 v[132:135], v[104:107], v[32:35], v[132:135]
	v_mfma_f32_16x16x32_bf16 v[128:131], v[112:115], v[32:35], v[128:131]
	v_mfma_f32_16x16x32_bf16 v[32:35], v[116:119], v[32:35], v[124:127]
	v_mfma_f32_16x16x32_bf16 v[120:123], v[88:91], v[40:43], v[120:123]
	v_mfma_f32_16x16x32_bf16 v[108:111], v[104:107], v[40:43], v[108:111]
	v_mfma_f32_16x16x32_bf16 v[100:103], v[112:115], v[40:43], v[100:103]
	v_mfma_f32_16x16x32_bf16 v[40:43], v[116:119], v[40:43], v[96:99]
	v_mfma_f32_16x16x32_bf16 v[92:95], v[88:91], v[56:59], v[92:95]
	v_mfma_f32_16x16x32_bf16 v[84:87], v[104:107], v[56:59], v[84:87]
	v_mfma_f32_16x16x32_bf16 v[76:79], v[112:115], v[56:59], v[76:79]
	v_mfma_f32_16x16x32_bf16 v[56:59], v[116:119], v[56:59], v[72:75]
	v_mfma_f32_16x16x32_bf16 v[64:67], v[88:91], v[60:63], v[64:67]
	v_mfma_f32_16x16x32_bf16 v[52:55], v[104:107], v[60:63], v[52:55]
	v_mfma_f32_16x16x32_bf16 v[72:75], v[112:115], v[60:63], v[48:51]
	v_mfma_f32_16x16x32_bf16 v[60:63], v[116:119], v[60:63], v[44:47]
	v_mfma_f32_16x16x32_bf16 v[96:99], v[88:91], v[68:71], v[36:39]
	v_mfma_f32_16x16x32_bf16 v[28:31], v[104:107], v[68:71], v[28:31]
	v_mfma_f32_16x16x32_bf16 v[124:127], v[112:115], v[68:71], v[24:27]
	v_mfma_f32_16x16x32_bf16 v[20:23], v[116:119], v[68:71], v[20:23]
	v_mfma_f32_16x16x32_bf16 v[12:15], v[88:91], v[80:83], v[12:15]
	v_mfma_f32_16x16x32_bf16 v[4:7], v[104:107], v[80:83], v[4:7]
	v_mfma_f32_16x16x32_bf16 v[0:3], v[112:115], v[80:83], v[0:3]
	v_mfma_f32_16x16x32_bf16 v[68:71], v[116:119], v[80:83], v[140:143]
	ds_read_b128 v[24:27], v183
	ds_read_b128 v[36:39], v183 offset:2048
	ds_read_b128 v[44:47], v183 offset:4096
	ds_read_b128 v[80:83], v183 offset:6144
	ds_read_b128 v[88:91], v183 offset:8192
	ds_read_b128 v[104:107], v183 offset:10240
	ds_read_b128 v[112:115], v183 offset:12288
	ds_read_b128 v[116:119], v183 offset:14336
	ds_read_b128 v[140:143], v182 offset:32768
	ds_read_b128 v[144:147], v182 offset:34816
	ds_read_b128 v[160:163], v182 offset:36864
	ds_read_b128 v[178:181], v182 offset:38912
	s_waitcnt lgkmcnt(3)
	v_mfma_f32_16x16x32_bf16 v[172:175], v[140:143], v[24:27], v[172:175]
	v_mov_b32_e32 v49, v188
	v_cmp_lt_i32_e32 vcc, v189, v202
	s_waitcnt lgkmcnt(2)
	v_mfma_f32_16x16x32_bf16 v[168:171], v[144:147], v[24:27], v[168:171]
	v_mov_b32_e32 v48, v188
	v_readlane_b32 s8, v253, 24
	s_waitcnt lgkmcnt(1)
	v_mfma_f32_16x16x32_bf16 v[164:167], v[160:163], v[24:27], v[164:167]
	v_and_b32_e32 v50, 0xffffff80, v48
	v_add_u32_e32 v51, s11, v50
	v_and_or_b32 v50, v48, 64, s12
	s_waitcnt lgkmcnt(0)
	v_mfma_f32_16x16x32_bf16 v[8:11], v[178:181], v[24:27], v[8:11]
	v_bfe_u32 v26, v49, 4, 1
	v_cndmask_b32_e32 v24, v203, v189, vcc
	v_cmp_eq_u32_e32 vcc, 0, v26
	v_lshlrev_b32_e32 v186, 2, v24
	v_mfma_f32_16x16x32_bf16 v[182:185], v[178:181], v[36:39], v[16:19]
	v_and_or_b32 v48, v49, 15, v51
	v_ashrrev_i32_e32 v51, 31, v50
	v_lshl_add_u64 v[50:51], v[50:51], 1, s[6:7]
	s_nop 0
	s_nop 0
	s_nop 0
	s_nop 0
	s_nop 0
	s_nop 0
	s_nop 0
	s_nop 0
	v_lshlrev_b32_e32 v176, 5, v26
	v_lshrrev_b32_e32 v27, 1, v49
	v_lshl_add_u64 v[24:25], v[50:51], 0, v[176:177]
	v_and_b32_e32 v176, 16, v27
	v_ashrrev_i32_e32 v49, 31, v48
	v_mfma_f32_16x16x32_bf16 v[156:159], v[140:143], v[36:39], v[156:159]
	v_lshl_add_u64 v[50:51], v[24:25], 0, v[176:177]
	v_lshlrev_b64 v[24:25], 11, v[48:49]
	s_waitcnt lgkmcnt(0)
	s_nop 0
	v_mfma_f32_16x16x32_bf16 v[152:155], v[144:147], v[36:39], v[152:155]
	v_mov_b32_e32 v26, v172
	v_mov_b32_e32 v27, v168
	s_nop 1
	v_permlane16_swap_b32_e32 v26, v27
	s_waitcnt lgkmcnt(0)
	s_nop 0
	v_lshl_add_u64 v[24:25], v[50:51], 0, v[24:25]
	v_mfma_f32_16x16x32_bf16 v[148:151], v[160:163], v[36:39], v[148:151]
	v_mov_b32_e32 v16, v173
	v_mov_b32_e32 v36, v169
	s_nop 1
	v_permlane16_swap_b32_e32 v16, v36
	s_waitcnt lgkmcnt(0)
	s_nop 0
	v_cvt_pk_bf16_f32 v16, v26, v16
	v_mfma_f32_16x16x32_bf16 v[190:193], v[178:181], v[44:47], v[32:35]
	v_readlane_b32 s9, v253, 25
	s_nop 1
	v_mov_b32_e32 v17, v174
	v_mov_b32_e32 v32, v170
	s_nop 1
	v_permlane16_swap_b32_e32 v17, v32
	s_waitcnt lgkmcnt(0)
	s_nop 0
	v_mov_b32_e32 v18, v175
	v_mov_b32_e32 v19, v171
	s_nop 1
	v_permlane16_swap_b32_e32 v18, v19
	v_cvt_pk_bf16_f32 v17, v17, v18
	v_cvt_pk_bf16_f32 v18, v27, v36
	v_cvt_pk_bf16_f32 v19, v32, v19
	global_store_dwordx4 v[24:25], v[16:19], off
	v_mfma_f32_16x16x32_bf16 v[120:123], v[140:143], v[80:83], v[120:123]
	s_nop 0
	s_nop 0
	s_nop 0
	s_nop 0
	s_nop 0
	s_nop 0
	s_nop 0
	s_nop 0
	s_nop 0
	v_mfma_f32_16x16x32_bf16 v[108:111], v[144:147], v[80:83], v[108:111]
	s_waitcnt lgkmcnt(0)
	s_nop 0
	v_mov_b32_e32 v26, v164
	v_mov_b32_e32 v16, v8
	s_nop 1
	v_permlane16_swap_b32_e32 v26, v16
	s_waitcnt lgkmcnt(0)
	s_nop 0
	v_mov_b32_e32 v8, v165
	v_mov_b32_e32 v17, v9
	s_nop 1
	v_permlane16_swap_b32_e32 v8, v17
	s_waitcnt lgkmcnt(0)
	s_nop 0
	v_mov_b32_e32 v9, v166
	v_mov_b32_e32 v18, v10
	s_nop 1
	v_permlane16_swap_b32_e32 v9, v18
	s_waitcnt lgkmcnt(0)
	s_nop 0
	v_mov_b32_e32 v10, v167
	s_nop 1
	v_permlane16_swap_b32_e32 v10, v11
	v_cvt_pk_bf16_f32 v8, v26, v8
	v_cvt_pk_bf16_f32 v9, v9, v10
	v_cvt_pk_bf16_f32 v10, v16, v17
	v_cvt_pk_bf16_f32 v11, v18, v11
	global_store_dwordx4 v[24:25], v[8:11], off offset:64
	v_mfma_f32_16x16x32_bf16 v[100:103], v[160:163], v[80:83], v[100:103]
	s_nop 0
	v_or_b32_e32 v8, 16, v48
	v_ashrrev_i32_e32 v9, 31, v8
	v_lshlrev_b64 v[8:9], 11, v[8:9]
	v_mfma_f32_16x16x32_bf16 v[80:83], v[178:181], v[80:83], v[40:43]
	s_nop 0
	s_nop 0
	s_nop 0
	v_mfma_f32_16x16x32_bf16 v[40:43], v[140:143], v[104:107], v[64:67]
	s_nop 0
	s_nop 1
	v_lshl_add_u64 v[64:65], v[50:51], 0, v[8:9]
	s_nop 0
	s_nop 0
	s_nop 0
	s_nop 0
	v_mfma_f32_16x16x32_bf16 v[136:139], v[140:143], v[44:47], v[136:139]
	s_waitcnt lgkmcnt(0)
	s_nop 0
	v_mfma_f32_16x16x32_bf16 v[132:135], v[144:147], v[44:47], v[132:135]
	v_mfma_f32_16x16x32_bf16 v[128:131], v[160:163], v[44:47], v[128:131]
	v_mfma_f32_16x16x32_bf16 v[44:47], v[144:147], v[104:107], v[52:55]
	v_mfma_f32_16x16x32_bf16 v[36:39], v[178:181], v[104:107], v[60:63]
	s_nop 1
	v_mov_b32_e32 v49, v156
	v_mov_b32_e32 v54, v152
	s_nop 1
	v_permlane16_swap_b32_e32 v49, v54
	s_waitcnt lgkmcnt(0)
	s_nop 0
	v_mov_b32_e32 v8, v157
	v_mov_b32_e32 v55, v153
	s_nop 1
	v_permlane16_swap_b32_e32 v8, v55
	s_nop 0
	v_mov_b32_e32 v53, v158
	v_mov_b32_e32 v60, v154
	s_nop 1
	v_permlane16_swap_b32_e32 v53, v60
	s_nop 0
	v_mov_b32_e32 v61, v159
	v_mov_b32_e32 v62, v155
	s_nop 1
	v_permlane16_swap_b32_e32 v61, v62
	v_cvt_pk_bf16_f32 v52, v49, v8
	v_cvt_pk_bf16_f32 v53, v53, v61
	v_cvt_pk_bf16_f32 v54, v54, v55
	v_cvt_pk_bf16_f32 v55, v60, v62
	v_mfma_f32_16x16x32_bf16 v[8:11], v[140:143], v[116:119], v[12:15]
	global_store_dwordx4 v[64:65], v[52:55], off
	s_nop 0
	s_nop 0
	v_mfma_f32_16x16x32_bf16 v[12:15], v[144:147], v[116:119], v[4:7]
	s_nop 0
	s_nop 0
	s_nop 0
	v_cndmask_b32_e32 v4, v148, v182, vcc
	ds_bpermute_b32 v54, v186, v4
	s_nop 0
	s_waitcnt lgkmcnt(1)
	s_nop 0
	v_mov_b32_e32 v60, v149
	v_mov_b32_e32 v49, v183
	s_nop 1
	v_permlane16_swap_b32_e32 v60, v49
	s_waitcnt lgkmcnt(1)
	s_nop 0
	s_waitcnt lgkmcnt(0)
	v_cndmask_b32_e32 v55, v54, v148, vcc
	v_cndmask_b32_e32 v54, v182, v54, vcc
	v_mov_b32_e32 v61, v150
	v_mov_b32_e32 v62, v184
	s_nop 1
	v_permlane16_swap_b32_e32 v61, v62
	s_waitcnt lgkmcnt(0)
	s_nop 0
	v_mov_b32_e32 v63, v151
	v_mov_b32_e32 v66, v185
	s_nop 1
	v_permlane16_swap_b32_e32 v63, v66
	v_cvt_pk_bf16_f32 v52, v55, v60
	v_cvt_pk_bf16_f32 v53, v61, v63
	v_cvt_pk_bf16_f32 v54, v54, v49
	v_cvt_pk_bf16_f32 v55, v62, v66
	global_store_dwordx4 v[64:65], v[52:55], off offset:64
	s_nop 0
	s_nop 0
	v_or_b32_e32 v52, 32, v48
	v_ashrrev_i32_e32 v53, 31, v52
	v_lshlrev_b64 v[52:53], 11, v[52:53]
	v_lshl_add_u64 v[60:61], v[50:51], 0, v[52:53]
	s_nop 0
	s_nop 0
	s_nop 0
	s_nop 0
	s_nop 0
	s_nop 0
	s_waitcnt lgkmcnt(0)
	s_nop 0
	v_mov_b32_e32 v55, v136
	v_mov_b32_e32 v49, v132
	s_nop 1
	v_permlane16_swap_b32_e32 v55, v49
	s_waitcnt lgkmcnt(0)
	s_nop 0
	v_mov_b32_e32 v62, v137
	v_mov_b32_e32 v63, v133
	s_nop 1
	v_permlane16_swap_b32_e32 v62, v63
	s_waitcnt lgkmcnt(0)
	s_nop 0
	v_mov_b32_e32 v64, v138
	v_mov_b32_e32 v65, v134
	s_nop 1
	v_permlane16_swap_b32_e32 v64, v65
	s_waitcnt lgkmcnt(0)
	s_nop 0
	v_mov_b32_e32 v53, v139
	v_mov_b32_e32 v66, v135
	s_nop 1
	v_permlane16_swap_b32_e32 v53, v66
	v_cvt_pk_bf16_f32 v52, v55, v62
	v_cvt_pk_bf16_f32 v53, v64, v53
	v_cvt_pk_bf16_f32 v54, v49, v63
	v_cvt_pk_bf16_f32 v55, v65, v66
	global_store_dwordx4 v[60:61], v[52:55], off
	s_nop 0
	s_nop 0
	s_nop 0
	s_nop 0
	s_nop 0
	s_nop 0
	s_nop 0
	s_nop 0
	s_waitcnt lgkmcnt(0)
	s_nop 0
	v_mov_b32_e32 v55, v128
	v_mov_b32_e32 v49, v190
	s_nop 1
	v_permlane16_swap_b32_e32 v55, v49
	s_waitcnt lgkmcnt(0)
	s_nop 0
	v_mov_b32_e32 v62, v129
	v_mov_b32_e32 v63, v191
	s_nop 1
	v_permlane16_swap_b32_e32 v62, v63
	s_waitcnt lgkmcnt(0)
	s_nop 0
	v_mov_b32_e32 v64, v130
	v_mov_b32_e32 v65, v192
	s_nop 1
	v_permlane16_swap_b32_e32 v64, v65
	s_waitcnt lgkmcnt(0)
	s_nop 0
	v_mov_b32_e32 v53, v131
	v_mov_b32_e32 v66, v193
	s_nop 1
	v_permlane16_swap_b32_e32 v53, v66
	v_cvt_pk_bf16_f32 v52, v55, v62
	v_cvt_pk_bf16_f32 v53, v64, v53
	v_cvt_pk_bf16_f32 v54, v49, v63
	v_cvt_pk_bf16_f32 v55, v65, v66
	global_store_dwordx4 v[60:61], v[52:55], off offset:64
	s_nop 0
	s_nop 0
	v_or_b32_e32 v52, 48, v48
	v_ashrrev_i32_e32 v53, 31, v52
	v_lshlrev_b64 v[52:53], 11, v[52:53]
	v_lshl_add_u64 v[60:61], v[50:51], 0, v[52:53]
	s_nop 0
	s_nop 0
	s_nop 0
	s_nop 0
	s_nop 0
	s_nop 0
	s_waitcnt lgkmcnt(0)
	s_nop 0
	v_mov_b32_e32 v55, v120
	v_mov_b32_e32 v49, v108
	s_nop 1
	v_permlane16_swap_b32_e32 v55, v49
	s_waitcnt lgkmcnt(0)
	s_nop 0
	v_mov_b32_e32 v62, v121
	v_mov_b32_e32 v63, v109
	s_nop 1
	v_permlane16_swap_b32_e32 v62, v63
	s_waitcnt lgkmcnt(0)
	s_nop 0
	v_mov_b32_e32 v64, v122
	v_mov_b32_e32 v65, v110
	s_nop 1
	v_permlane16_swap_b32_e32 v64, v65
	s_waitcnt lgkmcnt(0)
	s_nop 0
	v_mov_b32_e32 v53, v123
	v_mov_b32_e32 v66, v111
	s_nop 1
	v_permlane16_swap_b32_e32 v53, v66
	v_cvt_pk_bf16_f32 v52, v55, v62
	v_cvt_pk_bf16_f32 v53, v64, v53
	v_cvt_pk_bf16_f32 v54, v49, v63
	v_cvt_pk_bf16_f32 v55, v65, v66
	global_store_dwordx4 v[60:61], v[52:55], off
	s_nop 0
	s_nop 0
	s_nop 0
	s_nop 0
	s_nop 0
	s_nop 0
	s_nop 0
	s_nop 0
	s_waitcnt lgkmcnt(0)
	s_nop 0
	v_mov_b32_e32 v55, v100
	v_mov_b32_e32 v49, v80
	s_nop 1
	v_permlane16_swap_b32_e32 v55, v49
	s_waitcnt lgkmcnt(0)
	s_nop 0
	v_mov_b32_e32 v62, v101
	v_mov_b32_e32 v63, v81
	s_nop 1
	v_permlane16_swap_b32_e32 v62, v63
	s_waitcnt lgkmcnt(0)
	s_nop 0
	v_mov_b32_e32 v64, v102
	v_mov_b32_e32 v65, v82
	s_nop 1
	v_permlane16_swap_b32_e32 v64, v65
	s_waitcnt lgkmcnt(0)
	s_nop 0
	v_mov_b32_e32 v53, v103
	v_mov_b32_e32 v66, v83
	s_nop 1
	v_permlane16_swap_b32_e32 v53, v66
	v_mfma_f32_16x16x32_bf16 v[92:95], v[140:143], v[88:91], v[92:95]
	v_cvt_pk_bf16_f32 v52, v55, v62
	v_cvt_pk_bf16_f32 v53, v64, v53
	v_cvt_pk_bf16_f32 v54, v49, v63
	v_mfma_f32_16x16x32_bf16 v[84:87], v[144:147], v[88:91], v[84:87]
	v_cvt_pk_bf16_f32 v55, v65, v66
	global_store_dwordx4 v[60:61], v[52:55], off offset:64
	v_mfma_f32_16x16x32_bf16 v[76:79], v[160:163], v[88:91], v[76:79]
	s_nop 0
	v_or_b32_e32 v52, 64, v48
	v_ashrrev_i32_e32 v53, 31, v52
	v_lshlrev_b64 v[52:53], 11, v[52:53]
	v_lshl_add_u64 v[60:61], v[50:51], 0, v[52:53]
	s_nop 0
	s_nop 0
	s_nop 0
	s_nop 0
	s_nop 0
	s_nop 0
	s_nop 0
	s_nop 0
	v_mfma_f32_16x16x32_bf16 v[56:59], v[178:181], v[88:91], v[56:59]
	s_waitcnt lgkmcnt(0)
	s_nop 0
	v_mov_b32_e32 v55, v92
	v_mov_b32_e32 v49, v84
	s_nop 1
	v_permlane16_swap_b32_e32 v55, v49
	s_waitcnt lgkmcnt(0)
	s_nop 0
	v_mov_b32_e32 v62, v93
	v_mov_b32_e32 v63, v85
	s_nop 1
	v_permlane16_swap_b32_e32 v62, v63
	s_waitcnt lgkmcnt(0)
	s_nop 0
	v_mov_b32_e32 v64, v94
	v_mov_b32_e32 v65, v86
	s_nop 1
	v_permlane16_swap_b32_e32 v64, v65
	s_waitcnt lgkmcnt(0)
	s_nop 0
	v_mov_b32_e32 v53, v95
	v_mov_b32_e32 v66, v87
	s_nop 1
	v_permlane16_swap_b32_e32 v53, v66
	v_cvt_pk_bf16_f32 v52, v55, v62
	v_cvt_pk_bf16_f32 v53, v64, v53
	v_cvt_pk_bf16_f32 v54, v49, v63
	v_cvt_pk_bf16_f32 v55, v65, v66
	global_store_dwordx4 v[60:61], v[52:55], off
	s_nop 0
	s_nop 0
	s_nop 0
	s_nop 0
	s_nop 0
	s_nop 0
	s_nop 0
	s_nop 0
	s_waitcnt lgkmcnt(0)
	s_nop 0
	v_mov_b32_e32 v55, v76
	v_mov_b32_e32 v49, v56
	s_nop 1
	v_permlane16_swap_b32_e32 v55, v49
	s_waitcnt lgkmcnt(0)
	s_nop 0
	v_mov_b32_e32 v56, v77
	s_nop 1
	v_permlane16_swap_b32_e32 v56, v57
	s_waitcnt lgkmcnt(0)
	s_nop 0
	v_mov_b32_e32 v62, v78
	s_nop 1
	v_permlane16_swap_b32_e32 v62, v58
	s_waitcnt lgkmcnt(0)
	s_nop 0
	v_mov_b32_e32 v53, v79
	s_nop 1
	v_permlane16_swap_b32_e32 v53, v59
	v_cvt_pk_bf16_f32 v52, v55, v56
	v_cvt_pk_bf16_f32 v53, v62, v53
	v_cvt_pk_bf16_f32 v54, v49, v57
	v_cvt_pk_bf16_f32 v55, v58, v59
	global_store_dwordx4 v[60:61], v[52:55], off offset:64
	s_nop 0
	s_nop 0
	s_nop 0
	s_nop 0
	s_nop 0
	s_nop 0
	s_nop 0
	s_nop 0
	v_mfma_f32_16x16x32_bf16 v[32:35], v[160:163], v[104:107], v[72:75]
	v_or_b32_e32 v52, 0x50, v48
	v_ashrrev_i32_e32 v53, 31, v52
	v_lshlrev_b64 v[52:53], 11, v[52:53]
	s_waitcnt lgkmcnt(0)
	s_nop 0
	s_nop 1
	v_permlane16_swap_b32_e32 v40, v44
	s_waitcnt lgkmcnt(0)
	s_nop 0
	s_nop 1
	v_permlane16_swap_b32_e32 v41, v45
	s_waitcnt lgkmcnt(0)
	s_nop 0
	s_nop 1
	v_permlane16_swap_b32_e32 v42, v46
	s_waitcnt lgkmcnt(0)
	s_nop 0
	s_nop 1
	v_permlane16_swap_b32_e32 v43, v47
	v_lshl_add_u64 v[52:53], v[50:51], 0, v[52:53]
	v_cvt_pk_bf16_f32 v40, v40, v41
	v_cvt_pk_bf16_f32 v41, v42, v43
	v_cvt_pk_bf16_f32 v42, v44, v45
	v_cvt_pk_bf16_f32 v43, v46, v47
	global_store_dwordx4 v[52:53], v[40:43], off
	v_mfma_f32_16x16x32_bf16 v[24:27], v[140:143], v[112:115], v[96:99]
	s_nop 0
	s_nop 0
	s_nop 0
	s_nop 0
	s_nop 0
	s_nop 0
	s_nop 0
	s_nop 0
	s_nop 0
	v_mfma_f32_16x16x32_bf16 v[28:31], v[144:147], v[112:115], v[28:31]
	s_waitcnt lgkmcnt(0)
	s_nop 0
	s_nop 1
	v_permlane16_swap_b32_e32 v32, v36
	s_waitcnt lgkmcnt(0)
	s_nop 0
	s_nop 1
	v_permlane16_swap_b32_e32 v33, v37
	s_waitcnt lgkmcnt(0)
	s_nop 0
	s_nop 1
	v_permlane16_swap_b32_e32 v34, v38
	s_waitcnt lgkmcnt(0)
	s_nop 0
	s_nop 1
	v_permlane16_swap_b32_e32 v35, v39
	v_cvt_pk_bf16_f32 v32, v32, v33
	v_cvt_pk_bf16_f32 v33, v34, v35
	v_cvt_pk_bf16_f32 v34, v36, v37
	v_cvt_pk_bf16_f32 v35, v38, v39
	global_store_dwordx4 v[52:53], v[32:35], off offset:64
	s_nop 0
	s_nop 0
	s_nop 0
	s_nop 0
	s_nop 0
	s_nop 0
	s_nop 0
	s_nop 0
	v_mfma_f32_16x16x32_bf16 v[16:19], v[160:163], v[112:115], v[124:127]
	v_or_b32_e32 v32, 0x60, v48
	v_ashrrev_i32_e32 v33, 31, v32
	v_lshlrev_b64 v[32:33], 11, v[32:33]
	v_mfma_f32_16x16x32_bf16 v[20:23], v[178:181], v[112:115], v[20:23]
	s_waitcnt lgkmcnt(0)
	s_nop 0
	s_nop 1
	v_permlane16_swap_b32_e32 v24, v28
	s_waitcnt lgkmcnt(0)
	s_nop 0
	s_nop 1
	v_permlane16_swap_b32_e32 v25, v29
	s_waitcnt lgkmcnt(0)
	s_nop 0
	s_nop 1
	v_permlane16_swap_b32_e32 v26, v30
	s_waitcnt lgkmcnt(0)
	s_nop 0
	s_nop 1
	v_permlane16_swap_b32_e32 v27, v31
	v_lshl_add_u64 v[32:33], v[50:51], 0, v[32:33]
	v_cvt_pk_bf16_f32 v24, v24, v25
	v_cvt_pk_bf16_f32 v25, v26, v27
	v_cvt_pk_bf16_f32 v26, v28, v29
	v_cvt_pk_bf16_f32 v27, v30, v31
	global_store_dwordx4 v[32:33], v[24:27], off
	v_mfma_f32_16x16x32_bf16 v[0:3], v[160:163], v[116:119], v[0:3]
	s_nop 0
	s_nop 0
	s_nop 0
	s_nop 0
	s_nop 0
	s_nop 0
	s_nop 0
	s_nop 0
	s_nop 0
	v_mfma_f32_16x16x32_bf16 v[4:7], v[178:181], v[116:119], v[68:71]
	s_waitcnt lgkmcnt(0)
	s_nop 0
	s_nop 1
	v_permlane16_swap_b32_e32 v16, v20
	s_waitcnt lgkmcnt(0)
	s_nop 0
	s_nop 1
	v_permlane16_swap_b32_e32 v17, v21
	s_waitcnt lgkmcnt(0)
	s_nop 0
	s_nop 1
	v_permlane16_swap_b32_e32 v18, v22
	s_waitcnt lgkmcnt(0)
	s_nop 0
	s_nop 1
	v_permlane16_swap_b32_e32 v19, v23
	v_cvt_pk_bf16_f32 v16, v16, v17
	v_cvt_pk_bf16_f32 v17, v18, v19
	v_cvt_pk_bf16_f32 v18, v20, v21
	v_cvt_pk_bf16_f32 v19, v22, v23
	global_store_dwordx4 v[32:33], v[16:19], off offset:64
	s_nop 0
	s_nop 0
	s_nop 0
	s_nop 0
	s_nop 0
	s_nop 0
	s_nop 0
	s_nop 0
	v_or_b32_e32 v16, 0x70, v48
	v_ashrrev_i32_e32 v17, 31, v16
	v_lshlrev_b64 v[16:17], 11, v[16:17]
	s_waitcnt lgkmcnt(0)
	s_nop 0
	s_nop 1
	v_permlane16_swap_b32_e32 v8, v12
	s_waitcnt lgkmcnt(0)
	s_nop 0
	s_nop 1
	v_permlane16_swap_b32_e32 v9, v13
	s_waitcnt lgkmcnt(0)
	s_nop 0
	s_nop 1
	v_permlane16_swap_b32_e32 v10, v14
	s_waitcnt lgkmcnt(0)
	s_nop 0
	s_nop 1
	v_permlane16_swap_b32_e32 v11, v15
	v_lshl_add_u64 v[16:17], v[50:51], 0, v[16:17]
	v_cvt_pk_bf16_f32 v8, v8, v9
	v_cvt_pk_bf16_f32 v9, v10, v11
	v_cvt_pk_bf16_f32 v10, v12, v13
	v_cvt_pk_bf16_f32 v11, v14, v15
	global_store_dwordx4 v[16:17], v[8:11], off
	s_nop 1
	s_nop 0
	s_nop 0
	s_nop 0
	s_nop 0
	s_nop 0
	s_nop 0
	s_nop 0
	s_nop 0
	s_waitcnt lgkmcnt(0)
	s_nop 0
	s_nop 1
	v_permlane16_swap_b32_e32 v0, v4
	s_waitcnt lgkmcnt(0)
	s_nop 0
	s_nop 1
	v_permlane16_swap_b32_e32 v1, v5
	s_waitcnt lgkmcnt(0)
	s_nop 0
	s_nop 1
	v_permlane16_swap_b32_e32 v2, v6
	s_waitcnt lgkmcnt(0)
	s_nop 0
	s_nop 1
	v_permlane16_swap_b32_e32 v3, v7
	v_cvt_pk_bf16_f32 v0, v0, v1
	v_cvt_pk_bf16_f32 v1, v2, v3
	v_cvt_pk_bf16_f32 v2, v4, v5
	v_cvt_pk_bf16_f32 v3, v6, v7
	global_store_dwordx4 v[16:17], v[0:3], off offset:64
	s_load_dword s8, s[8:9], 0x0
	s_waitcnt lgkmcnt(0)
	s_add_i32 s10, s8, s10
	s_cmpk_gt_i32 s10, 0xff
	s_cbranch_scc0 .LBB0_146

.LBB0_398:
	s_andn2_b64 vcc, exec, s[0:1]
	s_cbranch_vccnz .LBB0_418
	s_add_i32 s0, s7, 0xfffffdc0
	s_and_b32 s1, s7, 7
	s_lshr_b32 s0, s0, 3
	s_mul_i32 s1, s1, 48
	s_add_i32 s1, s1, s0
	s_and_b32 s0, s1, 0xffff
	s_mul_i32 s0, s0, 0xaaab
	s_lshr_b32 s8, s0, 20
	s_mul_i32 s9, s8, 0xffffffe8
	s_add_i32 s1, s9, s1
	s_mul_i32 s9, s1, 0x2aab
	s_lshr_b32 s30, s9, 31
	s_lshr_b32 s9, s9, 16
	s_lshr_b32 s0, s0, 21
	s_add_i32 s9, s9, s30
	s_sext_i32_i16 s9, s9
	s_lshl_b32 s30, s0, 1
	s_add_i32 s30, s30, s9
	s_lshl_b32 s0, s0, 10
	s_lshl_b32 s9, s9, 8
	v_mov_b32_e32 v8, v188
	s_sub_i32 s8, s8, s30
	s_add_i32 s9, s9, s0
	s_mul_i32 s8, s8, 6
	v_ashrrev_i32_e32 v9, 3, v8
	v_add_u32_e32 v4, s9, v9
	s_movk_i32 s30, 0x300
	s_add_i32 s8, s8, s1
	v_mad_i64_i32 v[0:1], s[0:1], v4, s30, 0
	v_readlane_b32 s0, v255, 49
	v_readlane_b32 s1, v255, 50
	s_lshl_b32 s8, s8, 7
	v_add_u32_e32 v10, s8, v9
	v_mov_b64_e32 v[2:3], s[0:1]
	v_mad_i64_i32 v[2:3], s[0:1], v4, s30, v[2:3]
	v_lshlrev_b32_e32 v4, 4, v8
	v_and_b32_e32 v176, 0x70, v4
	v_mad_i64_i32 v[4:5], s[0:1], v10, s30, 0
	v_readlane_b32 s0, v255, 51
	v_readlane_b32 s1, v255, 52
	v_lshl_add_u64 v[2:3], v[2:3], 0, v[176:177]
	v_lshlrev_b32_e32 v12, 7, v8
	v_mov_b64_e32 v[6:7], s[0:1]
	v_mad_i64_i32 v[6:7], s[0:1], v10, s30, v[6:7]
	v_xor_b32_e32 v10, v9, v8
	v_lshlrev_b32_e32 v10, 4, v10
	v_lshl_add_u64 v[6:7], v[6:7], 0, v[176:177]
	v_and_b32_e32 v10, 0x70, v10
	v_lshl_or_b32 v176, v9, 7, v10
	v_lshrrev_b32_e32 v9, 4, v8
	v_bfe_u32 v14, v8, 4, 2
	v_and_b32_e32 v15, 7, v8
	v_add_co_u32_e32 v8, vcc, s77, v6
	v_bitop3_b32 v16, v9, v15, 3 bitop3:0x6c
	s_nop 0
	v_addc_co_u32_e32 v9, vcc, 0, v7, vcc
	v_add_co_u32_e32 v10, vcc, s28, v6
	s_mov_b32 s0, 0x2a000
	s_nop 0
	v_addc_co_u32_e32 v11, vcc, 0, v7, vcc
	global_load_dwordx4 v[68:71], v[8:9], off
	global_load_dwordx4 v[72:75], v[10:11], off
	v_add_co_u32_e32 v8, vcc, s54, v6
	v_and_b32_e32 v13, 0xffffc780, v12
	s_nop 0
	v_addc_co_u32_e32 v9, vcc, 0, v7, vcc
	v_add_co_u32_e32 v10, vcc, s0, v2
	s_mov_b32 s0, 0x24000
	s_nop 0
	v_addc_co_u32_e32 v11, vcc, 0, v3, vcc
	global_load_dwordx4 v[88:91], v[8:9], off
	global_load_dwordx4 v[96:99], v[10:11], off
	v_add_co_u32_e32 v8, vcc, s0, v2
	s_mov_b32 s0, 0x1e000
	s_nop 0
	v_addc_co_u32_e32 v9, vcc, 0, v3, vcc
	v_add_co_u32_e32 v10, vcc, s0, v2
	s_mov_b32 s0, 0x18000
	s_nop 0
	v_addc_co_u32_e32 v11, vcc, 0, v3, vcc
	global_load_dwordx4 v[108:111], v[8:9], off
	global_load_dwordx4 v[120:123], v[10:11], off
	v_add_co_u32_e32 v8, vcc, s0, v2
	v_and_b32_e32 v12, 0x2780, v12
	s_nop 0
	v_addc_co_u32_e32 v9, vcc, 0, v3, vcc
	v_add_co_u32_e32 v10, vcc, s77, v2
	v_bitop3_b32 v14, v14, v15, 4 bitop3:0x36
	s_nop 0
	v_addc_co_u32_e32 v11, vcc, 0, v3, vcc
	global_load_dwordx4 v[132:135], v[8:9], off
	global_load_dwordx4 v[136:139], v[10:11], off
	v_add_co_u32_e32 v8, vcc, s28, v2
	v_mov_b32_e32 v112, 0
	s_nop 0
	v_addc_co_u32_e32 v9, vcc, 0, v3, vcc
	v_add_co_u32_e32 v10, vcc, s54, v2
	s_mov_b64 s[0:1], 0
	s_nop 0
	v_addc_co_u32_e32 v11, vcc, 0, v3, vcc
	global_load_dwordx4 v[152:155], v[8:9], off
	global_load_dwordx4 v[160:163], v[10:11], off
	global_load_dwordx4 v[148:151], v[6:7], off
	global_load_dwordx4 v[168:171], v[2:3], off
	v_lshlrev_b32_e32 v2, 4, v16
	v_or_b32_e32 v185, v13, v2
	v_or_b32_e32 v184, v12, v2
	v_lshlrev_b32_e32 v2, 4, v14
	v_or_b32_e32 v183, v13, v2
	v_or_b32_e32 v182, v12, v2
	v_lshlrev_b32_e32 v2, 4, v15
	v_or_b32_e32 v0, v0, v2
	v_or_b32_e32 v4, v4, v2
	v_lshl_add_u64 v[178:179], s[34:35], 0, v[0:1]
	v_lshl_add_u64 v[180:181], s[84:85], 0, v[4:5]
	v_mov_b32_e32 v113, v112
	v_mov_b32_e32 v114, v112
	v_mov_b32_e32 v115, v112
	v_mov_b32_e32 v0, v112
	v_mov_b32_e32 v1, v112
	v_mov_b32_e32 v2, v112
	v_mov_b32_e32 v3, v112
	v_mov_b32_e32 v4, v112
	v_mov_b32_e32 v5, v112
	v_mov_b32_e32 v6, v112
	v_mov_b32_e32 v7, v112
	v_mov_b32_e32 v8, v112
	v_mov_b32_e32 v9, v112
	v_mov_b32_e32 v10, v112
	v_mov_b32_e32 v11, v112
	v_mov_b32_e32 v12, v112
	v_mov_b32_e32 v13, v112
	v_mov_b32_e32 v14, v112
	v_mov_b32_e32 v15, v112
	v_mov_b32_e32 v16, v112
	v_mov_b32_e32 v17, v112
	v_mov_b32_e32 v18, v112
	v_mov_b32_e32 v19, v112
	v_mov_b32_e32 v20, v112
	v_mov_b32_e32 v21, v112
	v_mov_b32_e32 v22, v112
	v_mov_b32_e32 v23, v112
	v_mov_b32_e32 v24, v112
	v_mov_b32_e32 v25, v112
	v_mov_b32_e32 v26, v112
	v_mov_b32_e32 v27, v112
	v_mov_b32_e32 v28, v112
	v_mov_b32_e32 v29, v112
	v_mov_b32_e32 v30, v112
	v_mov_b32_e32 v31, v112
	v_mov_b32_e32 v32, v112
	v_mov_b32_e32 v33, v112
	v_mov_b32_e32 v34, v112
	v_mov_b32_e32 v35, v112
	v_mov_b32_e32 v36, v112
	v_mov_b32_e32 v37, v112
	v_mov_b32_e32 v38, v112
	v_mov_b32_e32 v39, v112
	v_mov_b32_e32 v40, v112
	v_mov_b32_e32 v41, v112
	v_mov_b32_e32 v42, v112
	v_mov_b32_e32 v43, v112
	v_mov_b32_e32 v44, v112
	v_mov_b32_e32 v45, v112
	v_mov_b32_e32 v46, v112
	v_mov_b32_e32 v47, v112
	v_mov_b32_e32 v48, v112
	v_mov_b32_e32 v49, v112
	v_mov_b32_e32 v50, v112
	v_mov_b32_e32 v51, v112
	v_mov_b32_e32 v52, v112
	v_mov_b32_e32 v53, v112
	v_mov_b32_e32 v54, v112
	v_mov_b32_e32 v55, v112
	v_mov_b32_e32 v56, v112
	v_mov_b32_e32 v57, v112
	v_mov_b32_e32 v58, v112
	v_mov_b32_e32 v59, v112
	v_mov_b32_e32 v60, v112
	v_mov_b32_e32 v61, v112
	v_mov_b32_e32 v62, v112
	v_mov_b32_e32 v63, v112
	v_mov_b32_e32 v64, v112
	v_mov_b32_e32 v65, v112
	v_mov_b32_e32 v66, v112
	v_mov_b32_e32 v67, v112
	v_mov_b32_e32 v76, v112
	v_mov_b32_e32 v77, v112
	v_mov_b32_e32 v78, v112
	v_mov_b32_e32 v79, v112
	v_mov_b32_e32 v80, v112
	v_mov_b32_e32 v81, v112
	v_mov_b32_e32 v82, v112
	v_mov_b32_e32 v83, v112
	v_mov_b32_e32 v84, v112
	v_mov_b32_e32 v85, v112
	v_mov_b32_e32 v86, v112
	v_mov_b32_e32 v87, v112
	v_mov_b32_e32 v92, v112
	v_mov_b32_e32 v93, v112
	v_mov_b32_e32 v94, v112
	v_mov_b32_e32 v95, v112
	v_mov_b32_e32 v100, v112
	v_mov_b32_e32 v101, v112
	v_mov_b32_e32 v102, v112
	v_mov_b32_e32 v103, v112
	v_mov_b32_e32 v104, v112
	v_mov_b32_e32 v105, v112
	v_mov_b32_e32 v106, v112
	v_mov_b32_e32 v107, v112
	v_mov_b32_e32 v116, v112
	v_mov_b32_e32 v117, v112
	v_mov_b32_e32 v118, v112
	v_mov_b32_e32 v119, v112
	v_mov_b32_e32 v124, v112
	v_mov_b32_e32 v125, v112
	v_mov_b32_e32 v126, v112
	v_mov_b32_e32 v127, v112
	v_mov_b32_e32 v128, v112
	v_mov_b32_e32 v129, v112
	v_mov_b32_e32 v130, v112
	v_mov_b32_e32 v131, v112
	v_mov_b32_e32 v140, v112
	v_mov_b32_e32 v141, v112
	v_mov_b32_e32 v142, v112
	v_mov_b32_e32 v143, v112
	v_mov_b32_e32 v144, v112
	v_mov_b32_e32 v145, v112
	v_mov_b32_e32 v146, v112
	v_mov_b32_e32 v147, v112
	v_mov_b32_e32 v156, v112
	v_mov_b32_e32 v157, v112
	v_mov_b32_e32 v158, v112
	v_mov_b32_e32 v159, v112
	v_mov_b32_e32 v164, v112
	v_mov_b32_e32 v165, v112
	v_mov_b32_e32 v166, v112
	v_mov_b32_e32 v167, v112
	v_mov_b32_e32 v172, v112
	v_mov_b32_e32 v173, v112
	v_mov_b32_e32 v174, v112
	v_mov_b32_e32 v175, v112
	v_readlane_b32 vcc_lo, v253, 0
	s_cmpk_lt_u32 vcc_lo, 0x100
	s_cbranch_scc1 .Lprio_hi2
	s_setprio 2
	s_branch .Lprio_done2

.Lprio_done2:
	v_readlane_b32 s98, v253, 3
	v_readlane_b32 s99, v253, 4
	v_and_b32_e32 v224, 15, v188
	v_bfe_u32 v225, v188, 4, 2
	v_lshrrev_b32_e32 v226, 2, v224
	v_sub_u32_e32 v226, 0, v226
	v_and_b32_e32 v226, 3, v226
	v_xor_b32_e32 v225, v225, v226
	v_lshlrev_b32_e32 v225, 4, v225
	v_lshl_or_b32 v225, v224, 6, v225
	v_bfe_u32 v226, v188, 7, 1
	v_lshl_or_b32 v185, v226, 13, v225
	v_bfe_u32 v226, v188, 6, 1
	v_lshl_or_b32 v184, v226, 12, v225
	v_add_u32_e32 v184, 0x4000, v184
	v_lshrrev_b32_e32 v224, 3, v188
	v_bfe_u32 v225, v188, 2, 1
	v_lshrrev_b32_e32 v226, 2, v224
	v_sub_u32_e32 v226, 0, v226
	v_and_b32_e32 v226, 3, v226
	v_and_b32_e32 v227, 3, v188
	v_xor_b32_e32 v226, v227, v226
	v_lshlrev_b32_e32 v226, 4, v226
	v_xor_b32_e32 v224, v224, v225
	v_lshl_or_b32 v226, v224, 6, v226
	v_mul_u32_u24_e32 v225, 0x6000, v225
	v_add_u32_e32 v183, v225, v226
	s_mov_b32 m0, 0
	s_sub_u32 vcc_lo, s0, s98
	v_add_u32_e32 v186, vcc_lo, v178
	v_add_u32_e32 v187, vcc_lo, v180
	s_barrier
	s_waitcnt vmcnt(0)
	ds_write_b128 v183, v[168:171]
	ds_write_b128 v183, v[160:163] offset:2048
	ds_write_b128 v183, v[152:155] offset:4096
	ds_write_b128 v183, v[136:139] offset:6144
	ds_write_b128 v183, v[132:135] offset:8192
	ds_write_b128 v183, v[120:123] offset:10240
	ds_write_b128 v183, v[108:111] offset:12288
	ds_write_b128 v183, v[96:99] offset:14336
	ds_write_b128 v183, v[148:151] offset:16384
	ds_write_b128 v183, v[88:91] offset:18432
	ds_write_b128 v183, v[72:75] offset:20480
	ds_write_b128 v183, v[68:71] offset:22528
	v_cmp_gt_u32_e32 vcc, 0x6000, v183
	v_add_u32_e32 v182, 0xc000, v183
	v_add_u32_e32 v183, 0xffffa000, v183
	s_nop 0
	v_cndmask_b32_e32 v183, v183, v182, vcc
	v_add_u32_e32 v168, 0xa700000, v186
	global_load_dwordx4 v[168:171], v168, s[98:99] offset:128
	v_add_u32_e32 v160, 0xa706000, v186
	global_load_dwordx4 v[160:163], v160, s[98:99] offset:128
	v_add_u32_e32 v152, 0xa70c000, v186
	global_load_dwordx4 v[152:155], v152, s[98:99] offset:128
	v_add_u32_e32 v136, 0xa712000, v186
	global_load_dwordx4 v[136:139], v136, s[98:99] offset:128
	v_add_u32_e32 v132, 0xa718000, v186
	global_load_dwordx4 v[132:135], v132, s[98:99] offset:128
	v_add_u32_e32 v120, 0xa71e000, v186
	global_load_dwordx4 v[120:123], v120, s[98:99] offset:128
	v_add_u32_e32 v108, 0xa724000, v186
	global_load_dwordx4 v[108:111], v108, s[98:99] offset:128
	v_add_u32_e32 v96, 0xa72a000, v186
	global_load_dwordx4 v[96:99], v96, s[98:99] offset:128
	v_add_u32_e32 v148, 0x1f00000, v187
	global_load_dwordx4 v[148:151], v148, s[98:99] offset:128
	v_add_u32_e32 v88, 0x1f06000, v187
	global_load_dwordx4 v[88:91], v88, s[98:99] offset:128
	v_add_u32_e32 v72, 0x1f0c000, v187
	global_load_dwordx4 v[72:75], v72, s[98:99] offset:128
	v_add_u32_e32 v68, 0x1f12000, v187
	global_load_dwordx4 v[68:71], v68, s[98:99] offset:128
	s_add_u32 s0, s0, 0x80
	s_addc_u32 s1, s1, 0
.LBB0_400:
	s_waitcnt lgkmcnt(0)
	s_barrier
	ds_read_b128 v[224:227], v184
	ds_read_b128 v[228:231], v184 offset:1024
	ds_read_b128 v[232:235], v184 offset:2048
	ds_read_b128 v[236:239], v184 offset:3072
	ds_read_b128 v[190:193], v185
	ds_read_b128 v[194:197], v185 offset:1024
	ds_read_b128 v[198:201], v185 offset:2048
	ds_read_b128 v[204:207], v185 offset:3072
	ds_read_b128 v[208:211], v185 offset:4096
	ds_read_b128 v[212:215], v185 offset:5120
	ds_read_b128 v[216:219], v185 offset:6144
	ds_read_b128 v[220:223], v185 offset:7168
	s_movk_i32 vcc_lo, 0x6000
	s_cmp_eq_u32 m0, 2
	s_cselect_b32 vcc_lo, 0xffff4000, vcc_lo
	s_add_u32 m0, m0, 1
	s_cmp_eq_u32 m0, 3
	s_cselect_b32 m0, 0, m0
	v_add_u32_e32 v185, vcc_lo, v185
	v_add_u32_e32 v184, vcc_lo, v184
	v_xor_b32_e32 v185, 64, v185
	v_xor_b32_e32 v184, 64, v184
	s_waitcnt lgkmcnt(7)
	v_mfma_f32_16x16x32_bf16 v[172:175], v[224:227], v[190:193], v[172:175]
	v_mfma_f32_16x16x32_bf16 v[164:167], v[228:231], v[190:193], v[164:167]
	v_mfma_f32_16x16x32_bf16 v[156:159], v[232:235], v[190:193], v[156:159]
	v_mfma_f32_16x16x32_bf16 v[144:147], v[236:239], v[190:193], v[144:147]
	ds_read_b128 v[190:193], v185
	s_waitcnt lgkmcnt(7)
	v_mfma_f32_16x16x32_bf16 v[140:143], v[224:227], v[194:197], v[140:143]
	v_mfma_f32_16x16x32_bf16 v[128:131], v[228:231], v[194:197], v[128:131]
	v_mfma_f32_16x16x32_bf16 v[124:127], v[232:235], v[194:197], v[124:127]
	v_mfma_f32_16x16x32_bf16 v[116:119], v[236:239], v[194:197], v[116:119]
	ds_read_b128 v[194:197], v185 offset:1024
	s_waitcnt lgkmcnt(7)
	v_mfma_f32_16x16x32_bf16 v[104:107], v[224:227], v[198:201], v[104:107]
	v_mfma_f32_16x16x32_bf16 v[100:103], v[228:231], v[198:201], v[100:103]
	v_mfma_f32_16x16x32_bf16 v[92:95], v[232:235], v[198:201], v[92:95]
	v_mfma_f32_16x16x32_bf16 v[84:87], v[236:239], v[198:201], v[84:87]
	ds_read_b128 v[198:201], v185 offset:2048
	s_waitcnt lgkmcnt(7)
	v_mfma_f32_16x16x32_bf16 v[80:83], v[224:227], v[204:207], v[80:83]
	v_mfma_f32_16x16x32_bf16 v[76:79], v[228:231], v[204:207], v[76:79]
	v_mfma_f32_16x16x32_bf16 v[64:67], v[232:235], v[204:207], v[64:67]
	v_mfma_f32_16x16x32_bf16 v[60:63], v[236:239], v[204:207], v[60:63]
	ds_read_b128 v[204:207], v185 offset:3072
	s_waitcnt lgkmcnt(7)
	v_mfma_f32_16x16x32_bf16 v[56:59], v[224:227], v[208:211], v[56:59]
	v_mfma_f32_16x16x32_bf16 v[52:55], v[228:231], v[208:211], v[52:55]
	v_mfma_f32_16x16x32_bf16 v[48:51], v[232:235], v[208:211], v[48:51]
	v_mfma_f32_16x16x32_bf16 v[44:47], v[236:239], v[208:211], v[44:47]
	ds_read_b128 v[208:211], v185 offset:4096
	s_waitcnt lgkmcnt(7)
	v_mfma_f32_16x16x32_bf16 v[40:43], v[224:227], v[212:215], v[40:43]
	v_mfma_f32_16x16x32_bf16 v[36:39], v[228:231], v[212:215], v[36:39]
	v_mfma_f32_16x16x32_bf16 v[32:35], v[232:235], v[212:215], v[32:35]
	v_mfma_f32_16x16x32_bf16 v[28:31], v[236:239], v[212:215], v[28:31]
	ds_read_b128 v[212:215], v185 offset:5120
	s_waitcnt lgkmcnt(7)
	v_mfma_f32_16x16x32_bf16 v[24:27], v[224:227], v[216:219], v[24:27]
	v_mfma_f32_16x16x32_bf16 v[20:23], v[228:231], v[216:219], v[20:23]
	v_mfma_f32_16x16x32_bf16 v[16:19], v[232:235], v[216:219], v[16:19]
	v_mfma_f32_16x16x32_bf16 v[12:15], v[236:239], v[216:219], v[12:15]
	ds_read_b128 v[216:219], v185 offset:6144
	s_waitcnt lgkmcnt(7)
	v_mfma_f32_16x16x32_bf16 v[8:11], v[224:227], v[220:223], v[8:11]
	v_mfma_f32_16x16x32_bf16 v[4:7], v[228:231], v[220:223], v[4:7]
	v_mfma_f32_16x16x32_bf16 v[0:3], v[232:235], v[220:223], v[0:3]
	v_mfma_f32_16x16x32_bf16 v[112:115], v[236:239], v[220:223], v[112:115]
	ds_read_b128 v[220:223], v185 offset:7168
	ds_read_b128 v[224:227], v184
	ds_read_b128 v[228:231], v184 offset:1024
	ds_read_b128 v[232:235], v184 offset:2048
	ds_read_b128 v[236:239], v184 offset:3072
	s_movk_i32 vcc_lo, 0x6000
	s_cmp_eq_u32 m0, 2
	s_cselect_b32 vcc_lo, 0xffff4000, vcc_lo
	s_add_u32 m0, m0, 1
	s_cmp_eq_u32 m0, 3
	s_cselect_b32 m0, 0, m0
	v_add_u32_e32 v185, vcc_lo, v185
	v_add_u32_e32 v184, vcc_lo, v184
	v_xor_b32_e32 v185, 64, v185
	v_xor_b32_e32 v184, 64, v184
	s_sub_u32 vcc_lo, s0, s98
	v_add_u32_e32 v186, vcc_lo, v178
	v_add_u32_e32 v187, vcc_lo, v180
	s_barrier
	s_waitcnt lgkmcnt(0)
	v_mfma_f32_16x16x32_bf16 v[172:175], v[224:227], v[190:193], v[172:175]
	s_waitcnt vmcnt(11)
	v_mfma_f32_16x16x32_bf16 v[164:167], v[228:231], v[190:193], v[164:167]
	ds_write_b128 v183, v[168:171]
	v_add_u32_e32 v168, 0xa700000, v186
	v_mfma_f32_16x16x32_bf16 v[156:159], v[232:235], v[190:193], v[156:159]
	global_load_dwordx4 v[168:171], v168, s[98:99] offset:128
	v_mfma_f32_16x16x32_bf16 v[144:147], v[236:239], v[190:193], v[144:147]
	s_waitcnt vmcnt(11)
	ds_write_b128 v183, v[160:163] offset:2048
	v_mfma_f32_16x16x32_bf16 v[140:143], v[224:227], v[194:197], v[140:143]
	v_add_u32_e32 v160, 0xa706000, v186
	v_mfma_f32_16x16x32_bf16 v[128:131], v[228:231], v[194:197], v[128:131]
	global_load_dwordx4 v[160:163], v160, s[98:99] offset:128
	s_waitcnt vmcnt(11)
	v_mfma_f32_16x16x32_bf16 v[124:127], v[232:235], v[194:197], v[124:127]
	ds_write_b128 v183, v[152:155] offset:4096
	v_mfma_f32_16x16x32_bf16 v[116:119], v[236:239], v[194:197], v[116:119]
	v_add_u32_e32 v152, 0xa70c000, v186
	global_load_dwordx4 v[152:155], v152, s[98:99] offset:128
	v_mfma_f32_16x16x32_bf16 v[104:107], v[224:227], v[198:201], v[104:107]
	s_waitcnt vmcnt(11)
	v_mfma_f32_16x16x32_bf16 v[100:103], v[228:231], v[198:201], v[100:103]
	ds_write_b128 v183, v[136:139] offset:6144
	v_add_u32_e32 v136, 0xa712000, v186
	v_mfma_f32_16x16x32_bf16 v[92:95], v[232:235], v[198:201], v[92:95]
	global_load_dwordx4 v[136:139], v136, s[98:99] offset:128
	v_mfma_f32_16x16x32_bf16 v[84:87], v[236:239], v[198:201], v[84:87]
	s_waitcnt vmcnt(11)
	ds_write_b128 v183, v[132:135] offset:8192
	v_mfma_f32_16x16x32_bf16 v[80:83], v[224:227], v[204:207], v[80:83]
	v_add_u32_e32 v132, 0xa718000, v186
	v_mfma_f32_16x16x32_bf16 v[76:79], v[228:231], v[204:207], v[76:79]
	global_load_dwordx4 v[132:135], v132, s[98:99] offset:128
	s_waitcnt vmcnt(11)
	v_mfma_f32_16x16x32_bf16 v[64:67], v[232:235], v[204:207], v[64:67]
	ds_write_b128 v183, v[120:123] offset:10240
	v_mfma_f32_16x16x32_bf16 v[60:63], v[236:239], v[204:207], v[60:63]
	v_add_u32_e32 v120, 0xa71e000, v186
	global_load_dwordx4 v[120:123], v120, s[98:99] offset:128
	v_mfma_f32_16x16x32_bf16 v[56:59], v[224:227], v[208:211], v[56:59]
	s_waitcnt vmcnt(11)
	v_mfma_f32_16x16x32_bf16 v[52:55], v[228:231], v[208:211], v[52:55]
	ds_write_b128 v183, v[108:111] offset:12288
	v_add_u32_e32 v108, 0xa724000, v186
	v_mfma_f32_16x16x32_bf16 v[48:51], v[232:235], v[208:211], v[48:51]
	global_load_dwordx4 v[108:111], v108, s[98:99] offset:128
	v_mfma_f32_16x16x32_bf16 v[44:47], v[236:239], v[208:211], v[44:47]
	s_waitcnt vmcnt(11)
	ds_write_b128 v183, v[96:99] offset:14336
	v_mfma_f32_16x16x32_bf16 v[40:43], v[224:227], v[212:215], v[40:43]
	v_add_u32_e32 v96, 0xa72a000, v186
	v_mfma_f32_16x16x32_bf16 v[36:39], v[228:231], v[212:215], v[36:39]
	global_load_dwordx4 v[96:99], v96, s[98:99] offset:128
	s_waitcnt vmcnt(11)
	v_mfma_f32_16x16x32_bf16 v[32:35], v[232:235], v[212:215], v[32:35]
	ds_write_b128 v183, v[148:151] offset:16384
	v_mfma_f32_16x16x32_bf16 v[28:31], v[236:239], v[212:215], v[28:31]
	v_add_u32_e32 v148, 0x1f00000, v187
	global_load_dwordx4 v[148:151], v148, s[98:99] offset:128
	v_mfma_f32_16x16x32_bf16 v[24:27], v[224:227], v[216:219], v[24:27]
	s_waitcnt vmcnt(11)
	v_mfma_f32_16x16x32_bf16 v[20:23], v[228:231], v[216:219], v[20:23]
	ds_write_b128 v183, v[88:91] offset:18432
	v_add_u32_e32 v88, 0x1f06000, v187
	v_mfma_f32_16x16x32_bf16 v[16:19], v[232:235], v[216:219], v[16:19]
	global_load_dwordx4 v[88:91], v88, s[98:99] offset:128
	v_mfma_f32_16x16x32_bf16 v[12:15], v[236:239], v[216:219], v[12:15]
	s_waitcnt vmcnt(11)
	ds_write_b128 v183, v[72:75] offset:20480
	v_mfma_f32_16x16x32_bf16 v[8:11], v[224:227], v[220:223], v[8:11]
	v_add_u32_e32 v72, 0x1f0c000, v187
	v_mfma_f32_16x16x32_bf16 v[4:7], v[228:231], v[220:223], v[4:7]
	global_load_dwordx4 v[72:75], v72, s[98:99] offset:128
	s_waitcnt vmcnt(11)
	v_mfma_f32_16x16x32_bf16 v[0:3], v[232:235], v[220:223], v[0:3]
	ds_write_b128 v183, v[68:71] offset:22528
	v_mfma_f32_16x16x32_bf16 v[112:115], v[236:239], v[220:223], v[112:115]
	v_add_u32_e32 v68, 0x1f12000, v187
	global_load_dwordx4 v[68:71], v68, s[98:99] offset:128
	v_cmp_gt_u32_e32 vcc, 0x6000, v183
	v_add_u32_e32 v182, 0xc000, v183
	v_add_u32_e32 v183, 0xffffa000, v183
	s_nop 0
	v_cndmask_b32_e32 v183, v183, v182, vcc
	s_add_u32 s0, s0, 0x80
	s_addc_u32 s1, s1, 0
	s_cmpk_lg_i32 s0, 0x280
	s_cbranch_scc1 .LBB0_400
	s_waitcnt lgkmcnt(0)
	s_barrier
	ds_read_b128 v[224:227], v184
	ds_read_b128 v[228:231], v184 offset:1024
	ds_read_b128 v[232:235], v184 offset:2048
	ds_read_b128 v[236:239], v184 offset:3072
	ds_read_b128 v[190:193], v185
	ds_read_b128 v[194:197], v185 offset:1024
	ds_read_b128 v[198:201], v185 offset:2048
	ds_read_b128 v[204:207], v185 offset:3072
	ds_read_b128 v[208:211], v185 offset:4096
	ds_read_b128 v[212:215], v185 offset:5120
	ds_read_b128 v[216:219], v185 offset:6144
	ds_read_b128 v[220:223], v185 offset:7168
	s_movk_i32 vcc_lo, 0x6000
	s_cmp_eq_u32 m0, 2
	s_cselect_b32 vcc_lo, 0xffff4000, vcc_lo
	s_add_u32 m0, m0, 1
	s_cmp_eq_u32 m0, 3
	s_cselect_b32 m0, 0, m0
	v_add_u32_e32 v185, vcc_lo, v185
	v_add_u32_e32 v184, vcc_lo, v184
	v_xor_b32_e32 v185, 64, v185
	v_xor_b32_e32 v184, 64, v184
	s_waitcnt lgkmcnt(7)
	v_mfma_f32_16x16x32_bf16 v[172:175], v[224:227], v[190:193], v[172:175]
	v_mfma_f32_16x16x32_bf16 v[164:167], v[228:231], v[190:193], v[164:167]
	v_mfma_f32_16x16x32_bf16 v[156:159], v[232:235], v[190:193], v[156:159]
	v_mfma_f32_16x16x32_bf16 v[144:147], v[236:239], v[190:193], v[144:147]
	ds_read_b128 v[190:193], v185
	s_waitcnt lgkmcnt(7)
	v_mfma_f32_16x16x32_bf16 v[140:143], v[224:227], v[194:197], v[140:143]
	v_mfma_f32_16x16x32_bf16 v[128:131], v[228:231], v[194:197], v[128:131]
	v_mfma_f32_16x16x32_bf16 v[124:127], v[232:235], v[194:197], v[124:127]
	v_mfma_f32_16x16x32_bf16 v[116:119], v[236:239], v[194:197], v[116:119]
	ds_read_b128 v[194:197], v185 offset:1024
	s_waitcnt lgkmcnt(7)
	v_mfma_f32_16x16x32_bf16 v[104:107], v[224:227], v[198:201], v[104:107]
	v_mfma_f32_16x16x32_bf16 v[100:103], v[228:231], v[198:201], v[100:103]
	v_mfma_f32_16x16x32_bf16 v[92:95], v[232:235], v[198:201], v[92:95]
	v_mfma_f32_16x16x32_bf16 v[84:87], v[236:239], v[198:201], v[84:87]
	ds_read_b128 v[198:201], v185 offset:2048
	s_waitcnt lgkmcnt(7)
	v_mfma_f32_16x16x32_bf16 v[80:83], v[224:227], v[204:207], v[80:83]
	v_mfma_f32_16x16x32_bf16 v[76:79], v[228:231], v[204:207], v[76:79]
	v_mfma_f32_16x16x32_bf16 v[64:67], v[232:235], v[204:207], v[64:67]
	v_mfma_f32_16x16x32_bf16 v[60:63], v[236:239], v[204:207], v[60:63]
	ds_read_b128 v[204:207], v185 offset:3072
	s_waitcnt lgkmcnt(7)
	v_mfma_f32_16x16x32_bf16 v[56:59], v[224:227], v[208:211], v[56:59]
	v_mfma_f32_16x16x32_bf16 v[52:55], v[228:231], v[208:211], v[52:55]
	v_mfma_f32_16x16x32_bf16 v[48:51], v[232:235], v[208:211], v[48:51]
	v_mfma_f32_16x16x32_bf16 v[44:47], v[236:239], v[208:211], v[44:47]
	ds_read_b128 v[208:211], v185 offset:4096
	s_waitcnt lgkmcnt(7)
	v_mfma_f32_16x16x32_bf16 v[40:43], v[224:227], v[212:215], v[40:43]
	v_mfma_f32_16x16x32_bf16 v[36:39], v[228:231], v[212:215], v[36:39]
	v_mfma_f32_16x16x32_bf16 v[32:35], v[232:235], v[212:215], v[32:35]
	v_mfma_f32_16x16x32_bf16 v[28:31], v[236:239], v[212:215], v[28:31]
	ds_read_b128 v[212:215], v185 offset:5120
	s_waitcnt lgkmcnt(7)
	v_mfma_f32_16x16x32_bf16 v[24:27], v[224:227], v[216:219], v[24:27]
	v_mfma_f32_16x16x32_bf16 v[20:23], v[228:231], v[216:219], v[20:23]
	v_mfma_f32_16x16x32_bf16 v[16:19], v[232:235], v[216:219], v[16:19]
	v_mfma_f32_16x16x32_bf16 v[12:15], v[236:239], v[216:219], v[12:15]
	ds_read_b128 v[216:219], v185 offset:6144
	s_waitcnt lgkmcnt(7)
	v_mfma_f32_16x16x32_bf16 v[8:11], v[224:227], v[220:223], v[8:11]
	v_mfma_f32_16x16x32_bf16 v[4:7], v[228:231], v[220:223], v[4:7]
	v_mfma_f32_16x16x32_bf16 v[0:3], v[232:235], v[220:223], v[0:3]
	v_mfma_f32_16x16x32_bf16 v[112:115], v[236:239], v[220:223], v[112:115]
	ds_read_b128 v[220:223], v185 offset:7168
	ds_read_b128 v[224:227], v184
	ds_read_b128 v[228:231], v184 offset:1024
	ds_read_b128 v[232:235], v184 offset:2048
	ds_read_b128 v[236:239], v184 offset:3072
	s_movk_i32 vcc_lo, 0x6000
	s_cmp_eq_u32 m0, 2
	s_cselect_b32 vcc_lo, 0xffff4000, vcc_lo
	s_add_u32 m0, m0, 1
	s_cmp_eq_u32 m0, 3
	s_cselect_b32 m0, 0, m0
	v_add_u32_e32 v185, vcc_lo, v185
	v_add_u32_e32 v184, vcc_lo, v184
	v_xor_b32_e32 v185, 64, v185
	v_xor_b32_e32 v184, 64, v184
	s_waitcnt lgkmcnt(0)
	v_mfma_f32_16x16x32_bf16 v[172:175], v[224:227], v[190:193], v[172:175]
	v_mfma_f32_16x16x32_bf16 v[164:167], v[228:231], v[190:193], v[164:167]
	v_mfma_f32_16x16x32_bf16 v[156:159], v[232:235], v[190:193], v[156:159]
	v_mfma_f32_16x16x32_bf16 v[144:147], v[236:239], v[190:193], v[144:147]
	v_mfma_f32_16x16x32_bf16 v[140:143], v[224:227], v[194:197], v[140:143]
	v_mfma_f32_16x16x32_bf16 v[128:131], v[228:231], v[194:197], v[128:131]
	v_mfma_f32_16x16x32_bf16 v[124:127], v[232:235], v[194:197], v[124:127]
	v_mfma_f32_16x16x32_bf16 v[116:119], v[236:239], v[194:197], v[116:119]
	v_mfma_f32_16x16x32_bf16 v[104:107], v[224:227], v[198:201], v[104:107]
	v_mfma_f32_16x16x32_bf16 v[100:103], v[228:231], v[198:201], v[100:103]
	v_mfma_f32_16x16x32_bf16 v[92:95], v[232:235], v[198:201], v[92:95]
	v_mfma_f32_16x16x32_bf16 v[84:87], v[236:239], v[198:201], v[84:87]
	v_mfma_f32_16x16x32_bf16 v[80:83], v[224:227], v[204:207], v[80:83]
	v_mfma_f32_16x16x32_bf16 v[76:79], v[228:231], v[204:207], v[76:79]
	v_mfma_f32_16x16x32_bf16 v[64:67], v[232:235], v[204:207], v[64:67]
	v_mfma_f32_16x16x32_bf16 v[60:63], v[236:239], v[204:207], v[60:63]
	v_mfma_f32_16x16x32_bf16 v[56:59], v[224:227], v[208:211], v[56:59]
	v_mfma_f32_16x16x32_bf16 v[52:55], v[228:231], v[208:211], v[52:55]
	v_mfma_f32_16x16x32_bf16 v[48:51], v[232:235], v[208:211], v[48:51]
	v_mfma_f32_16x16x32_bf16 v[44:47], v[236:239], v[208:211], v[44:47]
	v_mfma_f32_16x16x32_bf16 v[40:43], v[224:227], v[212:215], v[40:43]
	v_mfma_f32_16x16x32_bf16 v[36:39], v[228:231], v[212:215], v[36:39]
	v_mfma_f32_16x16x32_bf16 v[32:35], v[232:235], v[212:215], v[32:35]
	v_mfma_f32_16x16x32_bf16 v[28:31], v[236:239], v[212:215], v[28:31]
	v_mfma_f32_16x16x32_bf16 v[24:27], v[224:227], v[216:219], v[24:27]
	v_mfma_f32_16x16x32_bf16 v[20:23], v[228:231], v[216:219], v[20:23]
	v_mfma_f32_16x16x32_bf16 v[16:19], v[232:235], v[216:219], v[16:19]
	v_mfma_f32_16x16x32_bf16 v[12:15], v[236:239], v[216:219], v[12:15]
	v_mfma_f32_16x16x32_bf16 v[8:11], v[224:227], v[220:223], v[8:11]
	v_mfma_f32_16x16x32_bf16 v[4:7], v[228:231], v[220:223], v[4:7]
	v_mfma_f32_16x16x32_bf16 v[0:3], v[232:235], v[220:223], v[0:3]
	v_mfma_f32_16x16x32_bf16 v[112:115], v[236:239], v[220:223], v[112:115]
	v_lshrrev_b32_e32 v224, 4, v188
	v_and_b32_e32 v225, 7, v188
	v_bitop3_b32 v226, v224, v225, 3 bitop3:0x6c
	v_lshlrev_b32_e32 v227, 7, v188
	v_bfe_u32 v228, v188, 4, 2
	v_and_b32_e32 v229, 0xffffc780, v227
	v_and_b32_e32 v227, 0x2780, v227
	v_bitop3_b32 v228, v228, v225, 4 bitop3:0x36
	v_lshlrev_b32_e32 v226, 4, v226
	v_lshlrev_b32_e32 v228, 4, v228
	v_or_b32_e32 v185, v229, v226
	v_or_b32_e32 v184, v227, v226
	v_or_b32_e32 v183, v229, v228
	v_or_b32_e32 v182, v227, v228
	s_waitcnt vmcnt(0)
	s_setprio 1
	s_barrier
	s_waitcnt vmcnt(11)
	ds_write_b128 v176, v[168:171]
	s_waitcnt vmcnt(10)
	ds_write_b128 v176, v[160:163] offset:4096
	s_waitcnt vmcnt(9)
	ds_write_b128 v176, v[152:155] offset:8192
	s_waitcnt vmcnt(8)
	ds_write_b128 v176, v[136:139] offset:12288
	s_waitcnt vmcnt(7)
	ds_write_b128 v176, v[132:135] offset:16384
	s_waitcnt vmcnt(6)
	ds_write_b128 v176, v[120:123] offset:20480
	s_waitcnt vmcnt(5)
	ds_write_b128 v176, v[108:111] offset:24576
	s_waitcnt vmcnt(4)
	ds_write_b128 v176, v[96:99] offset:28672
	s_waitcnt vmcnt(3)
	ds_write_b128 v176, v[148:151] offset:32768
	s_waitcnt vmcnt(2)
	ds_write_b128 v176, v[88:91] offset:36864
	s_waitcnt vmcnt(1)
	ds_write_b128 v176, v[72:75] offset:40960
	s_waitcnt vmcnt(0)
	ds_write_b128 v176, v[68:71] offset:45056
	s_waitcnt lgkmcnt(0)
	s_barrier
	ds_read_b128 v[68:71], v185
	ds_read_b128 v[72:75], v185 offset:2048
	ds_read_b128 v[88:91], v185 offset:4096
	ds_read_b128 v[96:99], v185 offset:6144
	ds_read_b128 v[108:111], v185 offset:8192
	ds_read_b128 v[120:123], v185 offset:10240
	ds_read_b128 v[132:135], v185 offset:12288
	ds_read_b128 v[136:139], v185 offset:14336
	ds_read_b128 v[148:151], v184 offset:32768
	ds_read_b128 v[152:155], v184 offset:34816
	ds_read_b128 v[160:163], v184 offset:36864
	ds_read_b128 v[168:171], v184 offset:38912
	s_waitcnt lgkmcnt(3)
	v_mfma_f32_16x16x32_bf16 v[172:175], v[148:151], v[68:71], v[172:175]
	s_waitcnt lgkmcnt(2)
	v_mfma_f32_16x16x32_bf16 v[164:167], v[152:155], v[68:71], v[164:167]
	s_waitcnt lgkmcnt(1)
	v_mfma_f32_16x16x32_bf16 v[156:159], v[160:163], v[68:71], v[156:159]
	s_waitcnt lgkmcnt(0)
	v_mfma_f32_16x16x32_bf16 v[68:71], v[168:171], v[68:71], v[144:147]
	v_mfma_f32_16x16x32_bf16 v[140:143], v[148:151], v[72:75], v[140:143]
	v_mfma_f32_16x16x32_bf16 v[128:131], v[152:155], v[72:75], v[128:131]
	v_mfma_f32_16x16x32_bf16 v[144:147], v[160:163], v[72:75], v[124:127]
	v_mfma_f32_16x16x32_bf16 v[72:75], v[168:171], v[72:75], v[116:119]
	v_mfma_f32_16x16x32_bf16 v[64:67], v[160:163], v[96:99], v[64:67]
	v_mfma_f32_16x16x32_bf16 v[60:63], v[168:171], v[96:99], v[60:63]
	v_mfma_f32_16x16x32_bf16 v[56:59], v[148:151], v[108:111], v[56:59]
	v_mfma_f32_16x16x32_bf16 v[52:55], v[152:155], v[108:111], v[52:55]
	v_mfma_f32_16x16x32_bf16 v[48:51], v[160:163], v[108:111], v[48:51]
	v_mfma_f32_16x16x32_bf16 v[44:47], v[168:171], v[108:111], v[44:47]
	v_mfma_f32_16x16x32_bf16 v[40:43], v[148:151], v[120:123], v[40:43]
	v_mfma_f32_16x16x32_bf16 v[36:39], v[152:155], v[120:123], v[36:39]
	v_mfma_f32_16x16x32_bf16 v[32:35], v[160:163], v[120:123], v[32:35]
	v_mfma_f32_16x16x32_bf16 v[28:31], v[168:171], v[120:123], v[28:31]
	v_mfma_f32_16x16x32_bf16 v[24:27], v[148:151], v[132:135], v[24:27]
	v_mfma_f32_16x16x32_bf16 v[20:23], v[152:155], v[132:135], v[20:23]
	v_mfma_f32_16x16x32_bf16 v[16:19], v[160:163], v[132:135], v[16:19]
	v_mfma_f32_16x16x32_bf16 v[12:15], v[168:171], v[132:135], v[12:15]
	v_mfma_f32_16x16x32_bf16 v[8:11], v[148:151], v[136:139], v[8:11]
	v_mfma_f32_16x16x32_bf16 v[4:7], v[152:155], v[136:139], v[4:7]
	v_mfma_f32_16x16x32_bf16 v[0:3], v[160:163], v[136:139], v[0:3]
	v_mfma_f32_16x16x32_bf16 v[178:181], v[148:151], v[88:91], v[104:107]
	v_mfma_f32_16x16x32_bf16 v[184:187], v[152:155], v[88:91], v[100:103]
	v_mfma_f32_16x16x32_bf16 v[190:193], v[160:163], v[88:91], v[92:95]
	v_mfma_f32_16x16x32_bf16 v[194:197], v[168:171], v[88:91], v[84:87]
	v_mfma_f32_16x16x32_bf16 v[198:201], v[148:151], v[96:99], v[80:83]
	v_mfma_f32_16x16x32_bf16 v[204:207], v[152:155], v[96:99], v[76:79]
	v_mfma_f32_16x16x32_bf16 v[148:151], v[168:171], v[136:139], v[112:115]
	s_nop 1
	ds_read_b128 v[76:79], v183
	ds_read_b128 v[80:83], v183 offset:2048
	ds_read_b128 v[132:135], v183 offset:4096
	ds_read_b128 v[136:139], v183 offset:6144
	ds_read_b128 v[152:155], v183 offset:8192
	ds_read_b128 v[160:163], v183 offset:10240
	ds_read_b128 v[168:171], v183 offset:12288
	ds_read_b128 v[208:211], v183 offset:14336
	ds_read_b128 v[212:215], v182 offset:32768
	ds_read_b128 v[216:219], v182 offset:34816
	ds_read_b128 v[220:223], v182 offset:36864
	ds_read_b128 v[224:227], v182 offset:38912
	s_waitcnt lgkmcnt(3)
	v_mfma_f32_16x16x32_bf16 v[124:127], v[212:215], v[76:79], v[172:175]
	s_movk_i32 s0, 0xfff
	s_waitcnt lgkmcnt(2)
	v_mfma_f32_16x16x32_bf16 v[120:123], v[216:219], v[76:79], v[164:167]
	s_waitcnt lgkmcnt(1)
	v_mfma_f32_16x16x32_bf16 v[116:119], v[220:223], v[76:79], v[156:159]
	s_waitcnt lgkmcnt(0)
	v_mfma_f32_16x16x32_bf16 v[112:115], v[224:227], v[76:79], v[68:71]
	v_mfma_f32_16x16x32_bf16 v[108:111], v[212:215], v[80:83], v[140:143]
	v_mfma_f32_16x16x32_bf16 v[104:107], v[216:219], v[80:83], v[128:131]
	v_mfma_f32_16x16x32_bf16 v[100:103], v[220:223], v[80:83], v[144:147]
	v_mfma_f32_16x16x32_bf16 v[96:99], v[224:227], v[80:83], v[72:75]
	v_mfma_f32_16x16x32_bf16 v[92:95], v[212:215], v[132:135], v[178:181]
	v_mfma_f32_16x16x32_bf16 v[88:91], v[216:219], v[132:135], v[184:187]
	v_mfma_f32_16x16x32_bf16 v[84:87], v[220:223], v[132:135], v[190:193]
	v_mfma_f32_16x16x32_bf16 v[80:83], v[224:227], v[132:135], v[194:197]
	v_mov_b32_e32 v132, v188
	v_mfma_f32_16x16x32_bf16 v[76:79], v[212:215], v[136:139], v[198:201]
	v_mfma_f32_16x16x32_bf16 v[72:75], v[216:219], v[136:139], v[204:207]
	v_mfma_f32_16x16x32_bf16 v[68:71], v[220:223], v[136:139], v[64:67]
	v_mfma_f32_16x16x32_bf16 v[64:67], v[224:227], v[136:139], v[60:63]
	v_mov_b32_e32 v137, v188
	v_mfma_f32_16x16x32_bf16 v[60:63], v[212:215], v[152:155], v[56:59]
	v_and_b32_e32 v143, 15, v137
	v_and_or_b32 v136, v132, 64, s8
	v_and_b32_e32 v176, 48, v137
	v_mfma_f32_16x16x32_bf16 v[56:59], v[216:219], v[152:155], v[52:55]
	v_mfma_f32_16x16x32_bf16 v[52:55], v[220:223], v[152:155], v[48:51]
	v_mfma_f32_16x16x32_bf16 v[48:51], v[224:227], v[152:155], v[44:47]
	v_mfma_f32_16x16x32_bf16 v[44:47], v[212:215], v[160:163], v[40:43]
	v_mfma_f32_16x16x32_bf16 v[40:43], v[216:219], v[160:163], v[36:39]
	v_mfma_f32_16x16x32_bf16 v[36:39], v[224:227], v[160:163], v[28:31]
	s_nop 2
	v_and_b32_e32 v28, 0xffffff80, v132
	v_add_u32_e32 v144, s9, v28
	v_or_b32_e32 v145, v144, v143
	v_mfma_f32_16x16x32_bf16 v[28:31], v[216:219], v[168:171], v[20:23]
	v_cmp_lt_i32_e32 vcc, s0, v144
	s_mov_b32 s0, 0x2aaaaaab
	v_and_b32_e32 v142, 0x380, v144
	v_lshlrev_b32_e32 v20, 3, v145
	v_ashrrev_i32_e32 v21, 31, v20
	v_lshl_add_u64 v[128:129], v[20:21], 2, s[4:5]
	global_load_dwordx2 v[138:139], v[128:129], off offset:16
	s_nop 0
	global_load_dwordx4 v[128:131], v[128:129], off
	v_mfma_f32_16x16x32_bf16 v[20:23], v[220:223], v[168:171], v[16:19]
	v_mfma_f32_16x16x32_bf16 v[16:19], v[224:227], v[168:171], v[12:15]
	s_nop 2
	v_mul_hi_i32 v12, v136, s0
	v_lshrrev_b32_e32 v13, 31, v12
	v_lshrrev_b32_e32 v12, 5, v12
	v_add_u32_e32 v132, v12, v13
	s_movk_i32 s0, 0xc0
	v_mfma_f32_16x16x32_bf16 v[12:15], v[216:219], v[208:211], v[4:7]
	s_nop 2
	v_mul_lo_u32 v4, v132, s0
	v_sub_u32_e32 v4, v136, v4
	v_cmp_eq_u32_e64 s[0:1], s19, v4
	s_and_b64 s[40:41], s[0:1], vcc
	v_readlane_b32 s0, v255, 45
	v_mfma_f32_16x16x32_bf16 v[32:35], v[220:223], v[160:163], v[32:35]
	v_readlane_b32 s1, v255, 46
	v_mfma_f32_16x16x32_bf16 v[24:27], v[212:215], v[168:171], v[24:27]
	s_nop 0
	v_lshl_add_u64 v[134:135], s[0:1], 0, v[176:177]
	v_readlane_b32 s0, v255, 47
	v_readlane_b32 s1, v255, 48
	v_mfma_f32_16x16x32_bf16 v[8:11], v[212:215], v[208:211], v[8:11]
	s_nop 0
	v_lshl_add_u64 v[132:133], s[0:1], 0, v[176:177]
	v_mfma_f32_16x16x32_bf16 v[0:3], v[220:223], v[208:211], v[0:3]
	v_mfma_f32_16x16x32_bf16 v[4:7], v[224:227], v[208:211], v[148:151]
	s_and_saveexec_b64 s[0:1], s[40:41]
	s_cbranch_execz .LBB0_403
	v_or_b32_e32 v140, v142, v143
	v_lshlrev_b32_e32 v176, 7, v140
	v_lshl_add_u64 v[154:155], v[134:135], 0, v[176:177]
	v_lshl_add_u64 v[156:157], v[132:133], 0, v[176:177]
	global_load_dwordx4 v[146:149], v[154:155], off
	global_load_dwordx4 v[150:153], v[156:157], off
	s_waitcnt vmcnt(0)
	v_pk_mul_f32 v[158:159], v[124:125], v[150:151]
	v_pk_mul_f32 v[140:141], v[116:117], v[150:151]
	v_mul_f32_e32 v150, v126, v148
	v_mul_f32_e32 v160, v118, v152
	v_mul_f32_e32 v162, v126, v152
	v_mul_f32_e32 v148, v118, v148
	v_mov_b32_e32 v118, v127
	v_mov_b32_e32 v152, v149
	v_mov_b32_e32 v126, v119
	v_pk_mul_f32 v[164:165], v[118:119], v[152:153]
	v_pk_mul_f32 v[118:119], v[126:127], v[152:153]
	v_mov_b32_e32 v151, v164
	v_mov_b32_e32 v161, v165
	v_mov_b32_e32 v149, v118
	v_mov_b32_e32 v163, v119
	v_pk_fma_f32 v[124:125], v[124:125], v[146:147], v[140:141] neg_lo:[0,0,1] neg_hi:[0,0,1]
	v_pk_add_f32 v[140:141], v[150:151], v[160:161] neg_lo:[0,1] neg_hi:[0,1]
	v_pk_fma_f32 v[116:117], v[116:117], v[146:147], v[158:159]
	v_pk_add_f32 v[118:119], v[148:149], v[162:163]
	global_load_dwordx4 v[146:149], v[154:155], off offset:64
	global_load_dwordx4 v[150:153], v[156:157], off offset:64
	s_waitcnt vmcnt(1)
	v_mul_f32_e32 v154, v122, v148
	s_waitcnt vmcnt(0)
	v_mul_f32_e32 v156, v114, v152
	v_mul_f32_e32 v158, v122, v152
	v_mul_f32_e32 v148, v114, v148
	v_mov_b32_e32 v114, v123
	v_mov_b32_e32 v152, v149
	v_pk_mul_f32 v[160:161], v[114:115], v[152:153]
	v_mov_b32_e32 v122, v115
	v_pk_mul_f32 v[126:127], v[120:121], v[150:151]
	v_pk_mul_f32 v[150:151], v[112:113], v[150:151]
	v_mov_b32_e32 v155, v160
	v_mov_b32_e32 v157, v161
	v_pk_mul_f32 v[114:115], v[122:123], v[152:153]
	v_pk_fma_f32 v[120:121], v[120:121], v[146:147], v[150:151] neg_lo:[0,0,1] neg_hi:[0,0,1]
	v_pk_add_f32 v[150:151], v[154:155], v[156:157] neg_lo:[0,1] neg_hi:[0,1]
	v_mov_b32_e32 v149, v114
	v_mov_b32_e32 v159, v115
	v_pk_fma_f32 v[112:113], v[112:113], v[146:147], v[126:127]
	v_pk_add_f32 v[114:115], v[148:149], v[158:159]
	v_mov_b32_e32 v122, v150
	v_mov_b32_e32 v123, v151
	v_mov_b32_e32 v126, v140
	v_mov_b32_e32 v127, v141

.LBB0_422:
	s_lshl_b32 s42, s42, 1
	s_ashr_i32 s9, s9, 5
	s_sub_i32 s42, s42, s43
	s_add_i32 s9, s9, s42
	s_lshl_b32 s9, s9, 3
	s_add_i32 s9, s9, s1
	s_lshl_b32 s94, s9, 7
	s_and_b64 s[42:43], s[92:93], exec
	s_mov_b32 s1, 0x2400000
	s_cselect_b32 s1, s1, 0x2200000
	s_add_u32 s42, s36, s1
	s_addc_u32 s43, s6, 0
	s_and_b32 s95, s0, 1
	s_bitcmp1_b32 s0, 0
	s_cselect_b64 s[0:1], -1, 0
	s_cmp_eq_u32 s95, 0
	s_cbranch_scc1 .LBB0_426
	v_mov_b32_e32 v6, v188
	s_mov_b32 s95, 0x8000
	v_ashrrev_i32_e32 v7, 3, v6
	v_lshlrev_b32_e32 v4, 4, v6
	v_and_b32_e32 v176, 0x70, v4
	v_add_u32_e32 v4, s94, v7
	v_ashrrev_i32_e32 v5, 31, v4
	v_add_u32_e32 v0, s8, v7
	v_lshlrev_b64 v[4:5], 9, v[4:5]
	v_ashrrev_i32_e32 v1, 31, v0
	v_lshl_add_u64 v[4:5], s[42:43], 0, v[4:5]
	v_xor_b32_e32 v8, v7, v6
	v_lshlrev_b64 v[0:1], 9, v[0:1]
	v_lshl_add_u64 v[178:179], v[4:5], 0, v[176:177]
	v_lshlrev_b32_e32 v4, 4, v8
	v_lshl_add_u64 v[2:3], s[46:47], 0, v[0:1]
	v_and_b32_e32 v4, 0x70, v4
	v_lshl_add_u64 v[2:3], v[2:3], 0, v[176:177]
	v_lshl_or_b32 v176, v7, 7, v4
	v_lshrrev_b32_e32 v4, 4, v6
	v_and_b32_e32 v11, 7, v6
	v_bitop3_b32 v12, v4, v11, 3 bitop3:0x6c
	v_add_co_u32_e32 v4, vcc, s28, v178
	v_lshlrev_b32_e32 v8, 7, v6
	s_nop 0
	v_addc_co_u32_e32 v5, vcc, 0, v179, vcc
	v_bfe_u32 v10, v6, 4, 2
	v_add_co_u32_e32 v6, vcc, s95, v178
	s_movk_i32 s16, 0x4000
	s_nop 0
	v_addc_co_u32_e32 v7, vcc, 0, v179, vcc
	global_load_dwordx4 v[20:23], v[4:5], off
	global_load_dwordx4 v[24:27], v[6:7], off
	v_add_co_u32_e32 v4, vcc, s16, v178
	s_mov_b32 s15, 0x1c000
	s_nop 0
	v_addc_co_u32_e32 v5, vcc, 0, v179, vcc
	v_add_co_u32_e32 v6, vcc, s15, v2
	s_mov_b32 s15, 0x18000
	s_nop 0
	v_addc_co_u32_e32 v7, vcc, 0, v3, vcc
	global_load_dwordx4 v[40:43], v[4:5], off
	global_load_dwordx4 v[48:51], v[6:7], off
	v_add_co_u32_e32 v4, vcc, s15, v2
	s_mov_b32 s15, 0x14000
	s_nop 0
	v_addc_co_u32_e32 v5, vcc, 0, v3, vcc
	v_add_co_u32_e32 v6, vcc, s15, v2
	v_and_b32_e32 v9, 0xffffc780, v8
	s_nop 0
	v_addc_co_u32_e32 v7, vcc, 0, v3, vcc
	global_load_dwordx4 v[68:71], v[4:5], off
	global_load_dwordx4 v[72:75], v[6:7], off
	v_add_co_u32_e32 v4, vcc, s14, v2
	v_and_b32_e32 v8, 0x2780, v8
	s_nop 0
	v_addc_co_u32_e32 v5, vcc, 0, v3, vcc
	v_add_co_u32_e32 v6, vcc, s28, v2
	v_bitop3_b32 v10, v10, v11, 4 bitop3:0x36
	s_nop 0
	v_addc_co_u32_e32 v7, vcc, 0, v3, vcc
	global_load_dwordx4 v[84:87], v[4:5], off
	global_load_dwordx4 v[92:95], v[6:7], off
	v_add_co_u32_e32 v4, vcc, s95, v2
	v_lshl_or_b32 v0, v11, 4, v0
	s_nop 0
	v_addc_co_u32_e32 v5, vcc, 0, v3, vcc
	v_add_co_u32_e32 v6, vcc, s16, v2
	v_mov_b32_e32 v140, 0
	s_nop 0
	v_addc_co_u32_e32 v7, vcc, 0, v3, vcc
	global_load_dwordx4 v[104:107], v[4:5], off
	global_load_dwordx4 v[112:115], v[6:7], off
	global_load_dwordx4 v[56:59], v[178:179], off
	global_load_dwordx4 v[116:119], v[2:3], off
	v_lshlrev_b32_e32 v2, 4, v12
	v_or_b32_e32 v185, v9, v2
	v_or_b32_e32 v184, v8, v2
	v_lshlrev_b32_e32 v2, 4, v10
	v_or_b32_e32 v183, v9, v2
	v_or_b32_e32 v182, v8, v2
	v_lshl_add_u64 v[180:181], s[58:59], 0, v[0:1]
	s_mov_b64 s[30:31], 0
	v_mov_b32_e32 v141, v140
	v_mov_b32_e32 v142, v140
	v_mov_b32_e32 v143, v140
	v_mov_b32_e32 v0, v140
	v_mov_b32_e32 v1, v140
	v_mov_b32_e32 v2, v140
	v_mov_b32_e32 v3, v140
	v_mov_b32_e32 v4, v140
	v_mov_b32_e32 v5, v140
	v_mov_b32_e32 v6, v140
	v_mov_b32_e32 v7, v140
	v_mov_b32_e32 v8, v140
	v_mov_b32_e32 v9, v140
	v_mov_b32_e32 v10, v140
	v_mov_b32_e32 v11, v140
	v_mov_b32_e32 v12, v140
	v_mov_b32_e32 v13, v140
	v_mov_b32_e32 v14, v140
	v_mov_b32_e32 v15, v140
	v_mov_b32_e32 v16, v140
	v_mov_b32_e32 v17, v140
	v_mov_b32_e32 v18, v140
	v_mov_b32_e32 v19, v140
	v_mov_b32_e32 v28, v140
	v_mov_b32_e32 v29, v140
	v_mov_b32_e32 v30, v140
	v_mov_b32_e32 v31, v140
	v_mov_b32_e32 v32, v140
	v_mov_b32_e32 v33, v140
	v_mov_b32_e32 v34, v140
	v_mov_b32_e32 v35, v140
	v_mov_b32_e32 v36, v140
	v_mov_b32_e32 v37, v140
	v_mov_b32_e32 v38, v140
	v_mov_b32_e32 v39, v140
	v_mov_b32_e32 v44, v140
	v_mov_b32_e32 v45, v140
	v_mov_b32_e32 v46, v140
	v_mov_b32_e32 v47, v140
	v_mov_b32_e32 v52, v140
	v_mov_b32_e32 v53, v140
	v_mov_b32_e32 v54, v140
	v_mov_b32_e32 v55, v140
	v_mov_b32_e32 v60, v140
	v_mov_b32_e32 v61, v140
	v_mov_b32_e32 v62, v140
	v_mov_b32_e32 v63, v140
	v_mov_b32_e32 v64, v140
	v_mov_b32_e32 v65, v140
	v_mov_b32_e32 v66, v140
	v_mov_b32_e32 v67, v140
	v_mov_b32_e32 v76, v140
	v_mov_b32_e32 v77, v140
	v_mov_b32_e32 v78, v140
	v_mov_b32_e32 v79, v140
	v_mov_b32_e32 v80, v140
	v_mov_b32_e32 v81, v140
	v_mov_b32_e32 v82, v140
	v_mov_b32_e32 v83, v140
	v_mov_b32_e32 v88, v140
	v_mov_b32_e32 v89, v140
	v_mov_b32_e32 v90, v140
	v_mov_b32_e32 v91, v140
	v_mov_b32_e32 v96, v140
	v_mov_b32_e32 v97, v140
	v_mov_b32_e32 v98, v140
	v_mov_b32_e32 v99, v140
	v_mov_b32_e32 v100, v140
	v_mov_b32_e32 v101, v140
	v_mov_b32_e32 v102, v140
	v_mov_b32_e32 v103, v140
	v_mov_b32_e32 v108, v140
	v_mov_b32_e32 v109, v140
	v_mov_b32_e32 v110, v140
	v_mov_b32_e32 v111, v140
	v_mov_b32_e32 v120, v140
	v_mov_b32_e32 v121, v140
	v_mov_b32_e32 v122, v140
	v_mov_b32_e32 v123, v140
	v_mov_b32_e32 v124, v140
	v_mov_b32_e32 v125, v140
	v_mov_b32_e32 v126, v140
	v_mov_b32_e32 v127, v140
	v_mov_b32_e32 v128, v140
	v_mov_b32_e32 v129, v140
	v_mov_b32_e32 v130, v140
	v_mov_b32_e32 v131, v140
	v_mov_b32_e32 v132, v140
	v_mov_b32_e32 v133, v140
	v_mov_b32_e32 v134, v140
	v_mov_b32_e32 v135, v140
	v_mov_b32_e32 v136, v140
	v_mov_b32_e32 v137, v140
	v_mov_b32_e32 v138, v140
	v_mov_b32_e32 v139, v140
	v_mov_b32_e32 v144, v140
	v_mov_b32_e32 v145, v140
	v_mov_b32_e32 v146, v140
	v_mov_b32_e32 v147, v140
	v_mov_b32_e32 v148, v140
	v_mov_b32_e32 v149, v140
	v_mov_b32_e32 v150, v140
	v_mov_b32_e32 v151, v140
	v_mov_b32_e32 v152, v140
	v_mov_b32_e32 v153, v140
	v_mov_b32_e32 v154, v140
	v_mov_b32_e32 v155, v140
	v_mov_b32_e32 v156, v140
	v_mov_b32_e32 v157, v140
	v_mov_b32_e32 v158, v140
	v_mov_b32_e32 v159, v140
	v_mov_b32_e32 v160, v140
	v_mov_b32_e32 v161, v140
	v_mov_b32_e32 v162, v140
	v_mov_b32_e32 v163, v140
	v_mov_b32_e32 v164, v140
	v_mov_b32_e32 v165, v140
	v_mov_b32_e32 v166, v140
	v_mov_b32_e32 v167, v140
	v_mov_b32_e32 v168, v140
	v_mov_b32_e32 v169, v140
	v_mov_b32_e32 v170, v140
	v_mov_b32_e32 v171, v140
	v_mov_b32_e32 v172, v140
	v_mov_b32_e32 v173, v140
	v_mov_b32_e32 v174, v140
	v_mov_b32_e32 v175, v140
	s_mov_b32 s15, 0xad00000
	s_mov_b32 s17, 0xad04000
	s_mov_b32 s52, 0xad08000
	s_mov_b32 s53, 0xad0c000
	s_mov_b32 s10, 0xad10000
	s_mov_b32 s11, 0xad14000
	s_mov_b32 s12, 0xad18000
	s_mov_b32 s13, 0xad1c000
	v_readlane_b32 vcc_lo, v253, 0
	s_cmpk_lt_u32 vcc_lo, 0x100
	s_cbranch_scc1 .Lprio_hi3
	s_setprio 2
	s_branch .Lprio_done3

.Lprio_done3:
	v_readlane_b32 s98, v253, 3
	v_readlane_b32 s99, v253, 4
	v_and_b32_e32 v224, 15, v188
	v_bfe_u32 v225, v188, 4, 2
	v_lshrrev_b32_e32 v226, 2, v224
	v_sub_u32_e32 v226, 0, v226
	v_and_b32_e32 v226, 3, v226
	v_xor_b32_e32 v225, v225, v226
	v_lshlrev_b32_e32 v225, 4, v225
	v_lshl_or_b32 v225, v224, 6, v225
	v_bfe_u32 v226, v188, 7, 1
	v_lshl_or_b32 v185, v226, 13, v225
	v_bfe_u32 v226, v188, 6, 1
	v_lshl_or_b32 v184, v226, 12, v225
	v_add_u32_e32 v184, 0x4000, v184
	v_lshrrev_b32_e32 v224, 3, v188
	v_bfe_u32 v225, v188, 2, 1
	v_lshrrev_b32_e32 v226, 2, v224
	v_sub_u32_e32 v226, 0, v226
	v_and_b32_e32 v226, 3, v226
	v_and_b32_e32 v227, 3, v188
	v_xor_b32_e32 v226, v227, v226
	v_lshlrev_b32_e32 v226, 4, v226
	v_xor_b32_e32 v224, v224, v225
	v_lshl_or_b32 v226, v224, 6, v226
	v_mul_u32_u24_e32 v225, 0x6000, v225
	v_add_u32_e32 v183, v225, v226
	s_mov_b32 m0, 0
	s_sub_u32 vcc_lo, s30, s98
	v_add_u32_e32 v186, vcc_lo, v178
	v_add_u32_e32 v187, vcc_lo, v180
	s_barrier
	s_waitcnt vmcnt(0)
	ds_write_b128 v183, v[116:119]
	ds_write_b128 v183, v[112:115] offset:2048
	ds_write_b128 v183, v[104:107] offset:4096
	ds_write_b128 v183, v[92:95] offset:6144
	ds_write_b128 v183, v[84:87] offset:8192
	ds_write_b128 v183, v[72:75] offset:10240
	ds_write_b128 v183, v[68:71] offset:12288
	ds_write_b128 v183, v[48:51] offset:14336
	ds_write_b128 v183, v[56:59] offset:16384
	ds_write_b128 v183, v[40:43] offset:18432
	ds_write_b128 v183, v[24:27] offset:20480
	ds_write_b128 v183, v[20:23] offset:22528
	v_cmp_gt_u32_e32 vcc, 0x6000, v183
	v_add_u32_e32 v182, 0xc000, v183
	v_add_u32_e32 v183, 0xffffa000, v183
	s_nop 0
	v_cndmask_b32_e32 v183, v183, v182, vcc
	v_add_u32_e32 v116, s15, v187
	global_load_dwordx4 v[116:119], v116, s[98:99] offset:128
	v_add_u32_e32 v112, s17, v187
	global_load_dwordx4 v[112:115], v112, s[98:99] offset:128
	v_add_u32_e32 v104, s52, v187
	global_load_dwordx4 v[104:107], v104, s[98:99] offset:128
	v_add_u32_e32 v92, s53, v187
	global_load_dwordx4 v[92:95], v92, s[98:99] offset:128
	v_add_u32_e32 v84, s10, v187
	global_load_dwordx4 v[84:87], v84, s[98:99] offset:128
	v_add_u32_e32 v72, s11, v187
	global_load_dwordx4 v[72:75], v72, s[98:99] offset:128
	v_add_u32_e32 v68, s12, v187
	global_load_dwordx4 v[68:71], v68, s[98:99] offset:128
	v_add_u32_e32 v48, s13, v187
	global_load_dwordx4 v[48:51], v48, s[98:99] offset:128
	v_mov_b32_e32 v56, v186
	global_load_dwordx4 v[56:59], v56, s[98:99] offset:128
	v_add_u32_e32 v40, s16, v186
	global_load_dwordx4 v[40:43], v40, s[98:99] offset:128
	v_add_u32_e32 v24, s95, v186
	global_load_dwordx4 v[24:27], v24, s[98:99] offset:128
	v_add_u32_e32 v20, s28, v186
	global_load_dwordx4 v[20:23], v20, s[98:99] offset:128
	s_add_u32 s30, s30, 0x80
	s_addc_u32 s31, s31, 0
.LBB0_424:
	s_waitcnt lgkmcnt(0)
	s_barrier
	ds_read_b128 v[224:227], v184
	ds_read_b128 v[228:231], v184 offset:1024
	ds_read_b128 v[232:235], v184 offset:2048
	ds_read_b128 v[236:239], v184 offset:3072
	ds_read_b128 v[190:193], v185
	ds_read_b128 v[194:197], v185 offset:1024
	ds_read_b128 v[198:201], v185 offset:2048
	ds_read_b128 v[204:207], v185 offset:3072
	ds_read_b128 v[208:211], v185 offset:4096
	ds_read_b128 v[212:215], v185 offset:5120
	ds_read_b128 v[216:219], v185 offset:6144
	ds_read_b128 v[220:223], v185 offset:7168
	s_movk_i32 vcc_lo, 0x6000
	s_cmp_eq_u32 m0, 2
	s_cselect_b32 vcc_lo, 0xffff4000, vcc_lo
	s_add_u32 m0, m0, 1
	s_cmp_eq_u32 m0, 3
	s_cselect_b32 m0, 0, m0
	v_add_u32_e32 v185, vcc_lo, v185
	v_add_u32_e32 v184, vcc_lo, v184
	v_xor_b32_e32 v185, 64, v185
	v_xor_b32_e32 v184, 64, v184
	s_waitcnt lgkmcnt(7)
	v_mfma_f32_16x16x32_bf16 v[172:175], v[190:193], v[224:227], v[172:175]
	v_mfma_f32_16x16x32_bf16 v[168:171], v[190:193], v[228:231], v[168:171]
	v_mfma_f32_16x16x32_bf16 v[164:167], v[190:193], v[232:235], v[164:167]
	v_mfma_f32_16x16x32_bf16 v[160:163], v[190:193], v[236:239], v[160:163]
	ds_read_b128 v[190:193], v185
	s_waitcnt lgkmcnt(7)
	v_mfma_f32_16x16x32_bf16 v[156:159], v[194:197], v[224:227], v[156:159]
	v_mfma_f32_16x16x32_bf16 v[152:155], v[194:197], v[228:231], v[152:155]
	v_mfma_f32_16x16x32_bf16 v[148:151], v[194:197], v[232:235], v[148:151]
	v_mfma_f32_16x16x32_bf16 v[144:147], v[194:197], v[236:239], v[144:147]
	ds_read_b128 v[194:197], v185 offset:1024
	s_waitcnt lgkmcnt(7)
	v_mfma_f32_16x16x32_bf16 v[136:139], v[198:201], v[224:227], v[136:139]
	v_mfma_f32_16x16x32_bf16 v[132:135], v[198:201], v[228:231], v[132:135]
	v_mfma_f32_16x16x32_bf16 v[128:131], v[198:201], v[232:235], v[128:131]
	v_mfma_f32_16x16x32_bf16 v[124:127], v[198:201], v[236:239], v[124:127]
	ds_read_b128 v[198:201], v185 offset:2048
	s_waitcnt lgkmcnt(7)
	v_mfma_f32_16x16x32_bf16 v[120:123], v[204:207], v[224:227], v[120:123]
	v_mfma_f32_16x16x32_bf16 v[108:111], v[204:207], v[228:231], v[108:111]
	v_mfma_f32_16x16x32_bf16 v[100:103], v[204:207], v[232:235], v[100:103]
	v_mfma_f32_16x16x32_bf16 v[96:99], v[204:207], v[236:239], v[96:99]
	ds_read_b128 v[204:207], v185 offset:3072
	s_waitcnt lgkmcnt(7)
	v_mfma_f32_16x16x32_bf16 v[88:91], v[208:211], v[224:227], v[88:91]
	v_mfma_f32_16x16x32_bf16 v[80:83], v[208:211], v[228:231], v[80:83]
	v_mfma_f32_16x16x32_bf16 v[76:79], v[208:211], v[232:235], v[76:79]
	v_mfma_f32_16x16x32_bf16 v[64:67], v[208:211], v[236:239], v[64:67]
	ds_read_b128 v[208:211], v185 offset:4096
	s_waitcnt lgkmcnt(7)
	v_mfma_f32_16x16x32_bf16 v[60:63], v[212:215], v[224:227], v[60:63]
	v_mfma_f32_16x16x32_bf16 v[52:55], v[212:215], v[228:231], v[52:55]
	v_mfma_f32_16x16x32_bf16 v[44:47], v[212:215], v[232:235], v[44:47]
	v_mfma_f32_16x16x32_bf16 v[36:39], v[212:215], v[236:239], v[36:39]
	ds_read_b128 v[212:215], v185 offset:5120
	s_waitcnt lgkmcnt(7)
	v_mfma_f32_16x16x32_bf16 v[32:35], v[216:219], v[224:227], v[32:35]
	v_mfma_f32_16x16x32_bf16 v[28:31], v[216:219], v[228:231], v[28:31]
	v_mfma_f32_16x16x32_bf16 v[16:19], v[216:219], v[232:235], v[16:19]
	v_mfma_f32_16x16x32_bf16 v[12:15], v[216:219], v[236:239], v[12:15]
	ds_read_b128 v[216:219], v185 offset:6144
	s_waitcnt lgkmcnt(7)
	v_mfma_f32_16x16x32_bf16 v[8:11], v[220:223], v[224:227], v[8:11]
	v_mfma_f32_16x16x32_bf16 v[4:7], v[220:223], v[228:231], v[4:7]
	v_mfma_f32_16x16x32_bf16 v[0:3], v[220:223], v[232:235], v[0:3]
	v_mfma_f32_16x16x32_bf16 v[140:143], v[220:223], v[236:239], v[140:143]
	ds_read_b128 v[220:223], v185 offset:7168
	ds_read_b128 v[224:227], v184
	ds_read_b128 v[228:231], v184 offset:1024
	ds_read_b128 v[232:235], v184 offset:2048
	ds_read_b128 v[236:239], v184 offset:3072
	s_movk_i32 vcc_lo, 0x6000
	s_cmp_eq_u32 m0, 2
	s_cselect_b32 vcc_lo, 0xffff4000, vcc_lo
	s_add_u32 m0, m0, 1
	s_cmp_eq_u32 m0, 3
	s_cselect_b32 m0, 0, m0
	v_add_u32_e32 v185, vcc_lo, v185
	v_add_u32_e32 v184, vcc_lo, v184
	v_xor_b32_e32 v185, 64, v185
	v_xor_b32_e32 v184, 64, v184
	s_sub_u32 vcc_lo, s30, s98
	v_add_u32_e32 v186, vcc_lo, v178
	v_add_u32_e32 v187, vcc_lo, v180
	s_barrier
	s_waitcnt lgkmcnt(0)
	v_mfma_f32_16x16x32_bf16 v[172:175], v[190:193], v[224:227], v[172:175]
	s_waitcnt vmcnt(11)
	v_mfma_f32_16x16x32_bf16 v[168:171], v[190:193], v[228:231], v[168:171]
	ds_write_b128 v183, v[116:119]
	v_add_u32_e32 v116, s15, v187
	v_mfma_f32_16x16x32_bf16 v[164:167], v[190:193], v[232:235], v[164:167]
	global_load_dwordx4 v[116:119], v116, s[98:99] offset:128
	v_mfma_f32_16x16x32_bf16 v[160:163], v[190:193], v[236:239], v[160:163]
	s_waitcnt vmcnt(11)
	ds_write_b128 v183, v[112:115] offset:2048
	v_mfma_f32_16x16x32_bf16 v[156:159], v[194:197], v[224:227], v[156:159]
	v_add_u32_e32 v112, s17, v187
	v_mfma_f32_16x16x32_bf16 v[152:155], v[194:197], v[228:231], v[152:155]
	global_load_dwordx4 v[112:115], v112, s[98:99] offset:128
	s_waitcnt vmcnt(11)
	v_mfma_f32_16x16x32_bf16 v[148:151], v[194:197], v[232:235], v[148:151]
	ds_write_b128 v183, v[104:107] offset:4096
	v_mfma_f32_16x16x32_bf16 v[144:147], v[194:197], v[236:239], v[144:147]
	v_add_u32_e32 v104, s52, v187
	global_load_dwordx4 v[104:107], v104, s[98:99] offset:128
	v_mfma_f32_16x16x32_bf16 v[136:139], v[198:201], v[224:227], v[136:139]
	s_waitcnt vmcnt(11)
	v_mfma_f32_16x16x32_bf16 v[132:135], v[198:201], v[228:231], v[132:135]
	ds_write_b128 v183, v[92:95] offset:6144
	v_add_u32_e32 v92, s53, v187
	v_mfma_f32_16x16x32_bf16 v[128:131], v[198:201], v[232:235], v[128:131]
	global_load_dwordx4 v[92:95], v92, s[98:99] offset:128
	v_mfma_f32_16x16x32_bf16 v[124:127], v[198:201], v[236:239], v[124:127]
	s_waitcnt vmcnt(11)
	ds_write_b128 v183, v[84:87] offset:8192
	v_mfma_f32_16x16x32_bf16 v[120:123], v[204:207], v[224:227], v[120:123]
	v_add_u32_e32 v84, s10, v187
	v_mfma_f32_16x16x32_bf16 v[108:111], v[204:207], v[228:231], v[108:111]
	global_load_dwordx4 v[84:87], v84, s[98:99] offset:128
	s_waitcnt vmcnt(11)
	v_mfma_f32_16x16x32_bf16 v[100:103], v[204:207], v[232:235], v[100:103]
	ds_write_b128 v183, v[72:75] offset:10240
	v_mfma_f32_16x16x32_bf16 v[96:99], v[204:207], v[236:239], v[96:99]
	v_add_u32_e32 v72, s11, v187
	global_load_dwordx4 v[72:75], v72, s[98:99] offset:128
	v_mfma_f32_16x16x32_bf16 v[88:91], v[208:211], v[224:227], v[88:91]
	s_waitcnt vmcnt(11)
	v_mfma_f32_16x16x32_bf16 v[80:83], v[208:211], v[228:231], v[80:83]
	ds_write_b128 v183, v[68:71] offset:12288
	v_add_u32_e32 v68, s12, v187
	v_mfma_f32_16x16x32_bf16 v[76:79], v[208:211], v[232:235], v[76:79]
	global_load_dwordx4 v[68:71], v68, s[98:99] offset:128
	v_mfma_f32_16x16x32_bf16 v[64:67], v[208:211], v[236:239], v[64:67]
	s_waitcnt vmcnt(11)
	ds_write_b128 v183, v[48:51] offset:14336
	v_mfma_f32_16x16x32_bf16 v[60:63], v[212:215], v[224:227], v[60:63]
	v_add_u32_e32 v48, s13, v187
	v_mfma_f32_16x16x32_bf16 v[52:55], v[212:215], v[228:231], v[52:55]
	global_load_dwordx4 v[48:51], v48, s[98:99] offset:128
	s_waitcnt vmcnt(11)
	v_mfma_f32_16x16x32_bf16 v[44:47], v[212:215], v[232:235], v[44:47]
	ds_write_b128 v183, v[56:59] offset:16384
	v_mfma_f32_16x16x32_bf16 v[36:39], v[212:215], v[236:239], v[36:39]
	v_mov_b32_e32 v56, v186
	global_load_dwordx4 v[56:59], v56, s[98:99] offset:128
	v_mfma_f32_16x16x32_bf16 v[32:35], v[216:219], v[224:227], v[32:35]
	s_waitcnt vmcnt(11)
	v_mfma_f32_16x16x32_bf16 v[28:31], v[216:219], v[228:231], v[28:31]
	ds_write_b128 v183, v[40:43] offset:18432
	v_add_u32_e32 v40, s16, v186
	v_mfma_f32_16x16x32_bf16 v[16:19], v[216:219], v[232:235], v[16:19]
	global_load_dwordx4 v[40:43], v40, s[98:99] offset:128
	v_mfma_f32_16x16x32_bf16 v[12:15], v[216:219], v[236:239], v[12:15]
	s_waitcnt vmcnt(11)
	ds_write_b128 v183, v[24:27] offset:20480
	v_mfma_f32_16x16x32_bf16 v[8:11], v[220:223], v[224:227], v[8:11]
	v_add_u32_e32 v24, s95, v186
	v_mfma_f32_16x16x32_bf16 v[4:7], v[220:223], v[228:231], v[4:7]
	global_load_dwordx4 v[24:27], v24, s[98:99] offset:128
	s_waitcnt vmcnt(11)
	v_mfma_f32_16x16x32_bf16 v[0:3], v[220:223], v[232:235], v[0:3]
	ds_write_b128 v183, v[20:23] offset:22528
	v_mfma_f32_16x16x32_bf16 v[140:143], v[220:223], v[236:239], v[140:143]
	v_add_u32_e32 v20, s28, v186
	global_load_dwordx4 v[20:23], v20, s[98:99] offset:128
	v_cmp_gt_u32_e32 vcc, 0x6000, v183
	v_add_u32_e32 v182, 0xc000, v183
	v_add_u32_e32 v183, 0xffffa000, v183
	s_nop 0
	v_cndmask_b32_e32 v183, v183, v182, vcc
	s_add_u32 s30, s30, 0x80
	s_addc_u32 s31, s31, 0
	s_cmpk_eq_i32 s30, 0x180
	s_cbranch_scc0 .LBB0_424
	s_waitcnt lgkmcnt(0)
	s_barrier
	ds_read_b128 v[224:227], v184
	ds_read_b128 v[228:231], v184 offset:1024
	ds_read_b128 v[232:235], v184 offset:2048
	ds_read_b128 v[236:239], v184 offset:3072
	ds_read_b128 v[190:193], v185
	ds_read_b128 v[194:197], v185 offset:1024
	ds_read_b128 v[198:201], v185 offset:2048
	ds_read_b128 v[204:207], v185 offset:3072
	ds_read_b128 v[208:211], v185 offset:4096
	ds_read_b128 v[212:215], v185 offset:5120
	ds_read_b128 v[216:219], v185 offset:6144
	ds_read_b128 v[220:223], v185 offset:7168
	s_movk_i32 vcc_lo, 0x6000
	s_cmp_eq_u32 m0, 2
	s_cselect_b32 vcc_lo, 0xffff4000, vcc_lo
	s_add_u32 m0, m0, 1
	s_cmp_eq_u32 m0, 3
	s_cselect_b32 m0, 0, m0
	v_add_u32_e32 v185, vcc_lo, v185
	v_add_u32_e32 v184, vcc_lo, v184
	v_xor_b32_e32 v185, 64, v185
	v_xor_b32_e32 v184, 64, v184
	s_waitcnt lgkmcnt(7)
	v_mfma_f32_16x16x32_bf16 v[172:175], v[190:193], v[224:227], v[172:175]
	v_mfma_f32_16x16x32_bf16 v[168:171], v[190:193], v[228:231], v[168:171]
	v_mfma_f32_16x16x32_bf16 v[164:167], v[190:193], v[232:235], v[164:167]
	v_mfma_f32_16x16x32_bf16 v[160:163], v[190:193], v[236:239], v[160:163]
	ds_read_b128 v[190:193], v185
	s_waitcnt lgkmcnt(7)
	v_mfma_f32_16x16x32_bf16 v[156:159], v[194:197], v[224:227], v[156:159]
	v_mfma_f32_16x16x32_bf16 v[152:155], v[194:197], v[228:231], v[152:155]
	v_mfma_f32_16x16x32_bf16 v[148:151], v[194:197], v[232:235], v[148:151]
	v_mfma_f32_16x16x32_bf16 v[144:147], v[194:197], v[236:239], v[144:147]
	ds_read_b128 v[194:197], v185 offset:1024
	s_waitcnt lgkmcnt(7)
	v_mfma_f32_16x16x32_bf16 v[136:139], v[198:201], v[224:227], v[136:139]
	v_mfma_f32_16x16x32_bf16 v[132:135], v[198:201], v[228:231], v[132:135]
	v_mfma_f32_16x16x32_bf16 v[128:131], v[198:201], v[232:235], v[128:131]
	v_mfma_f32_16x16x32_bf16 v[124:127], v[198:201], v[236:239], v[124:127]
	ds_read_b128 v[198:201], v185 offset:2048
	s_waitcnt lgkmcnt(7)
	v_mfma_f32_16x16x32_bf16 v[120:123], v[204:207], v[224:227], v[120:123]
	v_mfma_f32_16x16x32_bf16 v[108:111], v[204:207], v[228:231], v[108:111]
	v_mfma_f32_16x16x32_bf16 v[100:103], v[204:207], v[232:235], v[100:103]
	v_mfma_f32_16x16x32_bf16 v[96:99], v[204:207], v[236:239], v[96:99]
	ds_read_b128 v[204:207], v185 offset:3072
	s_waitcnt lgkmcnt(7)
	v_mfma_f32_16x16x32_bf16 v[88:91], v[208:211], v[224:227], v[88:91]
	v_mfma_f32_16x16x32_bf16 v[80:83], v[208:211], v[228:231], v[80:83]
	v_mfma_f32_16x16x32_bf16 v[76:79], v[208:211], v[232:235], v[76:79]
	v_mfma_f32_16x16x32_bf16 v[64:67], v[208:211], v[236:239], v[64:67]
	ds_read_b128 v[208:211], v185 offset:4096
	s_waitcnt lgkmcnt(7)
	v_mfma_f32_16x16x32_bf16 v[60:63], v[212:215], v[224:227], v[60:63]
	v_mfma_f32_16x16x32_bf16 v[52:55], v[212:215], v[228:231], v[52:55]
	v_mfma_f32_16x16x32_bf16 v[44:47], v[212:215], v[232:235], v[44:47]
	v_mfma_f32_16x16x32_bf16 v[36:39], v[212:215], v[236:239], v[36:39]
	ds_read_b128 v[212:215], v185 offset:5120
	s_waitcnt lgkmcnt(7)
	v_mfma_f32_16x16x32_bf16 v[32:35], v[216:219], v[224:227], v[32:35]
	v_mfma_f32_16x16x32_bf16 v[28:31], v[216:219], v[228:231], v[28:31]
	v_mfma_f32_16x16x32_bf16 v[16:19], v[216:219], v[232:235], v[16:19]
	v_mfma_f32_16x16x32_bf16 v[12:15], v[216:219], v[236:239], v[12:15]
	ds_read_b128 v[216:219], v185 offset:6144
	s_waitcnt lgkmcnt(7)
	v_mfma_f32_16x16x32_bf16 v[8:11], v[220:223], v[224:227], v[8:11]
	v_mfma_f32_16x16x32_bf16 v[4:7], v[220:223], v[228:231], v[4:7]
	v_mfma_f32_16x16x32_bf16 v[0:3], v[220:223], v[232:235], v[0:3]
	v_mfma_f32_16x16x32_bf16 v[140:143], v[220:223], v[236:239], v[140:143]
	ds_read_b128 v[220:223], v185 offset:7168
	ds_read_b128 v[224:227], v184
	ds_read_b128 v[228:231], v184 offset:1024
	ds_read_b128 v[232:235], v184 offset:2048
	ds_read_b128 v[236:239], v184 offset:3072
	s_movk_i32 vcc_lo, 0x6000
	s_cmp_eq_u32 m0, 2
	s_cselect_b32 vcc_lo, 0xffff4000, vcc_lo
	s_add_u32 m0, m0, 1
	s_cmp_eq_u32 m0, 3
	s_cselect_b32 m0, 0, m0
	v_add_u32_e32 v185, vcc_lo, v185
	v_add_u32_e32 v184, vcc_lo, v184
	v_xor_b32_e32 v185, 64, v185
	v_xor_b32_e32 v184, 64, v184
	s_waitcnt lgkmcnt(0)
	v_mfma_f32_16x16x32_bf16 v[172:175], v[190:193], v[224:227], v[172:175]
	v_mfma_f32_16x16x32_bf16 v[168:171], v[190:193], v[228:231], v[168:171]
	v_mfma_f32_16x16x32_bf16 v[164:167], v[190:193], v[232:235], v[164:167]
	v_mfma_f32_16x16x32_bf16 v[160:163], v[190:193], v[236:239], v[160:163]
	v_mfma_f32_16x16x32_bf16 v[156:159], v[194:197], v[224:227], v[156:159]
	v_mfma_f32_16x16x32_bf16 v[152:155], v[194:197], v[228:231], v[152:155]
	v_mfma_f32_16x16x32_bf16 v[148:151], v[194:197], v[232:235], v[148:151]
	v_mfma_f32_16x16x32_bf16 v[144:147], v[194:197], v[236:239], v[144:147]
	v_mfma_f32_16x16x32_bf16 v[136:139], v[198:201], v[224:227], v[136:139]
	v_mfma_f32_16x16x32_bf16 v[132:135], v[198:201], v[228:231], v[132:135]
	v_mfma_f32_16x16x32_bf16 v[128:131], v[198:201], v[232:235], v[128:131]
	v_mfma_f32_16x16x32_bf16 v[124:127], v[198:201], v[236:239], v[124:127]
	v_mfma_f32_16x16x32_bf16 v[120:123], v[204:207], v[224:227], v[120:123]
	v_mfma_f32_16x16x32_bf16 v[108:111], v[204:207], v[228:231], v[108:111]
	v_mfma_f32_16x16x32_bf16 v[100:103], v[204:207], v[232:235], v[100:103]
	v_mfma_f32_16x16x32_bf16 v[96:99], v[204:207], v[236:239], v[96:99]
	v_mfma_f32_16x16x32_bf16 v[88:91], v[208:211], v[224:227], v[88:91]
	v_mfma_f32_16x16x32_bf16 v[80:83], v[208:211], v[228:231], v[80:83]
	v_mfma_f32_16x16x32_bf16 v[76:79], v[208:211], v[232:235], v[76:79]
	v_mfma_f32_16x16x32_bf16 v[64:67], v[208:211], v[236:239], v[64:67]
	v_mfma_f32_16x16x32_bf16 v[60:63], v[212:215], v[224:227], v[60:63]
	v_mfma_f32_16x16x32_bf16 v[52:55], v[212:215], v[228:231], v[52:55]
	v_mfma_f32_16x16x32_bf16 v[44:47], v[212:215], v[232:235], v[44:47]
	v_mfma_f32_16x16x32_bf16 v[36:39], v[212:215], v[236:239], v[36:39]
	v_mfma_f32_16x16x32_bf16 v[32:35], v[216:219], v[224:227], v[32:35]
	v_mfma_f32_16x16x32_bf16 v[28:31], v[216:219], v[228:231], v[28:31]
	v_mfma_f32_16x16x32_bf16 v[16:19], v[216:219], v[232:235], v[16:19]
	v_mfma_f32_16x16x32_bf16 v[12:15], v[216:219], v[236:239], v[12:15]
	v_mfma_f32_16x16x32_bf16 v[8:11], v[220:223], v[224:227], v[8:11]
	v_mfma_f32_16x16x32_bf16 v[4:7], v[220:223], v[228:231], v[4:7]
	v_mfma_f32_16x16x32_bf16 v[0:3], v[220:223], v[232:235], v[0:3]
	v_mfma_f32_16x16x32_bf16 v[140:143], v[220:223], v[236:239], v[140:143]
	v_lshrrev_b32_e32 v224, 4, v188
	v_and_b32_e32 v225, 7, v188
	v_bitop3_b32 v226, v224, v225, 3 bitop3:0x6c
	v_lshlrev_b32_e32 v227, 7, v188
	v_bfe_u32 v228, v188, 4, 2
	v_and_b32_e32 v229, 0xffffc780, v227
	v_and_b32_e32 v227, 0x2780, v227
	v_bitop3_b32 v228, v228, v225, 4 bitop3:0x36
	v_lshlrev_b32_e32 v226, 4, v226
	v_lshlrev_b32_e32 v228, 4, v228
	v_or_b32_e32 v185, v229, v226
	v_or_b32_e32 v184, v227, v226
	v_or_b32_e32 v183, v229, v228
	v_or_b32_e32 v182, v227, v228
	s_waitcnt vmcnt(0)
	s_setprio 1
	s_barrier
	s_waitcnt vmcnt(10)
	ds_write_b128 v176, v[116:119]
	s_waitcnt vmcnt(9)
	ds_write_b128 v176, v[112:115] offset:4096
	s_waitcnt vmcnt(8)
	ds_write_b128 v176, v[104:107] offset:8192
	s_waitcnt vmcnt(7)
	ds_write_b128 v176, v[92:95] offset:12288
	s_waitcnt vmcnt(6)
	ds_write_b128 v176, v[84:87] offset:16384
	s_waitcnt vmcnt(5)
	ds_write_b128 v176, v[72:75] offset:20480
	s_waitcnt vmcnt(4)
	ds_write_b128 v176, v[68:71] offset:24576
	s_waitcnt vmcnt(3)
	ds_write_b128 v176, v[48:51] offset:28672
	ds_write_b128 v176, v[56:59] offset:32768
	s_waitcnt vmcnt(2)
	ds_write_b128 v176, v[40:43] offset:36864
	s_waitcnt vmcnt(1)
	ds_write_b128 v176, v[24:27] offset:40960
	s_waitcnt vmcnt(0)
	ds_write_b128 v176, v[20:23] offset:45056
	s_waitcnt lgkmcnt(0)
	s_barrier
	ds_read_b128 v[20:23], v185
	ds_read_b128 v[24:27], v185 offset:2048
	ds_read_b128 v[40:43], v185 offset:4096
	ds_read_b128 v[48:51], v185 offset:6144
	ds_read_b128 v[56:59], v185 offset:8192
	ds_read_b128 v[68:71], v185 offset:10240
	ds_read_b128 v[72:75], v185 offset:12288
	ds_read_b128 v[84:87], v185 offset:14336
	ds_read_b128 v[92:95], v184 offset:32768
	ds_read_b128 v[104:107], v184 offset:34816
	ds_read_b128 v[112:115], v184 offset:36864
	ds_read_b128 v[116:119], v184 offset:38912
	s_waitcnt lgkmcnt(3)
	v_mfma_f32_16x16x32_bf16 v[172:175], v[20:23], v[92:95], v[172:175]
	s_waitcnt lgkmcnt(2)
	v_mfma_f32_16x16x32_bf16 v[168:171], v[20:23], v[104:107], v[168:171]
	s_waitcnt lgkmcnt(1)
	v_mfma_f32_16x16x32_bf16 v[164:167], v[20:23], v[112:115], v[164:167]
	s_waitcnt lgkmcnt(0)
	v_mfma_f32_16x16x32_bf16 v[20:23], v[20:23], v[116:119], v[160:163]
	v_mfma_f32_16x16x32_bf16 v[156:159], v[24:27], v[92:95], v[156:159]
	v_mfma_f32_16x16x32_bf16 v[152:155], v[24:27], v[104:107], v[152:155]
	v_mfma_f32_16x16x32_bf16 v[148:151], v[24:27], v[112:115], v[148:151]
	v_mfma_f32_16x16x32_bf16 v[24:27], v[24:27], v[116:119], v[144:147]
	v_mfma_f32_16x16x32_bf16 v[136:139], v[40:43], v[92:95], v[136:139]
	v_mfma_f32_16x16x32_bf16 v[132:135], v[40:43], v[104:107], v[132:135]
	v_mfma_f32_16x16x32_bf16 v[128:131], v[40:43], v[112:115], v[128:131]
	v_mfma_f32_16x16x32_bf16 v[40:43], v[40:43], v[116:119], v[124:127]
	v_mfma_f32_16x16x32_bf16 v[144:147], v[48:51], v[92:95], v[120:123]
	v_mfma_f32_16x16x32_bf16 v[160:163], v[48:51], v[104:107], v[108:111]
	v_mfma_f32_16x16x32_bf16 v[178:181], v[48:51], v[112:115], v[100:103]
	v_mfma_f32_16x16x32_bf16 v[48:51], v[48:51], v[116:119], v[96:99]
	v_mfma_f32_16x16x32_bf16 v[16:19], v[72:75], v[112:115], v[16:19]
	v_mfma_f32_16x16x32_bf16 v[12:15], v[72:75], v[116:119], v[12:15]
	v_mfma_f32_16x16x32_bf16 v[8:11], v[84:87], v[92:95], v[8:11]
	v_mfma_f32_16x16x32_bf16 v[4:7], v[84:87], v[104:107], v[4:7]
	v_mfma_f32_16x16x32_bf16 v[0:3], v[84:87], v[112:115], v[0:3]
	v_mfma_f32_16x16x32_bf16 v[184:187], v[56:59], v[92:95], v[88:91]
	v_mfma_f32_16x16x32_bf16 v[190:193], v[56:59], v[104:107], v[80:83]
	v_mfma_f32_16x16x32_bf16 v[194:197], v[56:59], v[112:115], v[76:79]
	v_mfma_f32_16x16x32_bf16 v[56:59], v[56:59], v[116:119], v[64:67]
	v_mfma_f32_16x16x32_bf16 v[198:201], v[68:71], v[92:95], v[60:63]
	v_mfma_f32_16x16x32_bf16 v[52:55], v[68:71], v[104:107], v[52:55]
	v_mfma_f32_16x16x32_bf16 v[204:207], v[68:71], v[112:115], v[44:47]
	v_mfma_f32_16x16x32_bf16 v[208:211], v[68:71], v[116:119], v[36:39]
	v_mfma_f32_16x16x32_bf16 v[212:215], v[72:75], v[92:95], v[32:35]
	v_mfma_f32_16x16x32_bf16 v[216:219], v[72:75], v[104:107], v[28:31]
	v_mfma_f32_16x16x32_bf16 v[140:143], v[84:87], v[116:119], v[140:143]
	s_nop 1
	ds_read_b128 v[28:31], v183
	ds_read_b128 v[32:35], v183 offset:2048
	ds_read_b128 v[36:39], v183 offset:4096
	ds_read_b128 v[44:47], v183 offset:6144
	ds_read_b128 v[220:223], v183 offset:8192
	ds_read_b128 v[224:227], v183 offset:10240
	ds_read_b128 v[228:231], v183 offset:12288
	ds_read_b128 v[232:235], v183 offset:14336
	ds_read_b128 v[236:239], v182 offset:32768
	ds_read_b128 v[240:243], v182 offset:34816
	ds_read_b128 v[244:247], v182 offset:36864
	ds_read_b128 v[248:251], v182 offset:38912
	s_waitcnt lgkmcnt(3)
	v_mfma_f32_16x16x32_bf16 v[124:127], v[28:31], v[236:239], v[172:175]
	v_readlane_b32 s16, v255, 27
	s_mov_b64 s[30:31], 0
	v_readlane_b32 s17, v255, 28
	s_waitcnt lgkmcnt(2)
	v_mfma_f32_16x16x32_bf16 v[120:123], v[28:31], v[240:243], v[168:171]
	v_readlane_b32 s11, v255, 16
	v_readlane_b32 s10, v255, 18
	s_waitcnt lgkmcnt(1)
	v_mfma_f32_16x16x32_bf16 v[116:119], v[28:31], v[244:247], v[164:167]
	s_waitcnt lgkmcnt(0)
	v_mfma_f32_16x16x32_bf16 v[112:115], v[28:31], v[248:251], v[20:23]
	v_mfma_f32_16x16x32_bf16 v[108:111], v[32:35], v[236:239], v[156:159]
	v_mfma_f32_16x16x32_bf16 v[104:107], v[32:35], v[240:243], v[152:155]
	v_mfma_f32_16x16x32_bf16 v[100:103], v[32:35], v[244:247], v[148:151]
	v_mfma_f32_16x16x32_bf16 v[96:99], v[32:35], v[248:251], v[24:27]
	v_mfma_f32_16x16x32_bf16 v[92:95], v[36:39], v[236:239], v[136:139]
	v_mfma_f32_16x16x32_bf16 v[88:91], v[36:39], v[240:243], v[132:135]
	v_mfma_f32_16x16x32_bf16 v[84:87], v[36:39], v[244:247], v[128:131]
	v_mfma_f32_16x16x32_bf16 v[80:83], v[36:39], v[248:251], v[40:43]
	v_mfma_f32_16x16x32_bf16 v[76:79], v[44:47], v[236:239], v[144:147]
	v_mfma_f32_16x16x32_bf16 v[72:75], v[44:47], v[240:243], v[160:163]
	v_mfma_f32_16x16x32_bf16 v[68:71], v[44:47], v[244:247], v[178:181]
	v_mfma_f32_16x16x32_bf16 v[64:67], v[44:47], v[248:251], v[48:51]
	v_mfma_f32_16x16x32_bf16 v[60:63], v[220:223], v[236:239], v[184:187]
	v_mfma_f32_16x16x32_bf16 v[156:159], v[220:223], v[240:243], v[190:193]
	v_mfma_f32_16x16x32_bf16 v[152:155], v[220:223], v[244:247], v[194:197]
	v_mfma_f32_16x16x32_bf16 v[48:51], v[220:223], v[248:251], v[56:59]
	v_mfma_f32_16x16x32_bf16 v[44:47], v[224:227], v[236:239], v[198:201]
	v_mfma_f32_16x16x32_bf16 v[40:43], v[224:227], v[240:243], v[52:55]
	v_mfma_f32_16x16x32_bf16 v[36:39], v[224:227], v[244:247], v[204:207]
	v_mfma_f32_16x16x32_bf16 v[32:35], v[224:227], v[248:251], v[208:211]
	v_mfma_f32_16x16x32_bf16 v[28:31], v[228:231], v[236:239], v[212:215]
	v_mfma_f32_16x16x32_bf16 v[24:27], v[228:231], v[240:243], v[216:219]
	v_mfma_f32_16x16x32_bf16 v[20:23], v[228:231], v[244:247], v[16:19]
	v_mfma_f32_16x16x32_bf16 v[16:19], v[228:231], v[248:251], v[12:15]
	v_mfma_f32_16x16x32_bf16 v[12:15], v[232:235], v[236:239], v[8:11]
	v_mfma_f32_16x16x32_bf16 v[8:11], v[232:235], v[240:243], v[4:7]
	v_xor_b32_e32 v240, 32, v203
	v_mfma_f32_16x16x32_bf16 v[0:3], v[232:235], v[244:247], v[0:3]
	v_mfma_f32_16x16x32_bf16 v[4:7], v[232:235], v[248:251], v[140:143]
.LBB0_426:
	s_and_b64 vcc, exec, s[30:31]
	s_cbranch_vccz .LBB0_430
	s_nop 5
	v_mov_b32_e32 v6, v188
	s_mov_b32 s15, 0x1c000
	v_ashrrev_i32_e32 v7, 3, v6
	v_lshlrev_b32_e32 v4, 4, v6
	v_and_b32_e32 v176, 0x70, v4
	v_add_u32_e32 v4, s94, v7
	v_ashrrev_i32_e32 v5, 31, v4
	v_add_u32_e32 v0, s8, v7
	v_lshlrev_b64 v[4:5], 9, v[4:5]
	v_ashrrev_i32_e32 v1, 31, v0
	v_lshl_add_u64 v[4:5], s[42:43], 0, v[4:5]
	v_xor_b32_e32 v8, v7, v6
	v_lshlrev_b64 v[0:1], 9, v[0:1]
	v_lshl_add_u64 v[178:179], v[4:5], 0, v[176:177]
	v_lshlrev_b32_e32 v4, 4, v8
	v_lshl_add_u64 v[2:3], s[46:47], 0, v[0:1]
	v_and_b32_e32 v4, 0x70, v4
	v_lshl_add_u64 v[2:3], v[2:3], 0, v[176:177]
	v_lshl_or_b32 v176, v7, 7, v4
	v_lshrrev_b32_e32 v4, 4, v6
	v_and_b32_e32 v11, 7, v6
	v_bitop3_b32 v12, v4, v11, 3 bitop3:0x6c
	v_add_co_u32_e32 v4, vcc, s28, v178
	s_mov_b32 s42, 0x8000
	s_nop 0
	v_addc_co_u32_e32 v5, vcc, 0, v179, vcc
	v_lshlrev_b32_e32 v8, 7, v6
	v_bfe_u32 v10, v6, 4, 2
	v_add_co_u32_e32 v6, vcc, s42, v178
	s_movk_i32 s43, 0x4000
	s_nop 0
	v_addc_co_u32_e32 v7, vcc, 0, v179, vcc
	global_load_dwordx4 v[20:23], v[4:5], off
	global_load_dwordx4 v[24:27], v[6:7], off
	v_add_co_u32_e32 v4, vcc, s43, v178
	v_and_b32_e32 v9, 0xffffc780, v8
	s_nop 0
	v_addc_co_u32_e32 v5, vcc, 0, v179, vcc
	v_add_co_u32_e32 v6, vcc, s15, v2
	s_mov_b32 s15, 0x18000
	s_nop 0
	v_addc_co_u32_e32 v7, vcc, 0, v3, vcc
	global_load_dwordx4 v[40:43], v[4:5], off
	global_load_dwordx4 v[48:51], v[6:7], off
	v_add_co_u32_e32 v4, vcc, s15, v2
	s_mov_b32 s15, 0x14000
	s_nop 0
	v_addc_co_u32_e32 v5, vcc, 0, v3, vcc
	v_add_co_u32_e32 v6, vcc, s15, v2
	v_and_b32_e32 v8, 0x2780, v8
	s_nop 0
	v_addc_co_u32_e32 v7, vcc, 0, v3, vcc
	global_load_dwordx4 v[68:71], v[4:5], off
	global_load_dwordx4 v[72:75], v[6:7], off
	v_add_co_u32_e32 v4, vcc, s14, v2
	v_bitop3_b32 v10, v10, v11, 4 bitop3:0x36
	s_nop 0
	v_addc_co_u32_e32 v5, vcc, 0, v3, vcc
	v_add_co_u32_e32 v6, vcc, s28, v2
	v_lshl_or_b32 v0, v11, 4, v0
	s_nop 0
	v_addc_co_u32_e32 v7, vcc, 0, v3, vcc
	global_load_dwordx4 v[84:87], v[4:5], off
	global_load_dwordx4 v[92:95], v[6:7], off
	v_add_co_u32_e32 v4, vcc, s42, v2
	v_mov_b32_e32 v140, 0
	s_nop 0
	v_addc_co_u32_e32 v5, vcc, 0, v3, vcc
	v_add_co_u32_e32 v6, vcc, s43, v2
	v_lshl_add_u64 v[180:181], s[58:59], 0, v[0:1]
	s_nop 0
	v_addc_co_u32_e32 v7, vcc, 0, v3, vcc
	global_load_dwordx4 v[104:107], v[4:5], off
	global_load_dwordx4 v[112:115], v[6:7], off
	global_load_dwordx4 v[56:59], v[178:179], off
	global_load_dwordx4 v[116:119], v[2:3], off
	v_lshlrev_b32_e32 v2, 4, v12
	v_or_b32_e32 v185, v9, v2
	v_or_b32_e32 v184, v8, v2
	v_lshlrev_b32_e32 v2, 4, v10
	v_or_b32_e32 v183, v9, v2
	v_or_b32_e32 v182, v8, v2
	s_mov_b64 s[30:31], 0
	v_mov_b32_e32 v141, v140
	v_mov_b32_e32 v142, v140
	v_mov_b32_e32 v143, v140
	v_mov_b32_e32 v0, v140
	v_mov_b32_e32 v1, v140
	v_mov_b32_e32 v2, v140
	v_mov_b32_e32 v3, v140
	v_mov_b32_e32 v4, v140
	v_mov_b32_e32 v5, v140
	v_mov_b32_e32 v6, v140
	v_mov_b32_e32 v7, v140
	v_mov_b32_e32 v8, v140
	v_mov_b32_e32 v9, v140
	v_mov_b32_e32 v10, v140
	v_mov_b32_e32 v11, v140
	v_mov_b32_e32 v12, v140
	v_mov_b32_e32 v13, v140
	v_mov_b32_e32 v14, v140
	v_mov_b32_e32 v15, v140
	v_mov_b32_e32 v16, v140
	v_mov_b32_e32 v17, v140
	v_mov_b32_e32 v18, v140
	v_mov_b32_e32 v19, v140
	v_mov_b32_e32 v28, v140
	v_mov_b32_e32 v29, v140
	v_mov_b32_e32 v30, v140
	v_mov_b32_e32 v31, v140
	v_mov_b32_e32 v32, v140
	v_mov_b32_e32 v33, v140
	v_mov_b32_e32 v34, v140
	v_mov_b32_e32 v35, v140
	v_mov_b32_e32 v36, v140
	v_mov_b32_e32 v37, v140
	v_mov_b32_e32 v38, v140
	v_mov_b32_e32 v39, v140
	v_mov_b32_e32 v44, v140
	v_mov_b32_e32 v45, v140
	v_mov_b32_e32 v46, v140
	v_mov_b32_e32 v47, v140
	v_mov_b32_e32 v52, v140
	v_mov_b32_e32 v53, v140
	v_mov_b32_e32 v54, v140
	v_mov_b32_e32 v55, v140
	v_mov_b32_e32 v60, v140
	v_mov_b32_e32 v61, v140
	v_mov_b32_e32 v62, v140
	v_mov_b32_e32 v63, v140
	v_mov_b32_e32 v64, v140
	v_mov_b32_e32 v65, v140
	v_mov_b32_e32 v66, v140
	v_mov_b32_e32 v67, v140
	v_mov_b32_e32 v76, v140
	v_mov_b32_e32 v77, v140
	v_mov_b32_e32 v78, v140
	v_mov_b32_e32 v79, v140
	v_mov_b32_e32 v80, v140
	v_mov_b32_e32 v81, v140
	v_mov_b32_e32 v82, v140
	v_mov_b32_e32 v83, v140
	v_mov_b32_e32 v88, v140
	v_mov_b32_e32 v89, v140
	v_mov_b32_e32 v90, v140
	v_mov_b32_e32 v91, v140
	v_mov_b32_e32 v96, v140
	v_mov_b32_e32 v97, v140
	v_mov_b32_e32 v98, v140
	v_mov_b32_e32 v99, v140
	v_mov_b32_e32 v100, v140
	v_mov_b32_e32 v101, v140
	v_mov_b32_e32 v102, v140
	v_mov_b32_e32 v103, v140
	v_mov_b32_e32 v108, v140
	v_mov_b32_e32 v109, v140
	v_mov_b32_e32 v110, v140
	v_mov_b32_e32 v111, v140
	v_mov_b32_e32 v120, v140
	v_mov_b32_e32 v121, v140
	v_mov_b32_e32 v122, v140
	v_mov_b32_e32 v123, v140
	v_mov_b32_e32 v124, v140
	v_mov_b32_e32 v125, v140
	v_mov_b32_e32 v126, v140
	v_mov_b32_e32 v127, v140
	v_mov_b32_e32 v128, v140
	v_mov_b32_e32 v129, v140
	v_mov_b32_e32 v130, v140
	v_mov_b32_e32 v131, v140
	v_mov_b32_e32 v132, v140
	v_mov_b32_e32 v133, v140
	v_mov_b32_e32 v134, v140
	v_mov_b32_e32 v135, v140
	v_mov_b32_e32 v136, v140
	v_mov_b32_e32 v137, v140
	v_mov_b32_e32 v138, v140
	v_mov_b32_e32 v139, v140
	v_mov_b32_e32 v144, v140
	v_mov_b32_e32 v145, v140
	v_mov_b32_e32 v146, v140
	v_mov_b32_e32 v147, v140
	v_mov_b32_e32 v148, v140
	v_mov_b32_e32 v149, v140
	v_mov_b32_e32 v150, v140
	v_mov_b32_e32 v151, v140
	v_mov_b32_e32 v152, v140
	v_mov_b32_e32 v153, v140
	v_mov_b32_e32 v154, v140
	v_mov_b32_e32 v155, v140
	v_mov_b32_e32 v156, v140
	v_mov_b32_e32 v157, v140
	v_mov_b32_e32 v158, v140
	v_mov_b32_e32 v159, v140
	v_mov_b32_e32 v160, v140
	v_mov_b32_e32 v161, v140
	v_mov_b32_e32 v162, v140
	v_mov_b32_e32 v163, v140
	v_mov_b32_e32 v164, v140
	v_mov_b32_e32 v165, v140
	v_mov_b32_e32 v166, v140
	v_mov_b32_e32 v167, v140
	v_mov_b32_e32 v168, v140
	v_mov_b32_e32 v169, v140
	v_mov_b32_e32 v170, v140
	v_mov_b32_e32 v171, v140
	v_mov_b32_e32 v172, v140
	v_mov_b32_e32 v173, v140
	v_mov_b32_e32 v174, v140
	v_mov_b32_e32 v175, v140
	s_mov_b32 s14, 0xad00000
	s_mov_b32 s15, 0xad04000
	s_mov_b32 s16, 0xad08000
	s_mov_b32 s17, 0xad0c000
	s_mov_b32 s10, 0xad10000
	s_mov_b32 s11, 0xad14000
	s_mov_b32 s12, 0xad18000
	s_mov_b32 s13, 0xad1c000
	v_readlane_b32 vcc_lo, v253, 0
	s_cmpk_lt_u32 vcc_lo, 0x100
	s_cbranch_scc1 .Lprio_hi4
	s_setprio 2
	s_branch .Lprio_done4

.Lprio_done4:
	v_readlane_b32 s98, v253, 3
	v_readlane_b32 s99, v253, 4
	v_and_b32_e32 v224, 15, v188
	v_bfe_u32 v225, v188, 4, 2
	v_lshrrev_b32_e32 v226, 2, v224
	v_sub_u32_e32 v226, 0, v226
	v_and_b32_e32 v226, 3, v226
	v_xor_b32_e32 v225, v225, v226
	v_lshlrev_b32_e32 v225, 4, v225
	v_lshl_or_b32 v225, v224, 6, v225
	v_bfe_u32 v226, v188, 7, 1
	v_lshl_or_b32 v185, v226, 13, v225
	v_bfe_u32 v226, v188, 6, 1
	v_lshl_or_b32 v184, v226, 12, v225
	v_add_u32_e32 v184, 0x4000, v184
	v_lshrrev_b32_e32 v224, 3, v188
	v_bfe_u32 v225, v188, 2, 1
	v_lshrrev_b32_e32 v226, 2, v224
	v_sub_u32_e32 v226, 0, v226
	v_and_b32_e32 v226, 3, v226
	v_and_b32_e32 v227, 3, v188
	v_xor_b32_e32 v226, v227, v226
	v_lshlrev_b32_e32 v226, 4, v226
	v_xor_b32_e32 v224, v224, v225
	v_lshl_or_b32 v226, v224, 6, v226
	v_mul_u32_u24_e32 v225, 0x6000, v225
	v_add_u32_e32 v183, v225, v226
	s_mov_b32 m0, 0
	s_sub_u32 vcc_lo, s30, s98
	v_add_u32_e32 v186, vcc_lo, v178
	v_add_u32_e32 v187, vcc_lo, v180
	s_barrier
	s_waitcnt vmcnt(0)
	ds_write_b128 v183, v[116:119]
	ds_write_b128 v183, v[112:115] offset:2048
	ds_write_b128 v183, v[104:107] offset:4096
	ds_write_b128 v183, v[92:95] offset:6144
	ds_write_b128 v183, v[84:87] offset:8192
	ds_write_b128 v183, v[72:75] offset:10240
	ds_write_b128 v183, v[68:71] offset:12288
	ds_write_b128 v183, v[48:51] offset:14336
	ds_write_b128 v183, v[56:59] offset:16384
	ds_write_b128 v183, v[40:43] offset:18432
	ds_write_b128 v183, v[24:27] offset:20480
	ds_write_b128 v183, v[20:23] offset:22528
	v_cmp_gt_u32_e32 vcc, 0x6000, v183
	v_add_u32_e32 v182, 0xc000, v183
	v_add_u32_e32 v183, 0xffffa000, v183
	s_nop 0
	v_cndmask_b32_e32 v183, v183, v182, vcc
	v_add_u32_e32 v116, s14, v187
	global_load_dwordx4 v[116:119], v116, s[98:99] offset:128
	v_add_u32_e32 v112, s15, v187
	global_load_dwordx4 v[112:115], v112, s[98:99] offset:128
	v_add_u32_e32 v104, s16, v187
	global_load_dwordx4 v[104:107], v104, s[98:99] offset:128
	v_add_u32_e32 v92, s17, v187
	global_load_dwordx4 v[92:95], v92, s[98:99] offset:128
	v_add_u32_e32 v84, s10, v187
	global_load_dwordx4 v[84:87], v84, s[98:99] offset:128
	v_add_u32_e32 v72, s11, v187
	global_load_dwordx4 v[72:75], v72, s[98:99] offset:128
	v_add_u32_e32 v68, s12, v187
	global_load_dwordx4 v[68:71], v68, s[98:99] offset:128
	v_add_u32_e32 v48, s13, v187
	global_load_dwordx4 v[48:51], v48, s[98:99] offset:128
	v_mov_b32_e32 v56, v186
	global_load_dwordx4 v[56:59], v56, s[98:99] offset:128
	v_add_u32_e32 v40, s43, v186
	global_load_dwordx4 v[40:43], v40, s[98:99] offset:128
	v_add_u32_e32 v24, s42, v186
	global_load_dwordx4 v[24:27], v24, s[98:99] offset:128
	v_add_u32_e32 v20, s28, v186
	global_load_dwordx4 v[20:23], v20, s[98:99] offset:128
	s_add_u32 s30, s30, 0x80
	s_addc_u32 s31, s31, 0
.LBB0_428:
	s_waitcnt lgkmcnt(0)
	s_barrier
	ds_read_b128 v[224:227], v184
	ds_read_b128 v[228:231], v184 offset:1024
	ds_read_b128 v[232:235], v184 offset:2048
	ds_read_b128 v[236:239], v184 offset:3072
	ds_read_b128 v[190:193], v185
	ds_read_b128 v[194:197], v185 offset:1024
	ds_read_b128 v[198:201], v185 offset:2048
	ds_read_b128 v[204:207], v185 offset:3072
	ds_read_b128 v[208:211], v185 offset:4096
	ds_read_b128 v[212:215], v185 offset:5120
	ds_read_b128 v[216:219], v185 offset:6144
	ds_read_b128 v[220:223], v185 offset:7168
	s_movk_i32 vcc_lo, 0x6000
	s_cmp_eq_u32 m0, 2
	s_cselect_b32 vcc_lo, 0xffff4000, vcc_lo
	s_add_u32 m0, m0, 1
	s_cmp_eq_u32 m0, 3
	s_cselect_b32 m0, 0, m0
	v_add_u32_e32 v185, vcc_lo, v185
	v_add_u32_e32 v184, vcc_lo, v184
	v_xor_b32_e32 v185, 64, v185
	v_xor_b32_e32 v184, 64, v184
	s_waitcnt lgkmcnt(7)
	v_mfma_f32_16x16x32_bf16 v[172:175], v[224:227], v[190:193], v[172:175]
	v_mfma_f32_16x16x32_bf16 v[168:171], v[228:231], v[190:193], v[168:171]
	v_mfma_f32_16x16x32_bf16 v[164:167], v[232:235], v[190:193], v[164:167]
	v_mfma_f32_16x16x32_bf16 v[160:163], v[236:239], v[190:193], v[160:163]
	ds_read_b128 v[190:193], v185
	s_waitcnt lgkmcnt(7)
	v_mfma_f32_16x16x32_bf16 v[156:159], v[224:227], v[194:197], v[156:159]
	v_mfma_f32_16x16x32_bf16 v[152:155], v[228:231], v[194:197], v[152:155]
	v_mfma_f32_16x16x32_bf16 v[148:151], v[232:235], v[194:197], v[148:151]
	v_mfma_f32_16x16x32_bf16 v[144:147], v[236:239], v[194:197], v[144:147]
	ds_read_b128 v[194:197], v185 offset:1024
	s_waitcnt lgkmcnt(7)
	v_mfma_f32_16x16x32_bf16 v[136:139], v[224:227], v[198:201], v[136:139]
	v_mfma_f32_16x16x32_bf16 v[132:135], v[228:231], v[198:201], v[132:135]
	v_mfma_f32_16x16x32_bf16 v[128:131], v[232:235], v[198:201], v[128:131]
	v_mfma_f32_16x16x32_bf16 v[124:127], v[236:239], v[198:201], v[124:127]
	ds_read_b128 v[198:201], v185 offset:2048
	s_waitcnt lgkmcnt(7)
	v_mfma_f32_16x16x32_bf16 v[120:123], v[224:227], v[204:207], v[120:123]
	v_mfma_f32_16x16x32_bf16 v[108:111], v[228:231], v[204:207], v[108:111]
	v_mfma_f32_16x16x32_bf16 v[100:103], v[232:235], v[204:207], v[100:103]
	v_mfma_f32_16x16x32_bf16 v[96:99], v[236:239], v[204:207], v[96:99]
	ds_read_b128 v[204:207], v185 offset:3072
	s_waitcnt lgkmcnt(7)
	v_mfma_f32_16x16x32_bf16 v[88:91], v[224:227], v[208:211], v[88:91]
	v_mfma_f32_16x16x32_bf16 v[80:83], v[228:231], v[208:211], v[80:83]
	v_mfma_f32_16x16x32_bf16 v[76:79], v[232:235], v[208:211], v[76:79]
	v_mfma_f32_16x16x32_bf16 v[64:67], v[236:239], v[208:211], v[64:67]
	ds_read_b128 v[208:211], v185 offset:4096
	s_waitcnt lgkmcnt(7)
	v_mfma_f32_16x16x32_bf16 v[60:63], v[224:227], v[212:215], v[60:63]
	v_mfma_f32_16x16x32_bf16 v[52:55], v[228:231], v[212:215], v[52:55]
	v_mfma_f32_16x16x32_bf16 v[44:47], v[232:235], v[212:215], v[44:47]
	v_mfma_f32_16x16x32_bf16 v[36:39], v[236:239], v[212:215], v[36:39]
	ds_read_b128 v[212:215], v185 offset:5120
	s_waitcnt lgkmcnt(7)
	v_mfma_f32_16x16x32_bf16 v[32:35], v[224:227], v[216:219], v[32:35]
	v_mfma_f32_16x16x32_bf16 v[28:31], v[228:231], v[216:219], v[28:31]
	v_mfma_f32_16x16x32_bf16 v[16:19], v[232:235], v[216:219], v[16:19]
	v_mfma_f32_16x16x32_bf16 v[12:15], v[236:239], v[216:219], v[12:15]
	ds_read_b128 v[216:219], v185 offset:6144
	s_waitcnt lgkmcnt(7)
	v_mfma_f32_16x16x32_bf16 v[8:11], v[224:227], v[220:223], v[8:11]
	v_mfma_f32_16x16x32_bf16 v[4:7], v[228:231], v[220:223], v[4:7]
	v_mfma_f32_16x16x32_bf16 v[0:3], v[232:235], v[220:223], v[0:3]
	v_mfma_f32_16x16x32_bf16 v[140:143], v[236:239], v[220:223], v[140:143]
	ds_read_b128 v[220:223], v185 offset:7168
	ds_read_b128 v[224:227], v184
	ds_read_b128 v[228:231], v184 offset:1024
	ds_read_b128 v[232:235], v184 offset:2048
	ds_read_b128 v[236:239], v184 offset:3072
	s_movk_i32 vcc_lo, 0x6000
	s_cmp_eq_u32 m0, 2
	s_cselect_b32 vcc_lo, 0xffff4000, vcc_lo
	s_add_u32 m0, m0, 1
	s_cmp_eq_u32 m0, 3
	s_cselect_b32 m0, 0, m0
	v_add_u32_e32 v185, vcc_lo, v185
	v_add_u32_e32 v184, vcc_lo, v184
	v_xor_b32_e32 v185, 64, v185
	v_xor_b32_e32 v184, 64, v184
	s_sub_u32 vcc_lo, s30, s98
	v_add_u32_e32 v186, vcc_lo, v178
	v_add_u32_e32 v187, vcc_lo, v180
	s_barrier
	s_waitcnt lgkmcnt(0)
	v_mfma_f32_16x16x32_bf16 v[172:175], v[224:227], v[190:193], v[172:175]
	s_waitcnt vmcnt(11)
	v_mfma_f32_16x16x32_bf16 v[168:171], v[228:231], v[190:193], v[168:171]
	ds_write_b128 v183, v[116:119]
	v_add_u32_e32 v116, s14, v187
	v_mfma_f32_16x16x32_bf16 v[164:167], v[232:235], v[190:193], v[164:167]
	global_load_dwordx4 v[116:119], v116, s[98:99] offset:128
	v_mfma_f32_16x16x32_bf16 v[160:163], v[236:239], v[190:193], v[160:163]
	s_waitcnt vmcnt(11)
	ds_write_b128 v183, v[112:115] offset:2048
	v_mfma_f32_16x16x32_bf16 v[156:159], v[224:227], v[194:197], v[156:159]
	v_add_u32_e32 v112, s15, v187
	v_mfma_f32_16x16x32_bf16 v[152:155], v[228:231], v[194:197], v[152:155]
	global_load_dwordx4 v[112:115], v112, s[98:99] offset:128
	s_waitcnt vmcnt(11)
	v_mfma_f32_16x16x32_bf16 v[148:151], v[232:235], v[194:197], v[148:151]
	ds_write_b128 v183, v[104:107] offset:4096
	v_mfma_f32_16x16x32_bf16 v[144:147], v[236:239], v[194:197], v[144:147]
	v_add_u32_e32 v104, s16, v187
	global_load_dwordx4 v[104:107], v104, s[98:99] offset:128
	v_mfma_f32_16x16x32_bf16 v[136:139], v[224:227], v[198:201], v[136:139]
	s_waitcnt vmcnt(11)
	v_mfma_f32_16x16x32_bf16 v[132:135], v[228:231], v[198:201], v[132:135]
	ds_write_b128 v183, v[92:95] offset:6144
	v_add_u32_e32 v92, s17, v187
	v_mfma_f32_16x16x32_bf16 v[128:131], v[232:235], v[198:201], v[128:131]
	global_load_dwordx4 v[92:95], v92, s[98:99] offset:128
	v_mfma_f32_16x16x32_bf16 v[124:127], v[236:239], v[198:201], v[124:127]
	s_waitcnt vmcnt(11)
	ds_write_b128 v183, v[84:87] offset:8192
	v_mfma_f32_16x16x32_bf16 v[120:123], v[224:227], v[204:207], v[120:123]
	v_add_u32_e32 v84, s10, v187
	v_mfma_f32_16x16x32_bf16 v[108:111], v[228:231], v[204:207], v[108:111]
	global_load_dwordx4 v[84:87], v84, s[98:99] offset:128
	s_waitcnt vmcnt(11)
	v_mfma_f32_16x16x32_bf16 v[100:103], v[232:235], v[204:207], v[100:103]
	ds_write_b128 v183, v[72:75] offset:10240
	v_mfma_f32_16x16x32_bf16 v[96:99], v[236:239], v[204:207], v[96:99]
	v_add_u32_e32 v72, s11, v187
	global_load_dwordx4 v[72:75], v72, s[98:99] offset:128
	v_mfma_f32_16x16x32_bf16 v[88:91], v[224:227], v[208:211], v[88:91]
	s_waitcnt vmcnt(11)
	v_mfma_f32_16x16x32_bf16 v[80:83], v[228:231], v[208:211], v[80:83]
	ds_write_b128 v183, v[68:71] offset:12288
	v_add_u32_e32 v68, s12, v187
	v_mfma_f32_16x16x32_bf16 v[76:79], v[232:235], v[208:211], v[76:79]
	global_load_dwordx4 v[68:71], v68, s[98:99] offset:128
	v_mfma_f32_16x16x32_bf16 v[64:67], v[236:239], v[208:211], v[64:67]
	s_waitcnt vmcnt(11)
	ds_write_b128 v183, v[48:51] offset:14336
	v_mfma_f32_16x16x32_bf16 v[60:63], v[224:227], v[212:215], v[60:63]
	v_add_u32_e32 v48, s13, v187
	v_mfma_f32_16x16x32_bf16 v[52:55], v[228:231], v[212:215], v[52:55]
	global_load_dwordx4 v[48:51], v48, s[98:99] offset:128
	s_waitcnt vmcnt(11)
	v_mfma_f32_16x16x32_bf16 v[44:47], v[232:235], v[212:215], v[44:47]
	ds_write_b128 v183, v[56:59] offset:16384
	v_mfma_f32_16x16x32_bf16 v[36:39], v[236:239], v[212:215], v[36:39]
	v_mov_b32_e32 v56, v186
	global_load_dwordx4 v[56:59], v56, s[98:99] offset:128
	v_mfma_f32_16x16x32_bf16 v[32:35], v[224:227], v[216:219], v[32:35]
	s_waitcnt vmcnt(11)
	v_mfma_f32_16x16x32_bf16 v[28:31], v[228:231], v[216:219], v[28:31]
	ds_write_b128 v183, v[40:43] offset:18432
	v_add_u32_e32 v40, s43, v186
	v_mfma_f32_16x16x32_bf16 v[16:19], v[232:235], v[216:219], v[16:19]
	global_load_dwordx4 v[40:43], v40, s[98:99] offset:128
	v_mfma_f32_16x16x32_bf16 v[12:15], v[236:239], v[216:219], v[12:15]
	s_waitcnt vmcnt(11)
	ds_write_b128 v183, v[24:27] offset:20480
	v_mfma_f32_16x16x32_bf16 v[8:11], v[224:227], v[220:223], v[8:11]
	v_add_u32_e32 v24, s42, v186
	v_mfma_f32_16x16x32_bf16 v[4:7], v[228:231], v[220:223], v[4:7]
	global_load_dwordx4 v[24:27], v24, s[98:99] offset:128
	s_waitcnt vmcnt(11)
	v_mfma_f32_16x16x32_bf16 v[0:3], v[232:235], v[220:223], v[0:3]
	ds_write_b128 v183, v[20:23] offset:22528
	v_mfma_f32_16x16x32_bf16 v[140:143], v[236:239], v[220:223], v[140:143]
	v_add_u32_e32 v20, s28, v186
	global_load_dwordx4 v[20:23], v20, s[98:99] offset:128
	v_cmp_gt_u32_e32 vcc, 0x6000, v183
	v_add_u32_e32 v182, 0xc000, v183
	v_add_u32_e32 v183, 0xffffa000, v183
	s_nop 0
	v_cndmask_b32_e32 v183, v183, v182, vcc
	s_add_u32 s30, s30, 0x80
	s_addc_u32 s31, s31, 0
	s_cmpk_lg_i32 s30, 0x180
	s_cbranch_scc1 .LBB0_428
	s_waitcnt lgkmcnt(0)
	s_barrier
	ds_read_b128 v[224:227], v184
	ds_read_b128 v[228:231], v184 offset:1024
	ds_read_b128 v[232:235], v184 offset:2048
	ds_read_b128 v[236:239], v184 offset:3072
	ds_read_b128 v[190:193], v185
	ds_read_b128 v[194:197], v185 offset:1024
	ds_read_b128 v[198:201], v185 offset:2048
	ds_read_b128 v[204:207], v185 offset:3072
	ds_read_b128 v[208:211], v185 offset:4096
	ds_read_b128 v[212:215], v185 offset:5120
	ds_read_b128 v[216:219], v185 offset:6144
	ds_read_b128 v[220:223], v185 offset:7168
	s_movk_i32 vcc_lo, 0x6000
	s_cmp_eq_u32 m0, 2
	s_cselect_b32 vcc_lo, 0xffff4000, vcc_lo
	s_add_u32 m0, m0, 1
	s_cmp_eq_u32 m0, 3
	s_cselect_b32 m0, 0, m0
	v_add_u32_e32 v185, vcc_lo, v185
	v_add_u32_e32 v184, vcc_lo, v184
	v_xor_b32_e32 v185, 64, v185
	v_xor_b32_e32 v184, 64, v184
	s_waitcnt lgkmcnt(7)
	v_mfma_f32_16x16x32_bf16 v[172:175], v[224:227], v[190:193], v[172:175]
	v_mfma_f32_16x16x32_bf16 v[168:171], v[228:231], v[190:193], v[168:171]
	v_mfma_f32_16x16x32_bf16 v[164:167], v[232:235], v[190:193], v[164:167]
	v_mfma_f32_16x16x32_bf16 v[160:163], v[236:239], v[190:193], v[160:163]
	ds_read_b128 v[190:193], v185
	s_waitcnt lgkmcnt(7)
	v_mfma_f32_16x16x32_bf16 v[156:159], v[224:227], v[194:197], v[156:159]
	v_mfma_f32_16x16x32_bf16 v[152:155], v[228:231], v[194:197], v[152:155]
	v_mfma_f32_16x16x32_bf16 v[148:151], v[232:235], v[194:197], v[148:151]
	v_mfma_f32_16x16x32_bf16 v[144:147], v[236:239], v[194:197], v[144:147]
	ds_read_b128 v[194:197], v185 offset:1024
	s_waitcnt lgkmcnt(7)
	v_mfma_f32_16x16x32_bf16 v[136:139], v[224:227], v[198:201], v[136:139]
	v_mfma_f32_16x16x32_bf16 v[132:135], v[228:231], v[198:201], v[132:135]
	v_mfma_f32_16x16x32_bf16 v[128:131], v[232:235], v[198:201], v[128:131]
	v_mfma_f32_16x16x32_bf16 v[124:127], v[236:239], v[198:201], v[124:127]
	ds_read_b128 v[198:201], v185 offset:2048
	s_waitcnt lgkmcnt(7)
	v_mfma_f32_16x16x32_bf16 v[120:123], v[224:227], v[204:207], v[120:123]
	v_mfma_f32_16x16x32_bf16 v[108:111], v[228:231], v[204:207], v[108:111]
	v_mfma_f32_16x16x32_bf16 v[100:103], v[232:235], v[204:207], v[100:103]
	v_mfma_f32_16x16x32_bf16 v[96:99], v[236:239], v[204:207], v[96:99]
	ds_read_b128 v[204:207], v185 offset:3072
	s_waitcnt lgkmcnt(7)
	v_mfma_f32_16x16x32_bf16 v[88:91], v[224:227], v[208:211], v[88:91]
	v_mfma_f32_16x16x32_bf16 v[80:83], v[228:231], v[208:211], v[80:83]
	v_mfma_f32_16x16x32_bf16 v[76:79], v[232:235], v[208:211], v[76:79]
	v_mfma_f32_16x16x32_bf16 v[64:67], v[236:239], v[208:211], v[64:67]
	ds_read_b128 v[208:211], v185 offset:4096
	s_waitcnt lgkmcnt(7)
	v_mfma_f32_16x16x32_bf16 v[60:63], v[224:227], v[212:215], v[60:63]
	v_mfma_f32_16x16x32_bf16 v[52:55], v[228:231], v[212:215], v[52:55]
	v_mfma_f32_16x16x32_bf16 v[44:47], v[232:235], v[212:215], v[44:47]
	v_mfma_f32_16x16x32_bf16 v[36:39], v[236:239], v[212:215], v[36:39]
	ds_read_b128 v[212:215], v185 offset:5120
	s_waitcnt lgkmcnt(7)
	v_mfma_f32_16x16x32_bf16 v[32:35], v[224:227], v[216:219], v[32:35]
	v_mfma_f32_16x16x32_bf16 v[28:31], v[228:231], v[216:219], v[28:31]
	v_mfma_f32_16x16x32_bf16 v[16:19], v[232:235], v[216:219], v[16:19]
	v_mfma_f32_16x16x32_bf16 v[12:15], v[236:239], v[216:219], v[12:15]
	ds_read_b128 v[216:219], v185 offset:6144
	s_waitcnt lgkmcnt(7)
	v_mfma_f32_16x16x32_bf16 v[8:11], v[224:227], v[220:223], v[8:11]
	v_mfma_f32_16x16x32_bf16 v[4:7], v[228:231], v[220:223], v[4:7]
	v_mfma_f32_16x16x32_bf16 v[0:3], v[232:235], v[220:223], v[0:3]
	v_mfma_f32_16x16x32_bf16 v[140:143], v[236:239], v[220:223], v[140:143]
	ds_read_b128 v[220:223], v185 offset:7168
	ds_read_b128 v[224:227], v184
	ds_read_b128 v[228:231], v184 offset:1024
	ds_read_b128 v[232:235], v184 offset:2048
	ds_read_b128 v[236:239], v184 offset:3072
	s_movk_i32 vcc_lo, 0x6000
	s_cmp_eq_u32 m0, 2
	s_cselect_b32 vcc_lo, 0xffff4000, vcc_lo
	s_add_u32 m0, m0, 1
	s_cmp_eq_u32 m0, 3
	s_cselect_b32 m0, 0, m0
	v_add_u32_e32 v185, vcc_lo, v185
	v_add_u32_e32 v184, vcc_lo, v184
	v_xor_b32_e32 v185, 64, v185
	v_xor_b32_e32 v184, 64, v184
	s_waitcnt lgkmcnt(0)
	v_mfma_f32_16x16x32_bf16 v[172:175], v[224:227], v[190:193], v[172:175]
	v_mfma_f32_16x16x32_bf16 v[168:171], v[228:231], v[190:193], v[168:171]
	v_mfma_f32_16x16x32_bf16 v[164:167], v[232:235], v[190:193], v[164:167]
	v_mfma_f32_16x16x32_bf16 v[160:163], v[236:239], v[190:193], v[160:163]
	v_mfma_f32_16x16x32_bf16 v[156:159], v[224:227], v[194:197], v[156:159]
	v_mfma_f32_16x16x32_bf16 v[152:155], v[228:231], v[194:197], v[152:155]
	v_mfma_f32_16x16x32_bf16 v[148:151], v[232:235], v[194:197], v[148:151]
	v_mfma_f32_16x16x32_bf16 v[144:147], v[236:239], v[194:197], v[144:147]
	v_mfma_f32_16x16x32_bf16 v[136:139], v[224:227], v[198:201], v[136:139]
	v_mfma_f32_16x16x32_bf16 v[132:135], v[228:231], v[198:201], v[132:135]
	v_mfma_f32_16x16x32_bf16 v[128:131], v[232:235], v[198:201], v[128:131]
	v_mfma_f32_16x16x32_bf16 v[124:127], v[236:239], v[198:201], v[124:127]
	v_mfma_f32_16x16x32_bf16 v[120:123], v[224:227], v[204:207], v[120:123]
	v_mfma_f32_16x16x32_bf16 v[108:111], v[228:231], v[204:207], v[108:111]
	v_mfma_f32_16x16x32_bf16 v[100:103], v[232:235], v[204:207], v[100:103]
	v_mfma_f32_16x16x32_bf16 v[96:99], v[236:239], v[204:207], v[96:99]
	v_mfma_f32_16x16x32_bf16 v[88:91], v[224:227], v[208:211], v[88:91]
	v_mfma_f32_16x16x32_bf16 v[80:83], v[228:231], v[208:211], v[80:83]
	v_mfma_f32_16x16x32_bf16 v[76:79], v[232:235], v[208:211], v[76:79]
	v_mfma_f32_16x16x32_bf16 v[64:67], v[236:239], v[208:211], v[64:67]
	v_mfma_f32_16x16x32_bf16 v[60:63], v[224:227], v[212:215], v[60:63]
	v_mfma_f32_16x16x32_bf16 v[52:55], v[228:231], v[212:215], v[52:55]
	v_mfma_f32_16x16x32_bf16 v[44:47], v[232:235], v[212:215], v[44:47]
	v_mfma_f32_16x16x32_bf16 v[36:39], v[236:239], v[212:215], v[36:39]
	v_mfma_f32_16x16x32_bf16 v[32:35], v[224:227], v[216:219], v[32:35]
	v_mfma_f32_16x16x32_bf16 v[28:31], v[228:231], v[216:219], v[28:31]
	v_mfma_f32_16x16x32_bf16 v[16:19], v[232:235], v[216:219], v[16:19]
	v_mfma_f32_16x16x32_bf16 v[12:15], v[236:239], v[216:219], v[12:15]
	v_mfma_f32_16x16x32_bf16 v[8:11], v[224:227], v[220:223], v[8:11]
	v_mfma_f32_16x16x32_bf16 v[4:7], v[228:231], v[220:223], v[4:7]
	v_mfma_f32_16x16x32_bf16 v[0:3], v[232:235], v[220:223], v[0:3]
	v_mfma_f32_16x16x32_bf16 v[140:143], v[236:239], v[220:223], v[140:143]
	v_lshrrev_b32_e32 v224, 4, v188
	v_and_b32_e32 v225, 7, v188
	v_bitop3_b32 v226, v224, v225, 3 bitop3:0x6c
	v_lshlrev_b32_e32 v227, 7, v188
	v_bfe_u32 v228, v188, 4, 2
	v_and_b32_e32 v229, 0xffffc780, v227
	v_and_b32_e32 v227, 0x2780, v227
	v_bitop3_b32 v228, v228, v225, 4 bitop3:0x36
	v_lshlrev_b32_e32 v226, 4, v226
	v_lshlrev_b32_e32 v228, 4, v228
	v_or_b32_e32 v185, v229, v226
	v_or_b32_e32 v184, v227, v226
	v_or_b32_e32 v183, v229, v228
	v_or_b32_e32 v182, v227, v228
	s_waitcnt vmcnt(0)
	s_setprio 1
	s_barrier
	s_waitcnt vmcnt(10)
	ds_write_b128 v176, v[116:119]
	s_waitcnt vmcnt(9)
	ds_write_b128 v176, v[112:115] offset:4096
	s_waitcnt vmcnt(8)
	ds_write_b128 v176, v[104:107] offset:8192
	s_waitcnt vmcnt(7)
	ds_write_b128 v176, v[92:95] offset:12288
	s_waitcnt vmcnt(6)
	ds_write_b128 v176, v[84:87] offset:16384
	s_waitcnt vmcnt(5)
	ds_write_b128 v176, v[72:75] offset:20480
	s_waitcnt vmcnt(4)
	ds_write_b128 v176, v[68:71] offset:24576
	s_waitcnt vmcnt(3)
	ds_write_b128 v176, v[48:51] offset:28672
	ds_write_b128 v176, v[56:59] offset:32768
	s_waitcnt vmcnt(2)
	ds_write_b128 v176, v[40:43] offset:36864
	s_waitcnt vmcnt(1)
	ds_write_b128 v176, v[24:27] offset:40960
	s_waitcnt vmcnt(0)
	ds_write_b128 v176, v[20:23] offset:45056
	s_waitcnt lgkmcnt(0)
	s_barrier
	ds_read_b128 v[20:23], v185
	ds_read_b128 v[24:27], v185 offset:2048
	ds_read_b128 v[40:43], v185 offset:4096
	ds_read_b128 v[48:51], v185 offset:6144
	ds_read_b128 v[56:59], v185 offset:8192
	ds_read_b128 v[68:71], v185 offset:10240
	ds_read_b128 v[72:75], v185 offset:12288
	ds_read_b128 v[84:87], v185 offset:14336
	ds_read_b128 v[92:95], v184 offset:32768
	ds_read_b128 v[104:107], v184 offset:34816
	ds_read_b128 v[112:115], v184 offset:36864
	ds_read_b128 v[116:119], v184 offset:38912
	s_waitcnt lgkmcnt(3)
	v_mfma_f32_16x16x32_bf16 v[172:175], v[92:95], v[20:23], v[172:175]
	s_waitcnt lgkmcnt(2)
	v_mfma_f32_16x16x32_bf16 v[168:171], v[104:107], v[20:23], v[168:171]
	s_waitcnt lgkmcnt(1)
	v_mfma_f32_16x16x32_bf16 v[164:167], v[112:115], v[20:23], v[164:167]
	s_waitcnt lgkmcnt(0)
	v_mfma_f32_16x16x32_bf16 v[20:23], v[116:119], v[20:23], v[160:163]
	v_mfma_f32_16x16x32_bf16 v[156:159], v[92:95], v[24:27], v[156:159]
	v_mfma_f32_16x16x32_bf16 v[152:155], v[104:107], v[24:27], v[152:155]
	v_mfma_f32_16x16x32_bf16 v[148:151], v[112:115], v[24:27], v[148:151]
	v_mfma_f32_16x16x32_bf16 v[24:27], v[116:119], v[24:27], v[144:147]
	v_mfma_f32_16x16x32_bf16 v[136:139], v[92:95], v[40:43], v[136:139]
	v_mfma_f32_16x16x32_bf16 v[132:135], v[104:107], v[40:43], v[132:135]
	v_mfma_f32_16x16x32_bf16 v[128:131], v[112:115], v[40:43], v[128:131]
	v_mfma_f32_16x16x32_bf16 v[40:43], v[116:119], v[40:43], v[124:127]
	v_mfma_f32_16x16x32_bf16 v[144:147], v[92:95], v[48:51], v[120:123]
	v_mfma_f32_16x16x32_bf16 v[160:163], v[104:107], v[48:51], v[108:111]
	v_mfma_f32_16x16x32_bf16 v[178:181], v[112:115], v[48:51], v[100:103]
	v_mfma_f32_16x16x32_bf16 v[48:51], v[116:119], v[48:51], v[96:99]
	v_mfma_f32_16x16x32_bf16 v[16:19], v[112:115], v[72:75], v[16:19]
	v_mfma_f32_16x16x32_bf16 v[12:15], v[116:119], v[72:75], v[12:15]
	v_mfma_f32_16x16x32_bf16 v[8:11], v[92:95], v[84:87], v[8:11]
	v_mfma_f32_16x16x32_bf16 v[4:7], v[104:107], v[84:87], v[4:7]
	v_mfma_f32_16x16x32_bf16 v[0:3], v[112:115], v[84:87], v[0:3]
	v_mfma_f32_16x16x32_bf16 v[184:187], v[92:95], v[56:59], v[88:91]
	v_mfma_f32_16x16x32_bf16 v[190:193], v[104:107], v[56:59], v[80:83]
	v_mfma_f32_16x16x32_bf16 v[194:197], v[112:115], v[56:59], v[76:79]
	v_mfma_f32_16x16x32_bf16 v[198:201], v[116:119], v[56:59], v[64:67]
	v_mfma_f32_16x16x32_bf16 v[204:207], v[92:95], v[68:71], v[60:63]
	v_mfma_f32_16x16x32_bf16 v[208:211], v[104:107], v[68:71], v[52:55]
	v_mfma_f32_16x16x32_bf16 v[212:215], v[112:115], v[68:71], v[44:47]
	v_mfma_f32_16x16x32_bf16 v[216:219], v[116:119], v[68:71], v[36:39]
	v_mfma_f32_16x16x32_bf16 v[220:223], v[92:95], v[72:75], v[32:35]
	v_mfma_f32_16x16x32_bf16 v[224:227], v[104:107], v[72:75], v[28:31]
	v_mfma_f32_16x16x32_bf16 v[140:143], v[116:119], v[84:87], v[140:143]
	s_nop 1
	ds_read_b128 v[28:31], v183
	ds_read_b128 v[32:35], v183 offset:2048
	ds_read_b128 v[36:39], v183 offset:4096
	ds_read_b128 v[44:47], v183 offset:6144
	ds_read_b128 v[228:231], v183 offset:8192
	ds_read_b128 v[232:235], v183 offset:10240
	ds_read_b128 v[236:239], v183 offset:12288
	ds_read_b128 v[240:243], v183 offset:14336
	ds_read_b128 v[244:247], v182 offset:32768
	ds_read_b128 v[248:251], v182 offset:34816
	ds_read_b128 v[52:55], v182 offset:36864
	ds_read_b128 v[56:59], v182 offset:38912
	s_waitcnt lgkmcnt(3)
	v_mfma_f32_16x16x32_bf16 v[124:127], v[244:247], v[28:31], v[172:175]
	v_readlane_b32 s16, v255, 27
	v_readlane_b32 s17, v255, 28
	v_readlane_b32 s11, v255, 16
	s_waitcnt lgkmcnt(2)
	v_mfma_f32_16x16x32_bf16 v[120:123], v[248:251], v[28:31], v[168:171]
	v_readlane_b32 s10, v255, 18
	s_waitcnt lgkmcnt(1)
	v_mfma_f32_16x16x32_bf16 v[116:119], v[52:55], v[28:31], v[164:167]
	s_waitcnt lgkmcnt(0)
	v_mfma_f32_16x16x32_bf16 v[112:115], v[56:59], v[28:31], v[20:23]
	v_mfma_f32_16x16x32_bf16 v[108:111], v[244:247], v[32:35], v[156:159]
	v_mfma_f32_16x16x32_bf16 v[104:107], v[248:251], v[32:35], v[152:155]
	v_mfma_f32_16x16x32_bf16 v[100:103], v[52:55], v[32:35], v[148:151]
	v_mfma_f32_16x16x32_bf16 v[96:99], v[56:59], v[32:35], v[24:27]
	v_mfma_f32_16x16x32_bf16 v[92:95], v[244:247], v[36:39], v[136:139]
	v_mfma_f32_16x16x32_bf16 v[88:91], v[248:251], v[36:39], v[132:135]
	v_mfma_f32_16x16x32_bf16 v[84:87], v[52:55], v[36:39], v[128:131]
	v_mfma_f32_16x16x32_bf16 v[80:83], v[56:59], v[36:39], v[40:43]
	v_mfma_f32_16x16x32_bf16 v[76:79], v[244:247], v[44:47], v[144:147]
	v_mfma_f32_16x16x32_bf16 v[72:75], v[248:251], v[44:47], v[160:163]
	v_mfma_f32_16x16x32_bf16 v[68:71], v[52:55], v[44:47], v[178:181]
	v_mfma_f32_16x16x32_bf16 v[64:67], v[56:59], v[44:47], v[48:51]
	v_mfma_f32_16x16x32_bf16 v[60:63], v[244:247], v[228:231], v[184:187]
	v_mfma_f32_16x16x32_bf16 v[156:159], v[248:251], v[228:231], v[190:193]
	v_mfma_f32_16x16x32_bf16 v[152:155], v[52:55], v[228:231], v[194:197]
	v_mfma_f32_16x16x32_bf16 v[48:51], v[56:59], v[228:231], v[198:201]
	v_mfma_f32_16x16x32_bf16 v[44:47], v[244:247], v[232:235], v[204:207]
	v_mfma_f32_16x16x32_bf16 v[40:43], v[248:251], v[232:235], v[208:211]
	v_mfma_f32_16x16x32_bf16 v[36:39], v[52:55], v[232:235], v[212:215]
	v_mfma_f32_16x16x32_bf16 v[32:35], v[56:59], v[232:235], v[216:219]
	v_mfma_f32_16x16x32_bf16 v[28:31], v[244:247], v[236:239], v[220:223]
	v_mfma_f32_16x16x32_bf16 v[24:27], v[248:251], v[236:239], v[224:227]
	v_mfma_f32_16x16x32_bf16 v[20:23], v[52:55], v[236:239], v[16:19]
	v_mfma_f32_16x16x32_bf16 v[16:19], v[56:59], v[236:239], v[12:15]
	v_mfma_f32_16x16x32_bf16 v[12:15], v[244:247], v[240:243], v[8:11]
	v_mfma_f32_16x16x32_bf16 v[8:11], v[248:251], v[240:243], v[4:7]
	v_mfma_f32_16x16x32_bf16 v[0:3], v[52:55], v[240:243], v[0:3]
	v_mfma_f32_16x16x32_bf16 v[4:7], v[56:59], v[240:243], v[140:143]
	v_xor_b32_e32 v240, 32, v203

.LBB0_486:
	s_ashr_i32 s30, s36, 3
	s_lshl_b32 s40, s30, 1
	s_and_b32 s31, s30, -16
	s_and_b32 s40, s40, 14
	s_or_b32 s31, s40, s31
	s_bfe_u32 s40, s30, 0x10003
	s_or_b32 s31, s31, s40
	s_cmp_lt_i32 s30, 0
	s_cselect_b32 s30, s31, s30
	s_and_b32 s31, s36, 7
	s_mul_i32 s31, s31, 56
	s_add_i32 s30, s30, s31
	s_mul_hi_i32 s31, s30, 0x92492493
	s_add_i32 s31, s31, s30
	s_ashr_i32 s40, s31, 4
	s_lshr_b32 s41, s31, 31
	s_add_i32 s40, s40, s41
	s_mul_i32 s42, s40, 0xffffffe4
	s_add_i32 s42, s42, s30
	s_ashr_i32 s30, s31, 5
	s_mul_hi_i32 s31, s42, 0x92492493
	s_add_i32 s31, s31, s42
	s_add_i32 s30, s30, s41
	s_lshr_b32 s41, s31, 31
	s_ashr_i32 s31, s31, 2
	s_add_i32 s31, s31, s41
	s_lshl_b32 s41, s30, 1
	s_add_i32 s41, s41, s31
	s_sub_i32 s40, s40, s41
	s_mul_i32 s40, s40, 7
	s_add_i32 s41, s40, s42
	v_mov_b32_e32 v8, v188
	s_lshl_b32 s30, s30, 10
	s_lshl_b32 s40, s31, 8
	s_lshl_b32 s41, s41, 7
	s_add_i32 s40, s40, s30
	v_ashrrev_i32_e32 v9, 3, v8
	v_lshlrev_b32_e32 v4, 4, v8
	v_and_b32_e32 v176, 0x70, v4
	v_add_u32_e32 v4, s41, v9
	v_add_u32_e32 v0, s40, v9
	v_ashrrev_i32_e32 v5, 31, v4
	v_ashrrev_i32_e32 v1, 31, v0
	v_lshlrev_b64 v[4:5], 11, v[4:5]
	v_xor_b32_e32 v10, v9, v8
	v_lshlrev_b64 v[0:1], 11, v[0:1]
	v_lshl_add_u64 v[6:7], s[22:23], 0, v[4:5]
	v_lshlrev_b32_e32 v10, 4, v10
	v_lshl_add_u64 v[2:3], s[0:1], 0, v[0:1]
	v_lshl_add_u64 v[6:7], v[6:7], 0, v[176:177]
	v_and_b32_e32 v10, 0x70, v10
	s_mov_b32 s30, 0x30000
	v_lshl_add_u64 v[2:3], v[2:3], 0, v[176:177]
	v_lshl_or_b32 v176, v9, 7, v10
	v_lshlrev_b32_e32 v12, 7, v8
	v_lshrrev_b32_e32 v9, 4, v8
	v_bfe_u32 v14, v8, 4, 2
	v_and_b32_e32 v15, 7, v8
	v_add_co_u32_e32 v8, vcc, s30, v6
	v_bitop3_b32 v16, v9, v15, 3 bitop3:0x6c
	s_nop 0
	v_addc_co_u32_e32 v9, vcc, 0, v7, vcc
	s_mov_b32 s31, 0x20000
	v_add_co_u32_e32 v10, vcc, s31, v6
	s_mov_b32 s42, 0x10000
	s_nop 0
	v_addc_co_u32_e32 v11, vcc, 0, v7, vcc
	global_load_dwordx4 v[56:59], v[8:9], off
	global_load_dwordx4 v[64:67], v[10:11], off
	v_add_co_u32_e32 v8, vcc, s42, v6
	s_mov_b32 s43, 0x70000
	s_nop 0
	v_addc_co_u32_e32 v9, vcc, 0, v7, vcc
	v_add_co_u32_e32 v10, vcc, s43, v2
	s_mov_b32 s43, 0x60000
	s_nop 0
	v_addc_co_u32_e32 v11, vcc, 0, v3, vcc
	global_load_dwordx4 v[76:79], v[8:9], off
	global_load_dwordx4 v[84:87], v[10:11], off
	v_add_co_u32_e32 v8, vcc, s43, v2
	s_mov_b32 s43, 0x50000
	s_nop 0
	v_addc_co_u32_e32 v9, vcc, 0, v3, vcc
	v_add_co_u32_e32 v10, vcc, s43, v2
	s_mov_b32 s43, 0x40000
	s_nop 0
	v_addc_co_u32_e32 v11, vcc, 0, v3, vcc
	global_load_dwordx4 v[100:103], v[8:9], off
	global_load_dwordx4 v[104:107], v[10:11], off
	v_add_co_u32_e32 v8, vcc, s43, v2
	v_and_b32_e32 v13, 0xffffc780, v12
	s_nop 0
	v_addc_co_u32_e32 v9, vcc, 0, v3, vcc
	v_add_co_u32_e32 v10, vcc, s30, v2
	v_and_b32_e32 v12, 0x2780, v12
	s_nop 0
	v_addc_co_u32_e32 v11, vcc, 0, v3, vcc
	global_load_dwordx4 v[124:127], v[8:9], off
	global_load_dwordx4 v[128:131], v[10:11], off
	v_add_co_u32_e32 v8, vcc, s31, v2
	v_bitop3_b32 v14, v14, v15, 4 bitop3:0x36
	s_nop 0
	v_addc_co_u32_e32 v9, vcc, 0, v3, vcc
	v_add_co_u32_e32 v10, vcc, s42, v2
	v_mov_b32_e32 v116, 0
	s_nop 0
	v_addc_co_u32_e32 v11, vcc, 0, v3, vcc
	global_load_dwordx4 v[148:151], v[8:9], off
	global_load_dwordx4 v[152:155], v[10:11], off
	global_load_dwordx4 v[140:143], v[6:7], off
	global_load_dwordx4 v[160:163], v[2:3], off
	v_lshlrev_b32_e32 v2, 4, v16
	v_or_b32_e32 v185, v13, v2
	v_or_b32_e32 v184, v12, v2
	v_lshlrev_b32_e32 v2, 4, v14
	v_or_b32_e32 v183, v13, v2
	v_or_b32_e32 v182, v12, v2
	v_lshlrev_b32_e32 v2, 4, v15
	v_or_b32_e32 v0, v0, v2
	v_or_b32_e32 v4, v4, v2
	v_lshl_add_u64 v[178:179], s[34:35], 0, v[0:1]
	v_lshl_add_u64 v[180:181], s[2:3], 0, v[4:5]
	s_mov_b64 s[30:31], 0
	v_mov_b32_e32 v117, v116
	v_mov_b32_e32 v118, v116
	v_mov_b32_e32 v119, v116
	v_mov_b32_e32 v0, v116
	v_mov_b32_e32 v1, v116
	v_mov_b32_e32 v2, v116
	v_mov_b32_e32 v3, v116
	v_mov_b32_e32 v4, v116
	v_mov_b32_e32 v5, v116
	v_mov_b32_e32 v6, v116
	v_mov_b32_e32 v7, v116
	v_mov_b32_e32 v8, v116
	v_mov_b32_e32 v9, v116
	v_mov_b32_e32 v10, v116
	v_mov_b32_e32 v11, v116
	v_mov_b32_e32 v12, v116
	v_mov_b32_e32 v13, v116
	v_mov_b32_e32 v14, v116
	v_mov_b32_e32 v15, v116
	v_mov_b32_e32 v16, v116
	v_mov_b32_e32 v17, v116
	v_mov_b32_e32 v18, v116
	v_mov_b32_e32 v19, v116
	v_mov_b32_e32 v20, v116
	v_mov_b32_e32 v21, v116
	v_mov_b32_e32 v22, v116
	v_mov_b32_e32 v23, v116
	v_mov_b32_e32 v24, v116
	v_mov_b32_e32 v25, v116
	v_mov_b32_e32 v26, v116
	v_mov_b32_e32 v27, v116
	v_mov_b32_e32 v28, v116
	v_mov_b32_e32 v29, v116
	v_mov_b32_e32 v30, v116
	v_mov_b32_e32 v31, v116
	v_mov_b32_e32 v32, v116
	v_mov_b32_e32 v33, v116
	v_mov_b32_e32 v34, v116
	v_mov_b32_e32 v35, v116
	v_mov_b32_e32 v36, v116
	v_mov_b32_e32 v37, v116
	v_mov_b32_e32 v38, v116
	v_mov_b32_e32 v39, v116
	v_mov_b32_e32 v40, v116
	v_mov_b32_e32 v41, v116
	v_mov_b32_e32 v42, v116
	v_mov_b32_e32 v43, v116
	v_mov_b32_e32 v44, v116
	v_mov_b32_e32 v45, v116
	v_mov_b32_e32 v46, v116
	v_mov_b32_e32 v47, v116
	v_mov_b32_e32 v48, v116
	v_mov_b32_e32 v49, v116
	v_mov_b32_e32 v50, v116
	v_mov_b32_e32 v51, v116
	v_mov_b32_e32 v52, v116
	v_mov_b32_e32 v53, v116
	v_mov_b32_e32 v54, v116
	v_mov_b32_e32 v55, v116
	v_mov_b32_e32 v60, v116
	v_mov_b32_e32 v61, v116
	v_mov_b32_e32 v62, v116
	v_mov_b32_e32 v63, v116
	v_mov_b32_e32 v68, v116
	v_mov_b32_e32 v69, v116
	v_mov_b32_e32 v70, v116
	v_mov_b32_e32 v71, v116
	v_mov_b32_e32 v72, v116
	v_mov_b32_e32 v73, v116
	v_mov_b32_e32 v74, v116
	v_mov_b32_e32 v75, v116
	v_mov_b32_e32 v80, v116
	v_mov_b32_e32 v81, v116
	v_mov_b32_e32 v82, v116
	v_mov_b32_e32 v83, v116
	v_mov_b32_e32 v88, v116
	v_mov_b32_e32 v89, v116
	v_mov_b32_e32 v90, v116
	v_mov_b32_e32 v91, v116
	v_mov_b32_e32 v92, v116
	v_mov_b32_e32 v93, v116
	v_mov_b32_e32 v94, v116
	v_mov_b32_e32 v95, v116
	v_mov_b32_e32 v96, v116
	v_mov_b32_e32 v97, v116
	v_mov_b32_e32 v98, v116
	v_mov_b32_e32 v99, v116
	v_mov_b32_e32 v108, v116
	v_mov_b32_e32 v109, v116
	v_mov_b32_e32 v110, v116
	v_mov_b32_e32 v111, v116
	v_mov_b32_e32 v112, v116
	v_mov_b32_e32 v113, v116
	v_mov_b32_e32 v114, v116
	v_mov_b32_e32 v115, v116
	v_mov_b32_e32 v120, v116
	v_mov_b32_e32 v121, v116
	v_mov_b32_e32 v122, v116
	v_mov_b32_e32 v123, v116
	v_mov_b32_e32 v132, v116
	v_mov_b32_e32 v133, v116
	v_mov_b32_e32 v134, v116
	v_mov_b32_e32 v135, v116
	v_mov_b32_e32 v136, v116
	v_mov_b32_e32 v137, v116
	v_mov_b32_e32 v138, v116
	v_mov_b32_e32 v139, v116
	v_mov_b32_e32 v144, v116
	v_mov_b32_e32 v145, v116
	v_mov_b32_e32 v146, v116
	v_mov_b32_e32 v147, v116
	v_mov_b32_e32 v156, v116
	v_mov_b32_e32 v157, v116
	v_mov_b32_e32 v158, v116
	v_mov_b32_e32 v159, v116
	v_mov_b32_e32 v164, v116
	v_mov_b32_e32 v165, v116
	v_mov_b32_e32 v166, v116
	v_mov_b32_e32 v167, v116
	v_mov_b32_e32 v168, v116
	v_mov_b32_e32 v169, v116
	v_mov_b32_e32 v170, v116
	v_mov_b32_e32 v171, v116
	v_mov_b32_e32 v172, v116
	v_mov_b32_e32 v173, v116
	v_mov_b32_e32 v174, v116
	v_mov_b32_e32 v175, v116
	v_readlane_b32 vcc_lo, v253, 0
	s_cmpk_lt_u32 vcc_lo, 0x100
	s_cbranch_scc1 .Lprio_hi5
	s_setprio 2
	s_branch .Lprio_done5

.Lprio_done5:
	v_readlane_b32 s98, v253, 3
	v_readlane_b32 s99, v253, 4
	v_and_b32_e32 v224, 15, v188
	v_bfe_u32 v225, v188, 4, 2
	v_lshrrev_b32_e32 v226, 2, v224
	v_sub_u32_e32 v226, 0, v226
	v_and_b32_e32 v226, 3, v226
	v_xor_b32_e32 v225, v225, v226
	v_lshlrev_b32_e32 v225, 4, v225
	v_lshl_or_b32 v225, v224, 6, v225
	v_bfe_u32 v226, v188, 7, 1
	v_lshl_or_b32 v185, v226, 13, v225
	v_bfe_u32 v226, v188, 6, 1
	v_lshl_or_b32 v184, v226, 12, v225
	v_add_u32_e32 v184, 0x4000, v184
	v_lshrrev_b32_e32 v224, 3, v188
	v_bfe_u32 v225, v188, 2, 1
	v_lshrrev_b32_e32 v226, 2, v224
	v_sub_u32_e32 v226, 0, v226
	v_and_b32_e32 v226, 3, v226
	v_and_b32_e32 v227, 3, v188
	v_xor_b32_e32 v226, v227, v226
	v_lshlrev_b32_e32 v226, 4, v226
	v_xor_b32_e32 v224, v224, v225
	v_lshl_or_b32 v226, v224, 6, v226
	v_mul_u32_u24_e32 v225, 0x6000, v225
	v_add_u32_e32 v183, v225, v226
	s_mov_b32 m0, 0
	s_sub_u32 vcc_lo, s30, s98
	v_add_u32_e32 v186, vcc_lo, v178
	v_add_u32_e32 v187, vcc_lo, v180
	s_barrier
	s_waitcnt vmcnt(0)
	ds_write_b128 v183, v[160:163]
	ds_write_b128 v183, v[152:155] offset:2048
	ds_write_b128 v183, v[148:151] offset:4096
	ds_write_b128 v183, v[128:131] offset:6144
	ds_write_b128 v183, v[124:127] offset:8192
	ds_write_b128 v183, v[104:107] offset:10240
	ds_write_b128 v183, v[100:103] offset:12288
	ds_write_b128 v183, v[84:87] offset:14336
	ds_write_b128 v183, v[140:143] offset:16384
	ds_write_b128 v183, v[76:79] offset:18432
	ds_write_b128 v183, v[64:67] offset:20480
	ds_write_b128 v183, v[56:59] offset:22528
	v_cmp_gt_u32_e32 vcc, 0x6000, v183
	v_add_u32_e32 v182, 0xc000, v183
	v_add_u32_e32 v183, 0xffffa000, v183
	s_nop 0
	v_cndmask_b32_e32 v183, v183, v182, vcc
	v_add_u32_e32 v160, s26, v186
	global_load_dwordx4 v[160:163], v160, s[98:99] offset:128
	v_add_u32_e32 v152, s27, v186
	global_load_dwordx4 v[152:155], v152, s[98:99] offset:128
	v_add_u32_e32 v148, s20, v186
	global_load_dwordx4 v[148:151], v148, s[98:99] offset:128
	v_add_u32_e32 v128, s21, v186
	global_load_dwordx4 v[128:131], v128, s[98:99] offset:128
	v_add_u32_e32 v124, s56, v186
	global_load_dwordx4 v[124:127], v124, s[98:99] offset:128
	v_add_u32_e32 v104, s57, v186
	global_load_dwordx4 v[104:107], v104, s[98:99] offset:128
	v_add_u32_e32 v100, s24, v186
	global_load_dwordx4 v[100:103], v100, s[98:99] offset:128
	v_add_u32_e32 v84, s96, v186
	global_load_dwordx4 v[84:87], v84, s[98:99] offset:128
	v_add_u32_e32 v140, 0x1800000, v187
	global_load_dwordx4 v[140:143], v140, s[98:99] offset:128
	v_add_u32_e32 v76, 0x1810000, v187
	global_load_dwordx4 v[76:79], v76, s[98:99] offset:128
	v_add_u32_e32 v64, 0x1820000, v187
	global_load_dwordx4 v[64:67], v64, s[98:99] offset:128
	v_add_u32_e32 v56, 0x1830000, v187
	global_load_dwordx4 v[56:59], v56, s[98:99] offset:128
	s_add_u32 s30, s30, 0x80
	s_addc_u32 s31, s31, 0
.LBB0_487:
	s_waitcnt lgkmcnt(0)
	s_barrier
	ds_read_b128 v[224:227], v184
	ds_read_b128 v[228:231], v184 offset:1024
	ds_read_b128 v[232:235], v184 offset:2048
	ds_read_b128 v[236:239], v184 offset:3072
	ds_read_b128 v[190:193], v185
	ds_read_b128 v[194:197], v185 offset:1024
	ds_read_b128 v[198:201], v185 offset:2048
	ds_read_b128 v[204:207], v185 offset:3072
	ds_read_b128 v[208:211], v185 offset:4096
	ds_read_b128 v[212:215], v185 offset:5120
	ds_read_b128 v[216:219], v185 offset:6144
	ds_read_b128 v[220:223], v185 offset:7168
	s_movk_i32 vcc_lo, 0x6000
	s_cmp_eq_u32 m0, 2
	s_cselect_b32 vcc_lo, 0xffff4000, vcc_lo
	s_add_u32 m0, m0, 1
	s_cmp_eq_u32 m0, 3
	s_cselect_b32 m0, 0, m0
	v_add_u32_e32 v185, vcc_lo, v185
	v_add_u32_e32 v184, vcc_lo, v184
	v_xor_b32_e32 v185, 64, v185
	v_xor_b32_e32 v184, 64, v184
	s_waitcnt lgkmcnt(7)
	v_mfma_f32_16x16x32_bf16 v[172:175], v[224:227], v[190:193], v[172:175]
	v_mfma_f32_16x16x32_bf16 v[168:171], v[228:231], v[190:193], v[168:171]
	v_mfma_f32_16x16x32_bf16 v[164:167], v[232:235], v[190:193], v[164:167]
	v_mfma_f32_16x16x32_bf16 v[156:159], v[236:239], v[190:193], v[156:159]
	ds_read_b128 v[190:193], v185
	s_waitcnt lgkmcnt(7)
	v_mfma_f32_16x16x32_bf16 v[144:147], v[224:227], v[194:197], v[144:147]
	v_mfma_f32_16x16x32_bf16 v[136:139], v[228:231], v[194:197], v[136:139]
	v_mfma_f32_16x16x32_bf16 v[132:135], v[232:235], v[194:197], v[132:135]
	v_mfma_f32_16x16x32_bf16 v[120:123], v[236:239], v[194:197], v[120:123]
	ds_read_b128 v[194:197], v185 offset:1024
	s_waitcnt lgkmcnt(7)
	v_mfma_f32_16x16x32_bf16 v[112:115], v[224:227], v[198:201], v[112:115]
	v_mfma_f32_16x16x32_bf16 v[108:111], v[228:231], v[198:201], v[108:111]
	v_mfma_f32_16x16x32_bf16 v[96:99], v[232:235], v[198:201], v[96:99]
	v_mfma_f32_16x16x32_bf16 v[92:95], v[236:239], v[198:201], v[92:95]
	ds_read_b128 v[198:201], v185 offset:2048
	s_waitcnt lgkmcnt(7)
	v_mfma_f32_16x16x32_bf16 v[88:91], v[224:227], v[204:207], v[88:91]
	v_mfma_f32_16x16x32_bf16 v[80:83], v[228:231], v[204:207], v[80:83]
	v_mfma_f32_16x16x32_bf16 v[72:75], v[232:235], v[204:207], v[72:75]
	v_mfma_f32_16x16x32_bf16 v[68:71], v[236:239], v[204:207], v[68:71]
	ds_read_b128 v[204:207], v185 offset:3072
	s_waitcnt lgkmcnt(7)
	v_mfma_f32_16x16x32_bf16 v[60:63], v[224:227], v[208:211], v[60:63]
	v_mfma_f32_16x16x32_bf16 v[52:55], v[228:231], v[208:211], v[52:55]
	v_mfma_f32_16x16x32_bf16 v[48:51], v[232:235], v[208:211], v[48:51]
	v_mfma_f32_16x16x32_bf16 v[44:47], v[236:239], v[208:211], v[44:47]
	ds_read_b128 v[208:211], v185 offset:4096
	s_waitcnt lgkmcnt(7)
	v_mfma_f32_16x16x32_bf16 v[40:43], v[224:227], v[212:215], v[40:43]
	v_mfma_f32_16x16x32_bf16 v[36:39], v[228:231], v[212:215], v[36:39]
	v_mfma_f32_16x16x32_bf16 v[32:35], v[232:235], v[212:215], v[32:35]
	v_mfma_f32_16x16x32_bf16 v[28:31], v[236:239], v[212:215], v[28:31]
	ds_read_b128 v[212:215], v185 offset:5120
	s_waitcnt lgkmcnt(7)
	v_mfma_f32_16x16x32_bf16 v[24:27], v[224:227], v[216:219], v[24:27]
	v_mfma_f32_16x16x32_bf16 v[20:23], v[228:231], v[216:219], v[20:23]
	v_mfma_f32_16x16x32_bf16 v[16:19], v[232:235], v[216:219], v[16:19]
	v_mfma_f32_16x16x32_bf16 v[12:15], v[236:239], v[216:219], v[12:15]
	ds_read_b128 v[216:219], v185 offset:6144
	s_waitcnt lgkmcnt(7)
	v_mfma_f32_16x16x32_bf16 v[8:11], v[224:227], v[220:223], v[8:11]
	v_mfma_f32_16x16x32_bf16 v[4:7], v[228:231], v[220:223], v[4:7]
	v_mfma_f32_16x16x32_bf16 v[0:3], v[232:235], v[220:223], v[0:3]
	v_mfma_f32_16x16x32_bf16 v[116:119], v[236:239], v[220:223], v[116:119]
	ds_read_b128 v[220:223], v185 offset:7168
	ds_read_b128 v[224:227], v184
	ds_read_b128 v[228:231], v184 offset:1024
	ds_read_b128 v[232:235], v184 offset:2048
	ds_read_b128 v[236:239], v184 offset:3072
	s_movk_i32 vcc_lo, 0x6000
	s_cmp_eq_u32 m0, 2
	s_cselect_b32 vcc_lo, 0xffff4000, vcc_lo
	s_add_u32 m0, m0, 1
	s_cmp_eq_u32 m0, 3
	s_cselect_b32 m0, 0, m0
	v_add_u32_e32 v185, vcc_lo, v185
	v_add_u32_e32 v184, vcc_lo, v184
	v_xor_b32_e32 v185, 64, v185
	v_xor_b32_e32 v184, 64, v184
	s_sub_u32 vcc_lo, s30, s98
	v_add_u32_e32 v186, vcc_lo, v178
	v_add_u32_e32 v187, vcc_lo, v180
	s_barrier
	s_waitcnt lgkmcnt(0)
	v_mfma_f32_16x16x32_bf16 v[172:175], v[224:227], v[190:193], v[172:175]
	s_waitcnt vmcnt(11)
	v_mfma_f32_16x16x32_bf16 v[168:171], v[228:231], v[190:193], v[168:171]
	ds_write_b128 v183, v[160:163]
	v_add_u32_e32 v160, s26, v186
	v_mfma_f32_16x16x32_bf16 v[164:167], v[232:235], v[190:193], v[164:167]
	global_load_dwordx4 v[160:163], v160, s[98:99] offset:128
	v_mfma_f32_16x16x32_bf16 v[156:159], v[236:239], v[190:193], v[156:159]
	s_waitcnt vmcnt(11)
	ds_write_b128 v183, v[152:155] offset:2048
	v_mfma_f32_16x16x32_bf16 v[144:147], v[224:227], v[194:197], v[144:147]
	v_add_u32_e32 v152, s27, v186
	v_mfma_f32_16x16x32_bf16 v[136:139], v[228:231], v[194:197], v[136:139]
	global_load_dwordx4 v[152:155], v152, s[98:99] offset:128
	s_waitcnt vmcnt(11)
	v_mfma_f32_16x16x32_bf16 v[132:135], v[232:235], v[194:197], v[132:135]
	ds_write_b128 v183, v[148:151] offset:4096
	v_mfma_f32_16x16x32_bf16 v[120:123], v[236:239], v[194:197], v[120:123]
	v_add_u32_e32 v148, s20, v186
	global_load_dwordx4 v[148:151], v148, s[98:99] offset:128
	v_mfma_f32_16x16x32_bf16 v[112:115], v[224:227], v[198:201], v[112:115]
	s_waitcnt vmcnt(11)
	v_mfma_f32_16x16x32_bf16 v[108:111], v[228:231], v[198:201], v[108:111]
	ds_write_b128 v183, v[128:131] offset:6144
	v_add_u32_e32 v128, s21, v186
	v_mfma_f32_16x16x32_bf16 v[96:99], v[232:235], v[198:201], v[96:99]
	global_load_dwordx4 v[128:131], v128, s[98:99] offset:128
	v_mfma_f32_16x16x32_bf16 v[92:95], v[236:239], v[198:201], v[92:95]
	s_waitcnt vmcnt(11)
	ds_write_b128 v183, v[124:127] offset:8192
	v_mfma_f32_16x16x32_bf16 v[88:91], v[224:227], v[204:207], v[88:91]
	v_add_u32_e32 v124, s56, v186
	v_mfma_f32_16x16x32_bf16 v[80:83], v[228:231], v[204:207], v[80:83]
	global_load_dwordx4 v[124:127], v124, s[98:99] offset:128
	s_waitcnt vmcnt(11)
	v_mfma_f32_16x16x32_bf16 v[72:75], v[232:235], v[204:207], v[72:75]
	ds_write_b128 v183, v[104:107] offset:10240
	v_mfma_f32_16x16x32_bf16 v[68:71], v[236:239], v[204:207], v[68:71]
	v_add_u32_e32 v104, s57, v186
	global_load_dwordx4 v[104:107], v104, s[98:99] offset:128
	v_mfma_f32_16x16x32_bf16 v[60:63], v[224:227], v[208:211], v[60:63]
	s_waitcnt vmcnt(11)
	v_mfma_f32_16x16x32_bf16 v[52:55], v[228:231], v[208:211], v[52:55]
	ds_write_b128 v183, v[100:103] offset:12288
	v_add_u32_e32 v100, s24, v186
	v_mfma_f32_16x16x32_bf16 v[48:51], v[232:235], v[208:211], v[48:51]
	global_load_dwordx4 v[100:103], v100, s[98:99] offset:128
	v_mfma_f32_16x16x32_bf16 v[44:47], v[236:239], v[208:211], v[44:47]
	s_waitcnt vmcnt(11)
	ds_write_b128 v183, v[84:87] offset:14336
	v_mfma_f32_16x16x32_bf16 v[40:43], v[224:227], v[212:215], v[40:43]
	v_add_u32_e32 v84, s96, v186
	v_mfma_f32_16x16x32_bf16 v[36:39], v[228:231], v[212:215], v[36:39]
	global_load_dwordx4 v[84:87], v84, s[98:99] offset:128
	s_waitcnt vmcnt(11)
	v_mfma_f32_16x16x32_bf16 v[32:35], v[232:235], v[212:215], v[32:35]
	ds_write_b128 v183, v[140:143] offset:16384
	v_mfma_f32_16x16x32_bf16 v[28:31], v[236:239], v[212:215], v[28:31]
	v_add_u32_e32 v140, 0x1800000, v187
	global_load_dwordx4 v[140:143], v140, s[98:99] offset:128
	v_mfma_f32_16x16x32_bf16 v[24:27], v[224:227], v[216:219], v[24:27]
	s_waitcnt vmcnt(11)
	v_mfma_f32_16x16x32_bf16 v[20:23], v[228:231], v[216:219], v[20:23]
	ds_write_b128 v183, v[76:79] offset:18432
	v_add_u32_e32 v76, 0x1810000, v187
	v_mfma_f32_16x16x32_bf16 v[16:19], v[232:235], v[216:219], v[16:19]
	global_load_dwordx4 v[76:79], v76, s[98:99] offset:128
	v_mfma_f32_16x16x32_bf16 v[12:15], v[236:239], v[216:219], v[12:15]
	s_waitcnt vmcnt(11)
	ds_write_b128 v183, v[64:67] offset:20480
	v_mfma_f32_16x16x32_bf16 v[8:11], v[224:227], v[220:223], v[8:11]
	v_add_u32_e32 v64, 0x1820000, v187
	v_mfma_f32_16x16x32_bf16 v[4:7], v[228:231], v[220:223], v[4:7]
	global_load_dwordx4 v[64:67], v64, s[98:99] offset:128
	s_waitcnt vmcnt(11)
	v_mfma_f32_16x16x32_bf16 v[0:3], v[232:235], v[220:223], v[0:3]
	ds_write_b128 v183, v[56:59] offset:22528
	v_mfma_f32_16x16x32_bf16 v[116:119], v[236:239], v[220:223], v[116:119]
	v_add_u32_e32 v56, 0x1830000, v187
	global_load_dwordx4 v[56:59], v56, s[98:99] offset:128
	v_cmp_gt_u32_e32 vcc, 0x6000, v183
	v_add_u32_e32 v182, 0xc000, v183
	v_add_u32_e32 v183, 0xffffa000, v183
	s_nop 0
	v_cndmask_b32_e32 v183, v183, v182, vcc
	s_add_u32 s30, s30, 0x80
	s_addc_u32 s31, s31, 0
	s_cmpk_lg_i32 s30, 0x780
	s_cbranch_scc1 .LBB0_487
	s_waitcnt lgkmcnt(0)
	s_barrier
	ds_read_b128 v[224:227], v184
	ds_read_b128 v[228:231], v184 offset:1024
	ds_read_b128 v[232:235], v184 offset:2048
	ds_read_b128 v[236:239], v184 offset:3072
	ds_read_b128 v[190:193], v185
	ds_read_b128 v[194:197], v185 offset:1024
	ds_read_b128 v[198:201], v185 offset:2048
	ds_read_b128 v[204:207], v185 offset:3072
	ds_read_b128 v[208:211], v185 offset:4096
	ds_read_b128 v[212:215], v185 offset:5120
	ds_read_b128 v[216:219], v185 offset:6144
	ds_read_b128 v[220:223], v185 offset:7168
	s_movk_i32 vcc_lo, 0x6000
	s_cmp_eq_u32 m0, 2
	s_cselect_b32 vcc_lo, 0xffff4000, vcc_lo
	s_add_u32 m0, m0, 1
	s_cmp_eq_u32 m0, 3
	s_cselect_b32 m0, 0, m0
	v_add_u32_e32 v185, vcc_lo, v185
	v_add_u32_e32 v184, vcc_lo, v184
	v_xor_b32_e32 v185, 64, v185
	v_xor_b32_e32 v184, 64, v184
	s_waitcnt lgkmcnt(7)
	v_mfma_f32_16x16x32_bf16 v[172:175], v[224:227], v[190:193], v[172:175]
	v_mfma_f32_16x16x32_bf16 v[168:171], v[228:231], v[190:193], v[168:171]
	v_mfma_f32_16x16x32_bf16 v[164:167], v[232:235], v[190:193], v[164:167]
	v_mfma_f32_16x16x32_bf16 v[156:159], v[236:239], v[190:193], v[156:159]
	ds_read_b128 v[190:193], v185
	s_waitcnt lgkmcnt(7)
	v_mfma_f32_16x16x32_bf16 v[144:147], v[224:227], v[194:197], v[144:147]
	v_mfma_f32_16x16x32_bf16 v[136:139], v[228:231], v[194:197], v[136:139]
	v_mfma_f32_16x16x32_bf16 v[132:135], v[232:235], v[194:197], v[132:135]
	v_mfma_f32_16x16x32_bf16 v[120:123], v[236:239], v[194:197], v[120:123]
	ds_read_b128 v[194:197], v185 offset:1024
	s_waitcnt lgkmcnt(7)
	v_mfma_f32_16x16x32_bf16 v[112:115], v[224:227], v[198:201], v[112:115]
	v_mfma_f32_16x16x32_bf16 v[108:111], v[228:231], v[198:201], v[108:111]
	v_mfma_f32_16x16x32_bf16 v[96:99], v[232:235], v[198:201], v[96:99]
	v_mfma_f32_16x16x32_bf16 v[92:95], v[236:239], v[198:201], v[92:95]
	ds_read_b128 v[198:201], v185 offset:2048
	s_waitcnt lgkmcnt(7)
	v_mfma_f32_16x16x32_bf16 v[88:91], v[224:227], v[204:207], v[88:91]
	v_mfma_f32_16x16x32_bf16 v[80:83], v[228:231], v[204:207], v[80:83]
	v_mfma_f32_16x16x32_bf16 v[72:75], v[232:235], v[204:207], v[72:75]
	v_mfma_f32_16x16x32_bf16 v[68:71], v[236:239], v[204:207], v[68:71]
	ds_read_b128 v[204:207], v185 offset:3072
	s_waitcnt lgkmcnt(7)
	v_mfma_f32_16x16x32_bf16 v[60:63], v[224:227], v[208:211], v[60:63]
	v_mfma_f32_16x16x32_bf16 v[52:55], v[228:231], v[208:211], v[52:55]
	v_mfma_f32_16x16x32_bf16 v[48:51], v[232:235], v[208:211], v[48:51]
	v_mfma_f32_16x16x32_bf16 v[44:47], v[236:239], v[208:211], v[44:47]
	ds_read_b128 v[208:211], v185 offset:4096
	s_waitcnt lgkmcnt(7)
	v_mfma_f32_16x16x32_bf16 v[40:43], v[224:227], v[212:215], v[40:43]
	v_mfma_f32_16x16x32_bf16 v[36:39], v[228:231], v[212:215], v[36:39]
	v_mfma_f32_16x16x32_bf16 v[32:35], v[232:235], v[212:215], v[32:35]
	v_mfma_f32_16x16x32_bf16 v[28:31], v[236:239], v[212:215], v[28:31]
	ds_read_b128 v[212:215], v185 offset:5120
	s_waitcnt lgkmcnt(7)
	v_mfma_f32_16x16x32_bf16 v[24:27], v[224:227], v[216:219], v[24:27]
	v_mfma_f32_16x16x32_bf16 v[20:23], v[228:231], v[216:219], v[20:23]
	v_mfma_f32_16x16x32_bf16 v[16:19], v[232:235], v[216:219], v[16:19]
	v_mfma_f32_16x16x32_bf16 v[12:15], v[236:239], v[216:219], v[12:15]
	ds_read_b128 v[216:219], v185 offset:6144
	s_waitcnt lgkmcnt(7)
	v_mfma_f32_16x16x32_bf16 v[8:11], v[224:227], v[220:223], v[8:11]
	v_mfma_f32_16x16x32_bf16 v[4:7], v[228:231], v[220:223], v[4:7]
	v_mfma_f32_16x16x32_bf16 v[0:3], v[232:235], v[220:223], v[0:3]
	v_mfma_f32_16x16x32_bf16 v[116:119], v[236:239], v[220:223], v[116:119]
	ds_read_b128 v[220:223], v185 offset:7168
	ds_read_b128 v[224:227], v184
	ds_read_b128 v[228:231], v184 offset:1024
	ds_read_b128 v[232:235], v184 offset:2048
	ds_read_b128 v[236:239], v184 offset:3072
	s_movk_i32 vcc_lo, 0x6000
	s_cmp_eq_u32 m0, 2
	s_cselect_b32 vcc_lo, 0xffff4000, vcc_lo
	s_add_u32 m0, m0, 1
	s_cmp_eq_u32 m0, 3
	s_cselect_b32 m0, 0, m0
	v_add_u32_e32 v185, vcc_lo, v185
	v_add_u32_e32 v184, vcc_lo, v184
	v_xor_b32_e32 v185, 64, v185
	v_xor_b32_e32 v184, 64, v184
	s_waitcnt lgkmcnt(0)
	v_mfma_f32_16x16x32_bf16 v[172:175], v[224:227], v[190:193], v[172:175]
	v_mfma_f32_16x16x32_bf16 v[168:171], v[228:231], v[190:193], v[168:171]
	v_mfma_f32_16x16x32_bf16 v[164:167], v[232:235], v[190:193], v[164:167]
	v_mfma_f32_16x16x32_bf16 v[156:159], v[236:239], v[190:193], v[156:159]
	v_mfma_f32_16x16x32_bf16 v[144:147], v[224:227], v[194:197], v[144:147]
	v_mfma_f32_16x16x32_bf16 v[136:139], v[228:231], v[194:197], v[136:139]
	v_mfma_f32_16x16x32_bf16 v[132:135], v[232:235], v[194:197], v[132:135]
	v_mfma_f32_16x16x32_bf16 v[120:123], v[236:239], v[194:197], v[120:123]
	v_mfma_f32_16x16x32_bf16 v[112:115], v[224:227], v[198:201], v[112:115]
	v_mfma_f32_16x16x32_bf16 v[108:111], v[228:231], v[198:201], v[108:111]
	v_mfma_f32_16x16x32_bf16 v[96:99], v[232:235], v[198:201], v[96:99]
	v_mfma_f32_16x16x32_bf16 v[92:95], v[236:239], v[198:201], v[92:95]
	v_mfma_f32_16x16x32_bf16 v[88:91], v[224:227], v[204:207], v[88:91]
	v_mfma_f32_16x16x32_bf16 v[80:83], v[228:231], v[204:207], v[80:83]
	v_mfma_f32_16x16x32_bf16 v[72:75], v[232:235], v[204:207], v[72:75]
	v_mfma_f32_16x16x32_bf16 v[68:71], v[236:239], v[204:207], v[68:71]
	v_mfma_f32_16x16x32_bf16 v[60:63], v[224:227], v[208:211], v[60:63]
	v_mfma_f32_16x16x32_bf16 v[52:55], v[228:231], v[208:211], v[52:55]
	v_mfma_f32_16x16x32_bf16 v[48:51], v[232:235], v[208:211], v[48:51]
	v_mfma_f32_16x16x32_bf16 v[44:47], v[236:239], v[208:211], v[44:47]
	v_mfma_f32_16x16x32_bf16 v[40:43], v[224:227], v[212:215], v[40:43]
	v_mfma_f32_16x16x32_bf16 v[36:39], v[228:231], v[212:215], v[36:39]
	v_mfma_f32_16x16x32_bf16 v[32:35], v[232:235], v[212:215], v[32:35]
	v_mfma_f32_16x16x32_bf16 v[28:31], v[236:239], v[212:215], v[28:31]
	v_mfma_f32_16x16x32_bf16 v[24:27], v[224:227], v[216:219], v[24:27]
	v_mfma_f32_16x16x32_bf16 v[20:23], v[228:231], v[216:219], v[20:23]
	v_mfma_f32_16x16x32_bf16 v[16:19], v[232:235], v[216:219], v[16:19]
	v_mfma_f32_16x16x32_bf16 v[12:15], v[236:239], v[216:219], v[12:15]
	v_mfma_f32_16x16x32_bf16 v[8:11], v[224:227], v[220:223], v[8:11]
	v_mfma_f32_16x16x32_bf16 v[4:7], v[228:231], v[220:223], v[4:7]
	v_mfma_f32_16x16x32_bf16 v[0:3], v[232:235], v[220:223], v[0:3]
	v_mfma_f32_16x16x32_bf16 v[116:119], v[236:239], v[220:223], v[116:119]
	v_lshrrev_b32_e32 v224, 4, v188
	v_and_b32_e32 v225, 7, v188
	v_bitop3_b32 v226, v224, v225, 3 bitop3:0x6c
	v_lshlrev_b32_e32 v227, 7, v188
	v_bfe_u32 v228, v188, 4, 2
	v_and_b32_e32 v229, 0xffffc780, v227
	v_and_b32_e32 v227, 0x2780, v227
	v_bitop3_b32 v228, v228, v225, 4 bitop3:0x36
	v_lshlrev_b32_e32 v226, 4, v226
	v_lshlrev_b32_e32 v228, 4, v228
	v_or_b32_e32 v185, v229, v226
	v_or_b32_e32 v184, v227, v226
	v_or_b32_e32 v183, v229, v228
	v_or_b32_e32 v182, v227, v228
	s_waitcnt vmcnt(0)
	s_setprio 1
	s_barrier
	s_waitcnt vmcnt(11)
	ds_write_b128 v176, v[160:163]
	s_waitcnt vmcnt(10)
	ds_write_b128 v176, v[152:155] offset:4096
	s_waitcnt vmcnt(9)
	ds_write_b128 v176, v[148:151] offset:8192
	s_waitcnt vmcnt(8)
	ds_write_b128 v176, v[128:131] offset:12288
	s_waitcnt vmcnt(7)
	ds_write_b128 v176, v[124:127] offset:16384
	s_waitcnt vmcnt(6)
	ds_write_b128 v176, v[104:107] offset:20480
	s_waitcnt vmcnt(5)
	ds_write_b128 v176, v[100:103] offset:24576
	s_waitcnt vmcnt(4)
	ds_write_b128 v176, v[84:87] offset:28672
	s_waitcnt vmcnt(3)
	ds_write_b128 v176, v[140:143] offset:32768
	s_waitcnt vmcnt(2)
	ds_write_b128 v176, v[76:79] offset:36864
	s_waitcnt vmcnt(1)
	ds_write_b128 v176, v[64:67] offset:40960
	s_waitcnt vmcnt(0)
	ds_write_b128 v176, v[56:59] offset:45056
	s_waitcnt lgkmcnt(0)
	s_barrier
	ds_read_b128 v[56:59], v185
	ds_read_b128 v[64:67], v185 offset:2048
	ds_read_b128 v[76:79], v185 offset:4096
	ds_read_b128 v[84:87], v185 offset:6144
	ds_read_b128 v[100:103], v185 offset:8192
	ds_read_b128 v[104:107], v185 offset:10240
	ds_read_b128 v[124:127], v185 offset:12288
	ds_read_b128 v[128:131], v185 offset:14336
	ds_read_b128 v[140:143], v184 offset:32768
	ds_read_b128 v[148:151], v184 offset:34816
	ds_read_b128 v[152:155], v184 offset:36864
	ds_read_b128 v[160:163], v184 offset:38912
	s_waitcnt lgkmcnt(3)
	v_mfma_f32_16x16x32_bf16 v[172:175], v[140:143], v[56:59], v[172:175]
	s_waitcnt lgkmcnt(2)
	v_mfma_f32_16x16x32_bf16 v[168:171], v[148:151], v[56:59], v[168:171]
	s_waitcnt lgkmcnt(1)
	v_mfma_f32_16x16x32_bf16 v[164:167], v[152:155], v[56:59], v[164:167]
	s_waitcnt lgkmcnt(0)
	v_mfma_f32_16x16x32_bf16 v[56:59], v[160:163], v[56:59], v[156:159]
	v_mfma_f32_16x16x32_bf16 v[144:147], v[140:143], v[64:67], v[144:147]
	v_mfma_f32_16x16x32_bf16 v[136:139], v[148:151], v[64:67], v[136:139]
	v_mfma_f32_16x16x32_bf16 v[132:135], v[152:155], v[64:67], v[132:135]
	v_mfma_f32_16x16x32_bf16 v[64:67], v[160:163], v[64:67], v[120:123]
	v_mfma_f32_16x16x32_bf16 v[156:159], v[140:143], v[76:79], v[112:115]
	v_mfma_f32_16x16x32_bf16 v[178:181], v[148:151], v[76:79], v[108:111]
	v_mfma_f32_16x16x32_bf16 v[184:187], v[152:155], v[76:79], v[96:99]
	v_mfma_f32_16x16x32_bf16 v[76:79], v[160:163], v[76:79], v[92:95]
	v_mfma_f32_16x16x32_bf16 v[60:63], v[140:143], v[100:103], v[60:63]
	v_mfma_f32_16x16x32_bf16 v[52:55], v[148:151], v[100:103], v[52:55]
	v_mfma_f32_16x16x32_bf16 v[48:51], v[152:155], v[100:103], v[48:51]
	v_mfma_f32_16x16x32_bf16 v[44:47], v[160:163], v[100:103], v[44:47]
	v_mfma_f32_16x16x32_bf16 v[40:43], v[140:143], v[104:107], v[40:43]
	v_mfma_f32_16x16x32_bf16 v[36:39], v[148:151], v[104:107], v[36:39]
	v_mfma_f32_16x16x32_bf16 v[32:35], v[152:155], v[104:107], v[32:35]
	v_mfma_f32_16x16x32_bf16 v[28:31], v[160:163], v[104:107], v[28:31]
	v_mfma_f32_16x16x32_bf16 v[24:27], v[140:143], v[124:127], v[24:27]
	v_mfma_f32_16x16x32_bf16 v[20:23], v[148:151], v[124:127], v[20:23]
	v_mfma_f32_16x16x32_bf16 v[16:19], v[152:155], v[124:127], v[16:19]
	v_mfma_f32_16x16x32_bf16 v[12:15], v[160:163], v[124:127], v[12:15]
	v_mfma_f32_16x16x32_bf16 v[8:11], v[140:143], v[128:131], v[8:11]
	v_mfma_f32_16x16x32_bf16 v[4:7], v[148:151], v[128:131], v[4:7]
	v_mfma_f32_16x16x32_bf16 v[0:3], v[152:155], v[128:131], v[0:3]
	v_mfma_f32_16x16x32_bf16 v[190:193], v[140:143], v[84:87], v[88:91]
	v_mfma_f32_16x16x32_bf16 v[194:197], v[148:151], v[84:87], v[80:83]
	v_mfma_f32_16x16x32_bf16 v[198:201], v[152:155], v[84:87], v[72:75]
	v_mfma_f32_16x16x32_bf16 v[204:207], v[160:163], v[84:87], v[68:71]
	v_mfma_f32_16x16x32_bf16 v[140:143], v[160:163], v[128:131], v[116:119]
	s_nop 1
	ds_read_b128 v[68:71], v183
	ds_read_b128 v[72:75], v183 offset:2048
	ds_read_b128 v[80:83], v183 offset:4096
	ds_read_b128 v[128:131], v183 offset:6144
	ds_read_b128 v[148:151], v183 offset:8192
	ds_read_b128 v[152:155], v183 offset:10240
	ds_read_b128 v[160:163], v183 offset:12288
	ds_read_b128 v[208:211], v183 offset:14336
	ds_read_b128 v[212:215], v182 offset:32768
	ds_read_b128 v[216:219], v182 offset:34816
	ds_read_b128 v[220:223], v182 offset:36864
	ds_read_b128 v[224:227], v182 offset:38912
	s_waitcnt lgkmcnt(3)
	v_mfma_f32_16x16x32_bf16 v[124:127], v[212:215], v[68:71], v[172:175]
	s_movk_i32 s30, 0x6c0
	s_waitcnt lgkmcnt(2)
	v_mfma_f32_16x16x32_bf16 v[120:123], v[216:219], v[68:71], v[168:171]
	s_waitcnt lgkmcnt(1)
	v_mfma_f32_16x16x32_bf16 v[116:119], v[220:223], v[68:71], v[164:167]
	s_waitcnt lgkmcnt(0)
	v_mfma_f32_16x16x32_bf16 v[112:115], v[224:227], v[68:71], v[56:59]
	v_mfma_f32_16x16x32_bf16 v[108:111], v[212:215], v[72:75], v[144:147]
	v_mfma_f32_16x16x32_bf16 v[104:107], v[216:219], v[72:75], v[136:139]
	v_mfma_f32_16x16x32_bf16 v[100:103], v[220:223], v[72:75], v[132:135]
	v_mfma_f32_16x16x32_bf16 v[96:99], v[224:227], v[72:75], v[64:67]
	v_mfma_f32_16x16x32_bf16 v[92:95], v[212:215], v[80:83], v[156:159]
	v_mfma_f32_16x16x32_bf16 v[88:91], v[216:219], v[80:83], v[178:181]
	v_mfma_f32_16x16x32_bf16 v[84:87], v[220:223], v[80:83], v[184:187]
	v_mfma_f32_16x16x32_bf16 v[80:83], v[224:227], v[80:83], v[76:79]
	v_mfma_f32_16x16x32_bf16 v[76:79], v[212:215], v[128:131], v[190:193]
	v_mfma_f32_16x16x32_bf16 v[72:75], v[216:219], v[128:131], v[194:197]
	v_mfma_f32_16x16x32_bf16 v[68:71], v[220:223], v[128:131], v[198:201]
	v_mfma_f32_16x16x32_bf16 v[64:67], v[224:227], v[128:131], v[204:207]
	v_mov_b32_e32 v128, v188
	v_mov_b32_e32 v129, v188
	v_mfma_f32_16x16x32_bf16 v[60:63], v[212:215], v[148:151], v[60:63]
	s_nop 0
	v_and_or_b32 v134, v129, 64, s41
	v_mfma_f32_16x16x32_bf16 v[56:59], v[216:219], v[148:151], v[52:55]
	v_cmp_gt_i32_e32 vcc, s30, v134
	v_mfma_f32_16x16x32_bf16 v[52:55], v[220:223], v[148:151], v[48:51]
	v_mfma_f32_16x16x32_bf16 v[48:51], v[224:227], v[148:151], v[44:47]
	v_mfma_f32_16x16x32_bf16 v[44:47], v[212:215], v[152:155], v[40:43]
	v_mfma_f32_16x16x32_bf16 v[40:43], v[216:219], v[152:155], v[36:39]
	v_mfma_f32_16x16x32_bf16 v[36:39], v[220:223], v[152:155], v[32:35]
	v_mfma_f32_16x16x32_bf16 v[32:35], v[224:227], v[152:155], v[28:31]
	v_mfma_f32_16x16x32_bf16 v[28:31], v[212:215], v[160:163], v[24:27]
	v_mfma_f32_16x16x32_bf16 v[24:27], v[216:219], v[160:163], v[20:23]
	v_mfma_f32_16x16x32_bf16 v[20:23], v[220:223], v[160:163], v[16:19]
	v_mfma_f32_16x16x32_bf16 v[16:19], v[224:227], v[160:163], v[12:15]
	v_mfma_f32_16x16x32_bf16 v[12:15], v[212:215], v[208:211], v[8:11]
	v_mfma_f32_16x16x32_bf16 v[8:11], v[216:219], v[208:211], v[4:7]
	v_mfma_f32_16x16x32_bf16 v[4:7], v[220:223], v[208:211], v[0:3]
	v_mfma_f32_16x16x32_bf16 v[0:3], v[224:227], v[208:211], v[140:143]
	s_and_saveexec_b64 s[92:93], vcc
	s_cbranch_execz .LBB0_485
	v_and_b32_e32 v130, 0xffffff80, v129
	v_add_u32_e32 v183, s40, v130
	s_movk_i32 s30, 0xfff
	v_cmp_lt_i32_e64 s[48:49], s30, v183
	s_movk_i32 s30, 0x1000
	v_cmp_gt_i32_e64 s[44:45], s30, v183
	v_add_u32_e32 v130, 0xfffff000, v183
	v_bfe_u32 v141, v128, 4, 2
	s_movk_i32 s30, 0x27f
	v_ashrrev_i32_e32 v135, 10, v130
	v_ashrrev_i32_e32 v132, 8, v183
	v_cmp_lt_i32_e64 s[52:53], s30, v134
	s_movk_i32 s30, 0x280
	v_lshlrev_b32_e32 v130, 4, v141
	v_mov_b32_e32 v131, v177
	v_and_b32_e32 v140, 0x80, v129
	v_cmp_ne_u32_e64 s[50:51], s30, v134
	v_lshl_add_u64 v[138:139], s[84:85], 0, v[130:131]
	v_lshl_add_u64 v[136:137], s[82:83], 0, v[130:131]
	v_lshlrev_b32_e32 v130, 9, v132
	v_readlane_b32 s30, v255, 49
	v_and_b32_e32 v182, 15, v128
	v_and_b32_e32 v181, 0x380, v183
	v_or3_b32 v178, v130, s30, v140
	v_lshlrev_b32_e32 v130, 3, v132
	v_ashrrev_i32_e32 v131, 31, v130
	v_lshlrev_b64 v[132:133], 8, v[130:131]
	v_lshlrev_b32_e32 v130, 3, v135
	s_movk_i32 s30, 0x500
	v_bfe_u32 v129, v128, 4, 1
	v_lshrrev_b32_e32 v128, 2, v128
	v_mad_i64_i32 v[130:131], s[30:31], v130, s30, 0
	v_mov_b32_e32 v176, v134
	v_cmp_eq_u32_e64 s[40:41], 0, v129
	v_lshlrev_b32_e32 v180, 4, v129
	v_and_b32_e32 v179, 8, v128
	v_lshlrev_b32_e32 v128, 2, v141
	v_mov_b32_e32 v129, v177
	v_or_b32_e32 v132, v132, v140
	v_or_b32_e32 v130, v130, v181
	v_cmp_lt_i32_e64 s[46:47], s97, v134
	v_cmp_eq_u32_e64 s[42:43], 0, v141
	v_or_b32_e32 v140, v183, v182
	s_and_saveexec_b64 s[30:31], s[52:53]
	s_xor_b64 s[94:95], exec, s[30:31]
	s_cbranch_execz .LBB0_513
	s_and_saveexec_b64 s[30:31], s[50:51]
	s_xor_b64 s[30:31], exec, s[30:31]
	s_cbranch_execz .LBB0_492
	v_mul_f32_e32 v142, 0xbfb8aa3b, v124
	v_mul_f32_e32 v144, 0xbfb8aa3b, v120
	v_mul_f32_e32 v145, 0xbfb8aa3b, v125
	v_exp_f32_e32 v142, v142
	v_exp_f32_e32 v144, v144
	v_exp_f32_e32 v145, v145
	v_mul_f32_e32 v146, 0xbfb8aa3b, v121
	v_add_f32_e32 v142, 1.0, v142
	v_add_f32_e32 v144, 1.0, v144
	v_add_f32_e32 v145, 1.0, v145
	v_rcp_f32_e32 v142, v142
	v_rcp_f32_e32 v144, v144
	v_rcp_f32_e32 v145, v145
	v_exp_f32_e32 v146, v146
	v_mul_f32_e32 v142, v124, v142
	v_mul_f32_e32 v144, v120, v144
	v_mul_f32_e32 v145, v125, v145
	v_add_f32_e32 v120, 1.0, v146
	v_mul_f32_e32 v124, 0xbfb8aa3b, v126
	v_mul_f32_e32 v125, 0xbfb8aa3b, v122
	v_rcp_f32_e32 v120, v120
	v_exp_f32_e32 v124, v124
	v_exp_f32_e32 v125, v125
	v_ashrrev_i32_e32 v141, 31, v140
	v_mul_f32_e32 v146, v121, v120
	v_add_f32_e32 v120, 1.0, v124
	v_add_f32_e32 v121, 1.0, v125
	v_mul_f32_e32 v124, 0xbfb8aa3b, v127
	v_mul_f32_e32 v125, 0xbfb8aa3b, v123
	v_exp_f32_e32 v124, v124
	v_exp_f32_e32 v125, v125
	v_rcp_f32_e32 v120, v120
	v_rcp_f32_e32 v121, v121
	v_add_f32_e32 v124, 1.0, v124
	v_add_f32_e32 v125, 1.0, v125
	v_rcp_f32_e32 v124, v124
	v_rcp_f32_e32 v125, v125
	v_lshlrev_b64 v[140:141], 11, v[140:141]
	v_cmp_lt_i32_e32 vcc, v189, v202
	v_mul_f32_e32 v126, v126, v120
	v_mul_f32_e32 v122, v122, v121
	v_cndmask_b32_e32 v143, v203, v189, vcc
	v_mul_f32_e32 v127, v127, v124
	v_mul_f32_e32 v123, v123, v125
	v_lshl_add_u64 v[120:121], s[34:35], 0, v[140:141]
	v_lshlrev_b32_e32 v143, 2, v143
	v_lshl_add_u64 v[124:125], v[176:177], 1, v[120:121]
	s_nop 0
	s_nop 0
	s_nop 0
	s_nop 0
	s_nop 0
	s_nop 0
	s_nop 0
	s_nop 0
	s_mov_b32 s58, 0x96ff000
	s_waitcnt lgkmcnt(0)
	s_nop 0
	s_nop 1
	v_permlane16_swap_b32_e32 v142, v144
	s_waitcnt lgkmcnt(0)
	s_nop 0
	v_mov_b32_e32 v120, v145
	v_mov_b32_e32 v145, v146
	s_nop 1
	v_permlane16_swap_b32_e32 v120, v145
	s_waitcnt lgkmcnt(0)
	s_nop 0
	v_mov_b32_e32 v121, v126
	v_mov_b32_e32 v126, v122
	s_nop 1
	v_permlane16_swap_b32_e32 v121, v126
	s_waitcnt lgkmcnt(0)
	s_nop 0
	v_mov_b32_e32 v122, v127
	s_nop 1
	v_permlane16_swap_b32_e32 v122, v123
	v_cvt_pk_bf16_f32 v123, v126, v123
	v_lshlrev_b32_e32 v126, 1, v180
	v_mov_b32_e32 v127, v177
	v_lshlrev_b32_e32 v140, 1, v179
	v_mov_b32_e32 v141, v177
	v_lshl_add_u64 v[124:125], v[124:125], 0, v[126:127]
	v_lshl_add_u64 v[124:125], v[124:125], 0, v[140:141]
	v_add_co_u32_e32 v124, vcc, s58, v124
	v_cvt_pk_bf16_f32 v120, v142, v120
	v_cvt_pk_bf16_f32 v121, v121, v122
	v_cvt_pk_bf16_f32 v122, v144, v145
	v_addc_co_u32_e32 v125, vcc, 0, v125, vcc
	v_mul_f32_e32 v126, 0xbfb8aa3b, v116
	global_store_dwordx4 v[124:125], v[120:123], off offset:2688
	v_exp_f32_e32 v126, v126
	s_nop 0
	v_mul_f32_e32 v121, 0xbfb8aa3b, v112
	v_mul_f32_e32 v122, 0xbfb8aa3b, v117
	v_exp_f32_e32 v121, v121
	v_exp_f32_e32 v122, v122
	v_add_f32_e32 v120, 1.0, v126
	v_mul_f32_e32 v123, 0xbfb8aa3b, v113
	v_add_f32_e32 v121, 1.0, v121
	v_add_f32_e32 v122, 1.0, v122
	v_rcp_f32_e32 v120, v120
	v_rcp_f32_e32 v121, v121
	v_rcp_f32_e32 v122, v122
	v_exp_f32_e32 v123, v123
	v_mul_f32_e32 v116, v116, v120
	v_mul_f32_e32 v112, v112, v121
	v_mul_f32_e32 v117, v117, v122
	v_add_f32_e32 v120, 1.0, v123
	v_mul_f32_e32 v121, 0xbfb8aa3b, v118
	v_mul_f32_e32 v122, 0xbfb8aa3b, v114
	v_rcp_f32_e32 v120, v120
	v_exp_f32_e32 v121, v121
	v_exp_f32_e32 v122, v122
	v_mul_f32_e32 v123, 0xbfb8aa3b, v115
	v_mul_f32_e32 v113, v113, v120
	v_add_f32_e32 v120, 1.0, v121
	v_add_f32_e32 v121, 1.0, v122
	v_mul_f32_e32 v122, 0xbfb8aa3b, v119
	v_exp_f32_e32 v122, v122
	v_exp_f32_e32 v123, v123
	v_rcp_f32_e32 v120, v120
	v_rcp_f32_e32 v121, v121
	v_add_f32_e32 v122, 1.0, v122
	v_add_f32_e32 v123, 1.0, v123
	v_rcp_f32_e32 v122, v122
	v_rcp_f32_e32 v123, v123
	v_mul_f32_e32 v118, v118, v120
	v_mul_f32_e32 v114, v114, v121
	v_mul_f32_e32 v119, v119, v122
	v_mul_f32_e32 v115, v115, v123
	s_nop 0
	s_nop 0
	s_nop 0
	s_nop 0
	s_nop 0
	s_nop 0
	s_nop 0
	s_nop 0
	s_waitcnt lgkmcnt(0)
	s_nop 0
	v_mov_b32_e32 v120, v112
	s_nop 1
	v_permlane16_swap_b32_e32 v116, v120
	s_waitcnt lgkmcnt(0)
	s_nop 0
	v_mov_b32_e32 v112, v117
	v_mov_b32_e32 v117, v113
	s_nop 1
	v_permlane16_swap_b32_e32 v112, v117
	s_waitcnt lgkmcnt(0)
	s_nop 0
	v_mov_b32_e32 v113, v118
	v_mov_b32_e32 v118, v114
	s_nop 1
	v_permlane16_swap_b32_e32 v113, v118
	s_waitcnt lgkmcnt(0)
	s_nop 0
	v_mov_b32_e32 v114, v119
	s_nop 1
	v_permlane16_swap_b32_e32 v114, v115
	v_cvt_pk_bf16_f32 v112, v116, v112
	v_cvt_pk_bf16_f32 v113, v113, v114
	v_cvt_pk_bf16_f32 v114, v120, v117
	v_cvt_pk_bf16_f32 v115, v118, v115
	global_store_dwordx4 v[124:125], v[112:115], off offset:2752

.LBB0_801:
	s_waitcnt lgkmcnt(0)
	s_ashr_i32 s6, s8, 3
	s_lshl_b32 s9, s6, 1
	s_and_b32 s7, s6, -16
	s_and_b32 s9, s9, 14
	s_or_b32 s7, s9, s7
	s_bfe_u32 s9, s6, 0x10003
	s_or_b32 s7, s7, s9
	s_cmp_lt_i32 s6, 0
	s_cselect_b32 s6, s7, s6
	s_lshl_b32 s7, s8, 5
	s_and_b32 s7, s7, 0xe0
	s_add_i32 s6, s6, s7
	s_ashr_i32 s7, s6, 31
	s_lshr_b32 s7, s7, 27
	s_add_i32 s7, s6, s7
	s_and_b32 s9, s7, 0xffffffe0
	s_sub_i32 s6, s6, s9
	s_ashr_i32 s9, s6, 31
	s_lshr_b32 s9, s9, 29
	s_add_i32 s9, s6, s9
	s_ashr_i32 s10, s9, 3
	s_lshl_b32 s7, s7, 5
	s_and_b32 s7, s7, 0xfffffc00
	s_lshl_b32 s9, s10, 8
	s_add_i32 s9, s9, s7
	s_lshl_b32 s7, s10, 10
	s_lshl_b32 s6, s6, 7
	v_mov_b32_e32 v6, v188
	s_sub_i32 s10, s6, s7
	s_mov_b32 s11, 0x30000
	v_ashrrev_i32_e32 v7, 3, v6
	v_lshlrev_b32_e32 v4, 4, v6
	v_and_b32_e32 v176, 0x70, v4
	v_add_u32_e32 v4, s10, v7
	v_ashrrev_i32_e32 v5, 31, v4
	v_add_u32_e32 v0, s9, v7
	v_lshlrev_b64 v[4:5], 11, v[4:5]
	v_ashrrev_i32_e32 v1, 31, v0
	v_lshl_add_u64 v[4:5], s[2:3], 0, v[4:5]
	v_xor_b32_e32 v8, v7, v6
	v_lshlrev_b64 v[0:1], 11, v[0:1]
	v_lshl_add_u64 v[178:179], v[4:5], 0, v[176:177]
	v_lshlrev_b32_e32 v4, 4, v8
	v_lshl_add_u64 v[2:3], s[0:1], 0, v[0:1]
	v_and_b32_e32 v4, 0x70, v4
	v_lshl_add_u64 v[2:3], v[2:3], 0, v[176:177]
	v_lshl_or_b32 v176, v7, 7, v4
	v_lshrrev_b32_e32 v4, 4, v6
	v_and_b32_e32 v15, 7, v6
	v_bitop3_b32 v20, v4, v15, 3 bitop3:0x6c
	v_add_co_u32_e32 v4, vcc, s11, v178
	v_lshlrev_b32_e32 v12, 7, v6
	s_nop 0
	v_addc_co_u32_e32 v5, vcc, 0, v179, vcc
	v_bfe_u32 v14, v6, 4, 2
	v_add_co_u32_e32 v6, vcc, s12, v178
	s_mov_b32 s6, 0x70000
	s_nop 0
	v_addc_co_u32_e32 v7, vcc, 0, v179, vcc
	global_load_dwordx4 v[8:11], v[4:5], off
	global_load_dwordx4 v[16:19], v[6:7], off
	v_add_co_u32_e32 v4, vcc, s13, v178
	v_and_b32_e32 v13, 0xffffc780, v12
	s_nop 0
	v_addc_co_u32_e32 v5, vcc, 0, v179, vcc
	v_add_co_u32_e32 v6, vcc, s6, v2
	s_mov_b32 s6, 0x60000
	s_nop 0
	v_addc_co_u32_e32 v7, vcc, 0, v3, vcc
	global_load_dwordx4 v[32:35], v[4:5], off
	global_load_dwordx4 v[40:43], v[6:7], off
	v_add_co_u32_e32 v4, vcc, s6, v2
	s_mov_b32 s6, 0x50000
	s_nop 0
	v_addc_co_u32_e32 v5, vcc, 0, v3, vcc
	v_add_co_u32_e32 v6, vcc, s6, v2
	v_and_b32_e32 v12, 0x2780, v12
	s_nop 0
	v_addc_co_u32_e32 v7, vcc, 0, v3, vcc
	global_load_dwordx4 v[60:63], v[4:5], off
	global_load_dwordx4 v[68:71], v[6:7], off
	v_add_co_u32_e32 v4, vcc, 0x40000, v2
	v_bitop3_b32 v14, v14, v15, 4 bitop3:0x36
	s_nop 0
	v_addc_co_u32_e32 v5, vcc, 0, v3, vcc
	v_add_co_u32_e32 v6, vcc, s11, v2
	v_lshl_or_b32 v0, v15, 4, v0
	s_nop 0
	v_addc_co_u32_e32 v7, vcc, 0, v3, vcc
	global_load_dwordx4 v[80:83], v[4:5], off
	global_load_dwordx4 v[88:91], v[6:7], off
	v_add_co_u32_e32 v4, vcc, s12, v2
	v_mov_b32_e32 v140, 0
	s_nop 0
	v_addc_co_u32_e32 v5, vcc, 0, v3, vcc
	v_add_co_u32_e32 v6, vcc, 0x10000, v2
	v_lshl_add_u64 v[180:181], s[34:35], 0, v[0:1]
	s_nop 0
	v_addc_co_u32_e32 v7, vcc, 0, v3, vcc
	global_load_dwordx4 v[104:107], v[4:5], off
	global_load_dwordx4 v[112:115], v[6:7], off
	global_load_dwordx4 v[56:59], v[178:179], off
	global_load_dwordx4 v[116:119], v[2:3], off
	v_lshlrev_b32_e32 v2, 4, v20
	v_or_b32_e32 v185, v13, v2
	v_or_b32_e32 v184, v12, v2
	v_lshlrev_b32_e32 v2, 4, v14
	v_or_b32_e32 v183, v13, v2
	v_or_b32_e32 v182, v12, v2
	s_mov_b64 s[6:7], 0
	v_mov_b32_e32 v141, v140
	v_mov_b32_e32 v142, v140
	v_mov_b32_e32 v143, v140
	v_mov_b32_e32 v0, v140
	v_mov_b32_e32 v1, v140
	v_mov_b32_e32 v2, v140
	v_mov_b32_e32 v3, v140
	v_mov_b32_e32 v4, v140
	v_mov_b32_e32 v5, v140
	v_mov_b32_e32 v6, v140
	v_mov_b32_e32 v7, v140
	v_mov_b32_e32 v12, v140
	v_mov_b32_e32 v13, v140
	v_mov_b32_e32 v14, v140
	v_mov_b32_e32 v15, v140
	v_mov_b32_e32 v20, v140
	v_mov_b32_e32 v21, v140
	v_mov_b32_e32 v22, v140
	v_mov_b32_e32 v23, v140
	v_mov_b32_e32 v24, v140
	v_mov_b32_e32 v25, v140
	v_mov_b32_e32 v26, v140
	v_mov_b32_e32 v27, v140
	v_mov_b32_e32 v28, v140
	v_mov_b32_e32 v29, v140
	v_mov_b32_e32 v30, v140
	v_mov_b32_e32 v31, v140
	v_mov_b32_e32 v36, v140
	v_mov_b32_e32 v37, v140
	v_mov_b32_e32 v38, v140
	v_mov_b32_e32 v39, v140
	v_mov_b32_e32 v44, v140
	v_mov_b32_e32 v45, v140
	v_mov_b32_e32 v46, v140
	v_mov_b32_e32 v47, v140
	v_mov_b32_e32 v48, v140
	v_mov_b32_e32 v49, v140
	v_mov_b32_e32 v50, v140
	v_mov_b32_e32 v51, v140
	v_mov_b32_e32 v52, v140
	v_mov_b32_e32 v53, v140
	v_mov_b32_e32 v54, v140
	v_mov_b32_e32 v55, v140
	v_mov_b32_e32 v64, v140
	v_mov_b32_e32 v65, v140
	v_mov_b32_e32 v66, v140
	v_mov_b32_e32 v67, v140
	v_mov_b32_e32 v72, v140
	v_mov_b32_e32 v73, v140
	v_mov_b32_e32 v74, v140
	v_mov_b32_e32 v75, v140
	v_mov_b32_e32 v76, v140
	v_mov_b32_e32 v77, v140
	v_mov_b32_e32 v78, v140
	v_mov_b32_e32 v79, v140
	v_mov_b32_e32 v84, v140
	v_mov_b32_e32 v85, v140
	v_mov_b32_e32 v86, v140
	v_mov_b32_e32 v87, v140
	v_mov_b32_e32 v92, v140
	v_mov_b32_e32 v93, v140
	v_mov_b32_e32 v94, v140
	v_mov_b32_e32 v95, v140
	v_mov_b32_e32 v96, v140
	v_mov_b32_e32 v97, v140
	v_mov_b32_e32 v98, v140
	v_mov_b32_e32 v99, v140
	v_mov_b32_e32 v100, v140
	v_mov_b32_e32 v101, v140
	v_mov_b32_e32 v102, v140
	v_mov_b32_e32 v103, v140
	v_mov_b32_e32 v108, v140
	v_mov_b32_e32 v109, v140
	v_mov_b32_e32 v110, v140
	v_mov_b32_e32 v111, v140
	v_mov_b32_e32 v120, v140
	v_mov_b32_e32 v121, v140
	v_mov_b32_e32 v122, v140
	v_mov_b32_e32 v123, v140
	v_mov_b32_e32 v124, v140
	v_mov_b32_e32 v125, v140
	v_mov_b32_e32 v126, v140
	v_mov_b32_e32 v127, v140
	v_mov_b32_e32 v128, v140
	v_mov_b32_e32 v129, v140
	v_mov_b32_e32 v130, v140
	v_mov_b32_e32 v131, v140
	v_mov_b32_e32 v132, v140
	v_mov_b32_e32 v133, v140
	v_mov_b32_e32 v134, v140
	v_mov_b32_e32 v135, v140
	v_mov_b32_e32 v136, v140
	v_mov_b32_e32 v137, v140
	v_mov_b32_e32 v138, v140
	v_mov_b32_e32 v139, v140
	v_mov_b32_e32 v144, v140
	v_mov_b32_e32 v145, v140
	v_mov_b32_e32 v146, v140
	v_mov_b32_e32 v147, v140
	v_mov_b32_e32 v148, v140
	v_mov_b32_e32 v149, v140
	v_mov_b32_e32 v150, v140
	v_mov_b32_e32 v151, v140
	v_mov_b32_e32 v152, v140
	v_mov_b32_e32 v153, v140
	v_mov_b32_e32 v154, v140
	v_mov_b32_e32 v155, v140
	v_mov_b32_e32 v156, v140
	v_mov_b32_e32 v157, v140
	v_mov_b32_e32 v158, v140
	v_mov_b32_e32 v159, v140
	v_mov_b32_e32 v160, v140
	v_mov_b32_e32 v161, v140
	v_mov_b32_e32 v162, v140
	v_mov_b32_e32 v163, v140
	v_mov_b32_e32 v164, v140
	v_mov_b32_e32 v165, v140
	v_mov_b32_e32 v166, v140
	v_mov_b32_e32 v167, v140
	v_mov_b32_e32 v168, v140
	v_mov_b32_e32 v169, v140
	v_mov_b32_e32 v170, v140
	v_mov_b32_e32 v171, v140
	v_mov_b32_e32 v172, v140
	v_mov_b32_e32 v173, v140
	v_mov_b32_e32 v174, v140
	v_mov_b32_e32 v175, v140
	v_readlane_b32 vcc_lo, v253, 0
	s_cmpk_lt_u32 vcc_lo, 0x100
	s_cbranch_scc1 .Lprio_hi6
	s_setprio 2
	s_branch .Lprio_done6

.Lprio_done6:
	v_readlane_b32 s98, v253, 3
	v_readlane_b32 s99, v253, 4
	v_and_b32_e32 v224, 15, v188
	v_bfe_u32 v225, v188, 4, 2
	v_lshrrev_b32_e32 v226, 2, v224
	v_sub_u32_e32 v226, 0, v226
	v_and_b32_e32 v226, 3, v226
	v_xor_b32_e32 v225, v225, v226
	v_lshlrev_b32_e32 v225, 4, v225
	v_lshl_or_b32 v225, v224, 6, v225
	v_bfe_u32 v226, v188, 7, 1
	v_lshl_or_b32 v185, v226, 13, v225
	v_bfe_u32 v226, v188, 6, 1
	v_lshl_or_b32 v184, v226, 12, v225
	v_add_u32_e32 v184, 0x4000, v184
	v_lshrrev_b32_e32 v224, 3, v188
	v_bfe_u32 v225, v188, 2, 1
	v_lshrrev_b32_e32 v226, 2, v224
	v_sub_u32_e32 v226, 0, v226
	v_and_b32_e32 v226, 3, v226
	v_and_b32_e32 v227, 3, v188
	v_xor_b32_e32 v226, v227, v226
	v_lshlrev_b32_e32 v226, 4, v226
	v_xor_b32_e32 v224, v224, v225
	v_lshl_or_b32 v226, v224, 6, v226
	v_mul_u32_u24_e32 v225, 0x6000, v225
	v_add_u32_e32 v183, v225, v226
	s_mov_b32 m0, 0
	s_sub_u32 vcc_lo, s6, s98
	v_add_u32_e32 v186, vcc_lo, v178
	v_add_u32_e32 v187, vcc_lo, v180
	s_barrier
	s_waitcnt vmcnt(0)
	ds_write_b128 v183, v[116:119]
	ds_write_b128 v183, v[112:115] offset:2048
	ds_write_b128 v183, v[104:107] offset:4096
	ds_write_b128 v183, v[88:91] offset:6144
	ds_write_b128 v183, v[80:83] offset:8192
	ds_write_b128 v183, v[68:71] offset:10240
	ds_write_b128 v183, v[60:63] offset:12288
	ds_write_b128 v183, v[40:43] offset:14336
	ds_write_b128 v183, v[56:59] offset:16384
	ds_write_b128 v183, v[32:35] offset:18432
	ds_write_b128 v183, v[16:19] offset:20480
	ds_write_b128 v183, v[8:11] offset:22528
	v_cmp_gt_u32_e32 vcc, 0x6000, v183
	v_add_u32_e32 v182, 0xc000, v183
	v_add_u32_e32 v183, 0xffffa000, v183
	s_nop 0
	v_cndmask_b32_e32 v183, v183, v182, vcc
	v_add_u32_e32 v116, s26, v187
	global_load_dwordx4 v[116:119], v116, s[98:99] offset:128
	v_add_u32_e32 v112, s27, v187
	global_load_dwordx4 v[112:115], v112, s[98:99] offset:128
	v_add_u32_e32 v104, s20, v187
	global_load_dwordx4 v[104:107], v104, s[98:99] offset:128
	v_add_u32_e32 v88, s21, v187
	global_load_dwordx4 v[88:91], v88, s[98:99] offset:128
	v_add_u32_e32 v80, s56, v187
	global_load_dwordx4 v[80:83], v80, s[98:99] offset:128
	v_add_u32_e32 v68, s57, v187
	global_load_dwordx4 v[68:71], v68, s[98:99] offset:128
	v_add_u32_e32 v60, s24, v187
	global_load_dwordx4 v[60:63], v60, s[98:99] offset:128
	v_add_u32_e32 v40, s96, v187
	global_load_dwordx4 v[40:43], v40, s[98:99] offset:128
	v_mov_b32_e32 v56, v186
	global_load_dwordx4 v[56:59], v56, s[98:99] offset:128
	v_add_u32_e32 v32, s13, v186
	global_load_dwordx4 v[32:35], v32, s[98:99] offset:128
	v_add_u32_e32 v16, s12, v186
	global_load_dwordx4 v[16:19], v16, s[98:99] offset:128
	v_add_u32_e32 v8, s11, v186
	global_load_dwordx4 v[8:11], v8, s[98:99] offset:128
	s_add_u32 s6, s6, 0x80
	s_addc_u32 s7, s7, 0
.LBB0_802:
	s_waitcnt lgkmcnt(0)
	s_barrier
	ds_read_b128 v[224:227], v184
	ds_read_b128 v[228:231], v184 offset:1024
	ds_read_b128 v[232:235], v184 offset:2048
	ds_read_b128 v[236:239], v184 offset:3072
	ds_read_b128 v[190:193], v185
	ds_read_b128 v[194:197], v185 offset:1024
	ds_read_b128 v[198:201], v185 offset:2048
	ds_read_b128 v[204:207], v185 offset:3072
	ds_read_b128 v[208:211], v185 offset:4096
	ds_read_b128 v[212:215], v185 offset:5120
	ds_read_b128 v[216:219], v185 offset:6144
	ds_read_b128 v[220:223], v185 offset:7168
	s_movk_i32 vcc_lo, 0x6000
	s_cmp_eq_u32 m0, 2
	s_cselect_b32 vcc_lo, 0xffff4000, vcc_lo
	s_add_u32 m0, m0, 1
	s_cmp_eq_u32 m0, 3
	s_cselect_b32 m0, 0, m0
	v_add_u32_e32 v185, vcc_lo, v185
	v_add_u32_e32 v184, vcc_lo, v184
	v_xor_b32_e32 v185, 64, v185
	v_xor_b32_e32 v184, 64, v184
	s_waitcnt lgkmcnt(7)
	v_mfma_f32_16x16x32_bf16 v[172:175], v[224:227], v[190:193], v[172:175]
	v_mfma_f32_16x16x32_bf16 v[168:171], v[228:231], v[190:193], v[168:171]
	v_mfma_f32_16x16x32_bf16 v[164:167], v[232:235], v[190:193], v[164:167]
	v_mfma_f32_16x16x32_bf16 v[160:163], v[236:239], v[190:193], v[160:163]
	ds_read_b128 v[190:193], v185
	s_waitcnt lgkmcnt(7)
	v_mfma_f32_16x16x32_bf16 v[156:159], v[224:227], v[194:197], v[156:159]
	v_mfma_f32_16x16x32_bf16 v[152:155], v[228:231], v[194:197], v[152:155]
	v_mfma_f32_16x16x32_bf16 v[148:151], v[232:235], v[194:197], v[148:151]
	v_mfma_f32_16x16x32_bf16 v[144:147], v[236:239], v[194:197], v[144:147]
	ds_read_b128 v[194:197], v185 offset:1024
	s_waitcnt lgkmcnt(7)
	v_mfma_f32_16x16x32_bf16 v[136:139], v[224:227], v[198:201], v[136:139]
	v_mfma_f32_16x16x32_bf16 v[132:135], v[228:231], v[198:201], v[132:135]
	v_mfma_f32_16x16x32_bf16 v[128:131], v[232:235], v[198:201], v[128:131]
	v_mfma_f32_16x16x32_bf16 v[124:127], v[236:239], v[198:201], v[124:127]
	ds_read_b128 v[198:201], v185 offset:2048
	s_waitcnt lgkmcnt(7)
	v_mfma_f32_16x16x32_bf16 v[120:123], v[224:227], v[204:207], v[120:123]
	v_mfma_f32_16x16x32_bf16 v[108:111], v[228:231], v[204:207], v[108:111]
	v_mfma_f32_16x16x32_bf16 v[100:103], v[232:235], v[204:207], v[100:103]
	v_mfma_f32_16x16x32_bf16 v[96:99], v[236:239], v[204:207], v[96:99]
	ds_read_b128 v[204:207], v185 offset:3072
	s_waitcnt lgkmcnt(7)
	v_mfma_f32_16x16x32_bf16 v[92:95], v[224:227], v[208:211], v[92:95]
	v_mfma_f32_16x16x32_bf16 v[84:87], v[228:231], v[208:211], v[84:87]
	v_mfma_f32_16x16x32_bf16 v[76:79], v[232:235], v[208:211], v[76:79]
	v_mfma_f32_16x16x32_bf16 v[72:75], v[236:239], v[208:211], v[72:75]
	ds_read_b128 v[208:211], v185 offset:4096
	s_waitcnt lgkmcnt(7)
	v_mfma_f32_16x16x32_bf16 v[64:67], v[224:227], v[212:215], v[64:67]
	v_mfma_f32_16x16x32_bf16 v[52:55], v[228:231], v[212:215], v[52:55]
	v_mfma_f32_16x16x32_bf16 v[48:51], v[232:235], v[212:215], v[48:51]
	v_mfma_f32_16x16x32_bf16 v[44:47], v[236:239], v[212:215], v[44:47]
	ds_read_b128 v[212:215], v185 offset:5120
	s_waitcnt lgkmcnt(7)
	v_mfma_f32_16x16x32_bf16 v[36:39], v[224:227], v[216:219], v[36:39]
	v_mfma_f32_16x16x32_bf16 v[28:31], v[228:231], v[216:219], v[28:31]
	v_mfma_f32_16x16x32_bf16 v[24:27], v[232:235], v[216:219], v[24:27]
	v_mfma_f32_16x16x32_bf16 v[20:23], v[236:239], v[216:219], v[20:23]
	ds_read_b128 v[216:219], v185 offset:6144
	s_waitcnt lgkmcnt(7)
	v_mfma_f32_16x16x32_bf16 v[12:15], v[224:227], v[220:223], v[12:15]
	v_mfma_f32_16x16x32_bf16 v[4:7], v[228:231], v[220:223], v[4:7]
	v_mfma_f32_16x16x32_bf16 v[0:3], v[232:235], v[220:223], v[0:3]
	v_mfma_f32_16x16x32_bf16 v[140:143], v[236:239], v[220:223], v[140:143]
	ds_read_b128 v[220:223], v185 offset:7168
	ds_read_b128 v[224:227], v184
	ds_read_b128 v[228:231], v184 offset:1024
	ds_read_b128 v[232:235], v184 offset:2048
	ds_read_b128 v[236:239], v184 offset:3072
	s_movk_i32 vcc_lo, 0x6000
	s_cmp_eq_u32 m0, 2
	s_cselect_b32 vcc_lo, 0xffff4000, vcc_lo
	s_add_u32 m0, m0, 1
	s_cmp_eq_u32 m0, 3
	s_cselect_b32 m0, 0, m0
	v_add_u32_e32 v185, vcc_lo, v185
	v_add_u32_e32 v184, vcc_lo, v184
	v_xor_b32_e32 v185, 64, v185
	v_xor_b32_e32 v184, 64, v184
	s_sub_u32 vcc_lo, s6, s98
	v_add_u32_e32 v186, vcc_lo, v178
	v_add_u32_e32 v187, vcc_lo, v180
	s_barrier
	s_waitcnt lgkmcnt(0)
	v_mfma_f32_16x16x32_bf16 v[172:175], v[224:227], v[190:193], v[172:175]
	s_waitcnt vmcnt(11)
	v_mfma_f32_16x16x32_bf16 v[168:171], v[228:231], v[190:193], v[168:171]
	ds_write_b128 v183, v[116:119]
	v_add_u32_e32 v116, s26, v187
	v_mfma_f32_16x16x32_bf16 v[164:167], v[232:235], v[190:193], v[164:167]
	global_load_dwordx4 v[116:119], v116, s[98:99] offset:128
	v_mfma_f32_16x16x32_bf16 v[160:163], v[236:239], v[190:193], v[160:163]
	s_waitcnt vmcnt(11)
	ds_write_b128 v183, v[112:115] offset:2048
	v_mfma_f32_16x16x32_bf16 v[156:159], v[224:227], v[194:197], v[156:159]
	v_add_u32_e32 v112, s27, v187
	v_mfma_f32_16x16x32_bf16 v[152:155], v[228:231], v[194:197], v[152:155]
	global_load_dwordx4 v[112:115], v112, s[98:99] offset:128
	s_waitcnt vmcnt(11)
	v_mfma_f32_16x16x32_bf16 v[148:151], v[232:235], v[194:197], v[148:151]
	ds_write_b128 v183, v[104:107] offset:4096
	v_mfma_f32_16x16x32_bf16 v[144:147], v[236:239], v[194:197], v[144:147]
	v_add_u32_e32 v104, s20, v187
	global_load_dwordx4 v[104:107], v104, s[98:99] offset:128
	v_mfma_f32_16x16x32_bf16 v[136:139], v[224:227], v[198:201], v[136:139]
	s_waitcnt vmcnt(11)
	v_mfma_f32_16x16x32_bf16 v[132:135], v[228:231], v[198:201], v[132:135]
	ds_write_b128 v183, v[88:91] offset:6144
	v_add_u32_e32 v88, s21, v187
	v_mfma_f32_16x16x32_bf16 v[128:131], v[232:235], v[198:201], v[128:131]
	global_load_dwordx4 v[88:91], v88, s[98:99] offset:128
	v_mfma_f32_16x16x32_bf16 v[124:127], v[236:239], v[198:201], v[124:127]
	s_waitcnt vmcnt(11)
	ds_write_b128 v183, v[80:83] offset:8192
	v_mfma_f32_16x16x32_bf16 v[120:123], v[224:227], v[204:207], v[120:123]
	v_add_u32_e32 v80, s56, v187
	v_mfma_f32_16x16x32_bf16 v[108:111], v[228:231], v[204:207], v[108:111]
	global_load_dwordx4 v[80:83], v80, s[98:99] offset:128
	s_waitcnt vmcnt(11)
	v_mfma_f32_16x16x32_bf16 v[100:103], v[232:235], v[204:207], v[100:103]
	ds_write_b128 v183, v[68:71] offset:10240
	v_mfma_f32_16x16x32_bf16 v[96:99], v[236:239], v[204:207], v[96:99]
	v_add_u32_e32 v68, s57, v187
	global_load_dwordx4 v[68:71], v68, s[98:99] offset:128
	v_mfma_f32_16x16x32_bf16 v[92:95], v[224:227], v[208:211], v[92:95]
	s_waitcnt vmcnt(11)
	v_mfma_f32_16x16x32_bf16 v[84:87], v[228:231], v[208:211], v[84:87]
	ds_write_b128 v183, v[60:63] offset:12288
	v_add_u32_e32 v60, s24, v187
	v_mfma_f32_16x16x32_bf16 v[76:79], v[232:235], v[208:211], v[76:79]
	global_load_dwordx4 v[60:63], v60, s[98:99] offset:128
	v_mfma_f32_16x16x32_bf16 v[72:75], v[236:239], v[208:211], v[72:75]
	s_waitcnt vmcnt(11)
	ds_write_b128 v183, v[40:43] offset:14336
	v_mfma_f32_16x16x32_bf16 v[64:67], v[224:227], v[212:215], v[64:67]
	v_add_u32_e32 v40, s96, v187
	v_mfma_f32_16x16x32_bf16 v[52:55], v[228:231], v[212:215], v[52:55]
	global_load_dwordx4 v[40:43], v40, s[98:99] offset:128
	s_waitcnt vmcnt(11)
	v_mfma_f32_16x16x32_bf16 v[48:51], v[232:235], v[212:215], v[48:51]
	ds_write_b128 v183, v[56:59] offset:16384
	v_mfma_f32_16x16x32_bf16 v[44:47], v[236:239], v[212:215], v[44:47]
	v_mov_b32_e32 v56, v186
	global_load_dwordx4 v[56:59], v56, s[98:99] offset:128
	v_mfma_f32_16x16x32_bf16 v[36:39], v[224:227], v[216:219], v[36:39]
	s_waitcnt vmcnt(11)
	v_mfma_f32_16x16x32_bf16 v[28:31], v[228:231], v[216:219], v[28:31]
	ds_write_b128 v183, v[32:35] offset:18432
	v_add_u32_e32 v32, s13, v186
	v_mfma_f32_16x16x32_bf16 v[24:27], v[232:235], v[216:219], v[24:27]
	global_load_dwordx4 v[32:35], v32, s[98:99] offset:128
	v_mfma_f32_16x16x32_bf16 v[20:23], v[236:239], v[216:219], v[20:23]
	s_waitcnt vmcnt(11)
	ds_write_b128 v183, v[16:19] offset:20480
	v_mfma_f32_16x16x32_bf16 v[12:15], v[224:227], v[220:223], v[12:15]
	v_add_u32_e32 v16, s12, v186
	v_mfma_f32_16x16x32_bf16 v[4:7], v[228:231], v[220:223], v[4:7]
	global_load_dwordx4 v[16:19], v16, s[98:99] offset:128
	s_waitcnt vmcnt(11)
	v_mfma_f32_16x16x32_bf16 v[0:3], v[232:235], v[220:223], v[0:3]
	ds_write_b128 v183, v[8:11] offset:22528
	v_mfma_f32_16x16x32_bf16 v[140:143], v[236:239], v[220:223], v[140:143]
	v_add_u32_e32 v8, s11, v186
	global_load_dwordx4 v[8:11], v8, s[98:99] offset:128
	v_cmp_gt_u32_e32 vcc, 0x6000, v183
	v_add_u32_e32 v182, 0xc000, v183
	v_add_u32_e32 v183, 0xffffa000, v183
	s_nop 0
	v_cndmask_b32_e32 v183, v183, v182, vcc
	s_add_u32 s6, s6, 0x80
	s_addc_u32 s7, s7, 0
	s_cmpk_lg_i32 s6, 0x780
	s_cbranch_scc1 .LBB0_802
	s_waitcnt lgkmcnt(0)
	s_barrier
	ds_read_b128 v[224:227], v184
	ds_read_b128 v[228:231], v184 offset:1024
	ds_read_b128 v[232:235], v184 offset:2048
	ds_read_b128 v[236:239], v184 offset:3072
	ds_read_b128 v[190:193], v185
	ds_read_b128 v[194:197], v185 offset:1024
	ds_read_b128 v[198:201], v185 offset:2048
	ds_read_b128 v[204:207], v185 offset:3072
	ds_read_b128 v[208:211], v185 offset:4096
	ds_read_b128 v[212:215], v185 offset:5120
	ds_read_b128 v[216:219], v185 offset:6144
	ds_read_b128 v[220:223], v185 offset:7168
	s_movk_i32 vcc_lo, 0x6000
	s_cmp_eq_u32 m0, 2
	s_cselect_b32 vcc_lo, 0xffff4000, vcc_lo
	s_add_u32 m0, m0, 1
	s_cmp_eq_u32 m0, 3
	s_cselect_b32 m0, 0, m0
	v_add_u32_e32 v185, vcc_lo, v185
	v_add_u32_e32 v184, vcc_lo, v184
	v_xor_b32_e32 v185, 64, v185
	v_xor_b32_e32 v184, 64, v184
	s_waitcnt lgkmcnt(7)
	v_mfma_f32_16x16x32_bf16 v[172:175], v[224:227], v[190:193], v[172:175]
	v_mfma_f32_16x16x32_bf16 v[168:171], v[228:231], v[190:193], v[168:171]
	v_mfma_f32_16x16x32_bf16 v[164:167], v[232:235], v[190:193], v[164:167]
	v_mfma_f32_16x16x32_bf16 v[160:163], v[236:239], v[190:193], v[160:163]
	ds_read_b128 v[190:193], v185
	s_waitcnt lgkmcnt(7)
	v_mfma_f32_16x16x32_bf16 v[156:159], v[224:227], v[194:197], v[156:159]
	v_mfma_f32_16x16x32_bf16 v[152:155], v[228:231], v[194:197], v[152:155]
	v_mfma_f32_16x16x32_bf16 v[148:151], v[232:235], v[194:197], v[148:151]
	v_mfma_f32_16x16x32_bf16 v[144:147], v[236:239], v[194:197], v[144:147]
	ds_read_b128 v[194:197], v185 offset:1024
	s_waitcnt lgkmcnt(7)
	v_mfma_f32_16x16x32_bf16 v[136:139], v[224:227], v[198:201], v[136:139]
	v_mfma_f32_16x16x32_bf16 v[132:135], v[228:231], v[198:201], v[132:135]
	v_mfma_f32_16x16x32_bf16 v[128:131], v[232:235], v[198:201], v[128:131]
	v_mfma_f32_16x16x32_bf16 v[124:127], v[236:239], v[198:201], v[124:127]
	ds_read_b128 v[198:201], v185 offset:2048
	s_waitcnt lgkmcnt(7)
	v_mfma_f32_16x16x32_bf16 v[120:123], v[224:227], v[204:207], v[120:123]
	v_mfma_f32_16x16x32_bf16 v[108:111], v[228:231], v[204:207], v[108:111]
	v_mfma_f32_16x16x32_bf16 v[100:103], v[232:235], v[204:207], v[100:103]
	v_mfma_f32_16x16x32_bf16 v[96:99], v[236:239], v[204:207], v[96:99]
	ds_read_b128 v[204:207], v185 offset:3072
	s_waitcnt lgkmcnt(7)
	v_mfma_f32_16x16x32_bf16 v[92:95], v[224:227], v[208:211], v[92:95]
	v_mfma_f32_16x16x32_bf16 v[84:87], v[228:231], v[208:211], v[84:87]
	v_mfma_f32_16x16x32_bf16 v[76:79], v[232:235], v[208:211], v[76:79]
	v_mfma_f32_16x16x32_bf16 v[72:75], v[236:239], v[208:211], v[72:75]
	ds_read_b128 v[208:211], v185 offset:4096
	s_waitcnt lgkmcnt(7)
	v_mfma_f32_16x16x32_bf16 v[64:67], v[224:227], v[212:215], v[64:67]
	v_mfma_f32_16x16x32_bf16 v[52:55], v[228:231], v[212:215], v[52:55]
	v_mfma_f32_16x16x32_bf16 v[48:51], v[232:235], v[212:215], v[48:51]
	v_mfma_f32_16x16x32_bf16 v[44:47], v[236:239], v[212:215], v[44:47]
	ds_read_b128 v[212:215], v185 offset:5120
	s_waitcnt lgkmcnt(7)
	v_mfma_f32_16x16x32_bf16 v[36:39], v[224:227], v[216:219], v[36:39]
	v_mfma_f32_16x16x32_bf16 v[28:31], v[228:231], v[216:219], v[28:31]
	v_mfma_f32_16x16x32_bf16 v[24:27], v[232:235], v[216:219], v[24:27]
	v_mfma_f32_16x16x32_bf16 v[20:23], v[236:239], v[216:219], v[20:23]
	ds_read_b128 v[216:219], v185 offset:6144
	s_waitcnt lgkmcnt(7)
	v_mfma_f32_16x16x32_bf16 v[12:15], v[224:227], v[220:223], v[12:15]
	v_mfma_f32_16x16x32_bf16 v[4:7], v[228:231], v[220:223], v[4:7]
	v_mfma_f32_16x16x32_bf16 v[0:3], v[232:235], v[220:223], v[0:3]
	v_mfma_f32_16x16x32_bf16 v[140:143], v[236:239], v[220:223], v[140:143]
	ds_read_b128 v[220:223], v185 offset:7168
	ds_read_b128 v[224:227], v184
	ds_read_b128 v[228:231], v184 offset:1024
	ds_read_b128 v[232:235], v184 offset:2048
	ds_read_b128 v[236:239], v184 offset:3072
	s_movk_i32 vcc_lo, 0x6000
	s_cmp_eq_u32 m0, 2
	s_cselect_b32 vcc_lo, 0xffff4000, vcc_lo
	s_add_u32 m0, m0, 1
	s_cmp_eq_u32 m0, 3
	s_cselect_b32 m0, 0, m0
	v_add_u32_e32 v185, vcc_lo, v185
	v_add_u32_e32 v184, vcc_lo, v184
	v_xor_b32_e32 v185, 64, v185
	v_xor_b32_e32 v184, 64, v184
	s_waitcnt lgkmcnt(0)
	v_mfma_f32_16x16x32_bf16 v[172:175], v[224:227], v[190:193], v[172:175]
	v_mfma_f32_16x16x32_bf16 v[168:171], v[228:231], v[190:193], v[168:171]
	v_mfma_f32_16x16x32_bf16 v[164:167], v[232:235], v[190:193], v[164:167]
	v_mfma_f32_16x16x32_bf16 v[160:163], v[236:239], v[190:193], v[160:163]
	v_mfma_f32_16x16x32_bf16 v[156:159], v[224:227], v[194:197], v[156:159]
	v_mfma_f32_16x16x32_bf16 v[152:155], v[228:231], v[194:197], v[152:155]
	v_mfma_f32_16x16x32_bf16 v[148:151], v[232:235], v[194:197], v[148:151]
	v_mfma_f32_16x16x32_bf16 v[144:147], v[236:239], v[194:197], v[144:147]
	v_mfma_f32_16x16x32_bf16 v[136:139], v[224:227], v[198:201], v[136:139]
	v_mfma_f32_16x16x32_bf16 v[132:135], v[228:231], v[198:201], v[132:135]
	v_mfma_f32_16x16x32_bf16 v[128:131], v[232:235], v[198:201], v[128:131]
	v_mfma_f32_16x16x32_bf16 v[124:127], v[236:239], v[198:201], v[124:127]
	v_mfma_f32_16x16x32_bf16 v[120:123], v[224:227], v[204:207], v[120:123]
	v_mfma_f32_16x16x32_bf16 v[108:111], v[228:231], v[204:207], v[108:111]
	v_mfma_f32_16x16x32_bf16 v[100:103], v[232:235], v[204:207], v[100:103]
	v_mfma_f32_16x16x32_bf16 v[96:99], v[236:239], v[204:207], v[96:99]
	v_mfma_f32_16x16x32_bf16 v[92:95], v[224:227], v[208:211], v[92:95]
	v_mfma_f32_16x16x32_bf16 v[84:87], v[228:231], v[208:211], v[84:87]
	v_mfma_f32_16x16x32_bf16 v[76:79], v[232:235], v[208:211], v[76:79]
	v_mfma_f32_16x16x32_bf16 v[72:75], v[236:239], v[208:211], v[72:75]
	v_mfma_f32_16x16x32_bf16 v[64:67], v[224:227], v[212:215], v[64:67]
	v_mfma_f32_16x16x32_bf16 v[52:55], v[228:231], v[212:215], v[52:55]
	v_mfma_f32_16x16x32_bf16 v[48:51], v[232:235], v[212:215], v[48:51]
	v_mfma_f32_16x16x32_bf16 v[44:47], v[236:239], v[212:215], v[44:47]
	v_mfma_f32_16x16x32_bf16 v[36:39], v[224:227], v[216:219], v[36:39]
	v_mfma_f32_16x16x32_bf16 v[28:31], v[228:231], v[216:219], v[28:31]
	v_mfma_f32_16x16x32_bf16 v[24:27], v[232:235], v[216:219], v[24:27]
	v_mfma_f32_16x16x32_bf16 v[20:23], v[236:239], v[216:219], v[20:23]
	v_mfma_f32_16x16x32_bf16 v[12:15], v[224:227], v[220:223], v[12:15]
	v_mfma_f32_16x16x32_bf16 v[4:7], v[228:231], v[220:223], v[4:7]
	v_mfma_f32_16x16x32_bf16 v[0:3], v[232:235], v[220:223], v[0:3]
	v_mfma_f32_16x16x32_bf16 v[140:143], v[236:239], v[220:223], v[140:143]
	v_lshrrev_b32_e32 v224, 4, v188
	v_and_b32_e32 v225, 7, v188
	v_bitop3_b32 v226, v224, v225, 3 bitop3:0x6c
	v_lshlrev_b32_e32 v227, 7, v188
	v_bfe_u32 v228, v188, 4, 2
	v_and_b32_e32 v229, 0xffffc780, v227
	v_and_b32_e32 v227, 0x2780, v227
	v_bitop3_b32 v228, v228, v225, 4 bitop3:0x36
	v_lshlrev_b32_e32 v226, 4, v226
	v_lshlrev_b32_e32 v228, 4, v228
	v_or_b32_e32 v185, v229, v226
	v_or_b32_e32 v184, v227, v226
	v_or_b32_e32 v183, v229, v228
	v_or_b32_e32 v182, v227, v228
	s_waitcnt vmcnt(0)
	s_setprio 1
	s_barrier
	s_waitcnt vmcnt(10)
	ds_write_b128 v176, v[116:119]
	s_waitcnt vmcnt(9)
	ds_write_b128 v176, v[112:115] offset:4096
	s_waitcnt vmcnt(8)
	ds_write_b128 v176, v[104:107] offset:8192
	s_waitcnt vmcnt(7)
	ds_write_b128 v176, v[88:91] offset:12288
	s_waitcnt vmcnt(6)
	ds_write_b128 v176, v[80:83] offset:16384
	s_waitcnt vmcnt(5)
	ds_write_b128 v176, v[68:71] offset:20480
	s_waitcnt vmcnt(4)
	ds_write_b128 v176, v[60:63] offset:24576
	s_waitcnt vmcnt(3)
	ds_write_b128 v176, v[40:43] offset:28672
	ds_write_b128 v176, v[56:59] offset:32768
	s_waitcnt vmcnt(2)
	ds_write_b128 v176, v[32:35] offset:36864
	s_waitcnt vmcnt(1)
	ds_write_b128 v176, v[16:19] offset:40960
	s_waitcnt vmcnt(0)
	ds_write_b128 v176, v[8:11] offset:45056
	s_waitcnt lgkmcnt(0)
	s_barrier
	ds_read_b128 v[8:11], v185
	ds_read_b128 v[16:19], v185 offset:2048
	ds_read_b128 v[32:35], v185 offset:4096
	ds_read_b128 v[40:43], v185 offset:6144
	ds_read_b128 v[56:59], v185 offset:8192
	ds_read_b128 v[60:63], v185 offset:10240
	ds_read_b128 v[68:71], v185 offset:12288
	ds_read_b128 v[80:83], v185 offset:14336
	ds_read_b128 v[88:91], v184 offset:32768
	ds_read_b128 v[104:107], v184 offset:34816
	ds_read_b128 v[112:115], v184 offset:36864
	ds_read_b128 v[116:119], v184 offset:38912
	s_waitcnt lgkmcnt(3)
	v_mfma_f32_16x16x32_bf16 v[172:175], v[88:91], v[8:11], v[172:175]
	s_waitcnt lgkmcnt(2)
	v_mfma_f32_16x16x32_bf16 v[168:171], v[104:107], v[8:11], v[168:171]
	s_waitcnt lgkmcnt(1)
	v_mfma_f32_16x16x32_bf16 v[164:167], v[112:115], v[8:11], v[164:167]
	s_waitcnt lgkmcnt(0)
	v_mfma_f32_16x16x32_bf16 v[8:11], v[116:119], v[8:11], v[160:163]
	v_mfma_f32_16x16x32_bf16 v[156:159], v[88:91], v[16:19], v[156:159]
	v_mfma_f32_16x16x32_bf16 v[152:155], v[104:107], v[16:19], v[152:155]
	v_mfma_f32_16x16x32_bf16 v[148:151], v[112:115], v[16:19], v[148:151]
	v_mfma_f32_16x16x32_bf16 v[16:19], v[116:119], v[16:19], v[144:147]
	v_mfma_f32_16x16x32_bf16 v[136:139], v[88:91], v[32:35], v[136:139]
	v_mfma_f32_16x16x32_bf16 v[132:135], v[104:107], v[32:35], v[132:135]
	v_mfma_f32_16x16x32_bf16 v[128:131], v[112:115], v[32:35], v[128:131]
	v_mfma_f32_16x16x32_bf16 v[32:35], v[116:119], v[32:35], v[124:127]
	v_mfma_f32_16x16x32_bf16 v[120:123], v[88:91], v[40:43], v[120:123]
	v_mfma_f32_16x16x32_bf16 v[108:111], v[104:107], v[40:43], v[108:111]
	v_mfma_f32_16x16x32_bf16 v[100:103], v[112:115], v[40:43], v[100:103]
	v_mfma_f32_16x16x32_bf16 v[40:43], v[116:119], v[40:43], v[96:99]
	v_mfma_f32_16x16x32_bf16 v[92:95], v[88:91], v[56:59], v[92:95]
	v_mfma_f32_16x16x32_bf16 v[84:87], v[104:107], v[56:59], v[84:87]
	v_mfma_f32_16x16x32_bf16 v[76:79], v[112:115], v[56:59], v[76:79]
	v_mfma_f32_16x16x32_bf16 v[56:59], v[116:119], v[56:59], v[72:75]
	v_mfma_f32_16x16x32_bf16 v[64:67], v[88:91], v[60:63], v[64:67]
	v_mfma_f32_16x16x32_bf16 v[52:55], v[104:107], v[60:63], v[52:55]
	v_mfma_f32_16x16x32_bf16 v[72:75], v[112:115], v[60:63], v[48:51]
	v_mfma_f32_16x16x32_bf16 v[60:63], v[116:119], v[60:63], v[44:47]
	v_mfma_f32_16x16x32_bf16 v[96:99], v[88:91], v[68:71], v[36:39]
	v_mfma_f32_16x16x32_bf16 v[28:31], v[104:107], v[68:71], v[28:31]
	v_mfma_f32_16x16x32_bf16 v[124:127], v[112:115], v[68:71], v[24:27]
	v_mfma_f32_16x16x32_bf16 v[20:23], v[116:119], v[68:71], v[20:23]
	v_mfma_f32_16x16x32_bf16 v[12:15], v[88:91], v[80:83], v[12:15]
	v_mfma_f32_16x16x32_bf16 v[4:7], v[104:107], v[80:83], v[4:7]
	v_mfma_f32_16x16x32_bf16 v[0:3], v[112:115], v[80:83], v[0:3]
	v_mfma_f32_16x16x32_bf16 v[68:71], v[116:119], v[80:83], v[140:143]
	ds_read_b128 v[24:27], v183
	ds_read_b128 v[36:39], v183 offset:2048
	ds_read_b128 v[44:47], v183 offset:4096
	ds_read_b128 v[80:83], v183 offset:6144
	ds_read_b128 v[88:91], v183 offset:8192
	ds_read_b128 v[104:107], v183 offset:10240
	ds_read_b128 v[112:115], v183 offset:12288
	ds_read_b128 v[116:119], v183 offset:14336
	ds_read_b128 v[140:143], v182 offset:32768
	ds_read_b128 v[144:147], v182 offset:34816
	ds_read_b128 v[160:163], v182 offset:36864
	ds_read_b128 v[178:181], v182 offset:38912
	s_waitcnt lgkmcnt(3)
	v_mfma_f32_16x16x32_bf16 v[172:175], v[140:143], v[24:27], v[172:175]
	v_mov_b32_e32 v49, v188
	v_cmp_lt_i32_e32 vcc, v189, v202
	s_waitcnt lgkmcnt(2)
	v_mfma_f32_16x16x32_bf16 v[168:171], v[144:147], v[24:27], v[168:171]
	v_mov_b32_e32 v48, v188
	v_readlane_b32 s6, v253, 24
	s_waitcnt lgkmcnt(1)
	v_mfma_f32_16x16x32_bf16 v[164:167], v[160:163], v[24:27], v[164:167]
	v_and_b32_e32 v50, 0xffffff80, v48
	v_add_u32_e32 v51, s9, v50
	v_and_or_b32 v50, v48, 64, s10
	s_waitcnt lgkmcnt(0)
	v_mfma_f32_16x16x32_bf16 v[8:11], v[178:181], v[24:27], v[8:11]
	v_bfe_u32 v26, v49, 4, 1
	v_cndmask_b32_e32 v24, v203, v189, vcc
	v_cmp_eq_u32_e32 vcc, 0, v26
	v_lshlrev_b32_e32 v186, 2, v24
	v_mfma_f32_16x16x32_bf16 v[182:185], v[178:181], v[36:39], v[16:19]
	v_and_or_b32 v48, v49, 15, v51
	v_ashrrev_i32_e32 v51, 31, v50
	v_lshl_add_u64 v[50:51], v[50:51], 1, s[4:5]
	s_nop 0
	s_nop 0
	s_nop 0
	s_nop 0
	s_nop 0
	s_nop 0
	s_nop 0
	s_nop 0
	v_lshlrev_b32_e32 v176, 5, v26
	v_lshrrev_b32_e32 v27, 1, v49
	v_lshl_add_u64 v[24:25], v[50:51], 0, v[176:177]
	v_and_b32_e32 v176, 16, v27
	v_ashrrev_i32_e32 v49, 31, v48
	v_mfma_f32_16x16x32_bf16 v[156:159], v[140:143], v[36:39], v[156:159]
	v_lshl_add_u64 v[50:51], v[24:25], 0, v[176:177]
	v_lshlrev_b64 v[24:25], 11, v[48:49]
	s_waitcnt lgkmcnt(0)
	s_nop 0
	v_mfma_f32_16x16x32_bf16 v[152:155], v[144:147], v[36:39], v[152:155]
	v_mov_b32_e32 v26, v172
	v_mov_b32_e32 v27, v168
	s_nop 1
	v_permlane16_swap_b32_e32 v26, v27
	s_waitcnt lgkmcnt(0)
	s_nop 0
	v_lshl_add_u64 v[24:25], v[50:51], 0, v[24:25]
	v_mfma_f32_16x16x32_bf16 v[148:151], v[160:163], v[36:39], v[148:151]
	v_mov_b32_e32 v16, v173
	v_mov_b32_e32 v36, v169
	s_nop 1
	v_permlane16_swap_b32_e32 v16, v36
	s_waitcnt lgkmcnt(0)
	s_nop 0
	v_cvt_pk_bf16_f32 v16, v26, v16
	v_mfma_f32_16x16x32_bf16 v[190:193], v[178:181], v[44:47], v[32:35]
	v_readlane_b32 s7, v253, 25
	s_nop 1
	v_mov_b32_e32 v17, v174
	v_mov_b32_e32 v32, v170
	s_nop 1
	v_permlane16_swap_b32_e32 v17, v32
	s_waitcnt lgkmcnt(0)
	s_nop 0
	v_mov_b32_e32 v18, v175
	v_mov_b32_e32 v19, v171
	s_nop 1
	v_permlane16_swap_b32_e32 v18, v19
	v_cvt_pk_bf16_f32 v17, v17, v18
	v_cvt_pk_bf16_f32 v18, v27, v36
	v_cvt_pk_bf16_f32 v19, v32, v19
	global_store_dwordx4 v[24:25], v[16:19], off
	v_mfma_f32_16x16x32_bf16 v[120:123], v[140:143], v[80:83], v[120:123]
	s_nop 0
	s_nop 0
	s_nop 0
	s_nop 0
	s_nop 0
	s_nop 0
	s_nop 0
	s_nop 0
	s_nop 0
	v_mfma_f32_16x16x32_bf16 v[108:111], v[144:147], v[80:83], v[108:111]
	s_waitcnt lgkmcnt(0)
	s_nop 0
	v_mov_b32_e32 v26, v164
	v_mov_b32_e32 v16, v8
	s_nop 1
	v_permlane16_swap_b32_e32 v26, v16
	s_waitcnt lgkmcnt(0)
	s_nop 0
	v_mov_b32_e32 v8, v165
	v_mov_b32_e32 v17, v9
	s_nop 1
	v_permlane16_swap_b32_e32 v8, v17
	s_waitcnt lgkmcnt(0)
	s_nop 0
	v_mov_b32_e32 v9, v166
	v_mov_b32_e32 v18, v10
	s_nop 1
	v_permlane16_swap_b32_e32 v9, v18
	s_waitcnt lgkmcnt(0)
	s_nop 0
	v_mov_b32_e32 v10, v167
	s_nop 1
	v_permlane16_swap_b32_e32 v10, v11
	v_cvt_pk_bf16_f32 v8, v26, v8
	v_cvt_pk_bf16_f32 v9, v9, v10
	v_cvt_pk_bf16_f32 v10, v16, v17
	v_cvt_pk_bf16_f32 v11, v18, v11
	global_store_dwordx4 v[24:25], v[8:11], off offset:64
	v_mfma_f32_16x16x32_bf16 v[100:103], v[160:163], v[80:83], v[100:103]
	s_nop 0
	v_or_b32_e32 v8, 16, v48
	v_ashrrev_i32_e32 v9, 31, v8
	v_lshlrev_b64 v[8:9], 11, v[8:9]
	v_mfma_f32_16x16x32_bf16 v[80:83], v[178:181], v[80:83], v[40:43]
	s_nop 0
	s_nop 0
	s_nop 0
	v_mfma_f32_16x16x32_bf16 v[40:43], v[140:143], v[104:107], v[64:67]
	s_nop 0
	s_nop 1
	v_lshl_add_u64 v[64:65], v[50:51], 0, v[8:9]
	s_nop 0
	s_nop 0
	s_nop 0
	s_nop 0
	v_mfma_f32_16x16x32_bf16 v[136:139], v[140:143], v[44:47], v[136:139]
	s_waitcnt lgkmcnt(0)
	s_nop 0
	v_mfma_f32_16x16x32_bf16 v[132:135], v[144:147], v[44:47], v[132:135]
	v_mfma_f32_16x16x32_bf16 v[128:131], v[160:163], v[44:47], v[128:131]
	v_mfma_f32_16x16x32_bf16 v[44:47], v[144:147], v[104:107], v[52:55]
	v_mfma_f32_16x16x32_bf16 v[36:39], v[178:181], v[104:107], v[60:63]
	s_nop 1
	v_mov_b32_e32 v49, v156
	v_mov_b32_e32 v54, v152
	s_nop 1
	v_permlane16_swap_b32_e32 v49, v54
	s_waitcnt lgkmcnt(0)
	s_nop 0
	v_mov_b32_e32 v8, v157
	v_mov_b32_e32 v55, v153
	s_nop 1
	v_permlane16_swap_b32_e32 v8, v55
	s_nop 0
	v_mov_b32_e32 v53, v158
	v_mov_b32_e32 v60, v154
	s_nop 1
	v_permlane16_swap_b32_e32 v53, v60
	s_nop 0
	v_mov_b32_e32 v61, v159
	v_mov_b32_e32 v62, v155
	s_nop 1
	v_permlane16_swap_b32_e32 v61, v62
	v_cvt_pk_bf16_f32 v52, v49, v8
	v_cvt_pk_bf16_f32 v53, v53, v61
	v_cvt_pk_bf16_f32 v54, v54, v55
	v_cvt_pk_bf16_f32 v55, v60, v62
	v_mfma_f32_16x16x32_bf16 v[8:11], v[140:143], v[116:119], v[12:15]
	global_store_dwordx4 v[64:65], v[52:55], off
	s_nop 0
	s_nop 0
	v_mfma_f32_16x16x32_bf16 v[12:15], v[144:147], v[116:119], v[4:7]
	s_nop 0
	s_nop 0
	s_nop 0
	v_cndmask_b32_e32 v4, v148, v182, vcc
	ds_bpermute_b32 v54, v186, v4
	s_nop 0
	s_waitcnt lgkmcnt(1)
	s_nop 0
	v_mov_b32_e32 v60, v149
	v_mov_b32_e32 v49, v183
	s_nop 1
	v_permlane16_swap_b32_e32 v60, v49
	s_waitcnt lgkmcnt(1)
	s_nop 0
	s_waitcnt lgkmcnt(0)
	v_cndmask_b32_e32 v55, v54, v148, vcc
	v_cndmask_b32_e32 v54, v182, v54, vcc
	v_mov_b32_e32 v61, v150
	v_mov_b32_e32 v62, v184
	s_nop 1
	v_permlane16_swap_b32_e32 v61, v62
	s_waitcnt lgkmcnt(0)
	s_nop 0
	v_mov_b32_e32 v63, v151
	v_mov_b32_e32 v66, v185
	s_nop 1
	v_permlane16_swap_b32_e32 v63, v66
	v_cvt_pk_bf16_f32 v52, v55, v60
	v_cvt_pk_bf16_f32 v53, v61, v63
	v_cvt_pk_bf16_f32 v54, v54, v49
	v_cvt_pk_bf16_f32 v55, v62, v66
	global_store_dwordx4 v[64:65], v[52:55], off offset:64
	s_nop 0
	s_nop 0
	v_or_b32_e32 v52, 32, v48
	v_ashrrev_i32_e32 v53, 31, v52
	v_lshlrev_b64 v[52:53], 11, v[52:53]
	v_lshl_add_u64 v[60:61], v[50:51], 0, v[52:53]
	s_nop 0
	s_nop 0
	s_nop 0
	s_nop 0
	s_nop 0
	s_nop 0
	s_waitcnt lgkmcnt(0)
	s_nop 0
	v_mov_b32_e32 v55, v136
	v_mov_b32_e32 v49, v132
	s_nop 1
	v_permlane16_swap_b32_e32 v55, v49
	s_waitcnt lgkmcnt(0)
	s_nop 0
	v_mov_b32_e32 v62, v137
	v_mov_b32_e32 v63, v133
	s_nop 1
	v_permlane16_swap_b32_e32 v62, v63
	s_waitcnt lgkmcnt(0)
	s_nop 0
	v_mov_b32_e32 v64, v138
	v_mov_b32_e32 v65, v134
	s_nop 1
	v_permlane16_swap_b32_e32 v64, v65
	s_waitcnt lgkmcnt(0)
	s_nop 0
	v_mov_b32_e32 v53, v139
	v_mov_b32_e32 v66, v135
	s_nop 1
	v_permlane16_swap_b32_e32 v53, v66
	v_cvt_pk_bf16_f32 v52, v55, v62
	v_cvt_pk_bf16_f32 v53, v64, v53
	v_cvt_pk_bf16_f32 v54, v49, v63
	v_cvt_pk_bf16_f32 v55, v65, v66
	global_store_dwordx4 v[60:61], v[52:55], off
	s_nop 0
	s_nop 0
	s_nop 0
	s_nop 0
	s_nop 0
	s_nop 0
	s_nop 0
	s_nop 0
	s_waitcnt lgkmcnt(0)
	s_nop 0
	v_mov_b32_e32 v55, v128
	v_mov_b32_e32 v49, v190
	s_nop 1
	v_permlane16_swap_b32_e32 v55, v49
	s_waitcnt lgkmcnt(0)
	s_nop 0
	v_mov_b32_e32 v62, v129
	v_mov_b32_e32 v63, v191
	s_nop 1
	v_permlane16_swap_b32_e32 v62, v63
	s_waitcnt lgkmcnt(0)
	s_nop 0
	v_mov_b32_e32 v64, v130
	v_mov_b32_e32 v65, v192
	s_nop 1
	v_permlane16_swap_b32_e32 v64, v65
	s_waitcnt lgkmcnt(0)
	s_nop 0
	v_mov_b32_e32 v53, v131
	v_mov_b32_e32 v66, v193
	s_nop 1
	v_permlane16_swap_b32_e32 v53, v66
	v_cvt_pk_bf16_f32 v52, v55, v62
	v_cvt_pk_bf16_f32 v53, v64, v53
	v_cvt_pk_bf16_f32 v54, v49, v63
	v_cvt_pk_bf16_f32 v55, v65, v66
	global_store_dwordx4 v[60:61], v[52:55], off offset:64
	s_nop 0
	s_nop 0
	v_or_b32_e32 v52, 48, v48
	v_ashrrev_i32_e32 v53, 31, v52
	v_lshlrev_b64 v[52:53], 11, v[52:53]
	v_lshl_add_u64 v[60:61], v[50:51], 0, v[52:53]
	s_nop 0
	s_nop 0
	s_nop 0
	s_nop 0
	s_nop 0
	s_nop 0
	s_waitcnt lgkmcnt(0)
	s_nop 0
	v_mov_b32_e32 v55, v120
	v_mov_b32_e32 v49, v108
	s_nop 1
	v_permlane16_swap_b32_e32 v55, v49
	s_waitcnt lgkmcnt(0)
	s_nop 0
	v_mov_b32_e32 v62, v121
	v_mov_b32_e32 v63, v109
	s_nop 1
	v_permlane16_swap_b32_e32 v62, v63
	s_waitcnt lgkmcnt(0)
	s_nop 0
	v_mov_b32_e32 v64, v122
	v_mov_b32_e32 v65, v110
	s_nop 1
	v_permlane16_swap_b32_e32 v64, v65
	s_waitcnt lgkmcnt(0)
	s_nop 0
	v_mov_b32_e32 v53, v123
	v_mov_b32_e32 v66, v111
	s_nop 1
	v_permlane16_swap_b32_e32 v53, v66
	v_cvt_pk_bf16_f32 v52, v55, v62
	v_cvt_pk_bf16_f32 v53, v64, v53
	v_cvt_pk_bf16_f32 v54, v49, v63
	v_cvt_pk_bf16_f32 v55, v65, v66
	global_store_dwordx4 v[60:61], v[52:55], off
	s_nop 0
	s_nop 0
	s_nop 0
	s_nop 0
	s_nop 0
	s_nop 0
	s_nop 0
	s_nop 0
	s_waitcnt lgkmcnt(0)
	s_nop 0
	v_mov_b32_e32 v55, v100
	v_mov_b32_e32 v49, v80
	s_nop 1
	v_permlane16_swap_b32_e32 v55, v49
	s_waitcnt lgkmcnt(0)
	s_nop 0
	v_mov_b32_e32 v62, v101
	v_mov_b32_e32 v63, v81
	s_nop 1
	v_permlane16_swap_b32_e32 v62, v63
	s_waitcnt lgkmcnt(0)
	s_nop 0
	v_mov_b32_e32 v64, v102
	v_mov_b32_e32 v65, v82
	s_nop 1
	v_permlane16_swap_b32_e32 v64, v65
	s_waitcnt lgkmcnt(0)
	s_nop 0
	v_mov_b32_e32 v53, v103
	v_mov_b32_e32 v66, v83
	s_nop 1
	v_permlane16_swap_b32_e32 v53, v66
	v_mfma_f32_16x16x32_bf16 v[92:95], v[140:143], v[88:91], v[92:95]
	v_cvt_pk_bf16_f32 v52, v55, v62
	v_cvt_pk_bf16_f32 v53, v64, v53
	v_cvt_pk_bf16_f32 v54, v49, v63
	v_mfma_f32_16x16x32_bf16 v[84:87], v[144:147], v[88:91], v[84:87]
	v_cvt_pk_bf16_f32 v55, v65, v66
	global_store_dwordx4 v[60:61], v[52:55], off offset:64
	v_mfma_f32_16x16x32_bf16 v[76:79], v[160:163], v[88:91], v[76:79]
	s_nop 0
	v_or_b32_e32 v52, 64, v48
	v_ashrrev_i32_e32 v53, 31, v52
	v_lshlrev_b64 v[52:53], 11, v[52:53]
	v_lshl_add_u64 v[60:61], v[50:51], 0, v[52:53]
	s_nop 0
	s_nop 0
	s_nop 0
	s_nop 0
	s_nop 0
	s_nop 0
	s_nop 0
	s_nop 0
	v_mfma_f32_16x16x32_bf16 v[56:59], v[178:181], v[88:91], v[56:59]
	s_waitcnt lgkmcnt(0)
	s_nop 0
	v_mov_b32_e32 v55, v92
	v_mov_b32_e32 v49, v84
	s_nop 1
	v_permlane16_swap_b32_e32 v55, v49
	s_waitcnt lgkmcnt(0)
	s_nop 0
	v_mov_b32_e32 v62, v93
	v_mov_b32_e32 v63, v85
	s_nop 1
	v_permlane16_swap_b32_e32 v62, v63
	s_waitcnt lgkmcnt(0)
	s_nop 0
	v_mov_b32_e32 v64, v94
	v_mov_b32_e32 v65, v86
	s_nop 1
	v_permlane16_swap_b32_e32 v64, v65
	s_waitcnt lgkmcnt(0)
	s_nop 0
	v_mov_b32_e32 v53, v95
	v_mov_b32_e32 v66, v87
	s_nop 1
	v_permlane16_swap_b32_e32 v53, v66
	v_cvt_pk_bf16_f32 v52, v55, v62
	v_cvt_pk_bf16_f32 v53, v64, v53
	v_cvt_pk_bf16_f32 v54, v49, v63
	v_cvt_pk_bf16_f32 v55, v65, v66
	global_store_dwordx4 v[60:61], v[52:55], off
	s_nop 0
	s_nop 0
	s_nop 0
	s_nop 0
	s_nop 0
	s_nop 0
	s_nop 0
	s_nop 0
	s_waitcnt lgkmcnt(0)
	s_nop 0
	v_mov_b32_e32 v55, v76
	v_mov_b32_e32 v49, v56
	s_nop 1
	v_permlane16_swap_b32_e32 v55, v49
	s_waitcnt lgkmcnt(0)
	s_nop 0
	v_mov_b32_e32 v56, v77
	s_nop 1
	v_permlane16_swap_b32_e32 v56, v57
	s_waitcnt lgkmcnt(0)
	s_nop 0
	v_mov_b32_e32 v62, v78
	s_nop 1
	v_permlane16_swap_b32_e32 v62, v58
	s_waitcnt lgkmcnt(0)
	s_nop 0
	v_mov_b32_e32 v53, v79
	s_nop 1
	v_permlane16_swap_b32_e32 v53, v59
	v_cvt_pk_bf16_f32 v52, v55, v56
	v_cvt_pk_bf16_f32 v53, v62, v53
	v_cvt_pk_bf16_f32 v54, v49, v57
	v_cvt_pk_bf16_f32 v55, v58, v59
	global_store_dwordx4 v[60:61], v[52:55], off offset:64
	s_nop 0
	s_nop 0
	s_nop 0
	s_nop 0
	s_nop 0
	s_nop 0
	s_nop 0
	s_nop 0
	v_mfma_f32_16x16x32_bf16 v[32:35], v[160:163], v[104:107], v[72:75]
	v_or_b32_e32 v52, 0x50, v48
	v_ashrrev_i32_e32 v53, 31, v52
	v_lshlrev_b64 v[52:53], 11, v[52:53]
	s_waitcnt lgkmcnt(0)
	s_nop 0
	s_nop 1
	v_permlane16_swap_b32_e32 v40, v44
	s_waitcnt lgkmcnt(0)
	s_nop 0
	s_nop 1
	v_permlane16_swap_b32_e32 v41, v45
	s_waitcnt lgkmcnt(0)
	s_nop 0
	s_nop 1
	v_permlane16_swap_b32_e32 v42, v46
	s_waitcnt lgkmcnt(0)
	s_nop 0
	s_nop 1
	v_permlane16_swap_b32_e32 v43, v47
	v_lshl_add_u64 v[52:53], v[50:51], 0, v[52:53]
	v_cvt_pk_bf16_f32 v40, v40, v41
	v_cvt_pk_bf16_f32 v41, v42, v43
	v_cvt_pk_bf16_f32 v42, v44, v45
	v_cvt_pk_bf16_f32 v43, v46, v47
	global_store_dwordx4 v[52:53], v[40:43], off
	v_mfma_f32_16x16x32_bf16 v[24:27], v[140:143], v[112:115], v[96:99]
	s_nop 0
	s_nop 0
	s_nop 0
	s_nop 0
	s_nop 0
	s_nop 0
	s_nop 0
	s_nop 0
	s_nop 0
	v_mfma_f32_16x16x32_bf16 v[28:31], v[144:147], v[112:115], v[28:31]
	s_waitcnt lgkmcnt(0)
	s_nop 0
	s_nop 1
	v_permlane16_swap_b32_e32 v32, v36
	s_waitcnt lgkmcnt(0)
	s_nop 0
	s_nop 1
	v_permlane16_swap_b32_e32 v33, v37
	s_waitcnt lgkmcnt(0)
	s_nop 0
	s_nop 1
	v_permlane16_swap_b32_e32 v34, v38
	s_waitcnt lgkmcnt(0)
	s_nop 0
	s_nop 1
	v_permlane16_swap_b32_e32 v35, v39
	v_cvt_pk_bf16_f32 v32, v32, v33
	v_cvt_pk_bf16_f32 v33, v34, v35
	v_cvt_pk_bf16_f32 v34, v36, v37
	v_cvt_pk_bf16_f32 v35, v38, v39
	global_store_dwordx4 v[52:53], v[32:35], off offset:64
	s_nop 0
	s_nop 0
	s_nop 0
	s_nop 0
	s_nop 0
	s_nop 0
	s_nop 0
	s_nop 0
	v_mfma_f32_16x16x32_bf16 v[16:19], v[160:163], v[112:115], v[124:127]
	v_or_b32_e32 v32, 0x60, v48
	v_ashrrev_i32_e32 v33, 31, v32
	v_lshlrev_b64 v[32:33], 11, v[32:33]
	v_mfma_f32_16x16x32_bf16 v[20:23], v[178:181], v[112:115], v[20:23]
	s_waitcnt lgkmcnt(0)
	s_nop 0
	s_nop 1
	v_permlane16_swap_b32_e32 v24, v28
	s_waitcnt lgkmcnt(0)
	s_nop 0
	s_nop 1
	v_permlane16_swap_b32_e32 v25, v29
	s_waitcnt lgkmcnt(0)
	s_nop 0
	s_nop 1
	v_permlane16_swap_b32_e32 v26, v30
	s_waitcnt lgkmcnt(0)
	s_nop 0
	s_nop 1
	v_permlane16_swap_b32_e32 v27, v31
	v_lshl_add_u64 v[32:33], v[50:51], 0, v[32:33]
	v_cvt_pk_bf16_f32 v24, v24, v25
	v_cvt_pk_bf16_f32 v25, v26, v27
	v_cvt_pk_bf16_f32 v26, v28, v29
	v_cvt_pk_bf16_f32 v27, v30, v31
	global_store_dwordx4 v[32:33], v[24:27], off
	v_mfma_f32_16x16x32_bf16 v[0:3], v[160:163], v[116:119], v[0:3]
	s_nop 0
	s_nop 0
	s_nop 0
	s_nop 0
	s_nop 0
	s_nop 0
	s_nop 0
	s_nop 0
	s_nop 0
	v_mfma_f32_16x16x32_bf16 v[4:7], v[178:181], v[116:119], v[68:71]
	s_waitcnt lgkmcnt(0)
	s_nop 0
	s_nop 1
	v_permlane16_swap_b32_e32 v16, v20
	s_waitcnt lgkmcnt(0)
	s_nop 0
	s_nop 1
	v_permlane16_swap_b32_e32 v17, v21
	s_waitcnt lgkmcnt(0)
	s_nop 0
	s_nop 1
	v_permlane16_swap_b32_e32 v18, v22
	s_waitcnt lgkmcnt(0)
	s_nop 0
	s_nop 1
	v_permlane16_swap_b32_e32 v19, v23
	v_cvt_pk_bf16_f32 v16, v16, v17
	v_cvt_pk_bf16_f32 v17, v18, v19
	v_cvt_pk_bf16_f32 v18, v20, v21
	v_cvt_pk_bf16_f32 v19, v22, v23
	global_store_dwordx4 v[32:33], v[16:19], off offset:64
	s_nop 0
	s_nop 0
	s_nop 0
	s_nop 0
	s_nop 0
	s_nop 0
	s_nop 0
	s_nop 0
	v_or_b32_e32 v16, 0x70, v48
	v_ashrrev_i32_e32 v17, 31, v16
	v_lshlrev_b64 v[16:17], 11, v[16:17]
	s_waitcnt lgkmcnt(0)
	s_nop 0
	s_nop 1
	v_permlane16_swap_b32_e32 v8, v12
	s_waitcnt lgkmcnt(0)
	s_nop 0
	s_nop 1
	v_permlane16_swap_b32_e32 v9, v13
	s_waitcnt lgkmcnt(0)
	s_nop 0
	s_nop 1
	v_permlane16_swap_b32_e32 v10, v14
	s_waitcnt lgkmcnt(0)
	s_nop 0
	s_nop 1
	v_permlane16_swap_b32_e32 v11, v15
	v_lshl_add_u64 v[16:17], v[50:51], 0, v[16:17]
	v_cvt_pk_bf16_f32 v8, v8, v9
	v_cvt_pk_bf16_f32 v9, v10, v11
	v_cvt_pk_bf16_f32 v10, v12, v13
	v_cvt_pk_bf16_f32 v11, v14, v15
	global_store_dwordx4 v[16:17], v[8:11], off
	s_nop 1
	s_nop 0
	s_nop 0
	s_nop 0
	s_nop 0
	s_nop 0
	s_nop 0
	s_nop 0
	s_nop 0
	s_waitcnt lgkmcnt(0)
	s_nop 0
	s_nop 1
	v_permlane16_swap_b32_e32 v0, v4
	s_waitcnt lgkmcnt(0)
	s_nop 0
	s_nop 1
	v_permlane16_swap_b32_e32 v1, v5
	s_waitcnt lgkmcnt(0)
	s_nop 0
	s_nop 1
	v_permlane16_swap_b32_e32 v2, v6
	s_waitcnt lgkmcnt(0)
	s_nop 0
	s_nop 1
	v_permlane16_swap_b32_e32 v3, v7
	v_cvt_pk_bf16_f32 v0, v0, v1
	v_cvt_pk_bf16_f32 v1, v2, v3
	v_cvt_pk_bf16_f32 v2, v4, v5
	v_cvt_pk_bf16_f32 v3, v6, v7
	global_store_dwordx4 v[16:17], v[0:3], off offset:64
	s_load_dword s6, s[6:7], 0x0
	s_waitcnt lgkmcnt(0)
	s_add_i32 s8, s6, s8
	s_cmpk_gt_i32 s8, 0xff
	s_cbranch_scc0 .LBB0_801

.LBB0_1064:
	s_ashr_i32 s22, s52, 3
	s_lshl_b32 s31, s22, 1
	s_and_b32 s30, s22, -16
	s_and_b32 s31, s31, 14
	s_or_b32 s30, s31, s30
	s_bfe_u32 s31, s22, 0x10003
	s_or_b32 s23, s22, 63
	s_or_b32 s30, s30, s31
	s_cmpk_lt_i32 s23, 0x80
	s_cselect_b32 s22, s30, s22
	s_lshl_b32 s23, s52, 7
	s_and_b32 s23, s23, 0x380
	s_add_i32 s22, s22, s23
	s_ashr_i32 s23, s22, 31
	s_lshr_b32 s30, s23, 27
	s_add_i32 s30, s22, s30
	s_ashr_i32 s31, s30, 5
	s_andn2_b32 s30, s30, 31
	s_sub_i32 s30, s22, s30
	s_lshr_b32 s23, s23, 25
	s_add_i32 s22, s22, s23
	s_ashr_i32 s23, s30, 31
	s_lshr_b32 s23, s23, 29
	s_ashr_i32 s22, s22, 7
	s_add_i32 s23, s30, s23
	s_ashr_i32 s23, s23, 3
	s_lshl_b32 s38, s22, 2
	s_add_i32 s38, s38, s23
	s_sub_i32 s31, s31, s38
	s_lshl_b32 s42, s31, 3
	s_add_i32 s42, s42, s30
	s_lshl_b32 s22, s22, 10
	s_lshl_b32 s38, s23, 8
	s_add_i32 s38, s38, s22
	s_lshl_b32 s53, s42, 7
	s_ashr_i32 s44, s42, 3
	s_cmp_lg_u32 s44, 2
	s_cselect_b64 s[22:23], -1, 0
	s_mov_b64 s[30:31], -1
	s_and_b64 vcc, exec, s[22:23]
	s_mov_b32 s39, 0x30000
	s_cbranch_vccz .LBB0_1068
	v_mov_b32_e32 v8, v188
	s_mov_b32 s30, 0x20000
	v_ashrrev_i32_e32 v9, 3, v8
	v_lshlrev_b32_e32 v4, 4, v8
	v_and_b32_e32 v176, 0x70, v4
	v_add_u32_e32 v4, s53, v9
	v_add_u32_e32 v0, s38, v9
	v_ashrrev_i32_e32 v5, 31, v4
	v_ashrrev_i32_e32 v1, 31, v0
	v_lshlrev_b64 v[4:5], 11, v[4:5]
	v_xor_b32_e32 v10, v9, v8
	v_lshlrev_b64 v[0:1], 11, v[0:1]
	v_lshl_add_u64 v[6:7], s[2:3], 0, v[4:5]
	v_lshlrev_b32_e32 v10, 4, v10
	v_lshl_add_u64 v[2:3], s[0:1], 0, v[0:1]
	v_lshl_add_u64 v[6:7], v[6:7], 0, v[176:177]
	v_and_b32_e32 v10, 0x70, v10
	v_lshl_add_u64 v[2:3], v[2:3], 0, v[176:177]
	v_lshl_or_b32 v176, v9, 7, v10
	v_lshlrev_b32_e32 v12, 7, v8
	v_lshrrev_b32_e32 v9, 4, v8
	v_bfe_u32 v14, v8, 4, 2
	v_and_b32_e32 v15, 7, v8
	v_add_co_u32_e32 v8, vcc, s39, v6
	v_bitop3_b32 v16, v9, v15, 3 bitop3:0x6c
	s_nop 0
	v_addc_co_u32_e32 v9, vcc, 0, v7, vcc
	v_add_co_u32_e32 v10, vcc, s30, v6
	s_mov_b32 s31, 0x10000
	s_nop 0
	v_addc_co_u32_e32 v11, vcc, 0, v7, vcc
	global_load_dwordx4 v[20:23], v[8:9], off
	global_load_dwordx4 v[24:27], v[10:11], off
	v_add_co_u32_e32 v8, vcc, s31, v6
	s_mov_b32 s40, 0x70000
	s_nop 0
	v_addc_co_u32_e32 v9, vcc, 0, v7, vcc
	v_add_co_u32_e32 v10, vcc, s40, v2
	s_mov_b32 s40, 0x60000
	s_nop 0
	v_addc_co_u32_e32 v11, vcc, 0, v3, vcc
	global_load_dwordx4 v[40:43], v[8:9], off
	global_load_dwordx4 v[48:51], v[10:11], off
	v_add_co_u32_e32 v8, vcc, s40, v2
	s_mov_b32 s40, 0x50000
	s_nop 0
	v_addc_co_u32_e32 v9, vcc, 0, v3, vcc
	v_add_co_u32_e32 v10, vcc, s40, v2
	s_mov_b32 s40, 0x40000
	s_nop 0
	v_addc_co_u32_e32 v11, vcc, 0, v3, vcc
	global_load_dwordx4 v[60:63], v[8:9], off
	global_load_dwordx4 v[68:71], v[10:11], off
	v_add_co_u32_e32 v8, vcc, s40, v2
	v_and_b32_e32 v13, 0xffffc780, v12
	s_nop 0
	v_addc_co_u32_e32 v9, vcc, 0, v3, vcc
	v_add_co_u32_e32 v10, vcc, s39, v2
	v_and_b32_e32 v12, 0x2780, v12
	s_nop 0
	v_addc_co_u32_e32 v11, vcc, 0, v3, vcc
	global_load_dwordx4 v[80:83], v[8:9], off
	global_load_dwordx4 v[88:91], v[10:11], off
	v_add_co_u32_e32 v8, vcc, s30, v2
	v_bitop3_b32 v14, v14, v15, 4 bitop3:0x36
	s_nop 0
	v_addc_co_u32_e32 v9, vcc, 0, v3, vcc
	v_add_co_u32_e32 v10, vcc, s31, v2
	v_mov_b32_e32 v140, 0
	s_nop 0
	v_addc_co_u32_e32 v11, vcc, 0, v3, vcc
	global_load_dwordx4 v[104:107], v[8:9], off
	global_load_dwordx4 v[112:115], v[10:11], off
	global_load_dwordx4 v[100:103], v[6:7], off
	global_load_dwordx4 v[116:119], v[2:3], off
	v_lshlrev_b32_e32 v2, 4, v16
	v_or_b32_e32 v185, v13, v2
	v_or_b32_e32 v184, v12, v2
	v_lshlrev_b32_e32 v2, 4, v14
	v_or_b32_e32 v183, v13, v2
	v_or_b32_e32 v182, v12, v2
	v_lshlrev_b32_e32 v2, 4, v15
	v_or_b32_e32 v0, v0, v2
	v_or_b32_e32 v4, v4, v2
	v_lshl_add_u64 v[178:179], s[34:35], 0, v[0:1]
	v_lshl_add_u64 v[180:181], s[50:51], 0, v[4:5]
	s_mov_b64 s[30:31], 0
	v_mov_b32_e32 v141, v140
	v_mov_b32_e32 v142, v140
	v_mov_b32_e32 v143, v140
	v_mov_b32_e32 v0, v140
	v_mov_b32_e32 v1, v140
	v_mov_b32_e32 v2, v140
	v_mov_b32_e32 v3, v140
	v_mov_b32_e32 v4, v140
	v_mov_b32_e32 v5, v140
	v_mov_b32_e32 v6, v140
	v_mov_b32_e32 v7, v140
	v_mov_b32_e32 v8, v140
	v_mov_b32_e32 v9, v140
	v_mov_b32_e32 v10, v140
	v_mov_b32_e32 v11, v140
	v_mov_b32_e32 v12, v140
	v_mov_b32_e32 v13, v140
	v_mov_b32_e32 v14, v140
	v_mov_b32_e32 v15, v140
	v_mov_b32_e32 v16, v140
	v_mov_b32_e32 v17, v140
	v_mov_b32_e32 v18, v140
	v_mov_b32_e32 v19, v140
	v_mov_b32_e32 v28, v140
	v_mov_b32_e32 v29, v140
	v_mov_b32_e32 v30, v140
	v_mov_b32_e32 v31, v140
	v_mov_b32_e32 v32, v140
	v_mov_b32_e32 v33, v140
	v_mov_b32_e32 v34, v140
	v_mov_b32_e32 v35, v140
	v_mov_b32_e32 v36, v140
	v_mov_b32_e32 v37, v140
	v_mov_b32_e32 v38, v140
	v_mov_b32_e32 v39, v140
	v_mov_b32_e32 v44, v140
	v_mov_b32_e32 v45, v140
	v_mov_b32_e32 v46, v140
	v_mov_b32_e32 v47, v140
	v_mov_b32_e32 v52, v140
	v_mov_b32_e32 v53, v140
	v_mov_b32_e32 v54, v140
	v_mov_b32_e32 v55, v140
	v_mov_b32_e32 v56, v140
	v_mov_b32_e32 v57, v140
	v_mov_b32_e32 v58, v140
	v_mov_b32_e32 v59, v140
	v_mov_b32_e32 v64, v140
	v_mov_b32_e32 v65, v140
	v_mov_b32_e32 v66, v140
	v_mov_b32_e32 v67, v140
	v_mov_b32_e32 v72, v140
	v_mov_b32_e32 v73, v140
	v_mov_b32_e32 v74, v140
	v_mov_b32_e32 v75, v140
	v_mov_b32_e32 v76, v140
	v_mov_b32_e32 v77, v140
	v_mov_b32_e32 v78, v140
	v_mov_b32_e32 v79, v140
	v_mov_b32_e32 v84, v140
	v_mov_b32_e32 v85, v140
	v_mov_b32_e32 v86, v140
	v_mov_b32_e32 v87, v140
	v_mov_b32_e32 v92, v140
	v_mov_b32_e32 v93, v140
	v_mov_b32_e32 v94, v140
	v_mov_b32_e32 v95, v140
	v_mov_b32_e32 v96, v140
	v_mov_b32_e32 v97, v140
	v_mov_b32_e32 v98, v140
	v_mov_b32_e32 v99, v140
	v_mov_b32_e32 v108, v140
	v_mov_b32_e32 v109, v140
	v_mov_b32_e32 v110, v140
	v_mov_b32_e32 v111, v140
	v_mov_b32_e32 v120, v140
	v_mov_b32_e32 v121, v140
	v_mov_b32_e32 v122, v140
	v_mov_b32_e32 v123, v140
	v_mov_b32_e32 v124, v140
	v_mov_b32_e32 v125, v140
	v_mov_b32_e32 v126, v140
	v_mov_b32_e32 v127, v140
	v_mov_b32_e32 v128, v140
	v_mov_b32_e32 v129, v140
	v_mov_b32_e32 v130, v140
	v_mov_b32_e32 v131, v140
	v_mov_b32_e32 v132, v140
	v_mov_b32_e32 v133, v140
	v_mov_b32_e32 v134, v140
	v_mov_b32_e32 v135, v140
	v_mov_b32_e32 v136, v140
	v_mov_b32_e32 v137, v140
	v_mov_b32_e32 v138, v140
	v_mov_b32_e32 v139, v140
	v_mov_b32_e32 v144, v140
	v_mov_b32_e32 v145, v140
	v_mov_b32_e32 v146, v140
	v_mov_b32_e32 v147, v140
	v_mov_b32_e32 v148, v140
	v_mov_b32_e32 v149, v140
	v_mov_b32_e32 v150, v140
	v_mov_b32_e32 v151, v140
	v_mov_b32_e32 v152, v140
	v_mov_b32_e32 v153, v140
	v_mov_b32_e32 v154, v140
	v_mov_b32_e32 v155, v140
	v_mov_b32_e32 v156, v140
	v_mov_b32_e32 v157, v140
	v_mov_b32_e32 v158, v140
	v_mov_b32_e32 v159, v140
	v_mov_b32_e32 v160, v140
	v_mov_b32_e32 v161, v140
	v_mov_b32_e32 v162, v140
	v_mov_b32_e32 v163, v140
	v_mov_b32_e32 v164, v140
	v_mov_b32_e32 v165, v140
	v_mov_b32_e32 v166, v140
	v_mov_b32_e32 v167, v140
	v_mov_b32_e32 v168, v140
	v_mov_b32_e32 v169, v140
	v_mov_b32_e32 v170, v140
	v_mov_b32_e32 v171, v140
	v_mov_b32_e32 v172, v140
	v_mov_b32_e32 v173, v140
	v_mov_b32_e32 v174, v140
	v_mov_b32_e32 v175, v140
	s_mov_b32 s40, 0x820000
	s_mov_b32 s41, 0x830000
	v_readlane_b32 vcc_lo, v253, 0
	s_cmpk_lt_u32 vcc_lo, 0x100
	s_cbranch_scc1 .Lprio_hi7
	s_setprio 2
	s_branch .Lprio_done7

.Lprio_done7:
	v_readlane_b32 s98, v253, 3
	v_readlane_b32 s99, v253, 4
	v_and_b32_e32 v236, 15, v188
	v_bfe_u32 v237, v188, 4, 2
	v_lshrrev_b32_e32 v238, 2, v236
	v_sub_u32_e32 v238, 0, v238
	v_and_b32_e32 v238, 3, v238
	v_xor_b32_e32 v237, v237, v238
	v_lshlrev_b32_e32 v237, 4, v237
	v_lshl_or_b32 v237, v236, 6, v237
	v_bfe_u32 v238, v188, 7, 1
	v_lshl_or_b32 v185, v238, 13, v237
	v_bfe_u32 v238, v188, 6, 1
	v_lshl_or_b32 v184, v238, 12, v237
	v_add_u32_e32 v184, 0x4000, v184
	v_lshrrev_b32_e32 v236, 3, v188
	v_bfe_u32 v237, v188, 2, 1
	v_lshrrev_b32_e32 v238, 2, v236
	v_sub_u32_e32 v238, 0, v238
	v_and_b32_e32 v238, 3, v238
	v_and_b32_e32 v239, 3, v188
	v_xor_b32_e32 v238, v239, v238
	v_lshlrev_b32_e32 v238, 4, v238
	v_xor_b32_e32 v236, v236, v237
	v_lshl_or_b32 v238, v236, 6, v238
	v_mul_u32_u24_e32 v237, 0x6000, v237
	v_add_u32_e32 v183, v237, v238
	s_mov_b32 m0, 0
	s_sub_u32 vcc_lo, s30, s98
	v_add_u32_e32 v186, vcc_lo, v178
	v_add_u32_e32 v187, vcc_lo, v180
	s_barrier
	s_waitcnt vmcnt(0)
	ds_write_b128 v183, v[116:119]
	ds_write_b128 v183, v[112:115] offset:2048
	ds_write_b128 v183, v[104:107] offset:4096
	ds_write_b128 v183, v[88:91] offset:6144
	ds_write_b128 v183, v[80:83] offset:8192
	ds_write_b128 v183, v[68:71] offset:10240
	ds_write_b128 v183, v[60:63] offset:12288
	ds_write_b128 v183, v[48:51] offset:14336
	ds_write_b128 v183, v[100:103] offset:16384
	ds_write_b128 v183, v[40:43] offset:18432
	ds_write_b128 v183, v[24:27] offset:20480
	ds_write_b128 v183, v[20:23] offset:22528
	v_cmp_gt_u32_e32 vcc, 0x6000, v183
	v_add_u32_e32 v182, 0xc000, v183
	v_add_u32_e32 v183, 0xffffa000, v183
	s_nop 0
	v_cndmask_b32_e32 v183, v183, v182, vcc
	v_add_u32_e32 v116, s26, v186
	global_load_dwordx4 v[116:119], v116, s[98:99] offset:128
	v_add_u32_e32 v112, s27, v186
	global_load_dwordx4 v[112:115], v112, s[98:99] offset:128
	v_add_u32_e32 v104, s20, v186
	global_load_dwordx4 v[104:107], v104, s[98:99] offset:128
	v_add_u32_e32 v88, s21, v186
	global_load_dwordx4 v[88:91], v88, s[98:99] offset:128
	v_add_u32_e32 v80, s56, v186
	global_load_dwordx4 v[80:83], v80, s[98:99] offset:128
	v_add_u32_e32 v68, s57, v186
	global_load_dwordx4 v[68:71], v68, s[98:99] offset:128
	v_add_u32_e32 v60, s24, v186
	global_load_dwordx4 v[60:63], v60, s[98:99] offset:128
	v_add_u32_e32 v48, s96, v186
	global_load_dwordx4 v[48:51], v48, s[98:99] offset:128
	v_add_u32_e32 v100, s25, v187
	global_load_dwordx4 v[100:103], v100, s[98:99] offset:128
	v_add_u32_e32 v40, s33, v187
	global_load_dwordx4 v[40:43], v40, s[98:99] offset:128
	v_add_u32_e32 v24, s40, v187
	global_load_dwordx4 v[24:27], v24, s[98:99] offset:128
	v_add_u32_e32 v20, s41, v187
	global_load_dwordx4 v[20:23], v20, s[98:99] offset:128
	s_add_u32 s30, s30, 0x80
	s_addc_u32 s31, s31, 0
.LBB0_1066:
	s_waitcnt lgkmcnt(0)
	s_barrier
	ds_read_b128 v[236:239], v184
	ds_read_b128 v[240:243], v184 offset:1024
	ds_read_b128 v[244:247], v184 offset:2048
	ds_read_b128 v[248:251], v184 offset:3072
	ds_read_b128 v[204:207], v185
	ds_read_b128 v[208:211], v185 offset:1024
	ds_read_b128 v[212:215], v185 offset:2048
	ds_read_b128 v[216:219], v185 offset:3072
	ds_read_b128 v[220:223], v185 offset:4096
	ds_read_b128 v[224:227], v185 offset:5120
	ds_read_b128 v[228:231], v185 offset:6144
	ds_read_b128 v[232:235], v185 offset:7168
	s_movk_i32 vcc_lo, 0x6000
	s_cmp_eq_u32 m0, 2
	s_cselect_b32 vcc_lo, 0xffff4000, vcc_lo
	s_add_u32 m0, m0, 1
	s_cmp_eq_u32 m0, 3
	s_cselect_b32 m0, 0, m0
	v_add_u32_e32 v185, vcc_lo, v185
	v_add_u32_e32 v184, vcc_lo, v184
	v_xor_b32_e32 v185, 64, v185
	v_xor_b32_e32 v184, 64, v184
	s_waitcnt lgkmcnt(7)
	v_mfma_f32_16x16x32_bf16 v[172:175], v[236:239], v[204:207], v[172:175]
	v_mfma_f32_16x16x32_bf16 v[168:171], v[240:243], v[204:207], v[168:171]
	v_mfma_f32_16x16x32_bf16 v[164:167], v[244:247], v[204:207], v[164:167]
	v_mfma_f32_16x16x32_bf16 v[160:163], v[248:251], v[204:207], v[160:163]
	ds_read_b128 v[204:207], v185
	s_waitcnt lgkmcnt(7)
	v_mfma_f32_16x16x32_bf16 v[156:159], v[236:239], v[208:211], v[156:159]
	v_mfma_f32_16x16x32_bf16 v[152:155], v[240:243], v[208:211], v[152:155]
	v_mfma_f32_16x16x32_bf16 v[148:151], v[244:247], v[208:211], v[148:151]
	v_mfma_f32_16x16x32_bf16 v[144:147], v[248:251], v[208:211], v[144:147]
	ds_read_b128 v[208:211], v185 offset:1024
	s_waitcnt lgkmcnt(7)
	v_mfma_f32_16x16x32_bf16 v[136:139], v[236:239], v[212:215], v[136:139]
	v_mfma_f32_16x16x32_bf16 v[132:135], v[240:243], v[212:215], v[132:135]
	v_mfma_f32_16x16x32_bf16 v[128:131], v[244:247], v[212:215], v[128:131]
	v_mfma_f32_16x16x32_bf16 v[124:127], v[248:251], v[212:215], v[124:127]
	ds_read_b128 v[212:215], v185 offset:2048
	s_waitcnt lgkmcnt(7)
	v_mfma_f32_16x16x32_bf16 v[120:123], v[236:239], v[216:219], v[120:123]
	v_mfma_f32_16x16x32_bf16 v[108:111], v[240:243], v[216:219], v[108:111]
	v_mfma_f32_16x16x32_bf16 v[96:99], v[244:247], v[216:219], v[96:99]
	v_mfma_f32_16x16x32_bf16 v[92:95], v[248:251], v[216:219], v[92:95]
	ds_read_b128 v[216:219], v185 offset:3072
	s_waitcnt lgkmcnt(7)
	v_mfma_f32_16x16x32_bf16 v[84:87], v[236:239], v[220:223], v[84:87]
	v_mfma_f32_16x16x32_bf16 v[76:79], v[240:243], v[220:223], v[76:79]
	v_mfma_f32_16x16x32_bf16 v[72:75], v[244:247], v[220:223], v[72:75]
	v_mfma_f32_16x16x32_bf16 v[64:67], v[248:251], v[220:223], v[64:67]
	ds_read_b128 v[220:223], v185 offset:4096
	s_waitcnt lgkmcnt(7)
	v_mfma_f32_16x16x32_bf16 v[56:59], v[236:239], v[224:227], v[56:59]
	v_mfma_f32_16x16x32_bf16 v[52:55], v[240:243], v[224:227], v[52:55]
	v_mfma_f32_16x16x32_bf16 v[44:47], v[244:247], v[224:227], v[44:47]
	v_mfma_f32_16x16x32_bf16 v[36:39], v[248:251], v[224:227], v[36:39]
	ds_read_b128 v[224:227], v185 offset:5120
	s_waitcnt lgkmcnt(7)
	v_mfma_f32_16x16x32_bf16 v[32:35], v[236:239], v[228:231], v[32:35]
	v_mfma_f32_16x16x32_bf16 v[28:31], v[240:243], v[228:231], v[28:31]
	v_mfma_f32_16x16x32_bf16 v[16:19], v[244:247], v[228:231], v[16:19]
	v_mfma_f32_16x16x32_bf16 v[12:15], v[248:251], v[228:231], v[12:15]
	ds_read_b128 v[228:231], v185 offset:6144
	s_waitcnt lgkmcnt(7)
	v_mfma_f32_16x16x32_bf16 v[8:11], v[236:239], v[232:235], v[8:11]
	v_mfma_f32_16x16x32_bf16 v[4:7], v[240:243], v[232:235], v[4:7]
	v_mfma_f32_16x16x32_bf16 v[0:3], v[244:247], v[232:235], v[0:3]
	v_mfma_f32_16x16x32_bf16 v[140:143], v[248:251], v[232:235], v[140:143]
	ds_read_b128 v[232:235], v185 offset:7168
	ds_read_b128 v[236:239], v184
	ds_read_b128 v[240:243], v184 offset:1024
	ds_read_b128 v[244:247], v184 offset:2048
	ds_read_b128 v[248:251], v184 offset:3072
	s_movk_i32 vcc_lo, 0x6000
	s_cmp_eq_u32 m0, 2
	s_cselect_b32 vcc_lo, 0xffff4000, vcc_lo
	s_add_u32 m0, m0, 1
	s_cmp_eq_u32 m0, 3
	s_cselect_b32 m0, 0, m0
	v_add_u32_e32 v185, vcc_lo, v185
	v_add_u32_e32 v184, vcc_lo, v184
	v_xor_b32_e32 v185, 64, v185
	v_xor_b32_e32 v184, 64, v184
	s_sub_u32 vcc_lo, s30, s98
	v_add_u32_e32 v186, vcc_lo, v178
	v_add_u32_e32 v187, vcc_lo, v180
	s_barrier
	s_waitcnt lgkmcnt(0)
	v_mfma_f32_16x16x32_bf16 v[172:175], v[236:239], v[204:207], v[172:175]
	s_waitcnt vmcnt(11)
	v_mfma_f32_16x16x32_bf16 v[168:171], v[240:243], v[204:207], v[168:171]
	ds_write_b128 v183, v[116:119]
	v_add_u32_e32 v116, s26, v186
	v_mfma_f32_16x16x32_bf16 v[164:167], v[244:247], v[204:207], v[164:167]
	global_load_dwordx4 v[116:119], v116, s[98:99] offset:128
	v_mfma_f32_16x16x32_bf16 v[160:163], v[248:251], v[204:207], v[160:163]
	s_waitcnt vmcnt(11)
	ds_write_b128 v183, v[112:115] offset:2048
	v_mfma_f32_16x16x32_bf16 v[156:159], v[236:239], v[208:211], v[156:159]
	v_add_u32_e32 v112, s27, v186
	v_mfma_f32_16x16x32_bf16 v[152:155], v[240:243], v[208:211], v[152:155]
	global_load_dwordx4 v[112:115], v112, s[98:99] offset:128
	s_waitcnt vmcnt(11)
	v_mfma_f32_16x16x32_bf16 v[148:151], v[244:247], v[208:211], v[148:151]
	ds_write_b128 v183, v[104:107] offset:4096
	v_mfma_f32_16x16x32_bf16 v[144:147], v[248:251], v[208:211], v[144:147]
	v_add_u32_e32 v104, s20, v186
	global_load_dwordx4 v[104:107], v104, s[98:99] offset:128
	v_mfma_f32_16x16x32_bf16 v[136:139], v[236:239], v[212:215], v[136:139]
	s_waitcnt vmcnt(11)
	v_mfma_f32_16x16x32_bf16 v[132:135], v[240:243], v[212:215], v[132:135]
	ds_write_b128 v183, v[88:91] offset:6144
	v_add_u32_e32 v88, s21, v186
	v_mfma_f32_16x16x32_bf16 v[128:131], v[244:247], v[212:215], v[128:131]
	global_load_dwordx4 v[88:91], v88, s[98:99] offset:128
	v_mfma_f32_16x16x32_bf16 v[124:127], v[248:251], v[212:215], v[124:127]
	s_waitcnt vmcnt(11)
	ds_write_b128 v183, v[80:83] offset:8192
	v_mfma_f32_16x16x32_bf16 v[120:123], v[236:239], v[216:219], v[120:123]
	v_add_u32_e32 v80, s56, v186
	v_mfma_f32_16x16x32_bf16 v[108:111], v[240:243], v[216:219], v[108:111]
	global_load_dwordx4 v[80:83], v80, s[98:99] offset:128
	s_waitcnt vmcnt(11)
	v_mfma_f32_16x16x32_bf16 v[96:99], v[244:247], v[216:219], v[96:99]
	ds_write_b128 v183, v[68:71] offset:10240
	v_mfma_f32_16x16x32_bf16 v[92:95], v[248:251], v[216:219], v[92:95]
	v_add_u32_e32 v68, s57, v186
	global_load_dwordx4 v[68:71], v68, s[98:99] offset:128
	v_mfma_f32_16x16x32_bf16 v[84:87], v[236:239], v[220:223], v[84:87]
	s_waitcnt vmcnt(11)
	v_mfma_f32_16x16x32_bf16 v[76:79], v[240:243], v[220:223], v[76:79]
	ds_write_b128 v183, v[60:63] offset:12288
	v_add_u32_e32 v60, s24, v186
	v_mfma_f32_16x16x32_bf16 v[72:75], v[244:247], v[220:223], v[72:75]
	global_load_dwordx4 v[60:63], v60, s[98:99] offset:128
	v_mfma_f32_16x16x32_bf16 v[64:67], v[248:251], v[220:223], v[64:67]
	s_waitcnt vmcnt(11)
	ds_write_b128 v183, v[48:51] offset:14336
	v_mfma_f32_16x16x32_bf16 v[56:59], v[236:239], v[224:227], v[56:59]
	v_add_u32_e32 v48, s96, v186
	v_mfma_f32_16x16x32_bf16 v[52:55], v[240:243], v[224:227], v[52:55]
	global_load_dwordx4 v[48:51], v48, s[98:99] offset:128
	s_waitcnt vmcnt(11)
	v_mfma_f32_16x16x32_bf16 v[44:47], v[244:247], v[224:227], v[44:47]
	ds_write_b128 v183, v[100:103] offset:16384
	v_mfma_f32_16x16x32_bf16 v[36:39], v[248:251], v[224:227], v[36:39]
	v_add_u32_e32 v100, s25, v187
	global_load_dwordx4 v[100:103], v100, s[98:99] offset:128
	v_mfma_f32_16x16x32_bf16 v[32:35], v[236:239], v[228:231], v[32:35]
	s_waitcnt vmcnt(11)
	v_mfma_f32_16x16x32_bf16 v[28:31], v[240:243], v[228:231], v[28:31]
	ds_write_b128 v183, v[40:43] offset:18432
	v_add_u32_e32 v40, s33, v187
	v_mfma_f32_16x16x32_bf16 v[16:19], v[244:247], v[228:231], v[16:19]
	global_load_dwordx4 v[40:43], v40, s[98:99] offset:128
	v_mfma_f32_16x16x32_bf16 v[12:15], v[248:251], v[228:231], v[12:15]
	s_waitcnt vmcnt(11)
	ds_write_b128 v183, v[24:27] offset:20480
	v_mfma_f32_16x16x32_bf16 v[8:11], v[236:239], v[232:235], v[8:11]
	v_add_u32_e32 v24, s40, v187
	v_mfma_f32_16x16x32_bf16 v[4:7], v[240:243], v[232:235], v[4:7]
	global_load_dwordx4 v[24:27], v24, s[98:99] offset:128
	s_waitcnt vmcnt(11)
	v_mfma_f32_16x16x32_bf16 v[0:3], v[244:247], v[232:235], v[0:3]
	ds_write_b128 v183, v[20:23] offset:22528
	v_mfma_f32_16x16x32_bf16 v[140:143], v[248:251], v[232:235], v[140:143]
	v_add_u32_e32 v20, s41, v187
	global_load_dwordx4 v[20:23], v20, s[98:99] offset:128
	v_cmp_gt_u32_e32 vcc, 0x6000, v183
	v_add_u32_e32 v182, 0xc000, v183
	v_add_u32_e32 v183, 0xffffa000, v183
	s_nop 0
	v_cndmask_b32_e32 v183, v183, v182, vcc
	s_add_u32 s30, s30, 0x80
	s_addc_u32 s31, s31, 0
	s_cmpk_eq_i32 s30, 0x780
	s_cbranch_scc0 .LBB0_1066
	s_waitcnt lgkmcnt(0)
	s_barrier
	ds_read_b128 v[236:239], v184
	ds_read_b128 v[240:243], v184 offset:1024
	ds_read_b128 v[244:247], v184 offset:2048
	ds_read_b128 v[248:251], v184 offset:3072
	ds_read_b128 v[204:207], v185
	ds_read_b128 v[208:211], v185 offset:1024
	ds_read_b128 v[212:215], v185 offset:2048
	ds_read_b128 v[216:219], v185 offset:3072
	ds_read_b128 v[220:223], v185 offset:4096
	ds_read_b128 v[224:227], v185 offset:5120
	ds_read_b128 v[228:231], v185 offset:6144
	ds_read_b128 v[232:235], v185 offset:7168
	s_movk_i32 vcc_lo, 0x6000
	s_cmp_eq_u32 m0, 2
	s_cselect_b32 vcc_lo, 0xffff4000, vcc_lo
	s_add_u32 m0, m0, 1
	s_cmp_eq_u32 m0, 3
	s_cselect_b32 m0, 0, m0
	v_add_u32_e32 v185, vcc_lo, v185
	v_add_u32_e32 v184, vcc_lo, v184
	v_xor_b32_e32 v185, 64, v185
	v_xor_b32_e32 v184, 64, v184
	s_waitcnt lgkmcnt(7)
	v_mfma_f32_16x16x32_bf16 v[172:175], v[236:239], v[204:207], v[172:175]
	v_mfma_f32_16x16x32_bf16 v[168:171], v[240:243], v[204:207], v[168:171]
	v_mfma_f32_16x16x32_bf16 v[164:167], v[244:247], v[204:207], v[164:167]
	v_mfma_f32_16x16x32_bf16 v[160:163], v[248:251], v[204:207], v[160:163]
	ds_read_b128 v[204:207], v185
	s_waitcnt lgkmcnt(7)
	v_mfma_f32_16x16x32_bf16 v[156:159], v[236:239], v[208:211], v[156:159]
	v_mfma_f32_16x16x32_bf16 v[152:155], v[240:243], v[208:211], v[152:155]
	v_mfma_f32_16x16x32_bf16 v[148:151], v[244:247], v[208:211], v[148:151]
	v_mfma_f32_16x16x32_bf16 v[144:147], v[248:251], v[208:211], v[144:147]
	ds_read_b128 v[208:211], v185 offset:1024
	s_waitcnt lgkmcnt(7)
	v_mfma_f32_16x16x32_bf16 v[136:139], v[236:239], v[212:215], v[136:139]
	v_mfma_f32_16x16x32_bf16 v[132:135], v[240:243], v[212:215], v[132:135]
	v_mfma_f32_16x16x32_bf16 v[128:131], v[244:247], v[212:215], v[128:131]
	v_mfma_f32_16x16x32_bf16 v[124:127], v[248:251], v[212:215], v[124:127]
	ds_read_b128 v[212:215], v185 offset:2048
	s_waitcnt lgkmcnt(7)
	v_mfma_f32_16x16x32_bf16 v[120:123], v[236:239], v[216:219], v[120:123]
	v_mfma_f32_16x16x32_bf16 v[108:111], v[240:243], v[216:219], v[108:111]
	v_mfma_f32_16x16x32_bf16 v[96:99], v[244:247], v[216:219], v[96:99]
	v_mfma_f32_16x16x32_bf16 v[92:95], v[248:251], v[216:219], v[92:95]
	ds_read_b128 v[216:219], v185 offset:3072
	s_waitcnt lgkmcnt(7)
	v_mfma_f32_16x16x32_bf16 v[84:87], v[236:239], v[220:223], v[84:87]
	v_mfma_f32_16x16x32_bf16 v[76:79], v[240:243], v[220:223], v[76:79]
	v_mfma_f32_16x16x32_bf16 v[72:75], v[244:247], v[220:223], v[72:75]
	v_mfma_f32_16x16x32_bf16 v[64:67], v[248:251], v[220:223], v[64:67]
	ds_read_b128 v[220:223], v185 offset:4096
	s_waitcnt lgkmcnt(7)
	v_mfma_f32_16x16x32_bf16 v[56:59], v[236:239], v[224:227], v[56:59]
	v_mfma_f32_16x16x32_bf16 v[52:55], v[240:243], v[224:227], v[52:55]
	v_mfma_f32_16x16x32_bf16 v[44:47], v[244:247], v[224:227], v[44:47]
	v_mfma_f32_16x16x32_bf16 v[36:39], v[248:251], v[224:227], v[36:39]
	ds_read_b128 v[224:227], v185 offset:5120
	s_waitcnt lgkmcnt(7)
	v_mfma_f32_16x16x32_bf16 v[32:35], v[236:239], v[228:231], v[32:35]
	v_mfma_f32_16x16x32_bf16 v[28:31], v[240:243], v[228:231], v[28:31]
	v_mfma_f32_16x16x32_bf16 v[16:19], v[244:247], v[228:231], v[16:19]
	v_mfma_f32_16x16x32_bf16 v[12:15], v[248:251], v[228:231], v[12:15]
	ds_read_b128 v[228:231], v185 offset:6144
	s_waitcnt lgkmcnt(7)
	v_mfma_f32_16x16x32_bf16 v[8:11], v[236:239], v[232:235], v[8:11]
	v_mfma_f32_16x16x32_bf16 v[4:7], v[240:243], v[232:235], v[4:7]
	v_mfma_f32_16x16x32_bf16 v[0:3], v[244:247], v[232:235], v[0:3]
	v_mfma_f32_16x16x32_bf16 v[140:143], v[248:251], v[232:235], v[140:143]
	ds_read_b128 v[232:235], v185 offset:7168
	ds_read_b128 v[236:239], v184
	ds_read_b128 v[240:243], v184 offset:1024
	ds_read_b128 v[244:247], v184 offset:2048
	ds_read_b128 v[248:251], v184 offset:3072
	s_movk_i32 vcc_lo, 0x6000
	s_cmp_eq_u32 m0, 2
	s_cselect_b32 vcc_lo, 0xffff4000, vcc_lo
	s_add_u32 m0, m0, 1
	s_cmp_eq_u32 m0, 3
	s_cselect_b32 m0, 0, m0
	v_add_u32_e32 v185, vcc_lo, v185
	v_add_u32_e32 v184, vcc_lo, v184
	v_xor_b32_e32 v185, 64, v185
	v_xor_b32_e32 v184, 64, v184
	s_waitcnt lgkmcnt(0)
	v_mfma_f32_16x16x32_bf16 v[172:175], v[236:239], v[204:207], v[172:175]
	v_mfma_f32_16x16x32_bf16 v[168:171], v[240:243], v[204:207], v[168:171]
	v_mfma_f32_16x16x32_bf16 v[164:167], v[244:247], v[204:207], v[164:167]
	v_mfma_f32_16x16x32_bf16 v[160:163], v[248:251], v[204:207], v[160:163]
	v_mfma_f32_16x16x32_bf16 v[156:159], v[236:239], v[208:211], v[156:159]
	v_mfma_f32_16x16x32_bf16 v[152:155], v[240:243], v[208:211], v[152:155]
	v_mfma_f32_16x16x32_bf16 v[148:151], v[244:247], v[208:211], v[148:151]
	v_mfma_f32_16x16x32_bf16 v[144:147], v[248:251], v[208:211], v[144:147]
	v_mfma_f32_16x16x32_bf16 v[136:139], v[236:239], v[212:215], v[136:139]
	v_mfma_f32_16x16x32_bf16 v[132:135], v[240:243], v[212:215], v[132:135]
	v_mfma_f32_16x16x32_bf16 v[128:131], v[244:247], v[212:215], v[128:131]
	v_mfma_f32_16x16x32_bf16 v[124:127], v[248:251], v[212:215], v[124:127]
	v_mfma_f32_16x16x32_bf16 v[120:123], v[236:239], v[216:219], v[120:123]
	v_mfma_f32_16x16x32_bf16 v[108:111], v[240:243], v[216:219], v[108:111]
	v_mfma_f32_16x16x32_bf16 v[96:99], v[244:247], v[216:219], v[96:99]
	v_mfma_f32_16x16x32_bf16 v[92:95], v[248:251], v[216:219], v[92:95]
	v_mfma_f32_16x16x32_bf16 v[84:87], v[236:239], v[220:223], v[84:87]
	v_mfma_f32_16x16x32_bf16 v[76:79], v[240:243], v[220:223], v[76:79]
	v_mfma_f32_16x16x32_bf16 v[72:75], v[244:247], v[220:223], v[72:75]
	v_mfma_f32_16x16x32_bf16 v[64:67], v[248:251], v[220:223], v[64:67]
	v_mfma_f32_16x16x32_bf16 v[56:59], v[236:239], v[224:227], v[56:59]
	v_mfma_f32_16x16x32_bf16 v[52:55], v[240:243], v[224:227], v[52:55]
	v_mfma_f32_16x16x32_bf16 v[44:47], v[244:247], v[224:227], v[44:47]
	v_mfma_f32_16x16x32_bf16 v[36:39], v[248:251], v[224:227], v[36:39]
	v_mfma_f32_16x16x32_bf16 v[32:35], v[236:239], v[228:231], v[32:35]
	v_mfma_f32_16x16x32_bf16 v[28:31], v[240:243], v[228:231], v[28:31]
	v_mfma_f32_16x16x32_bf16 v[16:19], v[244:247], v[228:231], v[16:19]
	v_mfma_f32_16x16x32_bf16 v[12:15], v[248:251], v[228:231], v[12:15]
	v_mfma_f32_16x16x32_bf16 v[8:11], v[236:239], v[232:235], v[8:11]
	v_mfma_f32_16x16x32_bf16 v[4:7], v[240:243], v[232:235], v[4:7]
	v_mfma_f32_16x16x32_bf16 v[0:3], v[244:247], v[232:235], v[0:3]
	v_mfma_f32_16x16x32_bf16 v[140:143], v[248:251], v[232:235], v[140:143]
	v_lshrrev_b32_e32 v236, 4, v188
	v_and_b32_e32 v237, 7, v188
	v_bitop3_b32 v238, v236, v237, 3 bitop3:0x6c
	v_lshlrev_b32_e32 v239, 7, v188
	v_bfe_u32 v240, v188, 4, 2
	v_and_b32_e32 v241, 0xffffc780, v239
	v_and_b32_e32 v239, 0x2780, v239
	v_bitop3_b32 v240, v240, v237, 4 bitop3:0x36
	v_lshlrev_b32_e32 v238, 4, v238
	v_lshlrev_b32_e32 v240, 4, v240
	v_or_b32_e32 v185, v241, v238
	v_or_b32_e32 v184, v239, v238
	v_or_b32_e32 v183, v241, v240
	v_or_b32_e32 v182, v239, v240
	s_waitcnt vmcnt(0)
	s_setprio 1
	s_barrier
	s_waitcnt vmcnt(11)
	ds_write_b128 v176, v[116:119]
	s_waitcnt vmcnt(10)
	ds_write_b128 v176, v[112:115] offset:4096
	s_waitcnt vmcnt(9)
	ds_write_b128 v176, v[104:107] offset:8192
	s_waitcnt vmcnt(8)
	ds_write_b128 v176, v[88:91] offset:12288
	s_waitcnt vmcnt(7)
	ds_write_b128 v176, v[80:83] offset:16384
	s_waitcnt vmcnt(6)
	ds_write_b128 v176, v[68:71] offset:20480
	s_waitcnt vmcnt(5)
	ds_write_b128 v176, v[60:63] offset:24576
	s_waitcnt vmcnt(4)
	ds_write_b128 v176, v[48:51] offset:28672
	s_waitcnt vmcnt(3)
	ds_write_b128 v176, v[100:103] offset:32768
	s_waitcnt vmcnt(2)
	ds_write_b128 v176, v[40:43] offset:36864
	s_waitcnt vmcnt(1)
	ds_write_b128 v176, v[24:27] offset:40960
	s_waitcnt vmcnt(0)
	ds_write_b128 v176, v[20:23] offset:45056
	s_waitcnt lgkmcnt(0)
	s_barrier
	ds_read_b128 v[20:23], v185
	ds_read_b128 v[24:27], v185 offset:2048
	ds_read_b128 v[40:43], v185 offset:4096
	ds_read_b128 v[48:51], v185 offset:6144
	ds_read_b128 v[60:63], v185 offset:8192
	ds_read_b128 v[68:71], v185 offset:10240
	ds_read_b128 v[80:83], v185 offset:12288
	ds_read_b128 v[88:91], v185 offset:14336
	ds_read_b128 v[100:103], v184 offset:32768
	ds_read_b128 v[104:107], v184 offset:34816
	ds_read_b128 v[112:115], v184 offset:36864
	ds_read_b128 v[116:119], v184 offset:38912
	s_waitcnt lgkmcnt(3)
	v_mfma_f32_16x16x32_bf16 v[172:175], v[100:103], v[20:23], v[172:175]
	s_waitcnt lgkmcnt(2)
	v_mfma_f32_16x16x32_bf16 v[168:171], v[104:107], v[20:23], v[168:171]
	s_waitcnt lgkmcnt(1)
	v_mfma_f32_16x16x32_bf16 v[164:167], v[112:115], v[20:23], v[164:167]
	s_waitcnt lgkmcnt(0)
	v_mfma_f32_16x16x32_bf16 v[20:23], v[116:119], v[20:23], v[160:163]
	v_mfma_f32_16x16x32_bf16 v[156:159], v[100:103], v[24:27], v[156:159]
	v_mfma_f32_16x16x32_bf16 v[152:155], v[104:107], v[24:27], v[152:155]
	v_mfma_f32_16x16x32_bf16 v[148:151], v[112:115], v[24:27], v[148:151]
	v_mfma_f32_16x16x32_bf16 v[24:27], v[116:119], v[24:27], v[144:147]
	v_mfma_f32_16x16x32_bf16 v[136:139], v[100:103], v[40:43], v[136:139]
	v_mfma_f32_16x16x32_bf16 v[132:135], v[104:107], v[40:43], v[132:135]
	v_mfma_f32_16x16x32_bf16 v[128:131], v[112:115], v[40:43], v[128:131]
	v_mfma_f32_16x16x32_bf16 v[40:43], v[116:119], v[40:43], v[124:127]
	v_mfma_f32_16x16x32_bf16 v[144:147], v[100:103], v[48:51], v[120:123]
	v_mfma_f32_16x16x32_bf16 v[160:163], v[104:107], v[48:51], v[108:111]
	v_mfma_f32_16x16x32_bf16 v[178:181], v[112:115], v[48:51], v[96:99]
	v_mfma_f32_16x16x32_bf16 v[48:51], v[116:119], v[48:51], v[92:95]
	v_mfma_f32_16x16x32_bf16 v[184:187], v[100:103], v[60:63], v[84:87]
	v_mfma_f32_16x16x32_bf16 v[16:19], v[112:115], v[80:83], v[16:19]
	v_mfma_f32_16x16x32_bf16 v[12:15], v[116:119], v[80:83], v[12:15]
	v_mfma_f32_16x16x32_bf16 v[8:11], v[100:103], v[88:91], v[8:11]
	v_mfma_f32_16x16x32_bf16 v[4:7], v[104:107], v[88:91], v[4:7]
	v_mfma_f32_16x16x32_bf16 v[0:3], v[112:115], v[88:91], v[0:3]
	v_mfma_f32_16x16x32_bf16 v[190:193], v[104:107], v[60:63], v[76:79]
	v_mfma_f32_16x16x32_bf16 v[194:197], v[112:115], v[60:63], v[72:75]
	v_mfma_f32_16x16x32_bf16 v[198:201], v[116:119], v[60:63], v[64:67]
	v_mfma_f32_16x16x32_bf16 v[56:59], v[100:103], v[68:71], v[56:59]
	v_mfma_f32_16x16x32_bf16 v[52:55], v[104:107], v[68:71], v[52:55]
	v_mfma_f32_16x16x32_bf16 v[204:207], v[112:115], v[68:71], v[44:47]
	v_mfma_f32_16x16x32_bf16 v[208:211], v[116:119], v[68:71], v[36:39]
	v_mfma_f32_16x16x32_bf16 v[212:215], v[100:103], v[80:83], v[32:35]
	v_mfma_f32_16x16x32_bf16 v[216:219], v[104:107], v[80:83], v[28:31]
	v_mfma_f32_16x16x32_bf16 v[140:143], v[116:119], v[88:91], v[140:143]
	s_nop 1
	ds_read_b128 v[28:31], v183
	ds_read_b128 v[32:35], v183 offset:2048
	ds_read_b128 v[36:39], v183 offset:4096
	ds_read_b128 v[44:47], v183 offset:6144
	ds_read_b128 v[220:223], v183 offset:8192
	ds_read_b128 v[224:227], v183 offset:10240
	ds_read_b128 v[228:231], v183 offset:12288
	ds_read_b128 v[232:235], v183 offset:14336
	ds_read_b128 v[236:239], v182 offset:32768
	ds_read_b128 v[240:243], v182 offset:34816
	ds_read_b128 v[244:247], v182 offset:36864
	ds_read_b128 v[248:251], v182 offset:38912
	s_waitcnt lgkmcnt(3)
	v_mfma_f32_16x16x32_bf16 v[124:127], v[236:239], v[28:31], v[172:175]
	s_mov_b64 s[30:31], 0
	s_waitcnt lgkmcnt(2)
	v_mfma_f32_16x16x32_bf16 v[120:123], v[240:243], v[28:31], v[168:171]
	s_waitcnt lgkmcnt(1)
	v_mfma_f32_16x16x32_bf16 v[116:119], v[244:247], v[28:31], v[164:167]
	s_waitcnt lgkmcnt(0)
	v_mfma_f32_16x16x32_bf16 v[112:115], v[248:251], v[28:31], v[20:23]
	v_mfma_f32_16x16x32_bf16 v[108:111], v[236:239], v[32:35], v[156:159]
	v_mfma_f32_16x16x32_bf16 v[104:107], v[240:243], v[32:35], v[152:155]
	v_mfma_f32_16x16x32_bf16 v[100:103], v[244:247], v[32:35], v[148:151]
	v_mfma_f32_16x16x32_bf16 v[96:99], v[248:251], v[32:35], v[24:27]
	v_mfma_f32_16x16x32_bf16 v[92:95], v[236:239], v[36:39], v[136:139]
	v_mfma_f32_16x16x32_bf16 v[88:91], v[240:243], v[36:39], v[132:135]
	v_mfma_f32_16x16x32_bf16 v[84:87], v[244:247], v[36:39], v[128:131]
	v_mfma_f32_16x16x32_bf16 v[80:83], v[248:251], v[36:39], v[40:43]
	v_mfma_f32_16x16x32_bf16 v[76:79], v[236:239], v[44:47], v[144:147]
	v_mfma_f32_16x16x32_bf16 v[72:75], v[240:243], v[44:47], v[160:163]
	v_mfma_f32_16x16x32_bf16 v[68:71], v[244:247], v[44:47], v[178:181]
	v_mfma_f32_16x16x32_bf16 v[64:67], v[248:251], v[44:47], v[48:51]
	v_mfma_f32_16x16x32_bf16 v[60:63], v[236:239], v[220:223], v[184:187]
	v_mfma_f32_16x16x32_bf16 v[184:187], v[240:243], v[220:223], v[190:193]
	v_mfma_f32_16x16x32_bf16 v[180:183], v[244:247], v[220:223], v[194:197]
	v_mfma_f32_16x16x32_bf16 v[48:51], v[248:251], v[220:223], v[198:201]
	v_mfma_f32_16x16x32_bf16 v[44:47], v[236:239], v[224:227], v[56:59]
	v_mfma_f32_16x16x32_bf16 v[40:43], v[240:243], v[224:227], v[52:55]
	v_mfma_f32_16x16x32_bf16 v[36:39], v[244:247], v[224:227], v[204:207]
	v_mfma_f32_16x16x32_bf16 v[32:35], v[248:251], v[224:227], v[208:211]
	v_mfma_f32_16x16x32_bf16 v[28:31], v[236:239], v[228:231], v[212:215]
	v_mfma_f32_16x16x32_bf16 v[24:27], v[240:243], v[228:231], v[216:219]
	v_mfma_f32_16x16x32_bf16 v[20:23], v[244:247], v[228:231], v[16:19]
	v_mfma_f32_16x16x32_bf16 v[16:19], v[248:251], v[228:231], v[12:15]
	v_mfma_f32_16x16x32_bf16 v[12:15], v[236:239], v[232:235], v[8:11]
	v_mfma_f32_16x16x32_bf16 v[8:11], v[240:243], v[232:235], v[4:7]
	v_xor_b32_e32 v240, 32, v203
	v_mfma_f32_16x16x32_bf16 v[4:7], v[244:247], v[232:235], v[0:3]
	v_mfma_f32_16x16x32_bf16 v[0:3], v[248:251], v[232:235], v[140:143]
.LBB0_1068:
	s_and_b64 vcc, exec, s[30:31]
	s_cbranch_vccz .LBB0_1072
	s_nop 2
	v_mov_b32_e32 v8, v188
	s_mov_b32 s30, 0x20000
	v_ashrrev_i32_e32 v9, 3, v8
	v_lshlrev_b32_e32 v4, 4, v8
	v_and_b32_e32 v176, 0x70, v4
	v_add_u32_e32 v4, s53, v9
	v_add_u32_e32 v0, s38, v9
	v_ashrrev_i32_e32 v5, 31, v4
	v_ashrrev_i32_e32 v1, 31, v0
	v_lshlrev_b64 v[4:5], 11, v[4:5]
	v_xor_b32_e32 v10, v9, v8
	v_lshlrev_b64 v[0:1], 11, v[0:1]
	v_lshl_add_u64 v[6:7], s[2:3], 0, v[4:5]
	v_lshlrev_b32_e32 v10, 4, v10
	v_lshl_add_u64 v[2:3], s[0:1], 0, v[0:1]
	v_lshl_add_u64 v[6:7], v[6:7], 0, v[176:177]
	v_and_b32_e32 v10, 0x70, v10
	v_lshl_add_u64 v[2:3], v[2:3], 0, v[176:177]
	v_lshl_or_b32 v176, v9, 7, v10
	v_lshlrev_b32_e32 v12, 7, v8
	v_lshrrev_b32_e32 v9, 4, v8
	v_bfe_u32 v14, v8, 4, 2
	v_and_b32_e32 v15, 7, v8
	v_add_co_u32_e32 v8, vcc, s39, v6
	v_bitop3_b32 v16, v9, v15, 3 bitop3:0x6c
	s_nop 0
	v_addc_co_u32_e32 v9, vcc, 0, v7, vcc
	v_add_co_u32_e32 v10, vcc, s30, v6
	s_mov_b32 s31, 0x10000
	s_nop 0
	v_addc_co_u32_e32 v11, vcc, 0, v7, vcc
	global_load_dwordx4 v[20:23], v[8:9], off
	global_load_dwordx4 v[24:27], v[10:11], off
	v_add_co_u32_e32 v8, vcc, s31, v6
	s_mov_b32 s40, 0x70000
	s_nop 0
	v_addc_co_u32_e32 v9, vcc, 0, v7, vcc
	v_add_co_u32_e32 v10, vcc, s40, v2
	s_mov_b32 s40, 0x60000
	s_nop 0
	v_addc_co_u32_e32 v11, vcc, 0, v3, vcc
	global_load_dwordx4 v[40:43], v[8:9], off
	global_load_dwordx4 v[48:51], v[10:11], off
	v_add_co_u32_e32 v8, vcc, s40, v2
	s_mov_b32 s40, 0x50000
	s_nop 0
	v_addc_co_u32_e32 v9, vcc, 0, v3, vcc
	v_add_co_u32_e32 v10, vcc, s40, v2
	s_mov_b32 s40, 0x40000
	s_nop 0
	v_addc_co_u32_e32 v11, vcc, 0, v3, vcc
	global_load_dwordx4 v[60:63], v[8:9], off
	global_load_dwordx4 v[68:71], v[10:11], off
	v_add_co_u32_e32 v8, vcc, s40, v2
	v_and_b32_e32 v13, 0xffffc780, v12
	s_nop 0
	v_addc_co_u32_e32 v9, vcc, 0, v3, vcc
	v_add_co_u32_e32 v10, vcc, s39, v2
	v_and_b32_e32 v12, 0x2780, v12
	s_nop 0
	v_addc_co_u32_e32 v11, vcc, 0, v3, vcc
	global_load_dwordx4 v[80:83], v[8:9], off
	global_load_dwordx4 v[88:91], v[10:11], off
	v_add_co_u32_e32 v8, vcc, s30, v2
	v_bitop3_b32 v14, v14, v15, 4 bitop3:0x36
	s_nop 0
	v_addc_co_u32_e32 v9, vcc, 0, v3, vcc
	v_add_co_u32_e32 v10, vcc, s31, v2
	v_mov_b32_e32 v140, 0
	s_nop 0
	v_addc_co_u32_e32 v11, vcc, 0, v3, vcc
	global_load_dwordx4 v[104:107], v[8:9], off
	global_load_dwordx4 v[112:115], v[10:11], off
	global_load_dwordx4 v[100:103], v[6:7], off
	global_load_dwordx4 v[116:119], v[2:3], off
	v_lshlrev_b32_e32 v2, 4, v16
	v_or_b32_e32 v185, v13, v2
	v_or_b32_e32 v184, v12, v2
	v_lshlrev_b32_e32 v2, 4, v14
	v_or_b32_e32 v183, v13, v2
	v_or_b32_e32 v182, v12, v2
	v_lshlrev_b32_e32 v2, 4, v15
	v_or_b32_e32 v0, v0, v2
	v_or_b32_e32 v4, v4, v2
	v_lshl_add_u64 v[178:179], s[34:35], 0, v[0:1]
	v_lshl_add_u64 v[180:181], s[50:51], 0, v[4:5]
	s_mov_b64 s[30:31], 0
	v_mov_b32_e32 v141, v140
	v_mov_b32_e32 v142, v140
	v_mov_b32_e32 v143, v140
	v_mov_b32_e32 v0, v140
	v_mov_b32_e32 v1, v140
	v_mov_b32_e32 v2, v140
	v_mov_b32_e32 v3, v140
	v_mov_b32_e32 v4, v140
	v_mov_b32_e32 v5, v140
	v_mov_b32_e32 v6, v140
	v_mov_b32_e32 v7, v140
	v_mov_b32_e32 v8, v140
	v_mov_b32_e32 v9, v140
	v_mov_b32_e32 v10, v140
	v_mov_b32_e32 v11, v140
	v_mov_b32_e32 v12, v140
	v_mov_b32_e32 v13, v140
	v_mov_b32_e32 v14, v140
	v_mov_b32_e32 v15, v140
	v_mov_b32_e32 v16, v140
	v_mov_b32_e32 v17, v140
	v_mov_b32_e32 v18, v140
	v_mov_b32_e32 v19, v140
	v_mov_b32_e32 v28, v140
	v_mov_b32_e32 v29, v140
	v_mov_b32_e32 v30, v140
	v_mov_b32_e32 v31, v140
	v_mov_b32_e32 v32, v140
	v_mov_b32_e32 v33, v140
	v_mov_b32_e32 v34, v140
	v_mov_b32_e32 v35, v140
	v_mov_b32_e32 v36, v140
	v_mov_b32_e32 v37, v140
	v_mov_b32_e32 v38, v140
	v_mov_b32_e32 v39, v140
	v_mov_b32_e32 v44, v140
	v_mov_b32_e32 v45, v140
	v_mov_b32_e32 v46, v140
	v_mov_b32_e32 v47, v140
	v_mov_b32_e32 v52, v140
	v_mov_b32_e32 v53, v140
	v_mov_b32_e32 v54, v140
	v_mov_b32_e32 v55, v140
	v_mov_b32_e32 v56, v140
	v_mov_b32_e32 v57, v140
	v_mov_b32_e32 v58, v140
	v_mov_b32_e32 v59, v140
	v_mov_b32_e32 v64, v140
	v_mov_b32_e32 v65, v140
	v_mov_b32_e32 v66, v140
	v_mov_b32_e32 v67, v140
	v_mov_b32_e32 v72, v140
	v_mov_b32_e32 v73, v140
	v_mov_b32_e32 v74, v140
	v_mov_b32_e32 v75, v140
	v_mov_b32_e32 v76, v140
	v_mov_b32_e32 v77, v140
	v_mov_b32_e32 v78, v140
	v_mov_b32_e32 v79, v140
	v_mov_b32_e32 v84, v140
	v_mov_b32_e32 v85, v140
	v_mov_b32_e32 v86, v140
	v_mov_b32_e32 v87, v140
	v_mov_b32_e32 v92, v140
	v_mov_b32_e32 v93, v140
	v_mov_b32_e32 v94, v140
	v_mov_b32_e32 v95, v140
	v_mov_b32_e32 v96, v140
	v_mov_b32_e32 v97, v140
	v_mov_b32_e32 v98, v140
	v_mov_b32_e32 v99, v140
	v_mov_b32_e32 v108, v140
	v_mov_b32_e32 v109, v140
	v_mov_b32_e32 v110, v140
	v_mov_b32_e32 v111, v140
	v_mov_b32_e32 v120, v140
	v_mov_b32_e32 v121, v140
	v_mov_b32_e32 v122, v140
	v_mov_b32_e32 v123, v140
	v_mov_b32_e32 v124, v140
	v_mov_b32_e32 v125, v140
	v_mov_b32_e32 v126, v140
	v_mov_b32_e32 v127, v140
	v_mov_b32_e32 v128, v140
	v_mov_b32_e32 v129, v140
	v_mov_b32_e32 v130, v140
	v_mov_b32_e32 v131, v140
	v_mov_b32_e32 v132, v140
	v_mov_b32_e32 v133, v140
	v_mov_b32_e32 v134, v140
	v_mov_b32_e32 v135, v140
	v_mov_b32_e32 v136, v140
	v_mov_b32_e32 v137, v140
	v_mov_b32_e32 v138, v140
	v_mov_b32_e32 v139, v140
	v_mov_b32_e32 v144, v140
	v_mov_b32_e32 v145, v140
	v_mov_b32_e32 v146, v140
	v_mov_b32_e32 v147, v140
	v_mov_b32_e32 v148, v140
	v_mov_b32_e32 v149, v140
	v_mov_b32_e32 v150, v140
	v_mov_b32_e32 v151, v140
	v_mov_b32_e32 v152, v140
	v_mov_b32_e32 v153, v140
	v_mov_b32_e32 v154, v140
	v_mov_b32_e32 v155, v140
	v_mov_b32_e32 v156, v140
	v_mov_b32_e32 v157, v140
	v_mov_b32_e32 v158, v140
	v_mov_b32_e32 v159, v140
	v_mov_b32_e32 v160, v140
	v_mov_b32_e32 v161, v140
	v_mov_b32_e32 v162, v140
	v_mov_b32_e32 v163, v140
	v_mov_b32_e32 v164, v140
	v_mov_b32_e32 v165, v140
	v_mov_b32_e32 v166, v140
	v_mov_b32_e32 v167, v140
	v_mov_b32_e32 v168, v140
	v_mov_b32_e32 v169, v140
	v_mov_b32_e32 v170, v140
	v_mov_b32_e32 v171, v140
	v_mov_b32_e32 v172, v140
	v_mov_b32_e32 v173, v140
	v_mov_b32_e32 v174, v140
	v_mov_b32_e32 v175, v140
	s_mov_b32 s39, 0x820000
	s_mov_b32 s40, 0x830000
	v_readlane_b32 vcc_lo, v253, 0
	s_cmpk_lt_u32 vcc_lo, 0x100
	s_cbranch_scc1 .Lprio_hi8
	s_setprio 2
	s_branch .Lprio_done8

.Lprio_done8:
	v_readlane_b32 s98, v253, 3
	v_readlane_b32 s99, v253, 4
	v_and_b32_e32 v240, 15, v188
	v_bfe_u32 v241, v188, 4, 2
	v_lshrrev_b32_e32 v242, 2, v240
	v_sub_u32_e32 v242, 0, v242
	v_and_b32_e32 v242, 3, v242
	v_xor_b32_e32 v241, v241, v242
	v_lshlrev_b32_e32 v241, 4, v241
	v_lshl_or_b32 v241, v240, 6, v241
	v_bfe_u32 v242, v188, 7, 1
	v_lshl_or_b32 v185, v242, 13, v241
	v_bfe_u32 v242, v188, 6, 1
	v_lshl_or_b32 v184, v242, 12, v241
	v_add_u32_e32 v184, 0x4000, v184
	v_lshrrev_b32_e32 v240, 3, v188
	v_bfe_u32 v241, v188, 2, 1
	v_lshrrev_b32_e32 v242, 2, v240
	v_sub_u32_e32 v242, 0, v242
	v_and_b32_e32 v242, 3, v242
	v_and_b32_e32 v243, 3, v188
	v_xor_b32_e32 v242, v243, v242
	v_lshlrev_b32_e32 v242, 4, v242
	v_xor_b32_e32 v240, v240, v241
	v_lshl_or_b32 v242, v240, 6, v242
	v_mul_u32_u24_e32 v241, 0x6000, v241
	v_add_u32_e32 v183, v241, v242
	s_mov_b32 m0, 0
	s_sub_u32 vcc_lo, s30, s98
	v_add_u32_e32 v186, vcc_lo, v178
	v_add_u32_e32 v187, vcc_lo, v180
	s_barrier
	s_waitcnt vmcnt(0)
	ds_write_b128 v183, v[116:119]
	ds_write_b128 v183, v[112:115] offset:2048
	ds_write_b128 v183, v[104:107] offset:4096
	ds_write_b128 v183, v[88:91] offset:6144
	ds_write_b128 v183, v[80:83] offset:8192
	ds_write_b128 v183, v[68:71] offset:10240
	ds_write_b128 v183, v[60:63] offset:12288
	ds_write_b128 v183, v[48:51] offset:14336
	ds_write_b128 v183, v[100:103] offset:16384
	ds_write_b128 v183, v[40:43] offset:18432
	ds_write_b128 v183, v[24:27] offset:20480
	ds_write_b128 v183, v[20:23] offset:22528
	v_cmp_gt_u32_e32 vcc, 0x6000, v183
	v_add_u32_e32 v182, 0xc000, v183
	v_add_u32_e32 v183, 0xffffa000, v183
	s_nop 0
	v_cndmask_b32_e32 v183, v183, v182, vcc
	v_add_u32_e32 v116, s26, v186
	global_load_dwordx4 v[116:119], v116, s[98:99] offset:128
	v_add_u32_e32 v112, s27, v186
	global_load_dwordx4 v[112:115], v112, s[98:99] offset:128
	v_add_u32_e32 v104, s20, v186
	global_load_dwordx4 v[104:107], v104, s[98:99] offset:128
	v_add_u32_e32 v88, s21, v186
	global_load_dwordx4 v[88:91], v88, s[98:99] offset:128
	v_add_u32_e32 v80, s56, v186
	global_load_dwordx4 v[80:83], v80, s[98:99] offset:128
	v_add_u32_e32 v68, s57, v186
	global_load_dwordx4 v[68:71], v68, s[98:99] offset:128
	v_add_u32_e32 v60, s24, v186
	global_load_dwordx4 v[60:63], v60, s[98:99] offset:128
	v_add_u32_e32 v48, s96, v186
	global_load_dwordx4 v[48:51], v48, s[98:99] offset:128
	v_add_u32_e32 v100, s25, v187
	global_load_dwordx4 v[100:103], v100, s[98:99] offset:128
	v_add_u32_e32 v40, s33, v187
	global_load_dwordx4 v[40:43], v40, s[98:99] offset:128
	v_add_u32_e32 v24, s39, v187
	global_load_dwordx4 v[24:27], v24, s[98:99] offset:128
	v_add_u32_e32 v20, s40, v187
	global_load_dwordx4 v[20:23], v20, s[98:99] offset:128
	s_add_u32 s30, s30, 0x80
	s_addc_u32 s31, s31, 0
.LBB0_1070:
	s_waitcnt lgkmcnt(0)
	s_barrier
	ds_read_b128 v[240:243], v184
	ds_read_b128 v[244:247], v184 offset:1024
	ds_read_b128 v[248:251], v184 offset:2048
	ds_read_b128 v[204:207], v184 offset:3072
	ds_read_b128 v[208:211], v185
	ds_read_b128 v[212:215], v185 offset:1024
	ds_read_b128 v[216:219], v185 offset:2048
	ds_read_b128 v[220:223], v185 offset:3072
	ds_read_b128 v[224:227], v185 offset:4096
	ds_read_b128 v[228:231], v185 offset:5120
	ds_read_b128 v[232:235], v185 offset:6144
	ds_read_b128 v[236:239], v185 offset:7168
	s_movk_i32 vcc_lo, 0x6000
	s_cmp_eq_u32 m0, 2
	s_cselect_b32 vcc_lo, 0xffff4000, vcc_lo
	s_add_u32 m0, m0, 1
	s_cmp_eq_u32 m0, 3
	s_cselect_b32 m0, 0, m0
	v_add_u32_e32 v185, vcc_lo, v185
	v_add_u32_e32 v184, vcc_lo, v184
	v_xor_b32_e32 v185, 64, v185
	v_xor_b32_e32 v184, 64, v184
	s_waitcnt lgkmcnt(7)
	v_mfma_f32_16x16x32_bf16 v[172:175], v[208:211], v[240:243], v[172:175]
	v_mfma_f32_16x16x32_bf16 v[168:171], v[208:211], v[244:247], v[168:171]
	v_mfma_f32_16x16x32_bf16 v[164:167], v[208:211], v[248:251], v[164:167]
	v_mfma_f32_16x16x32_bf16 v[160:163], v[208:211], v[204:207], v[160:163]
	ds_read_b128 v[208:211], v185
	s_waitcnt lgkmcnt(7)
	v_mfma_f32_16x16x32_bf16 v[156:159], v[212:215], v[240:243], v[156:159]
	v_mfma_f32_16x16x32_bf16 v[152:155], v[212:215], v[244:247], v[152:155]
	v_mfma_f32_16x16x32_bf16 v[148:151], v[212:215], v[248:251], v[148:151]
	v_mfma_f32_16x16x32_bf16 v[144:147], v[212:215], v[204:207], v[144:147]
	ds_read_b128 v[212:215], v185 offset:1024
	s_waitcnt lgkmcnt(7)
	v_mfma_f32_16x16x32_bf16 v[136:139], v[216:219], v[240:243], v[136:139]
	v_mfma_f32_16x16x32_bf16 v[132:135], v[216:219], v[244:247], v[132:135]
	v_mfma_f32_16x16x32_bf16 v[128:131], v[216:219], v[248:251], v[128:131]
	v_mfma_f32_16x16x32_bf16 v[124:127], v[216:219], v[204:207], v[124:127]
	ds_read_b128 v[216:219], v185 offset:2048
	s_waitcnt lgkmcnt(7)
	v_mfma_f32_16x16x32_bf16 v[120:123], v[220:223], v[240:243], v[120:123]
	v_mfma_f32_16x16x32_bf16 v[108:111], v[220:223], v[244:247], v[108:111]
	v_mfma_f32_16x16x32_bf16 v[96:99], v[220:223], v[248:251], v[96:99]
	v_mfma_f32_16x16x32_bf16 v[92:95], v[220:223], v[204:207], v[92:95]
	ds_read_b128 v[220:223], v185 offset:3072
	s_waitcnt lgkmcnt(7)
	v_mfma_f32_16x16x32_bf16 v[84:87], v[224:227], v[240:243], v[84:87]
	v_mfma_f32_16x16x32_bf16 v[76:79], v[224:227], v[244:247], v[76:79]
	v_mfma_f32_16x16x32_bf16 v[72:75], v[224:227], v[248:251], v[72:75]
	v_mfma_f32_16x16x32_bf16 v[64:67], v[224:227], v[204:207], v[64:67]
	ds_read_b128 v[224:227], v185 offset:4096
	s_waitcnt lgkmcnt(7)
	v_mfma_f32_16x16x32_bf16 v[56:59], v[228:231], v[240:243], v[56:59]
	v_mfma_f32_16x16x32_bf16 v[52:55], v[228:231], v[244:247], v[52:55]
	v_mfma_f32_16x16x32_bf16 v[44:47], v[228:231], v[248:251], v[44:47]
	v_mfma_f32_16x16x32_bf16 v[36:39], v[228:231], v[204:207], v[36:39]
	ds_read_b128 v[228:231], v185 offset:5120
	s_waitcnt lgkmcnt(7)
	v_mfma_f32_16x16x32_bf16 v[32:35], v[232:235], v[240:243], v[32:35]
	v_mfma_f32_16x16x32_bf16 v[28:31], v[232:235], v[244:247], v[28:31]
	v_mfma_f32_16x16x32_bf16 v[16:19], v[232:235], v[248:251], v[16:19]
	v_mfma_f32_16x16x32_bf16 v[12:15], v[232:235], v[204:207], v[12:15]
	ds_read_b128 v[232:235], v185 offset:6144
	s_waitcnt lgkmcnt(7)
	v_mfma_f32_16x16x32_bf16 v[8:11], v[236:239], v[240:243], v[8:11]
	v_mfma_f32_16x16x32_bf16 v[4:7], v[236:239], v[244:247], v[4:7]
	v_mfma_f32_16x16x32_bf16 v[0:3], v[236:239], v[248:251], v[0:3]
	v_mfma_f32_16x16x32_bf16 v[140:143], v[236:239], v[204:207], v[140:143]
	ds_read_b128 v[236:239], v185 offset:7168
	ds_read_b128 v[240:243], v184
	ds_read_b128 v[244:247], v184 offset:1024
	ds_read_b128 v[248:251], v184 offset:2048
	ds_read_b128 v[204:207], v184 offset:3072
	s_movk_i32 vcc_lo, 0x6000
	s_cmp_eq_u32 m0, 2
	s_cselect_b32 vcc_lo, 0xffff4000, vcc_lo
	s_add_u32 m0, m0, 1
	s_cmp_eq_u32 m0, 3
	s_cselect_b32 m0, 0, m0
	v_add_u32_e32 v185, vcc_lo, v185
	v_add_u32_e32 v184, vcc_lo, v184
	v_xor_b32_e32 v185, 64, v185
	v_xor_b32_e32 v184, 64, v184
	s_sub_u32 vcc_lo, s30, s98
	v_add_u32_e32 v186, vcc_lo, v178
	v_add_u32_e32 v187, vcc_lo, v180
	s_barrier
	s_waitcnt lgkmcnt(0)
	v_mfma_f32_16x16x32_bf16 v[172:175], v[208:211], v[240:243], v[172:175]
	s_waitcnt vmcnt(11)
	v_mfma_f32_16x16x32_bf16 v[168:171], v[208:211], v[244:247], v[168:171]
	ds_write_b128 v183, v[116:119]
	v_add_u32_e32 v116, s26, v186
	v_mfma_f32_16x16x32_bf16 v[164:167], v[208:211], v[248:251], v[164:167]
	global_load_dwordx4 v[116:119], v116, s[98:99] offset:128
	v_mfma_f32_16x16x32_bf16 v[160:163], v[208:211], v[204:207], v[160:163]
	s_waitcnt vmcnt(11)
	ds_write_b128 v183, v[112:115] offset:2048
	v_mfma_f32_16x16x32_bf16 v[156:159], v[212:215], v[240:243], v[156:159]
	v_add_u32_e32 v112, s27, v186
	v_mfma_f32_16x16x32_bf16 v[152:155], v[212:215], v[244:247], v[152:155]
	global_load_dwordx4 v[112:115], v112, s[98:99] offset:128
	s_waitcnt vmcnt(11)
	v_mfma_f32_16x16x32_bf16 v[148:151], v[212:215], v[248:251], v[148:151]
	ds_write_b128 v183, v[104:107] offset:4096
	v_mfma_f32_16x16x32_bf16 v[144:147], v[212:215], v[204:207], v[144:147]
	v_add_u32_e32 v104, s20, v186
	global_load_dwordx4 v[104:107], v104, s[98:99] offset:128
	v_mfma_f32_16x16x32_bf16 v[136:139], v[216:219], v[240:243], v[136:139]
	s_waitcnt vmcnt(11)
	v_mfma_f32_16x16x32_bf16 v[132:135], v[216:219], v[244:247], v[132:135]
	ds_write_b128 v183, v[88:91] offset:6144
	v_add_u32_e32 v88, s21, v186
	v_mfma_f32_16x16x32_bf16 v[128:131], v[216:219], v[248:251], v[128:131]
	global_load_dwordx4 v[88:91], v88, s[98:99] offset:128
	v_mfma_f32_16x16x32_bf16 v[124:127], v[216:219], v[204:207], v[124:127]
	s_waitcnt vmcnt(11)
	ds_write_b128 v183, v[80:83] offset:8192
	v_mfma_f32_16x16x32_bf16 v[120:123], v[220:223], v[240:243], v[120:123]
	v_add_u32_e32 v80, s56, v186
	v_mfma_f32_16x16x32_bf16 v[108:111], v[220:223], v[244:247], v[108:111]
	global_load_dwordx4 v[80:83], v80, s[98:99] offset:128
	s_waitcnt vmcnt(11)
	v_mfma_f32_16x16x32_bf16 v[96:99], v[220:223], v[248:251], v[96:99]
	ds_write_b128 v183, v[68:71] offset:10240
	v_mfma_f32_16x16x32_bf16 v[92:95], v[220:223], v[204:207], v[92:95]
	v_add_u32_e32 v68, s57, v186
	global_load_dwordx4 v[68:71], v68, s[98:99] offset:128
	v_mfma_f32_16x16x32_bf16 v[84:87], v[224:227], v[240:243], v[84:87]
	s_waitcnt vmcnt(11)
	v_mfma_f32_16x16x32_bf16 v[76:79], v[224:227], v[244:247], v[76:79]
	ds_write_b128 v183, v[60:63] offset:12288
	v_add_u32_e32 v60, s24, v186
	v_mfma_f32_16x16x32_bf16 v[72:75], v[224:227], v[248:251], v[72:75]
	global_load_dwordx4 v[60:63], v60, s[98:99] offset:128
	v_mfma_f32_16x16x32_bf16 v[64:67], v[224:227], v[204:207], v[64:67]
	s_waitcnt vmcnt(11)
	ds_write_b128 v183, v[48:51] offset:14336
	v_mfma_f32_16x16x32_bf16 v[56:59], v[228:231], v[240:243], v[56:59]
	v_add_u32_e32 v48, s96, v186
	v_mfma_f32_16x16x32_bf16 v[52:55], v[228:231], v[244:247], v[52:55]
	global_load_dwordx4 v[48:51], v48, s[98:99] offset:128
	s_waitcnt vmcnt(11)
	v_mfma_f32_16x16x32_bf16 v[44:47], v[228:231], v[248:251], v[44:47]
	ds_write_b128 v183, v[100:103] offset:16384
	v_mfma_f32_16x16x32_bf16 v[36:39], v[228:231], v[204:207], v[36:39]
	v_add_u32_e32 v100, s25, v187
	global_load_dwordx4 v[100:103], v100, s[98:99] offset:128
	v_mfma_f32_16x16x32_bf16 v[32:35], v[232:235], v[240:243], v[32:35]
	s_waitcnt vmcnt(11)
	v_mfma_f32_16x16x32_bf16 v[28:31], v[232:235], v[244:247], v[28:31]
	ds_write_b128 v183, v[40:43] offset:18432
	v_add_u32_e32 v40, s33, v187
	v_mfma_f32_16x16x32_bf16 v[16:19], v[232:235], v[248:251], v[16:19]
	global_load_dwordx4 v[40:43], v40, s[98:99] offset:128
	v_mfma_f32_16x16x32_bf16 v[12:15], v[232:235], v[204:207], v[12:15]
	s_waitcnt vmcnt(11)
	ds_write_b128 v183, v[24:27] offset:20480
	v_mfma_f32_16x16x32_bf16 v[8:11], v[236:239], v[240:243], v[8:11]
	v_add_u32_e32 v24, s39, v187
	v_mfma_f32_16x16x32_bf16 v[4:7], v[236:239], v[244:247], v[4:7]
	global_load_dwordx4 v[24:27], v24, s[98:99] offset:128
	s_waitcnt vmcnt(11)
	v_mfma_f32_16x16x32_bf16 v[0:3], v[236:239], v[248:251], v[0:3]
	ds_write_b128 v183, v[20:23] offset:22528
	v_mfma_f32_16x16x32_bf16 v[140:143], v[236:239], v[204:207], v[140:143]
	v_add_u32_e32 v20, s40, v187
	global_load_dwordx4 v[20:23], v20, s[98:99] offset:128
	v_cmp_gt_u32_e32 vcc, 0x6000, v183
	v_add_u32_e32 v182, 0xc000, v183
	v_add_u32_e32 v183, 0xffffa000, v183
	s_nop 0
	v_cndmask_b32_e32 v183, v183, v182, vcc
	s_add_u32 s30, s30, 0x80
	s_addc_u32 s31, s31, 0
	s_cmpk_eq_i32 s30, 0x780
	s_cbranch_scc0 .LBB0_1070
	s_waitcnt lgkmcnt(0)
	s_barrier
	ds_read_b128 v[240:243], v184
	ds_read_b128 v[244:247], v184 offset:1024
	ds_read_b128 v[248:251], v184 offset:2048
	ds_read_b128 v[204:207], v184 offset:3072
	ds_read_b128 v[208:211], v185
	ds_read_b128 v[212:215], v185 offset:1024
	ds_read_b128 v[216:219], v185 offset:2048
	ds_read_b128 v[220:223], v185 offset:3072
	ds_read_b128 v[224:227], v185 offset:4096
	ds_read_b128 v[228:231], v185 offset:5120
	ds_read_b128 v[232:235], v185 offset:6144
	ds_read_b128 v[236:239], v185 offset:7168
	s_movk_i32 vcc_lo, 0x6000
	s_cmp_eq_u32 m0, 2
	s_cselect_b32 vcc_lo, 0xffff4000, vcc_lo
	s_add_u32 m0, m0, 1
	s_cmp_eq_u32 m0, 3
	s_cselect_b32 m0, 0, m0
	v_add_u32_e32 v185, vcc_lo, v185
	v_add_u32_e32 v184, vcc_lo, v184
	v_xor_b32_e32 v185, 64, v185
	v_xor_b32_e32 v184, 64, v184
	s_waitcnt lgkmcnt(7)
	v_mfma_f32_16x16x32_bf16 v[172:175], v[208:211], v[240:243], v[172:175]
	v_mfma_f32_16x16x32_bf16 v[168:171], v[208:211], v[244:247], v[168:171]
	v_mfma_f32_16x16x32_bf16 v[164:167], v[208:211], v[248:251], v[164:167]
	v_mfma_f32_16x16x32_bf16 v[160:163], v[208:211], v[204:207], v[160:163]
	ds_read_b128 v[208:211], v185
	s_waitcnt lgkmcnt(7)
	v_mfma_f32_16x16x32_bf16 v[156:159], v[212:215], v[240:243], v[156:159]
	v_mfma_f32_16x16x32_bf16 v[152:155], v[212:215], v[244:247], v[152:155]
	v_mfma_f32_16x16x32_bf16 v[148:151], v[212:215], v[248:251], v[148:151]
	v_mfma_f32_16x16x32_bf16 v[144:147], v[212:215], v[204:207], v[144:147]
	ds_read_b128 v[212:215], v185 offset:1024
	s_waitcnt lgkmcnt(7)
	v_mfma_f32_16x16x32_bf16 v[136:139], v[216:219], v[240:243], v[136:139]
	v_mfma_f32_16x16x32_bf16 v[132:135], v[216:219], v[244:247], v[132:135]
	v_mfma_f32_16x16x32_bf16 v[128:131], v[216:219], v[248:251], v[128:131]
	v_mfma_f32_16x16x32_bf16 v[124:127], v[216:219], v[204:207], v[124:127]
	ds_read_b128 v[216:219], v185 offset:2048
	s_waitcnt lgkmcnt(7)
	v_mfma_f32_16x16x32_bf16 v[120:123], v[220:223], v[240:243], v[120:123]
	v_mfma_f32_16x16x32_bf16 v[108:111], v[220:223], v[244:247], v[108:111]
	v_mfma_f32_16x16x32_bf16 v[96:99], v[220:223], v[248:251], v[96:99]
	v_mfma_f32_16x16x32_bf16 v[92:95], v[220:223], v[204:207], v[92:95]
	ds_read_b128 v[220:223], v185 offset:3072
	s_waitcnt lgkmcnt(7)
	v_mfma_f32_16x16x32_bf16 v[84:87], v[224:227], v[240:243], v[84:87]
	v_mfma_f32_16x16x32_bf16 v[76:79], v[224:227], v[244:247], v[76:79]
	v_mfma_f32_16x16x32_bf16 v[72:75], v[224:227], v[248:251], v[72:75]
	v_mfma_f32_16x16x32_bf16 v[64:67], v[224:227], v[204:207], v[64:67]
	ds_read_b128 v[224:227], v185 offset:4096
	s_waitcnt lgkmcnt(7)
	v_mfma_f32_16x16x32_bf16 v[56:59], v[228:231], v[240:243], v[56:59]
	v_mfma_f32_16x16x32_bf16 v[52:55], v[228:231], v[244:247], v[52:55]
	v_mfma_f32_16x16x32_bf16 v[44:47], v[228:231], v[248:251], v[44:47]
	v_mfma_f32_16x16x32_bf16 v[36:39], v[228:231], v[204:207], v[36:39]
	ds_read_b128 v[228:231], v185 offset:5120
	s_waitcnt lgkmcnt(7)
	v_mfma_f32_16x16x32_bf16 v[32:35], v[232:235], v[240:243], v[32:35]
	v_mfma_f32_16x16x32_bf16 v[28:31], v[232:235], v[244:247], v[28:31]
	v_mfma_f32_16x16x32_bf16 v[16:19], v[232:235], v[248:251], v[16:19]
	v_mfma_f32_16x16x32_bf16 v[12:15], v[232:235], v[204:207], v[12:15]
	ds_read_b128 v[232:235], v185 offset:6144
	s_waitcnt lgkmcnt(7)
	v_mfma_f32_16x16x32_bf16 v[8:11], v[236:239], v[240:243], v[8:11]
	v_mfma_f32_16x16x32_bf16 v[4:7], v[236:239], v[244:247], v[4:7]
	v_mfma_f32_16x16x32_bf16 v[0:3], v[236:239], v[248:251], v[0:3]
	v_mfma_f32_16x16x32_bf16 v[140:143], v[236:239], v[204:207], v[140:143]
	ds_read_b128 v[236:239], v185 offset:7168
	ds_read_b128 v[240:243], v184
	ds_read_b128 v[244:247], v184 offset:1024
	ds_read_b128 v[248:251], v184 offset:2048
	ds_read_b128 v[204:207], v184 offset:3072
	s_movk_i32 vcc_lo, 0x6000
	s_cmp_eq_u32 m0, 2
	s_cselect_b32 vcc_lo, 0xffff4000, vcc_lo
	s_add_u32 m0, m0, 1
	s_cmp_eq_u32 m0, 3
	s_cselect_b32 m0, 0, m0
	v_add_u32_e32 v185, vcc_lo, v185
	v_add_u32_e32 v184, vcc_lo, v184
	v_xor_b32_e32 v185, 64, v185
	v_xor_b32_e32 v184, 64, v184
	s_waitcnt lgkmcnt(0)
	v_mfma_f32_16x16x32_bf16 v[172:175], v[208:211], v[240:243], v[172:175]
	v_mfma_f32_16x16x32_bf16 v[168:171], v[208:211], v[244:247], v[168:171]
	v_mfma_f32_16x16x32_bf16 v[164:167], v[208:211], v[248:251], v[164:167]
	v_mfma_f32_16x16x32_bf16 v[160:163], v[208:211], v[204:207], v[160:163]
	v_mfma_f32_16x16x32_bf16 v[156:159], v[212:215], v[240:243], v[156:159]
	v_mfma_f32_16x16x32_bf16 v[152:155], v[212:215], v[244:247], v[152:155]
	v_mfma_f32_16x16x32_bf16 v[148:151], v[212:215], v[248:251], v[148:151]
	v_mfma_f32_16x16x32_bf16 v[144:147], v[212:215], v[204:207], v[144:147]
	v_mfma_f32_16x16x32_bf16 v[136:139], v[216:219], v[240:243], v[136:139]
	v_mfma_f32_16x16x32_bf16 v[132:135], v[216:219], v[244:247], v[132:135]
	v_mfma_f32_16x16x32_bf16 v[128:131], v[216:219], v[248:251], v[128:131]
	v_mfma_f32_16x16x32_bf16 v[124:127], v[216:219], v[204:207], v[124:127]
	v_mfma_f32_16x16x32_bf16 v[120:123], v[220:223], v[240:243], v[120:123]
	v_mfma_f32_16x16x32_bf16 v[108:111], v[220:223], v[244:247], v[108:111]
	v_mfma_f32_16x16x32_bf16 v[96:99], v[220:223], v[248:251], v[96:99]
	v_mfma_f32_16x16x32_bf16 v[92:95], v[220:223], v[204:207], v[92:95]
	v_mfma_f32_16x16x32_bf16 v[84:87], v[224:227], v[240:243], v[84:87]
	v_mfma_f32_16x16x32_bf16 v[76:79], v[224:227], v[244:247], v[76:79]
	v_mfma_f32_16x16x32_bf16 v[72:75], v[224:227], v[248:251], v[72:75]
	v_mfma_f32_16x16x32_bf16 v[64:67], v[224:227], v[204:207], v[64:67]
	v_mfma_f32_16x16x32_bf16 v[56:59], v[228:231], v[240:243], v[56:59]
	v_mfma_f32_16x16x32_bf16 v[52:55], v[228:231], v[244:247], v[52:55]
	v_mfma_f32_16x16x32_bf16 v[44:47], v[228:231], v[248:251], v[44:47]
	v_mfma_f32_16x16x32_bf16 v[36:39], v[228:231], v[204:207], v[36:39]
	v_mfma_f32_16x16x32_bf16 v[32:35], v[232:235], v[240:243], v[32:35]
	v_mfma_f32_16x16x32_bf16 v[28:31], v[232:235], v[244:247], v[28:31]
	v_mfma_f32_16x16x32_bf16 v[16:19], v[232:235], v[248:251], v[16:19]
	v_mfma_f32_16x16x32_bf16 v[12:15], v[232:235], v[204:207], v[12:15]
	v_mfma_f32_16x16x32_bf16 v[8:11], v[236:239], v[240:243], v[8:11]
	v_mfma_f32_16x16x32_bf16 v[4:7], v[236:239], v[244:247], v[4:7]
	v_mfma_f32_16x16x32_bf16 v[0:3], v[236:239], v[248:251], v[0:3]
	v_mfma_f32_16x16x32_bf16 v[140:143], v[236:239], v[204:207], v[140:143]
	v_lshrrev_b32_e32 v240, 4, v188
	v_and_b32_e32 v241, 7, v188
	v_bitop3_b32 v242, v240, v241, 3 bitop3:0x6c
	v_lshlrev_b32_e32 v243, 7, v188
	v_bfe_u32 v244, v188, 4, 2
	v_and_b32_e32 v245, 0xffffc780, v243
	v_and_b32_e32 v243, 0x2780, v243
	v_bitop3_b32 v244, v244, v241, 4 bitop3:0x36
	v_lshlrev_b32_e32 v242, 4, v242
	v_lshlrev_b32_e32 v244, 4, v244
	v_or_b32_e32 v185, v245, v242
	v_or_b32_e32 v184, v243, v242
	v_or_b32_e32 v183, v245, v244
	v_or_b32_e32 v182, v243, v244
	s_waitcnt vmcnt(0)
	s_setprio 1
	s_barrier
	s_waitcnt vmcnt(11)
	ds_write_b128 v176, v[116:119]
	s_waitcnt vmcnt(10)
	ds_write_b128 v176, v[112:115] offset:4096
	s_waitcnt vmcnt(9)
	ds_write_b128 v176, v[104:107] offset:8192
	s_waitcnt vmcnt(8)
	ds_write_b128 v176, v[88:91] offset:12288
	s_waitcnt vmcnt(7)
	ds_write_b128 v176, v[80:83] offset:16384
	s_waitcnt vmcnt(6)
	ds_write_b128 v176, v[68:71] offset:20480
	s_waitcnt vmcnt(5)
	ds_write_b128 v176, v[60:63] offset:24576
	s_waitcnt vmcnt(4)
	ds_write_b128 v176, v[48:51] offset:28672
	s_waitcnt vmcnt(3)
	ds_write_b128 v176, v[100:103] offset:32768
	s_waitcnt vmcnt(2)
	ds_write_b128 v176, v[40:43] offset:36864
	s_waitcnt vmcnt(1)
	ds_write_b128 v176, v[24:27] offset:40960
	s_waitcnt vmcnt(0)
	ds_write_b128 v176, v[20:23] offset:45056
	s_waitcnt lgkmcnt(0)
	s_barrier
	ds_read_b128 v[20:23], v185
	ds_read_b128 v[24:27], v185 offset:2048
	ds_read_b128 v[40:43], v185 offset:4096
	ds_read_b128 v[48:51], v185 offset:6144
	ds_read_b128 v[60:63], v185 offset:8192
	ds_read_b128 v[68:71], v185 offset:10240
	ds_read_b128 v[80:83], v185 offset:12288
	ds_read_b128 v[88:91], v185 offset:14336
	ds_read_b128 v[100:103], v184 offset:32768
	ds_read_b128 v[104:107], v184 offset:34816
	ds_read_b128 v[112:115], v184 offset:36864
	ds_read_b128 v[116:119], v184 offset:38912
	s_waitcnt lgkmcnt(3)
	v_mfma_f32_16x16x32_bf16 v[172:175], v[20:23], v[100:103], v[172:175]
	s_waitcnt lgkmcnt(2)
	v_mfma_f32_16x16x32_bf16 v[168:171], v[20:23], v[104:107], v[168:171]
	s_waitcnt lgkmcnt(1)
	v_mfma_f32_16x16x32_bf16 v[164:167], v[20:23], v[112:115], v[164:167]
	s_waitcnt lgkmcnt(0)
	v_mfma_f32_16x16x32_bf16 v[20:23], v[20:23], v[116:119], v[160:163]
	v_mfma_f32_16x16x32_bf16 v[156:159], v[24:27], v[100:103], v[156:159]
	v_mfma_f32_16x16x32_bf16 v[152:155], v[24:27], v[104:107], v[152:155]
	v_mfma_f32_16x16x32_bf16 v[148:151], v[24:27], v[112:115], v[148:151]
	v_mfma_f32_16x16x32_bf16 v[24:27], v[24:27], v[116:119], v[144:147]
	v_mfma_f32_16x16x32_bf16 v[136:139], v[40:43], v[100:103], v[136:139]
	v_mfma_f32_16x16x32_bf16 v[132:135], v[40:43], v[104:107], v[132:135]
	v_mfma_f32_16x16x32_bf16 v[128:131], v[40:43], v[112:115], v[128:131]
	v_mfma_f32_16x16x32_bf16 v[40:43], v[40:43], v[116:119], v[124:127]
	v_mfma_f32_16x16x32_bf16 v[144:147], v[48:51], v[100:103], v[120:123]
	v_mfma_f32_16x16x32_bf16 v[160:163], v[48:51], v[104:107], v[108:111]
	v_mfma_f32_16x16x32_bf16 v[178:181], v[48:51], v[112:115], v[96:99]
	v_mfma_f32_16x16x32_bf16 v[48:51], v[48:51], v[116:119], v[92:95]
	v_mfma_f32_16x16x32_bf16 v[184:187], v[60:63], v[100:103], v[84:87]
	v_mfma_f32_16x16x32_bf16 v[16:19], v[80:83], v[112:115], v[16:19]
	v_mfma_f32_16x16x32_bf16 v[12:15], v[80:83], v[116:119], v[12:15]
	v_mfma_f32_16x16x32_bf16 v[8:11], v[88:91], v[100:103], v[8:11]
	v_mfma_f32_16x16x32_bf16 v[4:7], v[88:91], v[104:107], v[4:7]
	v_mfma_f32_16x16x32_bf16 v[0:3], v[88:91], v[112:115], v[0:3]
	v_mfma_f32_16x16x32_bf16 v[204:207], v[60:63], v[104:107], v[76:79]
	v_mfma_f32_16x16x32_bf16 v[208:211], v[60:63], v[112:115], v[72:75]
	v_mfma_f32_16x16x32_bf16 v[212:215], v[60:63], v[116:119], v[64:67]
	v_mfma_f32_16x16x32_bf16 v[216:219], v[68:71], v[100:103], v[56:59]
	v_mfma_f32_16x16x32_bf16 v[220:223], v[68:71], v[104:107], v[52:55]
	v_mfma_f32_16x16x32_bf16 v[224:227], v[68:71], v[112:115], v[44:47]
	v_mfma_f32_16x16x32_bf16 v[228:231], v[68:71], v[116:119], v[36:39]
	v_mfma_f32_16x16x32_bf16 v[232:235], v[80:83], v[100:103], v[32:35]
	v_mfma_f32_16x16x32_bf16 v[236:239], v[80:83], v[104:107], v[28:31]
	v_mfma_f32_16x16x32_bf16 v[140:143], v[88:91], v[116:119], v[140:143]
	s_nop 1
	ds_read_b128 v[28:31], v183
	ds_read_b128 v[32:35], v183 offset:2048
	ds_read_b128 v[36:39], v183 offset:4096
	ds_read_b128 v[44:47], v183 offset:6144
	ds_read_b128 v[240:243], v183 offset:8192
	ds_read_b128 v[244:247], v183 offset:10240
	ds_read_b128 v[248:251], v183 offset:12288
	ds_read_b128 v[190:193], v183 offset:14336
	ds_read_b128 v[198:201], v182 offset:32768
	ds_read_b128 v[194:197], v182 offset:34816
	ds_read_b128 v[52:55], v182 offset:36864
	ds_read_b128 v[56:59], v182 offset:38912
	s_waitcnt lgkmcnt(3)
	v_mfma_f32_16x16x32_bf16 v[124:127], v[28:31], v[198:201], v[172:175]
	s_waitcnt lgkmcnt(2)
	v_mfma_f32_16x16x32_bf16 v[120:123], v[28:31], v[194:197], v[168:171]
	s_waitcnt lgkmcnt(1)
	v_mfma_f32_16x16x32_bf16 v[116:119], v[28:31], v[52:55], v[164:167]
	s_waitcnt lgkmcnt(0)
	v_mfma_f32_16x16x32_bf16 v[112:115], v[28:31], v[56:59], v[20:23]
	v_mfma_f32_16x16x32_bf16 v[108:111], v[32:35], v[198:201], v[156:159]
	v_mfma_f32_16x16x32_bf16 v[104:107], v[32:35], v[194:197], v[152:155]
	v_mfma_f32_16x16x32_bf16 v[100:103], v[32:35], v[52:55], v[148:151]
	v_mfma_f32_16x16x32_bf16 v[96:99], v[32:35], v[56:59], v[24:27]
	v_mfma_f32_16x16x32_bf16 v[92:95], v[36:39], v[198:201], v[136:139]
	v_mfma_f32_16x16x32_bf16 v[88:91], v[36:39], v[194:197], v[132:135]
	v_mfma_f32_16x16x32_bf16 v[84:87], v[36:39], v[52:55], v[128:131]
	v_mfma_f32_16x16x32_bf16 v[80:83], v[36:39], v[56:59], v[40:43]
	v_mfma_f32_16x16x32_bf16 v[76:79], v[44:47], v[198:201], v[144:147]
	v_mfma_f32_16x16x32_bf16 v[72:75], v[44:47], v[194:197], v[160:163]
	v_mfma_f32_16x16x32_bf16 v[68:71], v[44:47], v[52:55], v[178:181]
	v_mfma_f32_16x16x32_bf16 v[64:67], v[44:47], v[56:59], v[48:51]
	v_mfma_f32_16x16x32_bf16 v[60:63], v[240:243], v[198:201], v[184:187]
	v_mfma_f32_16x16x32_bf16 v[184:187], v[240:243], v[194:197], v[204:207]
	v_mfma_f32_16x16x32_bf16 v[180:183], v[240:243], v[52:55], v[208:211]
	v_mfma_f32_16x16x32_bf16 v[48:51], v[240:243], v[56:59], v[212:215]
	v_xor_b32_e32 v240, 32, v203
	v_mfma_f32_16x16x32_bf16 v[44:47], v[244:247], v[198:201], v[216:219]
	v_mfma_f32_16x16x32_bf16 v[40:43], v[244:247], v[194:197], v[220:223]
	v_mfma_f32_16x16x32_bf16 v[36:39], v[244:247], v[52:55], v[224:227]
	v_mfma_f32_16x16x32_bf16 v[32:35], v[244:247], v[56:59], v[228:231]
	v_mfma_f32_16x16x32_bf16 v[28:31], v[248:251], v[198:201], v[232:235]
	v_mfma_f32_16x16x32_bf16 v[24:27], v[248:251], v[194:197], v[236:239]
	v_mfma_f32_16x16x32_bf16 v[20:23], v[248:251], v[52:55], v[16:19]
	v_mfma_f32_16x16x32_bf16 v[16:19], v[248:251], v[56:59], v[12:15]
	v_mfma_f32_16x16x32_bf16 v[12:15], v[190:193], v[198:201], v[8:11]
	v_mfma_f32_16x16x32_bf16 v[8:11], v[190:193], v[194:197], v[4:7]
	v_mfma_f32_16x16x32_bf16 v[4:7], v[190:193], v[52:55], v[0:3]
	v_mfma_f32_16x16x32_bf16 v[0:3], v[190:193], v[56:59], v[140:143]

.LBB0_1441:
	s_setprio 0
	s_waitcnt vmcnt(0)
	s_waitcnt vmcnt(63) expcnt(7) lgkmcnt(15)
	s_barrier
	s_mov_b64 s[0:1], exec
	v_readlane_b32 s2, v253, 5
	v_readlane_b32 s3, v253, 6
	s_and_b64 s[2:3], s[0:1], s[2:3]
	s_mov_b64 exec, s[2:3]
	s_cbranch_execnz .LBB0_1442
	s_getpc_b64 s[98:99]
